# GEMM K-loops: snake order inside each group of 8 independent MFMAs (consecutive MFMAs share an operand register)
# speedup vs baseline: 1.0027x; 1.0027x over previous
.Lpk354_peel:
	ds_read_b128 v[166:169], v139
	ds_read_b128 v[170:173], v139 offset:1024
	ds_read_b128 v[178:181], v139 offset:2048
	ds_read_b128 v[182:185], v139 offset:3072
	ds_read_b128 v[186:189], v164
	ds_read_b128 v[190:193], v164 offset:1024
	ds_read_b128 v[194:197], v164 offset:2048
	ds_read_b128 v[198:201], v164 offset:3072
	s_add_u32 s2, s26, 0xfffc0080
	s_addc_u32 s3, s27, -1
	s_cmp_eq_u32 s52, 12
	s_cselect_b32 s3, s11, s3
	s_cselect_b32 s2, s13, s2
	s_cselect_b32 s29, s44, s47
	s_cselect_b32 s28, s45, s46
	v_lshl_add_u64 v[148:149], s[26:27], 0, v[142:143]
	s_add_i32 m0, s34, 0xc000
	ds_read_b128 v[202:205], v165
	ds_read_b128 v[206:209], v165 offset:1024
	ds_read_b128 v[210:213], v165 offset:2048
	ds_read_b128 v[214:217], v165 offset:3072
	ds_read_b128 v[218:221], v165 offset:4096
	ds_read_b128 v[222:225], v165 offset:5120
	ds_read_b128 v[226:229], v165 offset:6144
	ds_read_b128 v[230:233], v165 offset:7168
	global_load_lds_dwordx4 v[148:149], off
	v_lshl_add_u64 v[148:149], s[26:27], 0, v[144:145]
	s_add_i32 m0, s34, 0xe000
	s_nop 0
	global_load_lds_dwordx4 v[148:149], off
	s_waitcnt vmcnt(8)
	s_waitcnt lgkmcnt(0)
	s_barrier
	s_setprio 1
	s_waitcnt lgkmcnt(0)
	v_mfma_f32_16x16x32_bf16 v[126:129], v[166:169], v[202:205], 0
	v_mfma_f32_16x16x32_bf16 v[122:125], v[178:181], v[202:205], 0
	v_mfma_f32_16x16x32_bf16 v[106:109], v[178:181], v[210:213], 0
	v_mfma_f32_16x16x32_bf16 v[110:113], v[166:169], v[210:213], 0
	v_mfma_f32_16x16x32_bf16 v[94:97], v[166:169], v[218:221], 0
	v_mfma_f32_16x16x32_bf16 v[90:93], v[178:181], v[218:221], 0
	v_mfma_f32_16x16x32_bf16 v[74:77], v[178:181], v[226:229], 0
	v_mfma_f32_16x16x32_bf16 v[78:81], v[166:169], v[226:229], 0
	v_mfma_f32_16x16x32_bf16 v[126:129], v[170:173], v[206:209], v[126:129]
	v_mfma_f32_16x16x32_bf16 v[122:125], v[182:185], v[206:209], v[122:125]
	v_mfma_f32_16x16x32_bf16 v[106:109], v[182:185], v[214:217], v[106:109]
	v_mfma_f32_16x16x32_bf16 v[110:113], v[170:173], v[214:217], v[110:113]
	v_mfma_f32_16x16x32_bf16 v[94:97], v[170:173], v[222:225], v[94:97]
	v_mfma_f32_16x16x32_bf16 v[90:93], v[182:185], v[222:225], v[90:93]
	v_mfma_f32_16x16x32_bf16 v[74:77], v[182:185], v[230:233], v[74:77]
	v_mfma_f32_16x16x32_bf16 v[78:81], v[170:173], v[230:233], v[78:81]
	s_setprio 0
	s_setprio 1
	v_mfma_f32_16x16x32_bf16 v[118:121], v[186:189], v[202:205], 0
	v_mfma_f32_16x16x32_bf16 v[114:117], v[194:197], v[202:205], 0
	v_mfma_f32_16x16x32_bf16 v[98:101], v[194:197], v[210:213], 0
	v_mfma_f32_16x16x32_bf16 v[102:105], v[186:189], v[210:213], 0
	v_mfma_f32_16x16x32_bf16 v[86:89], v[186:189], v[218:221], 0
	v_mfma_f32_16x16x32_bf16 v[82:85], v[194:197], v[218:221], 0
	v_mfma_f32_16x16x32_bf16 v[66:69], v[194:197], v[226:229], 0
	v_mfma_f32_16x16x32_bf16 v[70:73], v[186:189], v[226:229], 0
	v_mfma_f32_16x16x32_bf16 v[118:121], v[190:193], v[206:209], v[118:121]
	v_mfma_f32_16x16x32_bf16 v[114:117], v[198:201], v[206:209], v[114:117]
	v_mfma_f32_16x16x32_bf16 v[98:101], v[198:201], v[214:217], v[98:101]
	v_mfma_f32_16x16x32_bf16 v[102:105], v[190:193], v[214:217], v[102:105]
	v_mfma_f32_16x16x32_bf16 v[86:89], v[190:193], v[222:225], v[86:89]
	v_mfma_f32_16x16x32_bf16 v[82:85], v[198:201], v[222:225], v[82:85]
	v_mfma_f32_16x16x32_bf16 v[66:69], v[198:201], v[230:233], v[66:69]
	v_mfma_f32_16x16x32_bf16 v[70:73], v[190:193], v[230:233], v[70:73]
	s_setprio 0
	s_barrier
	s_add_i32 s53, s41, s30
	v_lshl_add_u64 v[148:149], s[28:29], 0, v[132:133]
	s_mov_b32 m0, s53
	ds_read_b128 v[202:205], v165 offset:16384
	ds_read_b128 v[206:209], v165 offset:17408
	ds_read_b128 v[210:213], v165 offset:18432
	ds_read_b128 v[214:217], v165 offset:19456
	ds_read_b128 v[218:221], v165 offset:20480
	ds_read_b128 v[222:225], v165 offset:21504
	ds_read_b128 v[226:229], v165 offset:22528
	ds_read_b128 v[230:233], v165 offset:23552
	global_load_lds_dwordx4 v[148:149], off
	s_add_i32 m0, s53, 0x2000
	s_add_u32 s54, s28, 0x40000
	v_lshl_add_u64 v[174:175], s[28:29], 0, v[136:137]
	s_addc_u32 s55, s29, 0
	s_add_i32 s53, s42, s30
	global_load_lds_dwordx4 v[174:175], off
	v_lshl_add_u64 v[234:235], s[54:55], 0, v[132:133]
	s_mov_b32 m0, s53
	v_lshl_add_u64 v[236:237], s[2:3], 0, v[134:135]
	global_load_lds_dwordx4 v[234:235], off
	v_lshl_add_u64 v[234:235], s[54:55], 0, v[136:137]
	s_add_i32 m0, s53, 0x2000
	s_nop 0
	global_load_lds_dwordx4 v[234:235], off
	v_lshl_add_u64 v[234:235], s[2:3], 0, v[130:131]
	s_mov_b32 m0, s34
	s_nop 0
	global_load_lds_dwordx4 v[234:235], off
	s_mov_b32 m0, s25
	s_nop 0
	global_load_lds_dwordx4 v[236:237], off
	s_waitcnt vmcnt(8)
	s_waitcnt lgkmcnt(0)
	s_barrier
	s_setprio 1
	s_waitcnt lgkmcnt(0)
	v_mfma_f32_16x16x32_bf16 v[62:65], v[166:169], v[202:205], 0
	v_mfma_f32_16x16x32_bf16 v[58:61], v[178:181], v[202:205], 0
	v_mfma_f32_16x16x32_bf16 v[42:45], v[178:181], v[210:213], 0
	v_mfma_f32_16x16x32_bf16 v[46:49], v[166:169], v[210:213], 0
	v_mfma_f32_16x16x32_bf16 v[30:33], v[166:169], v[218:221], 0
	v_mfma_f32_16x16x32_bf16 v[26:29], v[178:181], v[218:221], 0
	v_mfma_f32_16x16x32_bf16 v[10:13], v[178:181], v[226:229], 0
	v_mfma_f32_16x16x32_bf16 v[14:17], v[166:169], v[226:229], 0
	v_mfma_f32_16x16x32_bf16 v[62:65], v[170:173], v[206:209], v[62:65]
	v_mfma_f32_16x16x32_bf16 v[58:61], v[182:185], v[206:209], v[58:61]
	v_mfma_f32_16x16x32_bf16 v[42:45], v[182:185], v[214:217], v[42:45]
	v_mfma_f32_16x16x32_bf16 v[46:49], v[170:173], v[214:217], v[46:49]
	v_mfma_f32_16x16x32_bf16 v[30:33], v[170:173], v[222:225], v[30:33]
	v_mfma_f32_16x16x32_bf16 v[26:29], v[182:185], v[222:225], v[26:29]
	v_mfma_f32_16x16x32_bf16 v[10:13], v[182:185], v[230:233], v[10:13]
	v_mfma_f32_16x16x32_bf16 v[14:17], v[170:173], v[230:233], v[14:17]
	s_setprio 0
	s_setprio 1
	v_mfma_f32_16x16x32_bf16 v[54:57], v[186:189], v[202:205], 0
	v_mfma_f32_16x16x32_bf16 v[50:53], v[194:197], v[202:205], 0
	v_mfma_f32_16x16x32_bf16 v[34:37], v[194:197], v[210:213], 0
	v_mfma_f32_16x16x32_bf16 v[38:41], v[186:189], v[210:213], 0
	v_mfma_f32_16x16x32_bf16 v[22:25], v[186:189], v[218:221], 0
	v_mfma_f32_16x16x32_bf16 v[18:21], v[194:197], v[218:221], 0
	v_mfma_f32_16x16x32_bf16 v[2:5], v[194:197], v[226:229], 0
	v_mfma_f32_16x16x32_bf16 v[6:9], v[186:189], v[226:229], 0
	v_mfma_f32_16x16x32_bf16 v[54:57], v[190:193], v[206:209], v[54:57]
	v_mfma_f32_16x16x32_bf16 v[50:53], v[198:201], v[206:209], v[50:53]
	v_mfma_f32_16x16x32_bf16 v[34:37], v[198:201], v[214:217], v[34:37]
	v_mfma_f32_16x16x32_bf16 v[38:41], v[190:193], v[214:217], v[38:41]
	v_mfma_f32_16x16x32_bf16 v[22:25], v[190:193], v[222:225], v[22:25]
	v_mfma_f32_16x16x32_bf16 v[18:21], v[198:201], v[222:225], v[18:21]
	v_mfma_f32_16x16x32_bf16 v[2:5], v[198:201], v[230:233], v[2:5]
	v_mfma_f32_16x16x32_bf16 v[6:9], v[190:193], v[230:233], v[6:9]
	s_setprio 0
	s_barrier
	s_add_i32 s53, 0, 0x18000
	v_add_u32_e32 v176, s53, v163
	s_add_i32 s54, 0, 0x1c000
	ds_read_b128 v[166:169], v176
	ds_read_b128 v[170:173], v176 offset:1024
	ds_read_b128 v[178:181], v176 offset:2048
	ds_read_b128 v[182:185], v176 offset:3072
	v_add_u32_e32 v176, s54, v163
	ds_read_b128 v[186:189], v176
	ds_read_b128 v[190:193], v176 offset:1024
	ds_read_b128 v[194:197], v176 offset:2048
	ds_read_b128 v[198:201], v176 offset:3072
	s_add_u32 s2, s2, 0x40000
	s_addc_u32 s3, s3, 0
	s_mov_b32 m0, s35
	v_lshl_add_u64 v[238:239], s[2:3], 0, v[130:131]
	ds_read_b128 v[202:205], v165 offset:32768
	ds_read_b128 v[206:209], v165 offset:33792
	ds_read_b128 v[210:213], v165 offset:34816
	ds_read_b128 v[214:217], v165 offset:35840
	ds_read_b128 v[218:221], v165 offset:36864
	ds_read_b128 v[222:225], v165 offset:37888
	ds_read_b128 v[226:229], v165 offset:38912
	ds_read_b128 v[230:233], v165 offset:39936
	global_load_lds_dwordx4 v[238:239], off
	v_lshl_add_u64 v[238:239], s[2:3], 0, v[134:135]
	s_mov_b32 m0, s36
	s_nop 0
	global_load_lds_dwordx4 v[238:239], off
	s_waitcnt vmcnt(8)
	s_waitcnt lgkmcnt(0)
	s_barrier
	s_setprio 1
	s_waitcnt lgkmcnt(0)
	v_mfma_f32_16x16x32_bf16 v[126:129], v[166:169], v[202:205], v[126:129]
	v_mfma_f32_16x16x32_bf16 v[122:125], v[178:181], v[202:205], v[122:125]
	v_mfma_f32_16x16x32_bf16 v[106:109], v[178:181], v[210:213], v[106:109]
	v_mfma_f32_16x16x32_bf16 v[110:113], v[166:169], v[210:213], v[110:113]
	v_mfma_f32_16x16x32_bf16 v[94:97], v[166:169], v[218:221], v[94:97]
	v_mfma_f32_16x16x32_bf16 v[90:93], v[178:181], v[218:221], v[90:93]
	v_mfma_f32_16x16x32_bf16 v[74:77], v[178:181], v[226:229], v[74:77]
	v_mfma_f32_16x16x32_bf16 v[78:81], v[166:169], v[226:229], v[78:81]
	v_mfma_f32_16x16x32_bf16 v[126:129], v[170:173], v[206:209], v[126:129]
	v_mfma_f32_16x16x32_bf16 v[122:125], v[182:185], v[206:209], v[122:125]
	v_mfma_f32_16x16x32_bf16 v[106:109], v[182:185], v[214:217], v[106:109]
	v_mfma_f32_16x16x32_bf16 v[110:113], v[170:173], v[214:217], v[110:113]
	v_mfma_f32_16x16x32_bf16 v[94:97], v[170:173], v[222:225], v[94:97]
	v_mfma_f32_16x16x32_bf16 v[90:93], v[182:185], v[222:225], v[90:93]
	v_mfma_f32_16x16x32_bf16 v[74:77], v[182:185], v[230:233], v[74:77]
	v_mfma_f32_16x16x32_bf16 v[78:81], v[170:173], v[230:233], v[78:81]
	s_setprio 0
	s_setprio 1
	v_mfma_f32_16x16x32_bf16 v[118:121], v[186:189], v[202:205], v[118:121]
	v_mfma_f32_16x16x32_bf16 v[114:117], v[194:197], v[202:205], v[114:117]
	v_mfma_f32_16x16x32_bf16 v[98:101], v[194:197], v[210:213], v[98:101]
	v_mfma_f32_16x16x32_bf16 v[102:105], v[186:189], v[210:213], v[102:105]
	v_mfma_f32_16x16x32_bf16 v[86:89], v[186:189], v[218:221], v[86:89]
	v_mfma_f32_16x16x32_bf16 v[82:85], v[194:197], v[218:221], v[82:85]
	v_mfma_f32_16x16x32_bf16 v[66:69], v[194:197], v[226:229], v[66:69]
	v_mfma_f32_16x16x32_bf16 v[70:73], v[186:189], v[226:229], v[70:73]
	v_mfma_f32_16x16x32_bf16 v[118:121], v[190:193], v[206:209], v[118:121]
	v_mfma_f32_16x16x32_bf16 v[114:117], v[198:201], v[206:209], v[114:117]
	v_mfma_f32_16x16x32_bf16 v[98:101], v[198:201], v[214:217], v[98:101]
	v_mfma_f32_16x16x32_bf16 v[102:105], v[190:193], v[214:217], v[102:105]
	v_mfma_f32_16x16x32_bf16 v[86:89], v[190:193], v[222:225], v[86:89]
	v_mfma_f32_16x16x32_bf16 v[82:85], v[198:201], v[222:225], v[82:85]
	v_mfma_f32_16x16x32_bf16 v[66:69], v[198:201], v[230:233], v[66:69]
	v_mfma_f32_16x16x32_bf16 v[70:73], v[190:193], v[230:233], v[70:73]
	s_setprio 0
	s_barrier
	s_add_i32 s2, s53, s30
	v_lshl_add_u64 v[148:149], v[148:149], 0, s[6:7]
	s_mov_b32 m0, s2
	ds_read_b128 v[202:205], v165 offset:49152
	ds_read_b128 v[206:209], v165 offset:50176
	ds_read_b128 v[210:213], v165 offset:51200
	ds_read_b128 v[214:217], v165 offset:52224
	ds_read_b128 v[218:221], v165 offset:53248
	ds_read_b128 v[222:225], v165 offset:54272
	ds_read_b128 v[226:229], v165 offset:55296
	ds_read_b128 v[230:233], v165 offset:56320
	global_load_lds_dwordx4 v[148:149], off
	s_add_i32 m0, s2, 0x2000
	s_add_u32 s2, s28, 0x40080
	v_lshl_add_u64 v[148:149], v[174:175], 0, s[6:7]
	s_addc_u32 s3, s29, 0
	s_add_i32 s28, s54, s30
	global_load_lds_dwordx4 v[148:149], off
	v_lshl_add_u64 v[148:149], s[2:3], 0, v[132:133]
	s_mov_b32 m0, s28
	s_nop 0
	global_load_lds_dwordx4 v[148:149], off
	v_lshl_add_u64 v[148:149], s[2:3], 0, v[136:137]
	s_add_i32 m0, s28, 0x2000
	s_nop 0
	global_load_lds_dwordx4 v[148:149], off
	v_lshl_add_u64 v[148:149], v[234:235], 0, s[6:7]
	s_mov_b32 m0, s38
	s_nop 0
	global_load_lds_dwordx4 v[148:149], off
	v_lshl_add_u64 v[148:149], v[236:237], 0, s[6:7]
	s_mov_b32 m0, s39
	s_nop 0
	global_load_lds_dwordx4 v[148:149], off
	s_waitcnt vmcnt(8)
	s_waitcnt lgkmcnt(0)
	s_barrier
	s_setprio 1
	s_waitcnt lgkmcnt(0)
	v_mfma_f32_16x16x32_bf16 v[62:65], v[166:169], v[202:205], v[62:65]
	v_mfma_f32_16x16x32_bf16 v[58:61], v[178:181], v[202:205], v[58:61]
	v_mfma_f32_16x16x32_bf16 v[42:45], v[178:181], v[210:213], v[42:45]
	v_mfma_f32_16x16x32_bf16 v[46:49], v[166:169], v[210:213], v[46:49]
	v_mfma_f32_16x16x32_bf16 v[30:33], v[166:169], v[218:221], v[30:33]
	v_mfma_f32_16x16x32_bf16 v[26:29], v[178:181], v[218:221], v[26:29]
	v_mfma_f32_16x16x32_bf16 v[10:13], v[178:181], v[226:229], v[10:13]
	v_mfma_f32_16x16x32_bf16 v[14:17], v[166:169], v[226:229], v[14:17]
	v_mfma_f32_16x16x32_bf16 v[62:65], v[170:173], v[206:209], v[62:65]
	v_mfma_f32_16x16x32_bf16 v[58:61], v[182:185], v[206:209], v[58:61]
	v_mfma_f32_16x16x32_bf16 v[42:45], v[182:185], v[214:217], v[42:45]
	v_mfma_f32_16x16x32_bf16 v[46:49], v[170:173], v[214:217], v[46:49]
	v_mfma_f32_16x16x32_bf16 v[30:33], v[170:173], v[222:225], v[30:33]
	v_mfma_f32_16x16x32_bf16 v[26:29], v[182:185], v[222:225], v[26:29]
	v_mfma_f32_16x16x32_bf16 v[10:13], v[182:185], v[230:233], v[10:13]
	v_mfma_f32_16x16x32_bf16 v[14:17], v[170:173], v[230:233], v[14:17]
	s_setprio 0
	s_setprio 1
	v_mfma_f32_16x16x32_bf16 v[54:57], v[186:189], v[202:205], v[54:57]
	v_mfma_f32_16x16x32_bf16 v[50:53], v[194:197], v[202:205], v[50:53]
	v_mfma_f32_16x16x32_bf16 v[34:37], v[194:197], v[210:213], v[34:37]
	v_mfma_f32_16x16x32_bf16 v[38:41], v[186:189], v[210:213], v[38:41]
	v_mfma_f32_16x16x32_bf16 v[22:25], v[186:189], v[218:221], v[22:25]
	v_mfma_f32_16x16x32_bf16 v[18:21], v[194:197], v[218:221], v[18:21]
	v_mfma_f32_16x16x32_bf16 v[2:5], v[194:197], v[226:229], v[2:5]
	v_mfma_f32_16x16x32_bf16 v[6:9], v[186:189], v[226:229], v[6:9]
	v_mfma_f32_16x16x32_bf16 v[54:57], v[190:193], v[206:209], v[54:57]
	v_mfma_f32_16x16x32_bf16 v[50:53], v[198:201], v[206:209], v[50:53]
	v_mfma_f32_16x16x32_bf16 v[34:37], v[198:201], v[214:217], v[34:37]
	v_mfma_f32_16x16x32_bf16 v[38:41], v[190:193], v[214:217], v[38:41]
	v_mfma_f32_16x16x32_bf16 v[22:25], v[190:193], v[222:225], v[22:25]
	v_mfma_f32_16x16x32_bf16 v[18:21], v[198:201], v[222:225], v[18:21]
	v_mfma_f32_16x16x32_bf16 v[2:5], v[198:201], v[230:233], v[2:5]
	v_mfma_f32_16x16x32_bf16 v[6:9], v[190:193], v[230:233], v[6:9]
	s_setprio 0
	s_barrier
	s_add_i32 s52, s52, 2
	s_add_u32 s26, s26, 0x100
	s_addc_u32 s27, s27, 0
	s_add_u32 s46, s46, 0x100
	s_addc_u32 s47, s47, 0
	s_cmp_gt_u32 s52, 13
	s_cbranch_scc0 .LBB0_354
	s_branch .Lpk354_exit
.LBB0_354:
	ds_read_b128 v[166:169], v139
	ds_read_b128 v[170:173], v139 offset:1024
	ds_read_b128 v[178:181], v139 offset:2048
	ds_read_b128 v[182:185], v139 offset:3072
	ds_read_b128 v[186:189], v164
	ds_read_b128 v[190:193], v164 offset:1024
	ds_read_b128 v[194:197], v164 offset:2048
	ds_read_b128 v[198:201], v164 offset:3072
	s_add_u32 s2, s26, 0xfffc0080
	s_addc_u32 s3, s27, -1
	s_cmp_eq_u32 s52, 12
	s_cselect_b32 s3, s11, s3
	s_cselect_b32 s2, s13, s2
	s_cselect_b32 s29, s44, s47
	s_cselect_b32 s28, s45, s46
	v_lshl_add_u64 v[148:149], s[26:27], 0, v[142:143]
	s_add_i32 m0, s34, 0xc000
	ds_read_b128 v[202:205], v165
	ds_read_b128 v[206:209], v165 offset:1024
	ds_read_b128 v[210:213], v165 offset:2048
	ds_read_b128 v[214:217], v165 offset:3072
	ds_read_b128 v[218:221], v165 offset:4096
	ds_read_b128 v[222:225], v165 offset:5120
	ds_read_b128 v[226:229], v165 offset:6144
	ds_read_b128 v[230:233], v165 offset:7168
	global_load_lds_dwordx4 v[148:149], off
	v_lshl_add_u64 v[148:149], s[26:27], 0, v[144:145]
	s_add_i32 m0, s34, 0xe000
	s_nop 0
	global_load_lds_dwordx4 v[148:149], off
	s_waitcnt vmcnt(8)
	s_waitcnt lgkmcnt(0)
	s_barrier
	s_setprio 1
	s_waitcnt lgkmcnt(0)
	v_mfma_f32_16x16x32_bf16 v[126:129], v[166:169], v[202:205], v[126:129]
	v_mfma_f32_16x16x32_bf16 v[122:125], v[178:181], v[202:205], v[122:125]
	v_mfma_f32_16x16x32_bf16 v[106:109], v[178:181], v[210:213], v[106:109]
	v_mfma_f32_16x16x32_bf16 v[110:113], v[166:169], v[210:213], v[110:113]
	v_mfma_f32_16x16x32_bf16 v[94:97], v[166:169], v[218:221], v[94:97]
	v_mfma_f32_16x16x32_bf16 v[90:93], v[178:181], v[218:221], v[90:93]
	v_mfma_f32_16x16x32_bf16 v[74:77], v[178:181], v[226:229], v[74:77]
	v_mfma_f32_16x16x32_bf16 v[78:81], v[166:169], v[226:229], v[78:81]
	v_mfma_f32_16x16x32_bf16 v[126:129], v[170:173], v[206:209], v[126:129]
	v_mfma_f32_16x16x32_bf16 v[122:125], v[182:185], v[206:209], v[122:125]
	v_mfma_f32_16x16x32_bf16 v[106:109], v[182:185], v[214:217], v[106:109]
	v_mfma_f32_16x16x32_bf16 v[110:113], v[170:173], v[214:217], v[110:113]
	v_mfma_f32_16x16x32_bf16 v[94:97], v[170:173], v[222:225], v[94:97]
	v_mfma_f32_16x16x32_bf16 v[90:93], v[182:185], v[222:225], v[90:93]
	v_mfma_f32_16x16x32_bf16 v[74:77], v[182:185], v[230:233], v[74:77]
	v_mfma_f32_16x16x32_bf16 v[78:81], v[170:173], v[230:233], v[78:81]
	s_setprio 0
	s_setprio 1
	v_mfma_f32_16x16x32_bf16 v[118:121], v[186:189], v[202:205], v[118:121]
	v_mfma_f32_16x16x32_bf16 v[114:117], v[194:197], v[202:205], v[114:117]
	v_mfma_f32_16x16x32_bf16 v[98:101], v[194:197], v[210:213], v[98:101]
	v_mfma_f32_16x16x32_bf16 v[102:105], v[186:189], v[210:213], v[102:105]
	v_mfma_f32_16x16x32_bf16 v[86:89], v[186:189], v[218:221], v[86:89]
	v_mfma_f32_16x16x32_bf16 v[82:85], v[194:197], v[218:221], v[82:85]
	v_mfma_f32_16x16x32_bf16 v[66:69], v[194:197], v[226:229], v[66:69]
	v_mfma_f32_16x16x32_bf16 v[70:73], v[186:189], v[226:229], v[70:73]
	v_mfma_f32_16x16x32_bf16 v[118:121], v[190:193], v[206:209], v[118:121]
	v_mfma_f32_16x16x32_bf16 v[114:117], v[198:201], v[206:209], v[114:117]
	v_mfma_f32_16x16x32_bf16 v[98:101], v[198:201], v[214:217], v[98:101]
	v_mfma_f32_16x16x32_bf16 v[102:105], v[190:193], v[214:217], v[102:105]
	v_mfma_f32_16x16x32_bf16 v[86:89], v[190:193], v[222:225], v[86:89]
	v_mfma_f32_16x16x32_bf16 v[82:85], v[198:201], v[222:225], v[82:85]
	v_mfma_f32_16x16x32_bf16 v[66:69], v[198:201], v[230:233], v[66:69]
	v_mfma_f32_16x16x32_bf16 v[70:73], v[190:193], v[230:233], v[70:73]
	s_setprio 0
	s_barrier
	s_add_i32 s53, s41, s30
	v_lshl_add_u64 v[148:149], s[28:29], 0, v[132:133]
	s_mov_b32 m0, s53
	ds_read_b128 v[202:205], v165 offset:16384
	ds_read_b128 v[206:209], v165 offset:17408
	ds_read_b128 v[210:213], v165 offset:18432
	ds_read_b128 v[214:217], v165 offset:19456
	ds_read_b128 v[218:221], v165 offset:20480
	ds_read_b128 v[222:225], v165 offset:21504
	ds_read_b128 v[226:229], v165 offset:22528
	ds_read_b128 v[230:233], v165 offset:23552
	global_load_lds_dwordx4 v[148:149], off
	s_add_i32 m0, s53, 0x2000
	s_add_u32 s54, s28, 0x40000
	v_lshl_add_u64 v[174:175], s[28:29], 0, v[136:137]
	s_addc_u32 s55, s29, 0
	s_add_i32 s53, s42, s30
	global_load_lds_dwordx4 v[174:175], off
	v_lshl_add_u64 v[234:235], s[54:55], 0, v[132:133]
	s_mov_b32 m0, s53
	v_lshl_add_u64 v[236:237], s[2:3], 0, v[134:135]
	global_load_lds_dwordx4 v[234:235], off
	v_lshl_add_u64 v[234:235], s[54:55], 0, v[136:137]
	s_add_i32 m0, s53, 0x2000
	s_nop 0
	global_load_lds_dwordx4 v[234:235], off
	v_lshl_add_u64 v[234:235], s[2:3], 0, v[130:131]
	s_mov_b32 m0, s34
	s_nop 0
	global_load_lds_dwordx4 v[234:235], off
	s_mov_b32 m0, s25
	s_nop 0
	global_load_lds_dwordx4 v[236:237], off
	s_waitcnt vmcnt(8)
	s_waitcnt lgkmcnt(0)
	s_barrier
	s_setprio 1
	s_waitcnt lgkmcnt(0)
	v_mfma_f32_16x16x32_bf16 v[62:65], v[166:169], v[202:205], v[62:65]
	v_mfma_f32_16x16x32_bf16 v[58:61], v[178:181], v[202:205], v[58:61]
	v_mfma_f32_16x16x32_bf16 v[42:45], v[178:181], v[210:213], v[42:45]
	v_mfma_f32_16x16x32_bf16 v[46:49], v[166:169], v[210:213], v[46:49]
	v_mfma_f32_16x16x32_bf16 v[30:33], v[166:169], v[218:221], v[30:33]
	v_mfma_f32_16x16x32_bf16 v[26:29], v[178:181], v[218:221], v[26:29]
	v_mfma_f32_16x16x32_bf16 v[10:13], v[178:181], v[226:229], v[10:13]
	v_mfma_f32_16x16x32_bf16 v[14:17], v[166:169], v[226:229], v[14:17]
	v_mfma_f32_16x16x32_bf16 v[62:65], v[170:173], v[206:209], v[62:65]
	v_mfma_f32_16x16x32_bf16 v[58:61], v[182:185], v[206:209], v[58:61]
	v_mfma_f32_16x16x32_bf16 v[42:45], v[182:185], v[214:217], v[42:45]
	v_mfma_f32_16x16x32_bf16 v[46:49], v[170:173], v[214:217], v[46:49]
	v_mfma_f32_16x16x32_bf16 v[30:33], v[170:173], v[222:225], v[30:33]
	v_mfma_f32_16x16x32_bf16 v[26:29], v[182:185], v[222:225], v[26:29]
	v_mfma_f32_16x16x32_bf16 v[10:13], v[182:185], v[230:233], v[10:13]
	v_mfma_f32_16x16x32_bf16 v[14:17], v[170:173], v[230:233], v[14:17]
	s_setprio 0
	s_setprio 1
	v_mfma_f32_16x16x32_bf16 v[54:57], v[186:189], v[202:205], v[54:57]
	v_mfma_f32_16x16x32_bf16 v[50:53], v[194:197], v[202:205], v[50:53]
	v_mfma_f32_16x16x32_bf16 v[34:37], v[194:197], v[210:213], v[34:37]
	v_mfma_f32_16x16x32_bf16 v[38:41], v[186:189], v[210:213], v[38:41]
	v_mfma_f32_16x16x32_bf16 v[22:25], v[186:189], v[218:221], v[22:25]
	v_mfma_f32_16x16x32_bf16 v[18:21], v[194:197], v[218:221], v[18:21]
	v_mfma_f32_16x16x32_bf16 v[2:5], v[194:197], v[226:229], v[2:5]
	v_mfma_f32_16x16x32_bf16 v[6:9], v[186:189], v[226:229], v[6:9]
	v_mfma_f32_16x16x32_bf16 v[54:57], v[190:193], v[206:209], v[54:57]
	v_mfma_f32_16x16x32_bf16 v[50:53], v[198:201], v[206:209], v[50:53]
	v_mfma_f32_16x16x32_bf16 v[34:37], v[198:201], v[214:217], v[34:37]
	v_mfma_f32_16x16x32_bf16 v[38:41], v[190:193], v[214:217], v[38:41]
	v_mfma_f32_16x16x32_bf16 v[22:25], v[190:193], v[222:225], v[22:25]
	v_mfma_f32_16x16x32_bf16 v[18:21], v[198:201], v[222:225], v[18:21]
	v_mfma_f32_16x16x32_bf16 v[2:5], v[198:201], v[230:233], v[2:5]
	v_mfma_f32_16x16x32_bf16 v[6:9], v[190:193], v[230:233], v[6:9]
	s_setprio 0
	s_barrier
	s_add_i32 s53, 0, 0x18000
	v_add_u32_e32 v176, s53, v163
	s_add_i32 s54, 0, 0x1c000
	ds_read_b128 v[166:169], v176
	ds_read_b128 v[170:173], v176 offset:1024
	ds_read_b128 v[178:181], v176 offset:2048
	ds_read_b128 v[182:185], v176 offset:3072
	v_add_u32_e32 v176, s54, v163
	ds_read_b128 v[186:189], v176
	ds_read_b128 v[190:193], v176 offset:1024
	ds_read_b128 v[194:197], v176 offset:2048
	ds_read_b128 v[198:201], v176 offset:3072
	s_add_u32 s2, s2, 0x40000
	s_addc_u32 s3, s3, 0
	s_mov_b32 m0, s35
	v_lshl_add_u64 v[238:239], s[2:3], 0, v[130:131]
	ds_read_b128 v[202:205], v165 offset:32768
	ds_read_b128 v[206:209], v165 offset:33792
	ds_read_b128 v[210:213], v165 offset:34816
	ds_read_b128 v[214:217], v165 offset:35840
	ds_read_b128 v[218:221], v165 offset:36864
	ds_read_b128 v[222:225], v165 offset:37888
	ds_read_b128 v[226:229], v165 offset:38912
	ds_read_b128 v[230:233], v165 offset:39936
	global_load_lds_dwordx4 v[238:239], off
	v_lshl_add_u64 v[238:239], s[2:3], 0, v[134:135]
	s_mov_b32 m0, s36
	s_nop 0
	global_load_lds_dwordx4 v[238:239], off
	s_waitcnt vmcnt(8)
	s_waitcnt lgkmcnt(0)
	s_barrier
	s_setprio 1
	s_waitcnt lgkmcnt(0)
	v_mfma_f32_16x16x32_bf16 v[126:129], v[166:169], v[202:205], v[126:129]
	v_mfma_f32_16x16x32_bf16 v[122:125], v[178:181], v[202:205], v[122:125]
	v_mfma_f32_16x16x32_bf16 v[106:109], v[178:181], v[210:213], v[106:109]
	v_mfma_f32_16x16x32_bf16 v[110:113], v[166:169], v[210:213], v[110:113]
	v_mfma_f32_16x16x32_bf16 v[94:97], v[166:169], v[218:221], v[94:97]
	v_mfma_f32_16x16x32_bf16 v[90:93], v[178:181], v[218:221], v[90:93]
	v_mfma_f32_16x16x32_bf16 v[74:77], v[178:181], v[226:229], v[74:77]
	v_mfma_f32_16x16x32_bf16 v[78:81], v[166:169], v[226:229], v[78:81]
	v_mfma_f32_16x16x32_bf16 v[126:129], v[170:173], v[206:209], v[126:129]
	v_mfma_f32_16x16x32_bf16 v[122:125], v[182:185], v[206:209], v[122:125]
	v_mfma_f32_16x16x32_bf16 v[106:109], v[182:185], v[214:217], v[106:109]
	v_mfma_f32_16x16x32_bf16 v[110:113], v[170:173], v[214:217], v[110:113]
	v_mfma_f32_16x16x32_bf16 v[94:97], v[170:173], v[222:225], v[94:97]
	v_mfma_f32_16x16x32_bf16 v[90:93], v[182:185], v[222:225], v[90:93]
	v_mfma_f32_16x16x32_bf16 v[74:77], v[182:185], v[230:233], v[74:77]
	v_mfma_f32_16x16x32_bf16 v[78:81], v[170:173], v[230:233], v[78:81]
	s_setprio 0
	s_setprio 1
	v_mfma_f32_16x16x32_bf16 v[118:121], v[186:189], v[202:205], v[118:121]
	v_mfma_f32_16x16x32_bf16 v[114:117], v[194:197], v[202:205], v[114:117]
	v_mfma_f32_16x16x32_bf16 v[98:101], v[194:197], v[210:213], v[98:101]
	v_mfma_f32_16x16x32_bf16 v[102:105], v[186:189], v[210:213], v[102:105]
	v_mfma_f32_16x16x32_bf16 v[86:89], v[186:189], v[218:221], v[86:89]
	v_mfma_f32_16x16x32_bf16 v[82:85], v[194:197], v[218:221], v[82:85]
	v_mfma_f32_16x16x32_bf16 v[66:69], v[194:197], v[226:229], v[66:69]
	v_mfma_f32_16x16x32_bf16 v[70:73], v[186:189], v[226:229], v[70:73]
	v_mfma_f32_16x16x32_bf16 v[118:121], v[190:193], v[206:209], v[118:121]
	v_mfma_f32_16x16x32_bf16 v[114:117], v[198:201], v[206:209], v[114:117]
	v_mfma_f32_16x16x32_bf16 v[98:101], v[198:201], v[214:217], v[98:101]
	v_mfma_f32_16x16x32_bf16 v[102:105], v[190:193], v[214:217], v[102:105]
	v_mfma_f32_16x16x32_bf16 v[86:89], v[190:193], v[222:225], v[86:89]
	v_mfma_f32_16x16x32_bf16 v[82:85], v[198:201], v[222:225], v[82:85]
	v_mfma_f32_16x16x32_bf16 v[66:69], v[198:201], v[230:233], v[66:69]
	v_mfma_f32_16x16x32_bf16 v[70:73], v[190:193], v[230:233], v[70:73]
	s_setprio 0
	s_barrier
	s_add_i32 s2, s53, s30
	v_lshl_add_u64 v[148:149], v[148:149], 0, s[6:7]
	s_mov_b32 m0, s2
	ds_read_b128 v[202:205], v165 offset:49152
	ds_read_b128 v[206:209], v165 offset:50176
	ds_read_b128 v[210:213], v165 offset:51200
	ds_read_b128 v[214:217], v165 offset:52224
	ds_read_b128 v[218:221], v165 offset:53248
	ds_read_b128 v[222:225], v165 offset:54272
	ds_read_b128 v[226:229], v165 offset:55296
	ds_read_b128 v[230:233], v165 offset:56320
	global_load_lds_dwordx4 v[148:149], off
	s_add_i32 m0, s2, 0x2000
	s_add_u32 s2, s28, 0x40080
	v_lshl_add_u64 v[148:149], v[174:175], 0, s[6:7]
	s_addc_u32 s3, s29, 0
	s_add_i32 s28, s54, s30
	global_load_lds_dwordx4 v[148:149], off
	v_lshl_add_u64 v[148:149], s[2:3], 0, v[132:133]
	s_mov_b32 m0, s28
	s_nop 0
	global_load_lds_dwordx4 v[148:149], off
	v_lshl_add_u64 v[148:149], s[2:3], 0, v[136:137]
	s_add_i32 m0, s28, 0x2000
	s_nop 0
	global_load_lds_dwordx4 v[148:149], off
	v_lshl_add_u64 v[148:149], v[234:235], 0, s[6:7]
	s_mov_b32 m0, s38
	s_nop 0
	global_load_lds_dwordx4 v[148:149], off
	v_lshl_add_u64 v[148:149], v[236:237], 0, s[6:7]
	s_mov_b32 m0, s39
	s_nop 0
	global_load_lds_dwordx4 v[148:149], off
	s_waitcnt vmcnt(8)
	s_waitcnt lgkmcnt(0)
	s_barrier
	s_setprio 1
	s_waitcnt lgkmcnt(0)
	v_mfma_f32_16x16x32_bf16 v[62:65], v[166:169], v[202:205], v[62:65]
	v_mfma_f32_16x16x32_bf16 v[58:61], v[178:181], v[202:205], v[58:61]
	v_mfma_f32_16x16x32_bf16 v[42:45], v[178:181], v[210:213], v[42:45]
	v_mfma_f32_16x16x32_bf16 v[46:49], v[166:169], v[210:213], v[46:49]
	v_mfma_f32_16x16x32_bf16 v[30:33], v[166:169], v[218:221], v[30:33]
	v_mfma_f32_16x16x32_bf16 v[26:29], v[178:181], v[218:221], v[26:29]
	v_mfma_f32_16x16x32_bf16 v[10:13], v[178:181], v[226:229], v[10:13]
	v_mfma_f32_16x16x32_bf16 v[14:17], v[166:169], v[226:229], v[14:17]
	v_mfma_f32_16x16x32_bf16 v[62:65], v[170:173], v[206:209], v[62:65]
	v_mfma_f32_16x16x32_bf16 v[58:61], v[182:185], v[206:209], v[58:61]
	v_mfma_f32_16x16x32_bf16 v[42:45], v[182:185], v[214:217], v[42:45]
	v_mfma_f32_16x16x32_bf16 v[46:49], v[170:173], v[214:217], v[46:49]
	v_mfma_f32_16x16x32_bf16 v[30:33], v[170:173], v[222:225], v[30:33]
	v_mfma_f32_16x16x32_bf16 v[26:29], v[182:185], v[222:225], v[26:29]
	v_mfma_f32_16x16x32_bf16 v[10:13], v[182:185], v[230:233], v[10:13]
	v_mfma_f32_16x16x32_bf16 v[14:17], v[170:173], v[230:233], v[14:17]
	s_setprio 0
	s_setprio 1
	v_mfma_f32_16x16x32_bf16 v[54:57], v[186:189], v[202:205], v[54:57]
	v_mfma_f32_16x16x32_bf16 v[50:53], v[194:197], v[202:205], v[50:53]
	v_mfma_f32_16x16x32_bf16 v[34:37], v[194:197], v[210:213], v[34:37]
	v_mfma_f32_16x16x32_bf16 v[38:41], v[186:189], v[210:213], v[38:41]
	v_mfma_f32_16x16x32_bf16 v[22:25], v[186:189], v[218:221], v[22:25]
	v_mfma_f32_16x16x32_bf16 v[18:21], v[194:197], v[218:221], v[18:21]
	v_mfma_f32_16x16x32_bf16 v[2:5], v[194:197], v[226:229], v[2:5]
	v_mfma_f32_16x16x32_bf16 v[6:9], v[186:189], v[226:229], v[6:9]
	v_mfma_f32_16x16x32_bf16 v[54:57], v[190:193], v[206:209], v[54:57]
	v_mfma_f32_16x16x32_bf16 v[50:53], v[198:201], v[206:209], v[50:53]
	v_mfma_f32_16x16x32_bf16 v[34:37], v[198:201], v[214:217], v[34:37]
	v_mfma_f32_16x16x32_bf16 v[38:41], v[190:193], v[214:217], v[38:41]
	v_mfma_f32_16x16x32_bf16 v[22:25], v[190:193], v[222:225], v[22:25]
	v_mfma_f32_16x16x32_bf16 v[18:21], v[198:201], v[222:225], v[18:21]
	v_mfma_f32_16x16x32_bf16 v[2:5], v[198:201], v[230:233], v[2:5]
	v_mfma_f32_16x16x32_bf16 v[6:9], v[190:193], v[230:233], v[6:9]
	s_setprio 0
	s_barrier
	s_add_i32 s52, s52, 2
	s_add_u32 s26, s26, 0x100
	s_addc_u32 s27, s27, 0
	s_add_u32 s46, s46, 0x100
	s_addc_u32 s47, s47, 0
	s_cmp_gt_u32 s52, 13
	s_cbranch_scc0 .LBB0_354

.LBB0_437:
	ds_read_b128 v[160:163], v133
	ds_read_b128 v[164:167], v133 offset:1024
	ds_read_b128 v[168:171], v133 offset:2048
	ds_read_b128 v[172:175], v133 offset:3072
	ds_read_b128 v[178:181], v135
	ds_read_b128 v[182:185], v135 offset:1024
	ds_read_b128 v[186:189], v135 offset:2048
	ds_read_b128 v[190:193], v135 offset:3072
	s_cmp_lg_u32 s8, 0x160000
	s_cselect_b32 s13, s8, 0
	s_cselect_b32 s12, s9, 0
	s_add_u32 s2, s6, s13
	s_addc_u32 s3, s7, s12
	s_add_u32 s14, s0, s13
	s_addc_u32 s15, s1, s12
	s_add_u32 s12, s2, 0x8000
	s_addc_u32 s13, s3, 0
	v_lshl_add_u64 v[226:227], v[148:149], 0, s[8:9]
	s_mov_b32 m0, s27
	v_lshl_add_u64 v[226:227], v[226:227], 0, s[10:11]
	ds_read_b128 v[194:197], v137
	ds_read_b128 v[198:201], v137 offset:1024
	ds_read_b128 v[202:205], v137 offset:2048
	ds_read_b128 v[206:209], v137 offset:3072
	ds_read_b128 v[210:213], v137 offset:4096
	ds_read_b128 v[214:217], v137 offset:5120
	ds_read_b128 v[218:221], v137 offset:6144
	ds_read_b128 v[222:225], v137 offset:7168
	global_load_lds_dwordx4 v[226:227], off
	v_lshl_add_u64 v[226:227], v[150:151], 0, s[8:9]
	v_lshl_add_u64 v[226:227], v[226:227], 0, s[10:11]
	s_mov_b32 m0, s28
	s_nop 0
	global_load_lds_dwordx4 v[226:227], off
	s_waitcnt vmcnt(8)
	s_waitcnt lgkmcnt(0)
	s_barrier
	s_setprio 1
	s_waitcnt lgkmcnt(0)
	v_mfma_f32_16x16x32_bf16 v[126:129], v[160:163], v[194:197], v[126:129]
	v_mfma_f32_16x16x32_bf16 v[122:125], v[168:171], v[194:197], v[122:125]
	v_mfma_f32_16x16x32_bf16 v[106:109], v[168:171], v[202:205], v[106:109]
	v_mfma_f32_16x16x32_bf16 v[114:117], v[160:163], v[202:205], v[114:117]
	v_mfma_f32_16x16x32_bf16 v[98:101], v[160:163], v[210:213], v[98:101]
	v_mfma_f32_16x16x32_bf16 v[90:93], v[168:171], v[210:213], v[90:93]
	v_mfma_f32_16x16x32_bf16 v[74:77], v[168:171], v[218:221], v[74:77]
	v_mfma_f32_16x16x32_bf16 v[82:85], v[160:163], v[218:221], v[82:85]
	v_mfma_f32_16x16x32_bf16 v[126:129], v[164:167], v[198:201], v[126:129]
	v_mfma_f32_16x16x32_bf16 v[122:125], v[172:175], v[198:201], v[122:125]
	v_mfma_f32_16x16x32_bf16 v[106:109], v[172:175], v[206:209], v[106:109]
	v_mfma_f32_16x16x32_bf16 v[114:117], v[164:167], v[206:209], v[114:117]
	v_mfma_f32_16x16x32_bf16 v[98:101], v[164:167], v[214:217], v[98:101]
	v_mfma_f32_16x16x32_bf16 v[90:93], v[172:175], v[214:217], v[90:93]
	v_mfma_f32_16x16x32_bf16 v[74:77], v[172:175], v[222:225], v[74:77]
	v_mfma_f32_16x16x32_bf16 v[82:85], v[164:167], v[222:225], v[82:85]
	s_setprio 0
	s_setprio 1
	v_mfma_f32_16x16x32_bf16 v[118:121], v[178:181], v[194:197], v[118:121]
	v_mfma_f32_16x16x32_bf16 v[110:113], v[186:189], v[194:197], v[110:113]
	v_mfma_f32_16x16x32_bf16 v[94:97], v[186:189], v[202:205], v[94:97]
	v_mfma_f32_16x16x32_bf16 v[102:105], v[178:181], v[202:205], v[102:105]
	v_mfma_f32_16x16x32_bf16 v[86:89], v[178:181], v[210:213], v[86:89]
	v_mfma_f32_16x16x32_bf16 v[78:81], v[186:189], v[210:213], v[78:81]
	v_mfma_f32_16x16x32_bf16 v[66:69], v[186:189], v[218:221], v[66:69]
	v_mfma_f32_16x16x32_bf16 v[70:73], v[178:181], v[218:221], v[70:73]
	v_mfma_f32_16x16x32_bf16 v[118:121], v[182:185], v[198:201], v[118:121]
	v_mfma_f32_16x16x32_bf16 v[110:113], v[190:193], v[198:201], v[110:113]
	v_mfma_f32_16x16x32_bf16 v[94:97], v[190:193], v[206:209], v[94:97]
	v_mfma_f32_16x16x32_bf16 v[102:105], v[182:185], v[206:209], v[102:105]
	v_mfma_f32_16x16x32_bf16 v[86:89], v[182:185], v[214:217], v[86:89]
	v_mfma_f32_16x16x32_bf16 v[78:81], v[190:193], v[214:217], v[78:81]
	v_mfma_f32_16x16x32_bf16 v[66:69], v[190:193], v[222:225], v[66:69]
	v_mfma_f32_16x16x32_bf16 v[70:73], v[182:185], v[222:225], v[70:73]
	s_setprio 0
	s_barrier
	s_mov_b32 m0, s29
	v_lshl_add_u64 v[226:227], s[14:15], 0, v[142:143]
	s_add_u32 s40, s14, 0x4000
	ds_read_b128 v[194:197], v137 offset:16384
	ds_read_b128 v[198:201], v137 offset:17408
	ds_read_b128 v[202:205], v137 offset:18432
	ds_read_b128 v[206:209], v137 offset:19456
	ds_read_b128 v[210:213], v137 offset:20480
	ds_read_b128 v[214:217], v137 offset:21504
	ds_read_b128 v[218:221], v137 offset:22528
	ds_read_b128 v[222:225], v137 offset:23552
	global_load_lds_dwordx4 v[226:227], off
	v_lshl_add_u64 v[226:227], s[14:15], 0, v[146:147]
	s_mov_b32 m0, s30
	s_addc_u32 s41, s15, 0
	global_load_lds_dwordx4 v[226:227], off
	v_lshl_add_u64 v[226:227], s[40:41], 0, v[142:143]
	s_mov_b32 m0, s31
	s_nop 0
	global_load_lds_dwordx4 v[226:227], off
	v_lshl_add_u64 v[226:227], s[40:41], 0, v[146:147]
	s_mov_b32 m0, s34
	s_nop 0
	global_load_lds_dwordx4 v[226:227], off
	v_lshl_add_u64 v[226:227], s[2:3], 0, v[140:141]
	s_mov_b32 m0, s19
	s_nop 0
	global_load_lds_dwordx4 v[226:227], off
	v_lshl_add_u64 v[226:227], s[2:3], 0, v[144:145]
	s_mov_b32 m0, s20
	s_nop 0
	global_load_lds_dwordx4 v[226:227], off
	s_waitcnt vmcnt(8)
	s_waitcnt lgkmcnt(0)
	s_barrier
	s_setprio 1
	s_waitcnt lgkmcnt(0)
	v_mfma_f32_16x16x32_bf16 v[62:65], v[160:163], v[194:197], v[62:65]
	v_mfma_f32_16x16x32_bf16 v[58:61], v[168:171], v[194:197], v[58:61]
	v_mfma_f32_16x16x32_bf16 v[42:45], v[168:171], v[202:205], v[42:45]
	v_mfma_f32_16x16x32_bf16 v[50:53], v[160:163], v[202:205], v[50:53]
	v_mfma_f32_16x16x32_bf16 v[34:37], v[160:163], v[210:213], v[34:37]
	v_mfma_f32_16x16x32_bf16 v[26:29], v[168:171], v[210:213], v[26:29]
	v_mfma_f32_16x16x32_bf16 v[10:13], v[168:171], v[218:221], v[10:13]
	v_mfma_f32_16x16x32_bf16 v[18:21], v[160:163], v[218:221], v[18:21]
	v_mfma_f32_16x16x32_bf16 v[62:65], v[164:167], v[198:201], v[62:65]
	v_mfma_f32_16x16x32_bf16 v[58:61], v[172:175], v[198:201], v[58:61]
	v_mfma_f32_16x16x32_bf16 v[42:45], v[172:175], v[206:209], v[42:45]
	v_mfma_f32_16x16x32_bf16 v[50:53], v[164:167], v[206:209], v[50:53]
	v_mfma_f32_16x16x32_bf16 v[34:37], v[164:167], v[214:217], v[34:37]
	v_mfma_f32_16x16x32_bf16 v[26:29], v[172:175], v[214:217], v[26:29]
	v_mfma_f32_16x16x32_bf16 v[10:13], v[172:175], v[222:225], v[10:13]
	v_mfma_f32_16x16x32_bf16 v[18:21], v[164:167], v[222:225], v[18:21]
	s_setprio 0
	s_setprio 1
	v_mfma_f32_16x16x32_bf16 v[54:57], v[178:181], v[194:197], v[54:57]
	v_mfma_f32_16x16x32_bf16 v[46:49], v[186:189], v[194:197], v[46:49]
	v_mfma_f32_16x16x32_bf16 v[30:33], v[186:189], v[202:205], v[30:33]
	v_mfma_f32_16x16x32_bf16 v[38:41], v[178:181], v[202:205], v[38:41]
	v_mfma_f32_16x16x32_bf16 v[22:25], v[178:181], v[210:213], v[22:25]
	v_mfma_f32_16x16x32_bf16 v[14:17], v[186:189], v[210:213], v[14:17]
	v_mfma_f32_16x16x32_bf16 v[2:5], v[186:189], v[218:221], v[2:5]
	v_mfma_f32_16x16x32_bf16 v[6:9], v[178:181], v[218:221], v[6:9]
	v_mfma_f32_16x16x32_bf16 v[54:57], v[182:185], v[198:201], v[54:57]
	v_mfma_f32_16x16x32_bf16 v[46:49], v[190:193], v[198:201], v[46:49]
	v_mfma_f32_16x16x32_bf16 v[30:33], v[190:193], v[206:209], v[30:33]
	v_mfma_f32_16x16x32_bf16 v[38:41], v[182:185], v[206:209], v[38:41]
	v_mfma_f32_16x16x32_bf16 v[22:25], v[182:185], v[214:217], v[22:25]
	v_mfma_f32_16x16x32_bf16 v[14:17], v[190:193], v[214:217], v[14:17]
	v_mfma_f32_16x16x32_bf16 v[2:5], v[190:193], v[222:225], v[2:5]
	v_mfma_f32_16x16x32_bf16 v[6:9], v[182:185], v[222:225], v[6:9]
	s_setprio 0
	s_barrier
	ds_read_b128 v[160:163], v139
	ds_read_b128 v[164:167], v139 offset:1024
	ds_read_b128 v[168:171], v139 offset:2048
	ds_read_b128 v[172:175], v139 offset:3072
	ds_read_b128 v[178:181], v159
	ds_read_b128 v[182:185], v159 offset:1024
	ds_read_b128 v[186:189], v159 offset:2048
	ds_read_b128 v[190:193], v159 offset:3072
	s_add_u32 s2, s2, 0x4000
	s_addc_u32 s3, s3, 0
	s_mov_b32 m0, s21
	v_lshl_add_u64 v[226:227], s[2:3], 0, v[140:141]
	ds_read_b128 v[194:197], v137 offset:32768
	ds_read_b128 v[198:201], v137 offset:33792
	ds_read_b128 v[202:205], v137 offset:34816
	ds_read_b128 v[206:209], v137 offset:35840
	ds_read_b128 v[210:213], v137 offset:36864
	ds_read_b128 v[214:217], v137 offset:37888
	ds_read_b128 v[218:221], v137 offset:38912
	ds_read_b128 v[222:225], v137 offset:39936
	global_load_lds_dwordx4 v[226:227], off
	v_lshl_add_u64 v[226:227], s[2:3], 0, v[144:145]
	s_mov_b32 m0, s22
	s_nop 0
	global_load_lds_dwordx4 v[226:227], off
	s_waitcnt vmcnt(8)
	s_waitcnt lgkmcnt(0)
	s_barrier
	s_setprio 1
	s_waitcnt lgkmcnt(0)
	v_mfma_f32_16x16x32_bf16 v[126:129], v[160:163], v[194:197], v[126:129]
	v_mfma_f32_16x16x32_bf16 v[122:125], v[168:171], v[194:197], v[122:125]
	v_mfma_f32_16x16x32_bf16 v[106:109], v[168:171], v[202:205], v[106:109]
	v_mfma_f32_16x16x32_bf16 v[114:117], v[160:163], v[202:205], v[114:117]
	v_mfma_f32_16x16x32_bf16 v[98:101], v[160:163], v[210:213], v[98:101]
	v_mfma_f32_16x16x32_bf16 v[90:93], v[168:171], v[210:213], v[90:93]
	v_mfma_f32_16x16x32_bf16 v[74:77], v[168:171], v[218:221], v[74:77]
	v_mfma_f32_16x16x32_bf16 v[82:85], v[160:163], v[218:221], v[82:85]
	v_mfma_f32_16x16x32_bf16 v[126:129], v[164:167], v[198:201], v[126:129]
	v_mfma_f32_16x16x32_bf16 v[122:125], v[172:175], v[198:201], v[122:125]
	v_mfma_f32_16x16x32_bf16 v[106:109], v[172:175], v[206:209], v[106:109]
	v_mfma_f32_16x16x32_bf16 v[114:117], v[164:167], v[206:209], v[114:117]
	v_mfma_f32_16x16x32_bf16 v[98:101], v[164:167], v[214:217], v[98:101]
	v_mfma_f32_16x16x32_bf16 v[90:93], v[172:175], v[214:217], v[90:93]
	v_mfma_f32_16x16x32_bf16 v[74:77], v[172:175], v[222:225], v[74:77]
	v_mfma_f32_16x16x32_bf16 v[82:85], v[164:167], v[222:225], v[82:85]
	s_setprio 0
	s_setprio 1
	v_mfma_f32_16x16x32_bf16 v[118:121], v[178:181], v[194:197], v[118:121]
	v_mfma_f32_16x16x32_bf16 v[110:113], v[186:189], v[194:197], v[110:113]
	v_mfma_f32_16x16x32_bf16 v[94:97], v[186:189], v[202:205], v[94:97]
	v_mfma_f32_16x16x32_bf16 v[102:105], v[178:181], v[202:205], v[102:105]
	v_mfma_f32_16x16x32_bf16 v[86:89], v[178:181], v[210:213], v[86:89]
	v_mfma_f32_16x16x32_bf16 v[78:81], v[186:189], v[210:213], v[78:81]
	v_mfma_f32_16x16x32_bf16 v[66:69], v[186:189], v[218:221], v[66:69]
	v_mfma_f32_16x16x32_bf16 v[70:73], v[178:181], v[218:221], v[70:73]
	v_mfma_f32_16x16x32_bf16 v[118:121], v[182:185], v[198:201], v[118:121]
	v_mfma_f32_16x16x32_bf16 v[110:113], v[190:193], v[198:201], v[110:113]
	v_mfma_f32_16x16x32_bf16 v[94:97], v[190:193], v[206:209], v[94:97]
	v_mfma_f32_16x16x32_bf16 v[102:105], v[182:185], v[206:209], v[102:105]
	v_mfma_f32_16x16x32_bf16 v[86:89], v[182:185], v[214:217], v[86:89]
	v_mfma_f32_16x16x32_bf16 v[78:81], v[190:193], v[214:217], v[78:81]
	v_mfma_f32_16x16x32_bf16 v[66:69], v[190:193], v[222:225], v[66:69]
	v_mfma_f32_16x16x32_bf16 v[70:73], v[182:185], v[222:225], v[70:73]
	s_setprio 0
	s_barrier
	s_add_u32 s2, s14, 0x8000
	s_addc_u32 s3, s15, 0
	s_mov_b32 m0, s35
	v_lshl_add_u64 v[226:227], s[2:3], 0, v[142:143]
	ds_read_b128 v[194:197], v137 offset:49152
	ds_read_b128 v[198:201], v137 offset:50176
	ds_read_b128 v[202:205], v137 offset:51200
	ds_read_b128 v[206:209], v137 offset:52224
	ds_read_b128 v[210:213], v137 offset:53248
	ds_read_b128 v[214:217], v137 offset:54272
	ds_read_b128 v[218:221], v137 offset:55296
	ds_read_b128 v[222:225], v137 offset:56320
	global_load_lds_dwordx4 v[226:227], off
	v_lshl_add_u64 v[226:227], s[2:3], 0, v[146:147]
	s_add_u32 s2, s14, 0xc000
	s_mov_b32 m0, s36
	s_addc_u32 s3, s15, 0
	global_load_lds_dwordx4 v[226:227], off
	v_lshl_add_u64 v[226:227], s[2:3], 0, v[142:143]
	s_mov_b32 m0, s37
	s_nop 0
	global_load_lds_dwordx4 v[226:227], off
	v_lshl_add_u64 v[226:227], s[2:3], 0, v[146:147]
	s_mov_b32 m0, s38
	s_nop 0
	global_load_lds_dwordx4 v[226:227], off
	v_lshl_add_u64 v[226:227], s[12:13], 0, v[140:141]
	s_mov_b32 m0, s24
	s_nop 0
	global_load_lds_dwordx4 v[226:227], off
	v_lshl_add_u64 v[226:227], s[12:13], 0, v[144:145]
	s_mov_b32 m0, s25
	s_nop 0
	global_load_lds_dwordx4 v[226:227], off
	s_waitcnt vmcnt(8)
	s_waitcnt lgkmcnt(0)
	s_barrier
	s_setprio 1
	s_waitcnt lgkmcnt(0)
	v_mfma_f32_16x16x32_bf16 v[62:65], v[160:163], v[194:197], v[62:65]
	v_mfma_f32_16x16x32_bf16 v[58:61], v[168:171], v[194:197], v[58:61]
	v_mfma_f32_16x16x32_bf16 v[42:45], v[168:171], v[202:205], v[42:45]
	v_mfma_f32_16x16x32_bf16 v[50:53], v[160:163], v[202:205], v[50:53]
	v_mfma_f32_16x16x32_bf16 v[34:37], v[160:163], v[210:213], v[34:37]
	v_mfma_f32_16x16x32_bf16 v[26:29], v[168:171], v[210:213], v[26:29]
	v_mfma_f32_16x16x32_bf16 v[10:13], v[168:171], v[218:221], v[10:13]
	v_mfma_f32_16x16x32_bf16 v[18:21], v[160:163], v[218:221], v[18:21]
	v_mfma_f32_16x16x32_bf16 v[62:65], v[164:167], v[198:201], v[62:65]
	v_mfma_f32_16x16x32_bf16 v[58:61], v[172:175], v[198:201], v[58:61]
	v_mfma_f32_16x16x32_bf16 v[42:45], v[172:175], v[206:209], v[42:45]
	v_mfma_f32_16x16x32_bf16 v[50:53], v[164:167], v[206:209], v[50:53]
	v_mfma_f32_16x16x32_bf16 v[34:37], v[164:167], v[214:217], v[34:37]
	v_mfma_f32_16x16x32_bf16 v[26:29], v[172:175], v[214:217], v[26:29]
	v_mfma_f32_16x16x32_bf16 v[10:13], v[172:175], v[222:225], v[10:13]
	v_mfma_f32_16x16x32_bf16 v[18:21], v[164:167], v[222:225], v[18:21]
	s_setprio 0
	s_setprio 1
	v_mfma_f32_16x16x32_bf16 v[54:57], v[178:181], v[194:197], v[54:57]
	v_mfma_f32_16x16x32_bf16 v[46:49], v[186:189], v[194:197], v[46:49]
	v_mfma_f32_16x16x32_bf16 v[30:33], v[186:189], v[202:205], v[30:33]
	v_mfma_f32_16x16x32_bf16 v[38:41], v[178:181], v[202:205], v[38:41]
	v_mfma_f32_16x16x32_bf16 v[22:25], v[178:181], v[210:213], v[22:25]
	v_mfma_f32_16x16x32_bf16 v[14:17], v[186:189], v[210:213], v[14:17]
	v_mfma_f32_16x16x32_bf16 v[2:5], v[186:189], v[218:221], v[2:5]
	v_mfma_f32_16x16x32_bf16 v[6:9], v[178:181], v[218:221], v[6:9]
	v_mfma_f32_16x16x32_bf16 v[54:57], v[182:185], v[198:201], v[54:57]
	v_mfma_f32_16x16x32_bf16 v[46:49], v[190:193], v[198:201], v[46:49]
	v_mfma_f32_16x16x32_bf16 v[30:33], v[190:193], v[206:209], v[30:33]
	v_mfma_f32_16x16x32_bf16 v[38:41], v[182:185], v[206:209], v[38:41]
	v_mfma_f32_16x16x32_bf16 v[22:25], v[182:185], v[214:217], v[22:25]
	v_mfma_f32_16x16x32_bf16 v[14:17], v[190:193], v[214:217], v[14:17]
	v_mfma_f32_16x16x32_bf16 v[2:5], v[190:193], v[222:225], v[2:5]
	v_mfma_f32_16x16x32_bf16 v[6:9], v[182:185], v[222:225], v[6:9]
	s_setprio 0
	s_barrier
	s_add_i32 s26, s26, 2
	s_add_u32 s8, s8, 0x10000
	s_addc_u32 s9, s9, 0
	s_cmp_gt_u32 s26, 41
	s_cbranch_scc0 .LBB0_437
	s_cmpk_lt_u32 s16, 0x100
	s_cbranch_scc0 .LBB0_440
	s_barrier

.Lpk451_peel:
	ds_read_b128 v[152:155], v149
	ds_read_b128 v[156:159], v149 offset:1024
	ds_read_b128 v[160:163], v149 offset:2048
	ds_read_b128 v[164:167], v149 offset:3072
	ds_read_b128 v[168:171], v150
	ds_read_b128 v[172:175], v150 offset:1024
	ds_read_b128 v[178:181], v150 offset:2048
	ds_read_b128 v[182:185], v150 offset:3072
	s_add_u32 s2, s28, 0xfffc0080
	s_addc_u32 s3, s29, -1
	s_cmp_eq_u32 s52, 12
	s_cselect_b32 s3, s11, s3
	s_cselect_b32 s2, s13, s2
	s_cselect_b32 s31, s44, s47
	s_cselect_b32 s30, s45, s46
	v_lshl_add_u64 v[146:147], s[28:29], 0, v[140:141]
	s_add_i32 m0, s25, 0xc000
	ds_read_b128 v[186:189], v151
	ds_read_b128 v[190:193], v151 offset:1024
	ds_read_b128 v[194:197], v151 offset:2048
	ds_read_b128 v[198:201], v151 offset:3072
	ds_read_b128 v[202:205], v151 offset:4096
	ds_read_b128 v[206:209], v151 offset:5120
	ds_read_b128 v[210:213], v151 offset:6144
	ds_read_b128 v[214:217], v151 offset:7168
	global_load_lds_dwordx4 v[146:147], off
	v_lshl_add_u64 v[146:147], s[28:29], 0, v[142:143]
	s_add_i32 m0, s25, 0xe000
	s_nop 0
	global_load_lds_dwordx4 v[146:147], off
	s_waitcnt vmcnt(8)
	s_waitcnt lgkmcnt(0)
	s_barrier
	s_setprio 1
	s_waitcnt lgkmcnt(0)
	v_mfma_f32_16x16x32_bf16 v[126:129], v[152:155], v[186:189], 0
	v_mfma_f32_16x16x32_bf16 v[122:125], v[160:163], v[186:189], 0
	v_mfma_f32_16x16x32_bf16 v[106:109], v[160:163], v[194:197], 0
	v_mfma_f32_16x16x32_bf16 v[110:113], v[152:155], v[194:197], 0
	v_mfma_f32_16x16x32_bf16 v[94:97], v[152:155], v[202:205], 0
	v_mfma_f32_16x16x32_bf16 v[90:93], v[160:163], v[202:205], 0
	v_mfma_f32_16x16x32_bf16 v[74:77], v[160:163], v[210:213], 0
	v_mfma_f32_16x16x32_bf16 v[78:81], v[152:155], v[210:213], 0
	v_mfma_f32_16x16x32_bf16 v[126:129], v[156:159], v[190:193], v[126:129]
	v_mfma_f32_16x16x32_bf16 v[122:125], v[164:167], v[190:193], v[122:125]
	v_mfma_f32_16x16x32_bf16 v[106:109], v[164:167], v[198:201], v[106:109]
	v_mfma_f32_16x16x32_bf16 v[110:113], v[156:159], v[198:201], v[110:113]
	v_mfma_f32_16x16x32_bf16 v[94:97], v[156:159], v[206:209], v[94:97]
	v_mfma_f32_16x16x32_bf16 v[90:93], v[164:167], v[206:209], v[90:93]
	v_mfma_f32_16x16x32_bf16 v[74:77], v[164:167], v[214:217], v[74:77]
	v_mfma_f32_16x16x32_bf16 v[78:81], v[156:159], v[214:217], v[78:81]
	s_setprio 0
	s_setprio 1
	v_mfma_f32_16x16x32_bf16 v[118:121], v[168:171], v[186:189], 0
	v_mfma_f32_16x16x32_bf16 v[114:117], v[178:181], v[186:189], 0
	v_mfma_f32_16x16x32_bf16 v[98:101], v[178:181], v[194:197], 0
	v_mfma_f32_16x16x32_bf16 v[102:105], v[168:171], v[194:197], 0
	v_mfma_f32_16x16x32_bf16 v[86:89], v[168:171], v[202:205], 0
	v_mfma_f32_16x16x32_bf16 v[82:85], v[178:181], v[202:205], 0
	v_mfma_f32_16x16x32_bf16 v[66:69], v[178:181], v[210:213], 0
	v_mfma_f32_16x16x32_bf16 v[70:73], v[168:171], v[210:213], 0
	v_mfma_f32_16x16x32_bf16 v[118:121], v[172:175], v[190:193], v[118:121]
	v_mfma_f32_16x16x32_bf16 v[114:117], v[182:185], v[190:193], v[114:117]
	v_mfma_f32_16x16x32_bf16 v[98:101], v[182:185], v[198:201], v[98:101]
	v_mfma_f32_16x16x32_bf16 v[102:105], v[172:175], v[198:201], v[102:105]
	v_mfma_f32_16x16x32_bf16 v[86:89], v[172:175], v[206:209], v[86:89]
	v_mfma_f32_16x16x32_bf16 v[82:85], v[182:185], v[206:209], v[82:85]
	v_mfma_f32_16x16x32_bf16 v[66:69], v[182:185], v[214:217], v[66:69]
	v_mfma_f32_16x16x32_bf16 v[70:73], v[172:175], v[214:217], v[70:73]
	s_setprio 0
	s_barrier
	s_add_i32 s53, s42, s34
	v_lshl_add_u64 v[146:147], s[30:31], 0, v[132:133]
	s_mov_b32 m0, s53
	ds_read_b128 v[186:189], v151 offset:16384
	ds_read_b128 v[190:193], v151 offset:17408
	ds_read_b128 v[194:197], v151 offset:18432
	ds_read_b128 v[198:201], v151 offset:19456
	ds_read_b128 v[202:205], v151 offset:20480
	ds_read_b128 v[206:209], v151 offset:21504
	ds_read_b128 v[210:213], v151 offset:22528
	ds_read_b128 v[214:217], v151 offset:23552
	global_load_lds_dwordx4 v[146:147], off
	s_add_i32 m0, s53, 0x2000
	s_add_u32 s54, s30, 0x40000
	v_lshl_add_u64 v[218:219], s[30:31], 0, v[136:137]
	s_addc_u32 s55, s31, 0
	s_add_i32 s53, s43, s34
	global_load_lds_dwordx4 v[218:219], off
	v_lshl_add_u64 v[220:221], s[54:55], 0, v[132:133]
	s_mov_b32 m0, s53
	v_lshl_add_u64 v[222:223], s[2:3], 0, v[134:135]
	global_load_lds_dwordx4 v[220:221], off
	v_lshl_add_u64 v[220:221], s[54:55], 0, v[136:137]
	s_add_i32 m0, s53, 0x2000
	s_nop 0
	global_load_lds_dwordx4 v[220:221], off
	v_lshl_add_u64 v[220:221], s[2:3], 0, v[130:131]
	s_mov_b32 m0, s25
	s_nop 0
	global_load_lds_dwordx4 v[220:221], off
	s_mov_b32 m0, s27
	s_nop 0
	global_load_lds_dwordx4 v[222:223], off
	s_waitcnt vmcnt(8)
	s_waitcnt lgkmcnt(0)
	s_barrier
	s_setprio 1
	s_waitcnt lgkmcnt(0)
	v_mfma_f32_16x16x32_bf16 v[62:65], v[152:155], v[186:189], 0
	v_mfma_f32_16x16x32_bf16 v[58:61], v[160:163], v[186:189], 0
	v_mfma_f32_16x16x32_bf16 v[42:45], v[160:163], v[194:197], 0
	v_mfma_f32_16x16x32_bf16 v[46:49], v[152:155], v[194:197], 0
	v_mfma_f32_16x16x32_bf16 v[30:33], v[152:155], v[202:205], 0
	v_mfma_f32_16x16x32_bf16 v[26:29], v[160:163], v[202:205], 0
	v_mfma_f32_16x16x32_bf16 v[10:13], v[160:163], v[210:213], 0
	v_mfma_f32_16x16x32_bf16 v[14:17], v[152:155], v[210:213], 0
	v_mfma_f32_16x16x32_bf16 v[62:65], v[156:159], v[190:193], v[62:65]
	v_mfma_f32_16x16x32_bf16 v[58:61], v[164:167], v[190:193], v[58:61]
	v_mfma_f32_16x16x32_bf16 v[42:45], v[164:167], v[198:201], v[42:45]
	v_mfma_f32_16x16x32_bf16 v[46:49], v[156:159], v[198:201], v[46:49]
	v_mfma_f32_16x16x32_bf16 v[30:33], v[156:159], v[206:209], v[30:33]
	v_mfma_f32_16x16x32_bf16 v[26:29], v[164:167], v[206:209], v[26:29]
	v_mfma_f32_16x16x32_bf16 v[10:13], v[164:167], v[214:217], v[10:13]
	v_mfma_f32_16x16x32_bf16 v[14:17], v[156:159], v[214:217], v[14:17]
	s_setprio 0
	s_setprio 1
	v_mfma_f32_16x16x32_bf16 v[54:57], v[168:171], v[186:189], 0
	v_mfma_f32_16x16x32_bf16 v[50:53], v[178:181], v[186:189], 0
	v_mfma_f32_16x16x32_bf16 v[34:37], v[178:181], v[194:197], 0
	v_mfma_f32_16x16x32_bf16 v[38:41], v[168:171], v[194:197], 0
	v_mfma_f32_16x16x32_bf16 v[22:25], v[168:171], v[202:205], 0
	v_mfma_f32_16x16x32_bf16 v[18:21], v[178:181], v[202:205], 0
	v_mfma_f32_16x16x32_bf16 v[2:5], v[178:181], v[210:213], 0
	v_mfma_f32_16x16x32_bf16 v[6:9], v[168:171], v[210:213], 0
	v_mfma_f32_16x16x32_bf16 v[54:57], v[172:175], v[190:193], v[54:57]
	v_mfma_f32_16x16x32_bf16 v[50:53], v[182:185], v[190:193], v[50:53]
	v_mfma_f32_16x16x32_bf16 v[34:37], v[182:185], v[198:201], v[34:37]
	v_mfma_f32_16x16x32_bf16 v[38:41], v[172:175], v[198:201], v[38:41]
	v_mfma_f32_16x16x32_bf16 v[22:25], v[172:175], v[206:209], v[22:25]
	v_mfma_f32_16x16x32_bf16 v[18:21], v[182:185], v[206:209], v[18:21]
	v_mfma_f32_16x16x32_bf16 v[2:5], v[182:185], v[214:217], v[2:5]
	v_mfma_f32_16x16x32_bf16 v[6:9], v[172:175], v[214:217], v[6:9]
	s_setprio 0
	s_barrier
	s_add_i32 s53, 0, 0x18000
	s_add_i32 s54, 0, 0x1c000
	v_add_u32_e32 v164, s53, v148
	v_add_u32_e32 v176, s54, v148
	ds_read_b128 v[152:155], v164
	ds_read_b128 v[156:159], v164 offset:1024
	ds_read_b128 v[160:163], v164 offset:2048
	ds_read_b128 v[164:167], v164 offset:3072
	ds_read_b128 v[168:171], v176
	ds_read_b128 v[172:175], v176 offset:1024
	ds_read_b128 v[178:181], v176 offset:2048
	ds_read_b128 v[182:185], v176 offset:3072
	s_add_u32 s2, s2, 0x40000
	s_addc_u32 s3, s3, 0
	s_mov_b32 m0, s36
	v_lshl_add_u64 v[224:225], s[2:3], 0, v[130:131]
	ds_read_b128 v[186:189], v151 offset:32768
	ds_read_b128 v[190:193], v151 offset:33792
	ds_read_b128 v[194:197], v151 offset:34816
	ds_read_b128 v[198:201], v151 offset:35840
	ds_read_b128 v[202:205], v151 offset:36864
	ds_read_b128 v[206:209], v151 offset:37888
	ds_read_b128 v[210:213], v151 offset:38912
	ds_read_b128 v[214:217], v151 offset:39936
	global_load_lds_dwordx4 v[224:225], off
	v_lshl_add_u64 v[224:225], s[2:3], 0, v[134:135]
	s_mov_b32 m0, s37
	s_nop 0
	global_load_lds_dwordx4 v[224:225], off
	s_waitcnt vmcnt(8)
	s_waitcnt lgkmcnt(0)
	s_barrier
	s_setprio 1
	s_waitcnt lgkmcnt(0)
	v_mfma_f32_16x16x32_bf16 v[126:129], v[152:155], v[186:189], v[126:129]
	v_mfma_f32_16x16x32_bf16 v[122:125], v[160:163], v[186:189], v[122:125]
	v_mfma_f32_16x16x32_bf16 v[106:109], v[160:163], v[194:197], v[106:109]
	v_mfma_f32_16x16x32_bf16 v[110:113], v[152:155], v[194:197], v[110:113]
	v_mfma_f32_16x16x32_bf16 v[94:97], v[152:155], v[202:205], v[94:97]
	v_mfma_f32_16x16x32_bf16 v[90:93], v[160:163], v[202:205], v[90:93]
	v_mfma_f32_16x16x32_bf16 v[74:77], v[160:163], v[210:213], v[74:77]
	v_mfma_f32_16x16x32_bf16 v[78:81], v[152:155], v[210:213], v[78:81]
	v_mfma_f32_16x16x32_bf16 v[126:129], v[156:159], v[190:193], v[126:129]
	v_mfma_f32_16x16x32_bf16 v[122:125], v[164:167], v[190:193], v[122:125]
	v_mfma_f32_16x16x32_bf16 v[106:109], v[164:167], v[198:201], v[106:109]
	v_mfma_f32_16x16x32_bf16 v[110:113], v[156:159], v[198:201], v[110:113]
	v_mfma_f32_16x16x32_bf16 v[94:97], v[156:159], v[206:209], v[94:97]
	v_mfma_f32_16x16x32_bf16 v[90:93], v[164:167], v[206:209], v[90:93]
	v_mfma_f32_16x16x32_bf16 v[74:77], v[164:167], v[214:217], v[74:77]
	v_mfma_f32_16x16x32_bf16 v[78:81], v[156:159], v[214:217], v[78:81]
	s_setprio 0
	s_setprio 1
	v_mfma_f32_16x16x32_bf16 v[118:121], v[168:171], v[186:189], v[118:121]
	v_mfma_f32_16x16x32_bf16 v[114:117], v[178:181], v[186:189], v[114:117]
	v_mfma_f32_16x16x32_bf16 v[98:101], v[178:181], v[194:197], v[98:101]
	v_mfma_f32_16x16x32_bf16 v[102:105], v[168:171], v[194:197], v[102:105]
	v_mfma_f32_16x16x32_bf16 v[86:89], v[168:171], v[202:205], v[86:89]
	v_mfma_f32_16x16x32_bf16 v[82:85], v[178:181], v[202:205], v[82:85]
	v_mfma_f32_16x16x32_bf16 v[66:69], v[178:181], v[210:213], v[66:69]
	v_mfma_f32_16x16x32_bf16 v[70:73], v[168:171], v[210:213], v[70:73]
	v_mfma_f32_16x16x32_bf16 v[118:121], v[172:175], v[190:193], v[118:121]
	v_mfma_f32_16x16x32_bf16 v[114:117], v[182:185], v[190:193], v[114:117]
	v_mfma_f32_16x16x32_bf16 v[98:101], v[182:185], v[198:201], v[98:101]
	v_mfma_f32_16x16x32_bf16 v[102:105], v[172:175], v[198:201], v[102:105]
	v_mfma_f32_16x16x32_bf16 v[86:89], v[172:175], v[206:209], v[86:89]
	v_mfma_f32_16x16x32_bf16 v[82:85], v[182:185], v[206:209], v[82:85]
	v_mfma_f32_16x16x32_bf16 v[66:69], v[182:185], v[214:217], v[66:69]
	v_mfma_f32_16x16x32_bf16 v[70:73], v[172:175], v[214:217], v[70:73]
	s_setprio 0
	s_barrier
	s_add_i32 s2, s53, s34
	v_lshl_add_u64 v[146:147], v[146:147], 0, s[6:7]
	s_mov_b32 m0, s2
	ds_read_b128 v[186:189], v151 offset:49152
	ds_read_b128 v[190:193], v151 offset:50176
	ds_read_b128 v[194:197], v151 offset:51200
	ds_read_b128 v[198:201], v151 offset:52224
	ds_read_b128 v[202:205], v151 offset:53248
	ds_read_b128 v[206:209], v151 offset:54272
	ds_read_b128 v[210:213], v151 offset:55296
	ds_read_b128 v[214:217], v151 offset:56320
	global_load_lds_dwordx4 v[146:147], off
	s_add_i32 m0, s2, 0x2000
	s_add_u32 s2, s30, 0x40080
	v_lshl_add_u64 v[146:147], v[218:219], 0, s[6:7]
	s_addc_u32 s3, s31, 0
	s_add_i32 s30, s54, s34
	global_load_lds_dwordx4 v[146:147], off
	v_lshl_add_u64 v[146:147], s[2:3], 0, v[132:133]
	s_mov_b32 m0, s30
	s_nop 0
	global_load_lds_dwordx4 v[146:147], off
	v_lshl_add_u64 v[146:147], s[2:3], 0, v[136:137]
	s_add_i32 m0, s30, 0x2000
	s_nop 0
	global_load_lds_dwordx4 v[146:147], off
	v_lshl_add_u64 v[146:147], v[220:221], 0, s[6:7]
	s_mov_b32 m0, s39
	s_nop 0
	global_load_lds_dwordx4 v[146:147], off
	v_lshl_add_u64 v[146:147], v[222:223], 0, s[6:7]
	s_mov_b32 m0, s40
	s_nop 0
	global_load_lds_dwordx4 v[146:147], off
	s_waitcnt vmcnt(8)
	s_waitcnt lgkmcnt(0)
	s_barrier
	s_setprio 1
	s_waitcnt lgkmcnt(0)
	v_mfma_f32_16x16x32_bf16 v[62:65], v[152:155], v[186:189], v[62:65]
	v_mfma_f32_16x16x32_bf16 v[58:61], v[160:163], v[186:189], v[58:61]
	v_mfma_f32_16x16x32_bf16 v[42:45], v[160:163], v[194:197], v[42:45]
	v_mfma_f32_16x16x32_bf16 v[46:49], v[152:155], v[194:197], v[46:49]
	v_mfma_f32_16x16x32_bf16 v[30:33], v[152:155], v[202:205], v[30:33]
	v_mfma_f32_16x16x32_bf16 v[26:29], v[160:163], v[202:205], v[26:29]
	v_mfma_f32_16x16x32_bf16 v[10:13], v[160:163], v[210:213], v[10:13]
	v_mfma_f32_16x16x32_bf16 v[14:17], v[152:155], v[210:213], v[14:17]
	v_mfma_f32_16x16x32_bf16 v[62:65], v[156:159], v[190:193], v[62:65]
	v_mfma_f32_16x16x32_bf16 v[58:61], v[164:167], v[190:193], v[58:61]
	v_mfma_f32_16x16x32_bf16 v[42:45], v[164:167], v[198:201], v[42:45]
	v_mfma_f32_16x16x32_bf16 v[46:49], v[156:159], v[198:201], v[46:49]
	v_mfma_f32_16x16x32_bf16 v[30:33], v[156:159], v[206:209], v[30:33]
	v_mfma_f32_16x16x32_bf16 v[26:29], v[164:167], v[206:209], v[26:29]
	v_mfma_f32_16x16x32_bf16 v[10:13], v[164:167], v[214:217], v[10:13]
	v_mfma_f32_16x16x32_bf16 v[14:17], v[156:159], v[214:217], v[14:17]
	s_setprio 0
	s_setprio 1
	v_mfma_f32_16x16x32_bf16 v[54:57], v[168:171], v[186:189], v[54:57]
	v_mfma_f32_16x16x32_bf16 v[50:53], v[178:181], v[186:189], v[50:53]
	v_mfma_f32_16x16x32_bf16 v[34:37], v[178:181], v[194:197], v[34:37]
	v_mfma_f32_16x16x32_bf16 v[38:41], v[168:171], v[194:197], v[38:41]
	v_mfma_f32_16x16x32_bf16 v[22:25], v[168:171], v[202:205], v[22:25]
	v_mfma_f32_16x16x32_bf16 v[18:21], v[178:181], v[202:205], v[18:21]
	v_mfma_f32_16x16x32_bf16 v[2:5], v[178:181], v[210:213], v[2:5]
	v_mfma_f32_16x16x32_bf16 v[6:9], v[168:171], v[210:213], v[6:9]
	v_mfma_f32_16x16x32_bf16 v[54:57], v[172:175], v[190:193], v[54:57]
	v_mfma_f32_16x16x32_bf16 v[50:53], v[182:185], v[190:193], v[50:53]
	v_mfma_f32_16x16x32_bf16 v[34:37], v[182:185], v[198:201], v[34:37]
	v_mfma_f32_16x16x32_bf16 v[38:41], v[172:175], v[198:201], v[38:41]
	v_mfma_f32_16x16x32_bf16 v[22:25], v[172:175], v[206:209], v[22:25]
	v_mfma_f32_16x16x32_bf16 v[18:21], v[182:185], v[206:209], v[18:21]
	v_mfma_f32_16x16x32_bf16 v[2:5], v[182:185], v[214:217], v[2:5]
	v_mfma_f32_16x16x32_bf16 v[6:9], v[172:175], v[214:217], v[6:9]
	s_setprio 0
	s_barrier
	s_add_i32 s52, s52, 2
	s_add_u32 s28, s28, 0x100
	s_addc_u32 s29, s29, 0
	s_add_u32 s46, s46, 0x100
	s_addc_u32 s47, s47, 0
	s_cmp_gt_u32 s52, 13
	s_cbranch_scc0 .LBB0_451
	s_branch .Lpk451_exit
.LBB0_451:
	ds_read_b128 v[152:155], v149
	ds_read_b128 v[156:159], v149 offset:1024
	ds_read_b128 v[160:163], v149 offset:2048
	ds_read_b128 v[164:167], v149 offset:3072
	ds_read_b128 v[168:171], v150
	ds_read_b128 v[172:175], v150 offset:1024
	ds_read_b128 v[178:181], v150 offset:2048
	ds_read_b128 v[182:185], v150 offset:3072
	s_add_u32 s2, s28, 0xfffc0080
	s_addc_u32 s3, s29, -1
	s_cmp_eq_u32 s52, 12
	s_cselect_b32 s3, s11, s3
	s_cselect_b32 s2, s13, s2
	s_cselect_b32 s31, s44, s47
	s_cselect_b32 s30, s45, s46
	v_lshl_add_u64 v[146:147], s[28:29], 0, v[140:141]
	s_add_i32 m0, s25, 0xc000
	ds_read_b128 v[186:189], v151
	ds_read_b128 v[190:193], v151 offset:1024
	ds_read_b128 v[194:197], v151 offset:2048
	ds_read_b128 v[198:201], v151 offset:3072
	ds_read_b128 v[202:205], v151 offset:4096
	ds_read_b128 v[206:209], v151 offset:5120
	ds_read_b128 v[210:213], v151 offset:6144
	ds_read_b128 v[214:217], v151 offset:7168
	global_load_lds_dwordx4 v[146:147], off
	v_lshl_add_u64 v[146:147], s[28:29], 0, v[142:143]
	s_add_i32 m0, s25, 0xe000
	s_nop 0
	global_load_lds_dwordx4 v[146:147], off
	s_waitcnt vmcnt(8)
	s_waitcnt lgkmcnt(0)
	s_barrier
	s_setprio 1
	s_waitcnt lgkmcnt(0)
	v_mfma_f32_16x16x32_bf16 v[126:129], v[152:155], v[186:189], v[126:129]
	v_mfma_f32_16x16x32_bf16 v[122:125], v[160:163], v[186:189], v[122:125]
	v_mfma_f32_16x16x32_bf16 v[106:109], v[160:163], v[194:197], v[106:109]
	v_mfma_f32_16x16x32_bf16 v[110:113], v[152:155], v[194:197], v[110:113]
	v_mfma_f32_16x16x32_bf16 v[94:97], v[152:155], v[202:205], v[94:97]
	v_mfma_f32_16x16x32_bf16 v[90:93], v[160:163], v[202:205], v[90:93]
	v_mfma_f32_16x16x32_bf16 v[74:77], v[160:163], v[210:213], v[74:77]
	v_mfma_f32_16x16x32_bf16 v[78:81], v[152:155], v[210:213], v[78:81]
	v_mfma_f32_16x16x32_bf16 v[126:129], v[156:159], v[190:193], v[126:129]
	v_mfma_f32_16x16x32_bf16 v[122:125], v[164:167], v[190:193], v[122:125]
	v_mfma_f32_16x16x32_bf16 v[106:109], v[164:167], v[198:201], v[106:109]
	v_mfma_f32_16x16x32_bf16 v[110:113], v[156:159], v[198:201], v[110:113]
	v_mfma_f32_16x16x32_bf16 v[94:97], v[156:159], v[206:209], v[94:97]
	v_mfma_f32_16x16x32_bf16 v[90:93], v[164:167], v[206:209], v[90:93]
	v_mfma_f32_16x16x32_bf16 v[74:77], v[164:167], v[214:217], v[74:77]
	v_mfma_f32_16x16x32_bf16 v[78:81], v[156:159], v[214:217], v[78:81]
	s_setprio 0
	s_setprio 1
	v_mfma_f32_16x16x32_bf16 v[118:121], v[168:171], v[186:189], v[118:121]
	v_mfma_f32_16x16x32_bf16 v[114:117], v[178:181], v[186:189], v[114:117]
	v_mfma_f32_16x16x32_bf16 v[98:101], v[178:181], v[194:197], v[98:101]
	v_mfma_f32_16x16x32_bf16 v[102:105], v[168:171], v[194:197], v[102:105]
	v_mfma_f32_16x16x32_bf16 v[86:89], v[168:171], v[202:205], v[86:89]
	v_mfma_f32_16x16x32_bf16 v[82:85], v[178:181], v[202:205], v[82:85]
	v_mfma_f32_16x16x32_bf16 v[66:69], v[178:181], v[210:213], v[66:69]
	v_mfma_f32_16x16x32_bf16 v[70:73], v[168:171], v[210:213], v[70:73]
	v_mfma_f32_16x16x32_bf16 v[118:121], v[172:175], v[190:193], v[118:121]
	v_mfma_f32_16x16x32_bf16 v[114:117], v[182:185], v[190:193], v[114:117]
	v_mfma_f32_16x16x32_bf16 v[98:101], v[182:185], v[198:201], v[98:101]
	v_mfma_f32_16x16x32_bf16 v[102:105], v[172:175], v[198:201], v[102:105]
	v_mfma_f32_16x16x32_bf16 v[86:89], v[172:175], v[206:209], v[86:89]
	v_mfma_f32_16x16x32_bf16 v[82:85], v[182:185], v[206:209], v[82:85]
	v_mfma_f32_16x16x32_bf16 v[66:69], v[182:185], v[214:217], v[66:69]
	v_mfma_f32_16x16x32_bf16 v[70:73], v[172:175], v[214:217], v[70:73]
	s_setprio 0
	s_barrier
	s_add_i32 s53, s42, s34
	v_lshl_add_u64 v[146:147], s[30:31], 0, v[132:133]
	s_mov_b32 m0, s53
	ds_read_b128 v[186:189], v151 offset:16384
	ds_read_b128 v[190:193], v151 offset:17408
	ds_read_b128 v[194:197], v151 offset:18432
	ds_read_b128 v[198:201], v151 offset:19456
	ds_read_b128 v[202:205], v151 offset:20480
	ds_read_b128 v[206:209], v151 offset:21504
	ds_read_b128 v[210:213], v151 offset:22528
	ds_read_b128 v[214:217], v151 offset:23552
	global_load_lds_dwordx4 v[146:147], off
	s_add_i32 m0, s53, 0x2000
	s_add_u32 s54, s30, 0x40000
	v_lshl_add_u64 v[218:219], s[30:31], 0, v[136:137]
	s_addc_u32 s55, s31, 0
	s_add_i32 s53, s43, s34
	global_load_lds_dwordx4 v[218:219], off
	v_lshl_add_u64 v[220:221], s[54:55], 0, v[132:133]
	s_mov_b32 m0, s53
	v_lshl_add_u64 v[222:223], s[2:3], 0, v[134:135]
	global_load_lds_dwordx4 v[220:221], off
	v_lshl_add_u64 v[220:221], s[54:55], 0, v[136:137]
	s_add_i32 m0, s53, 0x2000
	s_nop 0
	global_load_lds_dwordx4 v[220:221], off
	v_lshl_add_u64 v[220:221], s[2:3], 0, v[130:131]
	s_mov_b32 m0, s25
	s_nop 0
	global_load_lds_dwordx4 v[220:221], off
	s_mov_b32 m0, s27
	s_nop 0
	global_load_lds_dwordx4 v[222:223], off
	s_waitcnt vmcnt(8)
	s_waitcnt lgkmcnt(0)
	s_barrier
	s_setprio 1
	s_waitcnt lgkmcnt(0)
	v_mfma_f32_16x16x32_bf16 v[62:65], v[152:155], v[186:189], v[62:65]
	v_mfma_f32_16x16x32_bf16 v[58:61], v[160:163], v[186:189], v[58:61]
	v_mfma_f32_16x16x32_bf16 v[42:45], v[160:163], v[194:197], v[42:45]
	v_mfma_f32_16x16x32_bf16 v[46:49], v[152:155], v[194:197], v[46:49]
	v_mfma_f32_16x16x32_bf16 v[30:33], v[152:155], v[202:205], v[30:33]
	v_mfma_f32_16x16x32_bf16 v[26:29], v[160:163], v[202:205], v[26:29]
	v_mfma_f32_16x16x32_bf16 v[10:13], v[160:163], v[210:213], v[10:13]
	v_mfma_f32_16x16x32_bf16 v[14:17], v[152:155], v[210:213], v[14:17]
	v_mfma_f32_16x16x32_bf16 v[62:65], v[156:159], v[190:193], v[62:65]
	v_mfma_f32_16x16x32_bf16 v[58:61], v[164:167], v[190:193], v[58:61]
	v_mfma_f32_16x16x32_bf16 v[42:45], v[164:167], v[198:201], v[42:45]
	v_mfma_f32_16x16x32_bf16 v[46:49], v[156:159], v[198:201], v[46:49]
	v_mfma_f32_16x16x32_bf16 v[30:33], v[156:159], v[206:209], v[30:33]
	v_mfma_f32_16x16x32_bf16 v[26:29], v[164:167], v[206:209], v[26:29]
	v_mfma_f32_16x16x32_bf16 v[10:13], v[164:167], v[214:217], v[10:13]
	v_mfma_f32_16x16x32_bf16 v[14:17], v[156:159], v[214:217], v[14:17]
	s_setprio 0
	s_setprio 1
	v_mfma_f32_16x16x32_bf16 v[54:57], v[168:171], v[186:189], v[54:57]
	v_mfma_f32_16x16x32_bf16 v[50:53], v[178:181], v[186:189], v[50:53]
	v_mfma_f32_16x16x32_bf16 v[34:37], v[178:181], v[194:197], v[34:37]
	v_mfma_f32_16x16x32_bf16 v[38:41], v[168:171], v[194:197], v[38:41]
	v_mfma_f32_16x16x32_bf16 v[22:25], v[168:171], v[202:205], v[22:25]
	v_mfma_f32_16x16x32_bf16 v[18:21], v[178:181], v[202:205], v[18:21]
	v_mfma_f32_16x16x32_bf16 v[2:5], v[178:181], v[210:213], v[2:5]
	v_mfma_f32_16x16x32_bf16 v[6:9], v[168:171], v[210:213], v[6:9]
	v_mfma_f32_16x16x32_bf16 v[54:57], v[172:175], v[190:193], v[54:57]
	v_mfma_f32_16x16x32_bf16 v[50:53], v[182:185], v[190:193], v[50:53]
	v_mfma_f32_16x16x32_bf16 v[34:37], v[182:185], v[198:201], v[34:37]
	v_mfma_f32_16x16x32_bf16 v[38:41], v[172:175], v[198:201], v[38:41]
	v_mfma_f32_16x16x32_bf16 v[22:25], v[172:175], v[206:209], v[22:25]
	v_mfma_f32_16x16x32_bf16 v[18:21], v[182:185], v[206:209], v[18:21]
	v_mfma_f32_16x16x32_bf16 v[2:5], v[182:185], v[214:217], v[2:5]
	v_mfma_f32_16x16x32_bf16 v[6:9], v[172:175], v[214:217], v[6:9]
	s_setprio 0
	s_barrier
	s_add_i32 s53, 0, 0x18000
	s_add_i32 s54, 0, 0x1c000
	v_add_u32_e32 v164, s53, v148
	v_add_u32_e32 v176, s54, v148
	ds_read_b128 v[152:155], v164
	ds_read_b128 v[156:159], v164 offset:1024
	ds_read_b128 v[160:163], v164 offset:2048
	ds_read_b128 v[164:167], v164 offset:3072
	ds_read_b128 v[168:171], v176
	ds_read_b128 v[172:175], v176 offset:1024
	ds_read_b128 v[178:181], v176 offset:2048
	ds_read_b128 v[182:185], v176 offset:3072
	s_add_u32 s2, s2, 0x40000
	s_addc_u32 s3, s3, 0
	s_mov_b32 m0, s36
	v_lshl_add_u64 v[224:225], s[2:3], 0, v[130:131]
	ds_read_b128 v[186:189], v151 offset:32768
	ds_read_b128 v[190:193], v151 offset:33792
	ds_read_b128 v[194:197], v151 offset:34816
	ds_read_b128 v[198:201], v151 offset:35840
	ds_read_b128 v[202:205], v151 offset:36864
	ds_read_b128 v[206:209], v151 offset:37888
	ds_read_b128 v[210:213], v151 offset:38912
	ds_read_b128 v[214:217], v151 offset:39936
	global_load_lds_dwordx4 v[224:225], off
	v_lshl_add_u64 v[224:225], s[2:3], 0, v[134:135]
	s_mov_b32 m0, s37
	s_nop 0
	global_load_lds_dwordx4 v[224:225], off
	s_waitcnt vmcnt(8)
	s_waitcnt lgkmcnt(0)
	s_barrier
	s_setprio 1
	s_waitcnt lgkmcnt(0)
	v_mfma_f32_16x16x32_bf16 v[126:129], v[152:155], v[186:189], v[126:129]
	v_mfma_f32_16x16x32_bf16 v[122:125], v[160:163], v[186:189], v[122:125]
	v_mfma_f32_16x16x32_bf16 v[106:109], v[160:163], v[194:197], v[106:109]
	v_mfma_f32_16x16x32_bf16 v[110:113], v[152:155], v[194:197], v[110:113]
	v_mfma_f32_16x16x32_bf16 v[94:97], v[152:155], v[202:205], v[94:97]
	v_mfma_f32_16x16x32_bf16 v[90:93], v[160:163], v[202:205], v[90:93]
	v_mfma_f32_16x16x32_bf16 v[74:77], v[160:163], v[210:213], v[74:77]
	v_mfma_f32_16x16x32_bf16 v[78:81], v[152:155], v[210:213], v[78:81]
	v_mfma_f32_16x16x32_bf16 v[126:129], v[156:159], v[190:193], v[126:129]
	v_mfma_f32_16x16x32_bf16 v[122:125], v[164:167], v[190:193], v[122:125]
	v_mfma_f32_16x16x32_bf16 v[106:109], v[164:167], v[198:201], v[106:109]
	v_mfma_f32_16x16x32_bf16 v[110:113], v[156:159], v[198:201], v[110:113]
	v_mfma_f32_16x16x32_bf16 v[94:97], v[156:159], v[206:209], v[94:97]
	v_mfma_f32_16x16x32_bf16 v[90:93], v[164:167], v[206:209], v[90:93]
	v_mfma_f32_16x16x32_bf16 v[74:77], v[164:167], v[214:217], v[74:77]
	v_mfma_f32_16x16x32_bf16 v[78:81], v[156:159], v[214:217], v[78:81]
	s_setprio 0
	s_setprio 1
	v_mfma_f32_16x16x32_bf16 v[118:121], v[168:171], v[186:189], v[118:121]
	v_mfma_f32_16x16x32_bf16 v[114:117], v[178:181], v[186:189], v[114:117]
	v_mfma_f32_16x16x32_bf16 v[98:101], v[178:181], v[194:197], v[98:101]
	v_mfma_f32_16x16x32_bf16 v[102:105], v[168:171], v[194:197], v[102:105]
	v_mfma_f32_16x16x32_bf16 v[86:89], v[168:171], v[202:205], v[86:89]
	v_mfma_f32_16x16x32_bf16 v[82:85], v[178:181], v[202:205], v[82:85]
	v_mfma_f32_16x16x32_bf16 v[66:69], v[178:181], v[210:213], v[66:69]
	v_mfma_f32_16x16x32_bf16 v[70:73], v[168:171], v[210:213], v[70:73]
	v_mfma_f32_16x16x32_bf16 v[118:121], v[172:175], v[190:193], v[118:121]
	v_mfma_f32_16x16x32_bf16 v[114:117], v[182:185], v[190:193], v[114:117]
	v_mfma_f32_16x16x32_bf16 v[98:101], v[182:185], v[198:201], v[98:101]
	v_mfma_f32_16x16x32_bf16 v[102:105], v[172:175], v[198:201], v[102:105]
	v_mfma_f32_16x16x32_bf16 v[86:89], v[172:175], v[206:209], v[86:89]
	v_mfma_f32_16x16x32_bf16 v[82:85], v[182:185], v[206:209], v[82:85]
	v_mfma_f32_16x16x32_bf16 v[66:69], v[182:185], v[214:217], v[66:69]
	v_mfma_f32_16x16x32_bf16 v[70:73], v[172:175], v[214:217], v[70:73]
	s_setprio 0
	s_barrier
	s_add_i32 s2, s53, s34
	v_lshl_add_u64 v[146:147], v[146:147], 0, s[6:7]
	s_mov_b32 m0, s2
	ds_read_b128 v[186:189], v151 offset:49152
	ds_read_b128 v[190:193], v151 offset:50176
	ds_read_b128 v[194:197], v151 offset:51200
	ds_read_b128 v[198:201], v151 offset:52224
	ds_read_b128 v[202:205], v151 offset:53248
	ds_read_b128 v[206:209], v151 offset:54272
	ds_read_b128 v[210:213], v151 offset:55296
	ds_read_b128 v[214:217], v151 offset:56320
	global_load_lds_dwordx4 v[146:147], off
	s_add_i32 m0, s2, 0x2000
	s_add_u32 s2, s30, 0x40080
	v_lshl_add_u64 v[146:147], v[218:219], 0, s[6:7]
	s_addc_u32 s3, s31, 0
	s_add_i32 s30, s54, s34
	global_load_lds_dwordx4 v[146:147], off
	v_lshl_add_u64 v[146:147], s[2:3], 0, v[132:133]
	s_mov_b32 m0, s30
	s_nop 0
	global_load_lds_dwordx4 v[146:147], off
	v_lshl_add_u64 v[146:147], s[2:3], 0, v[136:137]
	s_add_i32 m0, s30, 0x2000
	s_nop 0
	global_load_lds_dwordx4 v[146:147], off
	v_lshl_add_u64 v[146:147], v[220:221], 0, s[6:7]
	s_mov_b32 m0, s39
	s_nop 0
	global_load_lds_dwordx4 v[146:147], off
	v_lshl_add_u64 v[146:147], v[222:223], 0, s[6:7]
	s_mov_b32 m0, s40
	s_nop 0
	global_load_lds_dwordx4 v[146:147], off
	s_waitcnt vmcnt(8)
	s_waitcnt lgkmcnt(0)
	s_barrier
	s_setprio 1
	s_waitcnt lgkmcnt(0)
	v_mfma_f32_16x16x32_bf16 v[62:65], v[152:155], v[186:189], v[62:65]
	v_mfma_f32_16x16x32_bf16 v[58:61], v[160:163], v[186:189], v[58:61]
	v_mfma_f32_16x16x32_bf16 v[42:45], v[160:163], v[194:197], v[42:45]
	v_mfma_f32_16x16x32_bf16 v[46:49], v[152:155], v[194:197], v[46:49]
	v_mfma_f32_16x16x32_bf16 v[30:33], v[152:155], v[202:205], v[30:33]
	v_mfma_f32_16x16x32_bf16 v[26:29], v[160:163], v[202:205], v[26:29]
	v_mfma_f32_16x16x32_bf16 v[10:13], v[160:163], v[210:213], v[10:13]
	v_mfma_f32_16x16x32_bf16 v[14:17], v[152:155], v[210:213], v[14:17]
	v_mfma_f32_16x16x32_bf16 v[62:65], v[156:159], v[190:193], v[62:65]
	v_mfma_f32_16x16x32_bf16 v[58:61], v[164:167], v[190:193], v[58:61]
	v_mfma_f32_16x16x32_bf16 v[42:45], v[164:167], v[198:201], v[42:45]
	v_mfma_f32_16x16x32_bf16 v[46:49], v[156:159], v[198:201], v[46:49]
	v_mfma_f32_16x16x32_bf16 v[30:33], v[156:159], v[206:209], v[30:33]
	v_mfma_f32_16x16x32_bf16 v[26:29], v[164:167], v[206:209], v[26:29]
	v_mfma_f32_16x16x32_bf16 v[10:13], v[164:167], v[214:217], v[10:13]
	v_mfma_f32_16x16x32_bf16 v[14:17], v[156:159], v[214:217], v[14:17]
	s_setprio 0
	s_setprio 1
	v_mfma_f32_16x16x32_bf16 v[54:57], v[168:171], v[186:189], v[54:57]
	v_mfma_f32_16x16x32_bf16 v[50:53], v[178:181], v[186:189], v[50:53]
	v_mfma_f32_16x16x32_bf16 v[34:37], v[178:181], v[194:197], v[34:37]
	v_mfma_f32_16x16x32_bf16 v[38:41], v[168:171], v[194:197], v[38:41]
	v_mfma_f32_16x16x32_bf16 v[22:25], v[168:171], v[202:205], v[22:25]
	v_mfma_f32_16x16x32_bf16 v[18:21], v[178:181], v[202:205], v[18:21]
	v_mfma_f32_16x16x32_bf16 v[2:5], v[178:181], v[210:213], v[2:5]
	v_mfma_f32_16x16x32_bf16 v[6:9], v[168:171], v[210:213], v[6:9]
	v_mfma_f32_16x16x32_bf16 v[54:57], v[172:175], v[190:193], v[54:57]
	v_mfma_f32_16x16x32_bf16 v[50:53], v[182:185], v[190:193], v[50:53]
	v_mfma_f32_16x16x32_bf16 v[34:37], v[182:185], v[198:201], v[34:37]
	v_mfma_f32_16x16x32_bf16 v[38:41], v[172:175], v[198:201], v[38:41]
	v_mfma_f32_16x16x32_bf16 v[22:25], v[172:175], v[206:209], v[22:25]
	v_mfma_f32_16x16x32_bf16 v[18:21], v[182:185], v[206:209], v[18:21]
	v_mfma_f32_16x16x32_bf16 v[2:5], v[182:185], v[214:217], v[2:5]
	v_mfma_f32_16x16x32_bf16 v[6:9], v[172:175], v[214:217], v[6:9]
	s_setprio 0
	s_barrier
	s_add_i32 s52, s52, 2
	s_add_u32 s28, s28, 0x100
	s_addc_u32 s29, s29, 0
	s_add_u32 s46, s46, 0x100
	s_addc_u32 s47, s47, 0
	s_cmp_gt_u32 s52, 13
	s_cbranch_scc0 .LBB0_451

.Lpk495_peel:
	ds_read_b128 v[152:155], v149
	ds_read_b128 v[156:159], v149 offset:1024
	ds_read_b128 v[160:163], v149 offset:2048
	ds_read_b128 v[164:167], v149 offset:3072
	ds_read_b128 v[168:171], v150
	ds_read_b128 v[172:175], v150 offset:1024
	ds_read_b128 v[178:181], v150 offset:2048
	ds_read_b128 v[182:185], v150 offset:3072
	s_add_u32 s2, s18, 0x4000
	s_addc_u32 s3, s19, 0
	s_cmp_eq_u32 s50, 40
	s_cselect_b32 s2, s45, s2
	s_cselect_b32 s3, s44, s3
	s_cselect_b32 s23, s46, s49
	s_cselect_b32 s22, s47, s48
	s_add_u32 s20, s2, 0x8000
	s_addc_u32 s21, s3, 0
	v_lshl_add_u64 v[144:145], s[18:19], 0, v[138:139]
	s_add_i32 m0, s29, 0xc000
	ds_read_b128 v[186:189], v151
	ds_read_b128 v[190:193], v151 offset:1024
	ds_read_b128 v[194:197], v151 offset:2048
	ds_read_b128 v[198:201], v151 offset:3072
	ds_read_b128 v[202:205], v151 offset:4096
	ds_read_b128 v[206:209], v151 offset:5120
	ds_read_b128 v[210:213], v151 offset:6144
	ds_read_b128 v[214:217], v151 offset:7168
	global_load_lds_dwordx4 v[144:145], off
	v_lshl_add_u64 v[144:145], s[18:19], 0, v[140:141]
	s_add_i32 m0, s29, 0xe000
	s_nop 0
	global_load_lds_dwordx4 v[144:145], off
	s_waitcnt vmcnt(8)
	s_waitcnt lgkmcnt(0)
	s_barrier
	s_setprio 1
	s_waitcnt lgkmcnt(0)
	v_mfma_f32_16x16x32_bf16 v[126:129], v[152:155], v[186:189], 0
	v_mfma_f32_16x16x32_bf16 v[122:125], v[160:163], v[186:189], 0
	v_mfma_f32_16x16x32_bf16 v[106:109], v[160:163], v[194:197], 0
	v_mfma_f32_16x16x32_bf16 v[114:117], v[152:155], v[194:197], 0
	v_mfma_f32_16x16x32_bf16 v[98:101], v[152:155], v[202:205], 0
	v_mfma_f32_16x16x32_bf16 v[90:93], v[160:163], v[202:205], 0
	v_mfma_f32_16x16x32_bf16 v[74:77], v[160:163], v[210:213], 0
	v_mfma_f32_16x16x32_bf16 v[82:85], v[152:155], v[210:213], 0
	v_mfma_f32_16x16x32_bf16 v[126:129], v[156:159], v[190:193], v[126:129]
	v_mfma_f32_16x16x32_bf16 v[122:125], v[164:167], v[190:193], v[122:125]
	v_mfma_f32_16x16x32_bf16 v[106:109], v[164:167], v[198:201], v[106:109]
	v_mfma_f32_16x16x32_bf16 v[114:117], v[156:159], v[198:201], v[114:117]
	v_mfma_f32_16x16x32_bf16 v[98:101], v[156:159], v[206:209], v[98:101]
	v_mfma_f32_16x16x32_bf16 v[90:93], v[164:167], v[206:209], v[90:93]
	v_mfma_f32_16x16x32_bf16 v[74:77], v[164:167], v[214:217], v[74:77]
	v_mfma_f32_16x16x32_bf16 v[82:85], v[156:159], v[214:217], v[82:85]
	s_setprio 0
	s_setprio 1
	v_mfma_f32_16x16x32_bf16 v[118:121], v[168:171], v[186:189], 0
	v_mfma_f32_16x16x32_bf16 v[110:113], v[178:181], v[186:189], 0
	v_mfma_f32_16x16x32_bf16 v[94:97], v[178:181], v[194:197], 0
	v_mfma_f32_16x16x32_bf16 v[102:105], v[168:171], v[194:197], 0
	v_mfma_f32_16x16x32_bf16 v[86:89], v[168:171], v[202:205], 0
	v_mfma_f32_16x16x32_bf16 v[78:81], v[178:181], v[202:205], 0
	v_mfma_f32_16x16x32_bf16 v[66:69], v[178:181], v[210:213], 0
	v_mfma_f32_16x16x32_bf16 v[70:73], v[168:171], v[210:213], 0
	v_mfma_f32_16x16x32_bf16 v[118:121], v[172:175], v[190:193], v[118:121]
	v_mfma_f32_16x16x32_bf16 v[110:113], v[182:185], v[190:193], v[110:113]
	v_mfma_f32_16x16x32_bf16 v[94:97], v[182:185], v[198:201], v[94:97]
	v_mfma_f32_16x16x32_bf16 v[102:105], v[172:175], v[198:201], v[102:105]
	v_mfma_f32_16x16x32_bf16 v[86:89], v[172:175], v[206:209], v[86:89]
	v_mfma_f32_16x16x32_bf16 v[78:81], v[182:185], v[206:209], v[78:81]
	v_mfma_f32_16x16x32_bf16 v[66:69], v[182:185], v[214:217], v[66:69]
	v_mfma_f32_16x16x32_bf16 v[70:73], v[172:175], v[214:217], v[70:73]
	s_setprio 0
	s_barrier
	s_add_i32 s51, s38, s28
	v_lshl_add_u64 v[144:145], s[22:23], 0, v[132:133]
	s_mov_b32 m0, s51
	ds_read_b128 v[186:189], v151 offset:16384
	ds_read_b128 v[190:193], v151 offset:17408
	ds_read_b128 v[194:197], v151 offset:18432
	ds_read_b128 v[198:201], v151 offset:19456
	ds_read_b128 v[202:205], v151 offset:20480
	ds_read_b128 v[206:209], v151 offset:21504
	ds_read_b128 v[210:213], v151 offset:22528
	ds_read_b128 v[214:217], v151 offset:23552
	global_load_lds_dwordx4 v[144:145], off
	s_add_i32 m0, s51, 0x2000
	s_add_u32 s52, s22, 0x4000
	v_lshl_add_u64 v[144:145], s[22:23], 0, v[136:137]
	s_addc_u32 s53, s23, 0
	s_add_i32 s51, s39, s28
	global_load_lds_dwordx4 v[144:145], off
	v_lshl_add_u64 v[144:145], s[52:53], 0, v[132:133]
	s_mov_b32 m0, s51
	s_nop 0
	global_load_lds_dwordx4 v[144:145], off
	v_lshl_add_u64 v[144:145], s[52:53], 0, v[136:137]
	s_add_i32 m0, s51, 0x2000
	s_nop 0
	global_load_lds_dwordx4 v[144:145], off
	v_lshl_add_u64 v[144:145], s[2:3], 0, v[130:131]
	s_mov_b32 m0, s29
	s_nop 0
	global_load_lds_dwordx4 v[144:145], off
	v_lshl_add_u64 v[144:145], s[2:3], 0, v[134:135]
	s_mov_b32 m0, s30
	s_nop 0
	global_load_lds_dwordx4 v[144:145], off
	s_waitcnt vmcnt(8)
	s_waitcnt lgkmcnt(0)
	s_barrier
	s_setprio 1
	s_waitcnt lgkmcnt(0)
	v_mfma_f32_16x16x32_bf16 v[62:65], v[152:155], v[186:189], 0
	v_mfma_f32_16x16x32_bf16 v[58:61], v[160:163], v[186:189], 0
	v_mfma_f32_16x16x32_bf16 v[42:45], v[160:163], v[194:197], 0
	v_mfma_f32_16x16x32_bf16 v[50:53], v[152:155], v[194:197], 0
	v_mfma_f32_16x16x32_bf16 v[34:37], v[152:155], v[202:205], 0
	v_mfma_f32_16x16x32_bf16 v[26:29], v[160:163], v[202:205], 0
	v_mfma_f32_16x16x32_bf16 v[10:13], v[160:163], v[210:213], 0
	v_mfma_f32_16x16x32_bf16 v[18:21], v[152:155], v[210:213], 0
	v_mfma_f32_16x16x32_bf16 v[62:65], v[156:159], v[190:193], v[62:65]
	v_mfma_f32_16x16x32_bf16 v[58:61], v[164:167], v[190:193], v[58:61]
	v_mfma_f32_16x16x32_bf16 v[42:45], v[164:167], v[198:201], v[42:45]
	v_mfma_f32_16x16x32_bf16 v[50:53], v[156:159], v[198:201], v[50:53]
	v_mfma_f32_16x16x32_bf16 v[34:37], v[156:159], v[206:209], v[34:37]
	v_mfma_f32_16x16x32_bf16 v[26:29], v[164:167], v[206:209], v[26:29]
	v_mfma_f32_16x16x32_bf16 v[10:13], v[164:167], v[214:217], v[10:13]
	v_mfma_f32_16x16x32_bf16 v[18:21], v[156:159], v[214:217], v[18:21]
	s_setprio 0
	s_setprio 1
	v_mfma_f32_16x16x32_bf16 v[54:57], v[168:171], v[186:189], 0
	v_mfma_f32_16x16x32_bf16 v[46:49], v[178:181], v[186:189], 0
	v_mfma_f32_16x16x32_bf16 v[30:33], v[178:181], v[194:197], 0
	v_mfma_f32_16x16x32_bf16 v[38:41], v[168:171], v[194:197], 0
	v_mfma_f32_16x16x32_bf16 v[22:25], v[168:171], v[202:205], 0
	v_mfma_f32_16x16x32_bf16 v[14:17], v[178:181], v[202:205], 0
	v_mfma_f32_16x16x32_bf16 v[2:5], v[178:181], v[210:213], 0
	v_mfma_f32_16x16x32_bf16 v[6:9], v[168:171], v[210:213], 0
	v_mfma_f32_16x16x32_bf16 v[54:57], v[172:175], v[190:193], v[54:57]
	v_mfma_f32_16x16x32_bf16 v[46:49], v[182:185], v[190:193], v[46:49]
	v_mfma_f32_16x16x32_bf16 v[30:33], v[182:185], v[198:201], v[30:33]
	v_mfma_f32_16x16x32_bf16 v[38:41], v[172:175], v[198:201], v[38:41]
	v_mfma_f32_16x16x32_bf16 v[22:25], v[172:175], v[206:209], v[22:25]
	v_mfma_f32_16x16x32_bf16 v[14:17], v[182:185], v[206:209], v[14:17]
	v_mfma_f32_16x16x32_bf16 v[2:5], v[182:185], v[214:217], v[2:5]
	v_mfma_f32_16x16x32_bf16 v[6:9], v[172:175], v[214:217], v[6:9]
	s_setprio 0
	s_barrier
	s_add_i32 s51, 0, 0x18000
	v_add_u32_e32 v144, s51, v147
	s_add_i32 s52, 0, 0x1c000
	ds_read_b128 v[152:155], v144
	ds_read_b128 v[156:159], v144 offset:1024
	ds_read_b128 v[160:163], v144 offset:2048
	ds_read_b128 v[164:167], v144 offset:3072
	v_add_u32_e32 v144, s52, v147
	ds_read_b128 v[168:171], v144
	ds_read_b128 v[172:175], v144 offset:1024
	ds_read_b128 v[178:181], v144 offset:2048
	ds_read_b128 v[182:185], v144 offset:3072
	s_add_u32 s2, s2, 0x4000
	s_addc_u32 s3, s3, 0
	s_mov_b32 m0, s31
	v_lshl_add_u64 v[144:145], s[2:3], 0, v[130:131]
	ds_read_b128 v[186:189], v151 offset:32768
	ds_read_b128 v[190:193], v151 offset:33792
	ds_read_b128 v[194:197], v151 offset:34816
	ds_read_b128 v[198:201], v151 offset:35840
	ds_read_b128 v[202:205], v151 offset:36864
	ds_read_b128 v[206:209], v151 offset:37888
	ds_read_b128 v[210:213], v151 offset:38912
	ds_read_b128 v[214:217], v151 offset:39936
	global_load_lds_dwordx4 v[144:145], off
	v_lshl_add_u64 v[144:145], s[2:3], 0, v[134:135]
	s_mov_b32 m0, s34
	s_nop 0
	global_load_lds_dwordx4 v[144:145], off
	s_waitcnt vmcnt(8)
	s_waitcnt lgkmcnt(0)
	s_barrier
	s_setprio 1
	s_waitcnt lgkmcnt(0)
	v_mfma_f32_16x16x32_bf16 v[126:129], v[152:155], v[186:189], v[126:129]
	v_mfma_f32_16x16x32_bf16 v[122:125], v[160:163], v[186:189], v[122:125]
	v_mfma_f32_16x16x32_bf16 v[106:109], v[160:163], v[194:197], v[106:109]
	v_mfma_f32_16x16x32_bf16 v[114:117], v[152:155], v[194:197], v[114:117]
	v_mfma_f32_16x16x32_bf16 v[98:101], v[152:155], v[202:205], v[98:101]
	v_mfma_f32_16x16x32_bf16 v[90:93], v[160:163], v[202:205], v[90:93]
	v_mfma_f32_16x16x32_bf16 v[74:77], v[160:163], v[210:213], v[74:77]
	v_mfma_f32_16x16x32_bf16 v[82:85], v[152:155], v[210:213], v[82:85]
	v_mfma_f32_16x16x32_bf16 v[126:129], v[156:159], v[190:193], v[126:129]
	v_mfma_f32_16x16x32_bf16 v[122:125], v[164:167], v[190:193], v[122:125]
	v_mfma_f32_16x16x32_bf16 v[106:109], v[164:167], v[198:201], v[106:109]
	v_mfma_f32_16x16x32_bf16 v[114:117], v[156:159], v[198:201], v[114:117]
	v_mfma_f32_16x16x32_bf16 v[98:101], v[156:159], v[206:209], v[98:101]
	v_mfma_f32_16x16x32_bf16 v[90:93], v[164:167], v[206:209], v[90:93]
	v_mfma_f32_16x16x32_bf16 v[74:77], v[164:167], v[214:217], v[74:77]
	v_mfma_f32_16x16x32_bf16 v[82:85], v[156:159], v[214:217], v[82:85]
	s_setprio 0
	s_setprio 1
	v_mfma_f32_16x16x32_bf16 v[118:121], v[168:171], v[186:189], v[118:121]
	v_mfma_f32_16x16x32_bf16 v[110:113], v[178:181], v[186:189], v[110:113]
	v_mfma_f32_16x16x32_bf16 v[94:97], v[178:181], v[194:197], v[94:97]
	v_mfma_f32_16x16x32_bf16 v[102:105], v[168:171], v[194:197], v[102:105]
	v_mfma_f32_16x16x32_bf16 v[86:89], v[168:171], v[202:205], v[86:89]
	v_mfma_f32_16x16x32_bf16 v[78:81], v[178:181], v[202:205], v[78:81]
	v_mfma_f32_16x16x32_bf16 v[66:69], v[178:181], v[210:213], v[66:69]
	v_mfma_f32_16x16x32_bf16 v[70:73], v[168:171], v[210:213], v[70:73]
	v_mfma_f32_16x16x32_bf16 v[118:121], v[172:175], v[190:193], v[118:121]
	v_mfma_f32_16x16x32_bf16 v[110:113], v[182:185], v[190:193], v[110:113]
	v_mfma_f32_16x16x32_bf16 v[94:97], v[182:185], v[198:201], v[94:97]
	v_mfma_f32_16x16x32_bf16 v[102:105], v[172:175], v[198:201], v[102:105]
	v_mfma_f32_16x16x32_bf16 v[86:89], v[172:175], v[206:209], v[86:89]
	v_mfma_f32_16x16x32_bf16 v[78:81], v[182:185], v[206:209], v[78:81]
	v_mfma_f32_16x16x32_bf16 v[66:69], v[182:185], v[214:217], v[66:69]
	v_mfma_f32_16x16x32_bf16 v[70:73], v[172:175], v[214:217], v[70:73]
	s_setprio 0
	s_barrier
	s_add_u32 s2, s22, 0x8000
	s_addc_u32 s3, s23, 0
	s_add_i32 s51, s51, s28
	v_lshl_add_u64 v[144:145], s[2:3], 0, v[132:133]
	s_mov_b32 m0, s51
	ds_read_b128 v[186:189], v151 offset:49152
	ds_read_b128 v[190:193], v151 offset:50176
	ds_read_b128 v[194:197], v151 offset:51200
	ds_read_b128 v[198:201], v151 offset:52224
	ds_read_b128 v[202:205], v151 offset:53248
	ds_read_b128 v[206:209], v151 offset:54272
	ds_read_b128 v[210:213], v151 offset:55296
	ds_read_b128 v[214:217], v151 offset:56320
	global_load_lds_dwordx4 v[144:145], off
	s_add_i32 m0, s51, 0x2000
	v_lshl_add_u64 v[144:145], s[2:3], 0, v[136:137]
	s_add_u32 s2, s22, 0xc000
	s_addc_u32 s3, s23, 0
	s_add_i32 s22, s52, s28
	global_load_lds_dwordx4 v[144:145], off
	v_lshl_add_u64 v[144:145], s[2:3], 0, v[132:133]
	s_mov_b32 m0, s22
	s_nop 0
	global_load_lds_dwordx4 v[144:145], off
	v_lshl_add_u64 v[144:145], s[2:3], 0, v[136:137]
	s_add_i32 m0, s22, 0x2000
	s_nop 0
	global_load_lds_dwordx4 v[144:145], off
	v_lshl_add_u64 v[144:145], s[20:21], 0, v[130:131]
	s_mov_b32 m0, s36
	s_nop 0
	global_load_lds_dwordx4 v[144:145], off
	v_lshl_add_u64 v[144:145], s[20:21], 0, v[134:135]
	s_mov_b32 m0, s37
	s_nop 0
	global_load_lds_dwordx4 v[144:145], off
	s_waitcnt vmcnt(8)
	s_waitcnt lgkmcnt(0)
	s_barrier
	s_setprio 1
	s_waitcnt lgkmcnt(0)
	v_mfma_f32_16x16x32_bf16 v[62:65], v[152:155], v[186:189], v[62:65]
	v_mfma_f32_16x16x32_bf16 v[58:61], v[160:163], v[186:189], v[58:61]
	v_mfma_f32_16x16x32_bf16 v[42:45], v[160:163], v[194:197], v[42:45]
	v_mfma_f32_16x16x32_bf16 v[50:53], v[152:155], v[194:197], v[50:53]
	v_mfma_f32_16x16x32_bf16 v[34:37], v[152:155], v[202:205], v[34:37]
	v_mfma_f32_16x16x32_bf16 v[26:29], v[160:163], v[202:205], v[26:29]
	v_mfma_f32_16x16x32_bf16 v[10:13], v[160:163], v[210:213], v[10:13]
	v_mfma_f32_16x16x32_bf16 v[18:21], v[152:155], v[210:213], v[18:21]
	v_mfma_f32_16x16x32_bf16 v[62:65], v[156:159], v[190:193], v[62:65]
	v_mfma_f32_16x16x32_bf16 v[58:61], v[164:167], v[190:193], v[58:61]
	v_mfma_f32_16x16x32_bf16 v[42:45], v[164:167], v[198:201], v[42:45]
	v_mfma_f32_16x16x32_bf16 v[50:53], v[156:159], v[198:201], v[50:53]
	v_mfma_f32_16x16x32_bf16 v[34:37], v[156:159], v[206:209], v[34:37]
	v_mfma_f32_16x16x32_bf16 v[26:29], v[164:167], v[206:209], v[26:29]
	v_mfma_f32_16x16x32_bf16 v[10:13], v[164:167], v[214:217], v[10:13]
	v_mfma_f32_16x16x32_bf16 v[18:21], v[156:159], v[214:217], v[18:21]
	s_setprio 0
	s_setprio 1
	v_mfma_f32_16x16x32_bf16 v[54:57], v[168:171], v[186:189], v[54:57]
	v_mfma_f32_16x16x32_bf16 v[46:49], v[178:181], v[186:189], v[46:49]
	v_mfma_f32_16x16x32_bf16 v[30:33], v[178:181], v[194:197], v[30:33]
	v_mfma_f32_16x16x32_bf16 v[38:41], v[168:171], v[194:197], v[38:41]
	v_mfma_f32_16x16x32_bf16 v[22:25], v[168:171], v[202:205], v[22:25]
	v_mfma_f32_16x16x32_bf16 v[14:17], v[178:181], v[202:205], v[14:17]
	v_mfma_f32_16x16x32_bf16 v[2:5], v[178:181], v[210:213], v[2:5]
	v_mfma_f32_16x16x32_bf16 v[6:9], v[168:171], v[210:213], v[6:9]
	v_mfma_f32_16x16x32_bf16 v[54:57], v[172:175], v[190:193], v[54:57]
	v_mfma_f32_16x16x32_bf16 v[46:49], v[182:185], v[190:193], v[46:49]
	v_mfma_f32_16x16x32_bf16 v[30:33], v[182:185], v[198:201], v[30:33]
	v_mfma_f32_16x16x32_bf16 v[38:41], v[172:175], v[198:201], v[38:41]
	v_mfma_f32_16x16x32_bf16 v[22:25], v[172:175], v[206:209], v[22:25]
	v_mfma_f32_16x16x32_bf16 v[14:17], v[182:185], v[206:209], v[14:17]
	v_mfma_f32_16x16x32_bf16 v[2:5], v[182:185], v[214:217], v[2:5]
	v_mfma_f32_16x16x32_bf16 v[6:9], v[172:175], v[214:217], v[6:9]
	s_setprio 0
	s_barrier
	s_add_i32 s50, s50, 2
	s_add_u32 s18, s18, 0x10000
	s_addc_u32 s19, s19, 0
	s_add_u32 s48, s48, 0x10000
	s_addc_u32 s49, s49, 0
	s_cmp_gt_u32 s50, 41
	s_cbranch_scc0 .LBB0_495
	s_branch .Lpk495_exit
.LBB0_495:
	ds_read_b128 v[152:155], v149
	ds_read_b128 v[156:159], v149 offset:1024
	ds_read_b128 v[160:163], v149 offset:2048
	ds_read_b128 v[164:167], v149 offset:3072
	ds_read_b128 v[168:171], v150
	ds_read_b128 v[172:175], v150 offset:1024
	ds_read_b128 v[178:181], v150 offset:2048
	ds_read_b128 v[182:185], v150 offset:3072
	s_add_u32 s2, s18, 0x4000
	s_addc_u32 s3, s19, 0
	s_cmp_eq_u32 s50, 40
	s_cselect_b32 s2, s45, s2
	s_cselect_b32 s3, s44, s3
	s_cselect_b32 s23, s46, s49
	s_cselect_b32 s22, s47, s48
	s_add_u32 s20, s2, 0x8000
	s_addc_u32 s21, s3, 0
	v_lshl_add_u64 v[144:145], s[18:19], 0, v[138:139]
	s_add_i32 m0, s29, 0xc000
	ds_read_b128 v[186:189], v151
	ds_read_b128 v[190:193], v151 offset:1024
	ds_read_b128 v[194:197], v151 offset:2048
	ds_read_b128 v[198:201], v151 offset:3072
	ds_read_b128 v[202:205], v151 offset:4096
	ds_read_b128 v[206:209], v151 offset:5120
	ds_read_b128 v[210:213], v151 offset:6144
	ds_read_b128 v[214:217], v151 offset:7168
	global_load_lds_dwordx4 v[144:145], off
	v_lshl_add_u64 v[144:145], s[18:19], 0, v[140:141]
	s_add_i32 m0, s29, 0xe000
	s_nop 0
	global_load_lds_dwordx4 v[144:145], off
	s_waitcnt vmcnt(8)
	s_waitcnt lgkmcnt(0)
	s_barrier
	s_setprio 1
	s_waitcnt lgkmcnt(0)
	v_mfma_f32_16x16x32_bf16 v[126:129], v[152:155], v[186:189], v[126:129]
	v_mfma_f32_16x16x32_bf16 v[122:125], v[160:163], v[186:189], v[122:125]
	v_mfma_f32_16x16x32_bf16 v[106:109], v[160:163], v[194:197], v[106:109]
	v_mfma_f32_16x16x32_bf16 v[114:117], v[152:155], v[194:197], v[114:117]
	v_mfma_f32_16x16x32_bf16 v[98:101], v[152:155], v[202:205], v[98:101]
	v_mfma_f32_16x16x32_bf16 v[90:93], v[160:163], v[202:205], v[90:93]
	v_mfma_f32_16x16x32_bf16 v[74:77], v[160:163], v[210:213], v[74:77]
	v_mfma_f32_16x16x32_bf16 v[82:85], v[152:155], v[210:213], v[82:85]
	v_mfma_f32_16x16x32_bf16 v[126:129], v[156:159], v[190:193], v[126:129]
	v_mfma_f32_16x16x32_bf16 v[122:125], v[164:167], v[190:193], v[122:125]
	v_mfma_f32_16x16x32_bf16 v[106:109], v[164:167], v[198:201], v[106:109]
	v_mfma_f32_16x16x32_bf16 v[114:117], v[156:159], v[198:201], v[114:117]
	v_mfma_f32_16x16x32_bf16 v[98:101], v[156:159], v[206:209], v[98:101]
	v_mfma_f32_16x16x32_bf16 v[90:93], v[164:167], v[206:209], v[90:93]
	v_mfma_f32_16x16x32_bf16 v[74:77], v[164:167], v[214:217], v[74:77]
	v_mfma_f32_16x16x32_bf16 v[82:85], v[156:159], v[214:217], v[82:85]
	s_setprio 0
	s_setprio 1
	v_mfma_f32_16x16x32_bf16 v[118:121], v[168:171], v[186:189], v[118:121]
	v_mfma_f32_16x16x32_bf16 v[110:113], v[178:181], v[186:189], v[110:113]
	v_mfma_f32_16x16x32_bf16 v[94:97], v[178:181], v[194:197], v[94:97]
	v_mfma_f32_16x16x32_bf16 v[102:105], v[168:171], v[194:197], v[102:105]
	v_mfma_f32_16x16x32_bf16 v[86:89], v[168:171], v[202:205], v[86:89]
	v_mfma_f32_16x16x32_bf16 v[78:81], v[178:181], v[202:205], v[78:81]
	v_mfma_f32_16x16x32_bf16 v[66:69], v[178:181], v[210:213], v[66:69]
	v_mfma_f32_16x16x32_bf16 v[70:73], v[168:171], v[210:213], v[70:73]
	v_mfma_f32_16x16x32_bf16 v[118:121], v[172:175], v[190:193], v[118:121]
	v_mfma_f32_16x16x32_bf16 v[110:113], v[182:185], v[190:193], v[110:113]
	v_mfma_f32_16x16x32_bf16 v[94:97], v[182:185], v[198:201], v[94:97]
	v_mfma_f32_16x16x32_bf16 v[102:105], v[172:175], v[198:201], v[102:105]
	v_mfma_f32_16x16x32_bf16 v[86:89], v[172:175], v[206:209], v[86:89]
	v_mfma_f32_16x16x32_bf16 v[78:81], v[182:185], v[206:209], v[78:81]
	v_mfma_f32_16x16x32_bf16 v[66:69], v[182:185], v[214:217], v[66:69]
	v_mfma_f32_16x16x32_bf16 v[70:73], v[172:175], v[214:217], v[70:73]
	s_setprio 0
	s_barrier
	s_add_i32 s51, s38, s28
	v_lshl_add_u64 v[144:145], s[22:23], 0, v[132:133]
	s_mov_b32 m0, s51
	ds_read_b128 v[186:189], v151 offset:16384
	ds_read_b128 v[190:193], v151 offset:17408
	ds_read_b128 v[194:197], v151 offset:18432
	ds_read_b128 v[198:201], v151 offset:19456
	ds_read_b128 v[202:205], v151 offset:20480
	ds_read_b128 v[206:209], v151 offset:21504
	ds_read_b128 v[210:213], v151 offset:22528
	ds_read_b128 v[214:217], v151 offset:23552
	global_load_lds_dwordx4 v[144:145], off
	s_add_i32 m0, s51, 0x2000
	s_add_u32 s52, s22, 0x4000
	v_lshl_add_u64 v[144:145], s[22:23], 0, v[136:137]
	s_addc_u32 s53, s23, 0
	s_add_i32 s51, s39, s28
	global_load_lds_dwordx4 v[144:145], off
	v_lshl_add_u64 v[144:145], s[52:53], 0, v[132:133]
	s_mov_b32 m0, s51
	s_nop 0
	global_load_lds_dwordx4 v[144:145], off
	v_lshl_add_u64 v[144:145], s[52:53], 0, v[136:137]
	s_add_i32 m0, s51, 0x2000
	s_nop 0
	global_load_lds_dwordx4 v[144:145], off
	v_lshl_add_u64 v[144:145], s[2:3], 0, v[130:131]
	s_mov_b32 m0, s29
	s_nop 0
	global_load_lds_dwordx4 v[144:145], off
	v_lshl_add_u64 v[144:145], s[2:3], 0, v[134:135]
	s_mov_b32 m0, s30
	s_nop 0
	global_load_lds_dwordx4 v[144:145], off
	s_waitcnt vmcnt(8)
	s_waitcnt lgkmcnt(0)
	s_barrier
	s_setprio 1
	s_waitcnt lgkmcnt(0)
	v_mfma_f32_16x16x32_bf16 v[62:65], v[152:155], v[186:189], v[62:65]
	v_mfma_f32_16x16x32_bf16 v[58:61], v[160:163], v[186:189], v[58:61]
	v_mfma_f32_16x16x32_bf16 v[42:45], v[160:163], v[194:197], v[42:45]
	v_mfma_f32_16x16x32_bf16 v[50:53], v[152:155], v[194:197], v[50:53]
	v_mfma_f32_16x16x32_bf16 v[34:37], v[152:155], v[202:205], v[34:37]
	v_mfma_f32_16x16x32_bf16 v[26:29], v[160:163], v[202:205], v[26:29]
	v_mfma_f32_16x16x32_bf16 v[10:13], v[160:163], v[210:213], v[10:13]
	v_mfma_f32_16x16x32_bf16 v[18:21], v[152:155], v[210:213], v[18:21]
	v_mfma_f32_16x16x32_bf16 v[62:65], v[156:159], v[190:193], v[62:65]
	v_mfma_f32_16x16x32_bf16 v[58:61], v[164:167], v[190:193], v[58:61]
	v_mfma_f32_16x16x32_bf16 v[42:45], v[164:167], v[198:201], v[42:45]
	v_mfma_f32_16x16x32_bf16 v[50:53], v[156:159], v[198:201], v[50:53]
	v_mfma_f32_16x16x32_bf16 v[34:37], v[156:159], v[206:209], v[34:37]
	v_mfma_f32_16x16x32_bf16 v[26:29], v[164:167], v[206:209], v[26:29]
	v_mfma_f32_16x16x32_bf16 v[10:13], v[164:167], v[214:217], v[10:13]
	v_mfma_f32_16x16x32_bf16 v[18:21], v[156:159], v[214:217], v[18:21]
	s_setprio 0
	s_setprio 1
	v_mfma_f32_16x16x32_bf16 v[54:57], v[168:171], v[186:189], v[54:57]
	v_mfma_f32_16x16x32_bf16 v[46:49], v[178:181], v[186:189], v[46:49]
	v_mfma_f32_16x16x32_bf16 v[30:33], v[178:181], v[194:197], v[30:33]
	v_mfma_f32_16x16x32_bf16 v[38:41], v[168:171], v[194:197], v[38:41]
	v_mfma_f32_16x16x32_bf16 v[22:25], v[168:171], v[202:205], v[22:25]
	v_mfma_f32_16x16x32_bf16 v[14:17], v[178:181], v[202:205], v[14:17]
	v_mfma_f32_16x16x32_bf16 v[2:5], v[178:181], v[210:213], v[2:5]
	v_mfma_f32_16x16x32_bf16 v[6:9], v[168:171], v[210:213], v[6:9]
	v_mfma_f32_16x16x32_bf16 v[54:57], v[172:175], v[190:193], v[54:57]
	v_mfma_f32_16x16x32_bf16 v[46:49], v[182:185], v[190:193], v[46:49]
	v_mfma_f32_16x16x32_bf16 v[30:33], v[182:185], v[198:201], v[30:33]
	v_mfma_f32_16x16x32_bf16 v[38:41], v[172:175], v[198:201], v[38:41]
	v_mfma_f32_16x16x32_bf16 v[22:25], v[172:175], v[206:209], v[22:25]
	v_mfma_f32_16x16x32_bf16 v[14:17], v[182:185], v[206:209], v[14:17]
	v_mfma_f32_16x16x32_bf16 v[2:5], v[182:185], v[214:217], v[2:5]
	v_mfma_f32_16x16x32_bf16 v[6:9], v[172:175], v[214:217], v[6:9]
	s_setprio 0
	s_barrier
	s_add_i32 s51, 0, 0x18000
	v_add_u32_e32 v144, s51, v147
	s_add_i32 s52, 0, 0x1c000
	ds_read_b128 v[152:155], v144
	ds_read_b128 v[156:159], v144 offset:1024
	ds_read_b128 v[160:163], v144 offset:2048
	ds_read_b128 v[164:167], v144 offset:3072
	v_add_u32_e32 v144, s52, v147
	ds_read_b128 v[168:171], v144
	ds_read_b128 v[172:175], v144 offset:1024
	ds_read_b128 v[178:181], v144 offset:2048
	ds_read_b128 v[182:185], v144 offset:3072
	s_add_u32 s2, s2, 0x4000
	s_addc_u32 s3, s3, 0
	s_mov_b32 m0, s31
	v_lshl_add_u64 v[144:145], s[2:3], 0, v[130:131]
	ds_read_b128 v[186:189], v151 offset:32768
	ds_read_b128 v[190:193], v151 offset:33792
	ds_read_b128 v[194:197], v151 offset:34816
	ds_read_b128 v[198:201], v151 offset:35840
	ds_read_b128 v[202:205], v151 offset:36864
	ds_read_b128 v[206:209], v151 offset:37888
	ds_read_b128 v[210:213], v151 offset:38912
	ds_read_b128 v[214:217], v151 offset:39936
	global_load_lds_dwordx4 v[144:145], off
	v_lshl_add_u64 v[144:145], s[2:3], 0, v[134:135]
	s_mov_b32 m0, s34
	s_nop 0
	global_load_lds_dwordx4 v[144:145], off
	s_waitcnt vmcnt(8)
	s_waitcnt lgkmcnt(0)
	s_barrier
	s_setprio 1
	s_waitcnt lgkmcnt(0)
	v_mfma_f32_16x16x32_bf16 v[126:129], v[152:155], v[186:189], v[126:129]
	v_mfma_f32_16x16x32_bf16 v[122:125], v[160:163], v[186:189], v[122:125]
	v_mfma_f32_16x16x32_bf16 v[106:109], v[160:163], v[194:197], v[106:109]
	v_mfma_f32_16x16x32_bf16 v[114:117], v[152:155], v[194:197], v[114:117]
	v_mfma_f32_16x16x32_bf16 v[98:101], v[152:155], v[202:205], v[98:101]
	v_mfma_f32_16x16x32_bf16 v[90:93], v[160:163], v[202:205], v[90:93]
	v_mfma_f32_16x16x32_bf16 v[74:77], v[160:163], v[210:213], v[74:77]
	v_mfma_f32_16x16x32_bf16 v[82:85], v[152:155], v[210:213], v[82:85]
	v_mfma_f32_16x16x32_bf16 v[126:129], v[156:159], v[190:193], v[126:129]
	v_mfma_f32_16x16x32_bf16 v[122:125], v[164:167], v[190:193], v[122:125]
	v_mfma_f32_16x16x32_bf16 v[106:109], v[164:167], v[198:201], v[106:109]
	v_mfma_f32_16x16x32_bf16 v[114:117], v[156:159], v[198:201], v[114:117]
	v_mfma_f32_16x16x32_bf16 v[98:101], v[156:159], v[206:209], v[98:101]
	v_mfma_f32_16x16x32_bf16 v[90:93], v[164:167], v[206:209], v[90:93]
	v_mfma_f32_16x16x32_bf16 v[74:77], v[164:167], v[214:217], v[74:77]
	v_mfma_f32_16x16x32_bf16 v[82:85], v[156:159], v[214:217], v[82:85]
	s_setprio 0
	s_setprio 1
	v_mfma_f32_16x16x32_bf16 v[118:121], v[168:171], v[186:189], v[118:121]
	v_mfma_f32_16x16x32_bf16 v[110:113], v[178:181], v[186:189], v[110:113]
	v_mfma_f32_16x16x32_bf16 v[94:97], v[178:181], v[194:197], v[94:97]
	v_mfma_f32_16x16x32_bf16 v[102:105], v[168:171], v[194:197], v[102:105]
	v_mfma_f32_16x16x32_bf16 v[86:89], v[168:171], v[202:205], v[86:89]
	v_mfma_f32_16x16x32_bf16 v[78:81], v[178:181], v[202:205], v[78:81]
	v_mfma_f32_16x16x32_bf16 v[66:69], v[178:181], v[210:213], v[66:69]
	v_mfma_f32_16x16x32_bf16 v[70:73], v[168:171], v[210:213], v[70:73]
	v_mfma_f32_16x16x32_bf16 v[118:121], v[172:175], v[190:193], v[118:121]
	v_mfma_f32_16x16x32_bf16 v[110:113], v[182:185], v[190:193], v[110:113]
	v_mfma_f32_16x16x32_bf16 v[94:97], v[182:185], v[198:201], v[94:97]
	v_mfma_f32_16x16x32_bf16 v[102:105], v[172:175], v[198:201], v[102:105]
	v_mfma_f32_16x16x32_bf16 v[86:89], v[172:175], v[206:209], v[86:89]
	v_mfma_f32_16x16x32_bf16 v[78:81], v[182:185], v[206:209], v[78:81]
	v_mfma_f32_16x16x32_bf16 v[66:69], v[182:185], v[214:217], v[66:69]
	v_mfma_f32_16x16x32_bf16 v[70:73], v[172:175], v[214:217], v[70:73]
	s_setprio 0
	s_barrier
	s_add_u32 s2, s22, 0x8000
	s_addc_u32 s3, s23, 0
	s_add_i32 s51, s51, s28
	v_lshl_add_u64 v[144:145], s[2:3], 0, v[132:133]
	s_mov_b32 m0, s51
	ds_read_b128 v[186:189], v151 offset:49152
	ds_read_b128 v[190:193], v151 offset:50176
	ds_read_b128 v[194:197], v151 offset:51200
	ds_read_b128 v[198:201], v151 offset:52224
	ds_read_b128 v[202:205], v151 offset:53248
	ds_read_b128 v[206:209], v151 offset:54272
	ds_read_b128 v[210:213], v151 offset:55296
	ds_read_b128 v[214:217], v151 offset:56320
	global_load_lds_dwordx4 v[144:145], off
	s_add_i32 m0, s51, 0x2000
	v_lshl_add_u64 v[144:145], s[2:3], 0, v[136:137]
	s_add_u32 s2, s22, 0xc000
	s_addc_u32 s3, s23, 0
	s_add_i32 s22, s52, s28
	global_load_lds_dwordx4 v[144:145], off
	v_lshl_add_u64 v[144:145], s[2:3], 0, v[132:133]
	s_mov_b32 m0, s22
	s_nop 0
	global_load_lds_dwordx4 v[144:145], off
	v_lshl_add_u64 v[144:145], s[2:3], 0, v[136:137]
	s_add_i32 m0, s22, 0x2000
	s_nop 0
	global_load_lds_dwordx4 v[144:145], off
	v_lshl_add_u64 v[144:145], s[20:21], 0, v[130:131]
	s_mov_b32 m0, s36
	s_nop 0
	global_load_lds_dwordx4 v[144:145], off
	v_lshl_add_u64 v[144:145], s[20:21], 0, v[134:135]
	s_mov_b32 m0, s37
	s_nop 0
	global_load_lds_dwordx4 v[144:145], off
	s_waitcnt vmcnt(8)
	s_waitcnt lgkmcnt(0)
	s_barrier
	s_setprio 1
	s_waitcnt lgkmcnt(0)
	v_mfma_f32_16x16x32_bf16 v[62:65], v[152:155], v[186:189], v[62:65]
	v_mfma_f32_16x16x32_bf16 v[58:61], v[160:163], v[186:189], v[58:61]
	v_mfma_f32_16x16x32_bf16 v[42:45], v[160:163], v[194:197], v[42:45]
	v_mfma_f32_16x16x32_bf16 v[50:53], v[152:155], v[194:197], v[50:53]
	v_mfma_f32_16x16x32_bf16 v[34:37], v[152:155], v[202:205], v[34:37]
	v_mfma_f32_16x16x32_bf16 v[26:29], v[160:163], v[202:205], v[26:29]
	v_mfma_f32_16x16x32_bf16 v[10:13], v[160:163], v[210:213], v[10:13]
	v_mfma_f32_16x16x32_bf16 v[18:21], v[152:155], v[210:213], v[18:21]
	v_mfma_f32_16x16x32_bf16 v[62:65], v[156:159], v[190:193], v[62:65]
	v_mfma_f32_16x16x32_bf16 v[58:61], v[164:167], v[190:193], v[58:61]
	v_mfma_f32_16x16x32_bf16 v[42:45], v[164:167], v[198:201], v[42:45]
	v_mfma_f32_16x16x32_bf16 v[50:53], v[156:159], v[198:201], v[50:53]
	v_mfma_f32_16x16x32_bf16 v[34:37], v[156:159], v[206:209], v[34:37]
	v_mfma_f32_16x16x32_bf16 v[26:29], v[164:167], v[206:209], v[26:29]
	v_mfma_f32_16x16x32_bf16 v[10:13], v[164:167], v[214:217], v[10:13]
	v_mfma_f32_16x16x32_bf16 v[18:21], v[156:159], v[214:217], v[18:21]
	s_setprio 0
	s_setprio 1
	v_mfma_f32_16x16x32_bf16 v[54:57], v[168:171], v[186:189], v[54:57]
	v_mfma_f32_16x16x32_bf16 v[46:49], v[178:181], v[186:189], v[46:49]
	v_mfma_f32_16x16x32_bf16 v[30:33], v[178:181], v[194:197], v[30:33]
	v_mfma_f32_16x16x32_bf16 v[38:41], v[168:171], v[194:197], v[38:41]
	v_mfma_f32_16x16x32_bf16 v[22:25], v[168:171], v[202:205], v[22:25]
	v_mfma_f32_16x16x32_bf16 v[14:17], v[178:181], v[202:205], v[14:17]
	v_mfma_f32_16x16x32_bf16 v[2:5], v[178:181], v[210:213], v[2:5]
	v_mfma_f32_16x16x32_bf16 v[6:9], v[168:171], v[210:213], v[6:9]
	v_mfma_f32_16x16x32_bf16 v[54:57], v[172:175], v[190:193], v[54:57]
	v_mfma_f32_16x16x32_bf16 v[46:49], v[182:185], v[190:193], v[46:49]
	v_mfma_f32_16x16x32_bf16 v[30:33], v[182:185], v[198:201], v[30:33]
	v_mfma_f32_16x16x32_bf16 v[38:41], v[172:175], v[198:201], v[38:41]
	v_mfma_f32_16x16x32_bf16 v[22:25], v[172:175], v[206:209], v[22:25]
	v_mfma_f32_16x16x32_bf16 v[14:17], v[182:185], v[206:209], v[14:17]
	v_mfma_f32_16x16x32_bf16 v[2:5], v[182:185], v[214:217], v[2:5]
	v_mfma_f32_16x16x32_bf16 v[6:9], v[172:175], v[214:217], v[6:9]
	s_setprio 0
	s_barrier
	s_add_i32 s50, s50, 2
	s_add_u32 s18, s18, 0x10000
	s_addc_u32 s19, s19, 0
	s_add_u32 s48, s48, 0x10000
	s_addc_u32 s49, s49, 0
	s_cmp_gt_u32 s50, 41
	s_cbranch_scc0 .LBB0_495

.Lpk555_peel:
	ds_read_b128 v[154:157], v151
	ds_read_b128 v[158:161], v151 offset:1024
	ds_read_b128 v[162:165], v151 offset:2048
	ds_read_b128 v[166:169], v151 offset:3072
	ds_read_b128 v[170:173], v152
	ds_read_b128 v[178:181], v152 offset:1024
	ds_read_b128 v[182:185], v152 offset:2048
	ds_read_b128 v[186:189], v152 offset:3072
	s_add_u32 s2, s26, 0xfffc0080
	s_addc_u32 s3, s27, -1
	s_cmp_eq_u32 s52, 12
	s_cselect_b32 s3, s11, s3
	s_cselect_b32 s2, s13, s2
	s_cselect_b32 s29, s48, s51
	s_cselect_b32 s28, s49, s50
	v_lshl_add_u64 v[144:145], s[26:27], 0, v[138:139]
	s_add_i32 m0, s37, 0xc000
	ds_read_b128 v[190:193], v153
	ds_read_b128 v[194:197], v153 offset:1024
	ds_read_b128 v[198:201], v153 offset:2048
	ds_read_b128 v[202:205], v153 offset:3072
	ds_read_b128 v[206:209], v153 offset:4096
	ds_read_b128 v[210:213], v153 offset:5120
	ds_read_b128 v[214:217], v153 offset:6144
	ds_read_b128 v[218:221], v153 offset:7168
	global_load_lds_dwordx4 v[144:145], off
	v_lshl_add_u64 v[144:145], s[26:27], 0, v[140:141]
	s_add_i32 m0, s37, 0xe000
	s_nop 0
	global_load_lds_dwordx4 v[144:145], off
	s_waitcnt vmcnt(8)
	s_waitcnt lgkmcnt(0)
	s_barrier
	s_setprio 1
	s_waitcnt lgkmcnt(0)
	v_mfma_f32_16x16x32_bf16 v[126:129], v[154:157], v[190:193], 0
	v_mfma_f32_16x16x32_bf16 v[122:125], v[162:165], v[190:193], 0
	v_mfma_f32_16x16x32_bf16 v[106:109], v[162:165], v[198:201], 0
	v_mfma_f32_16x16x32_bf16 v[114:117], v[154:157], v[198:201], 0
	v_mfma_f32_16x16x32_bf16 v[98:101], v[154:157], v[206:209], 0
	v_mfma_f32_16x16x32_bf16 v[90:93], v[162:165], v[206:209], 0
	v_mfma_f32_16x16x32_bf16 v[74:77], v[162:165], v[214:217], 0
	v_mfma_f32_16x16x32_bf16 v[82:85], v[154:157], v[214:217], 0
	v_mfma_f32_16x16x32_bf16 v[126:129], v[158:161], v[194:197], v[126:129]
	v_mfma_f32_16x16x32_bf16 v[122:125], v[166:169], v[194:197], v[122:125]
	v_mfma_f32_16x16x32_bf16 v[106:109], v[166:169], v[202:205], v[106:109]
	v_mfma_f32_16x16x32_bf16 v[114:117], v[158:161], v[202:205], v[114:117]
	v_mfma_f32_16x16x32_bf16 v[98:101], v[158:161], v[210:213], v[98:101]
	v_mfma_f32_16x16x32_bf16 v[90:93], v[166:169], v[210:213], v[90:93]
	v_mfma_f32_16x16x32_bf16 v[74:77], v[166:169], v[218:221], v[74:77]
	v_mfma_f32_16x16x32_bf16 v[82:85], v[158:161], v[218:221], v[82:85]
	s_setprio 0
	s_setprio 1
	v_mfma_f32_16x16x32_bf16 v[118:121], v[170:173], v[190:193], 0
	v_mfma_f32_16x16x32_bf16 v[110:113], v[182:185], v[190:193], 0
	v_mfma_f32_16x16x32_bf16 v[94:97], v[182:185], v[198:201], 0
	v_mfma_f32_16x16x32_bf16 v[102:105], v[170:173], v[198:201], 0
	v_mfma_f32_16x16x32_bf16 v[86:89], v[170:173], v[206:209], 0
	v_mfma_f32_16x16x32_bf16 v[78:81], v[182:185], v[206:209], 0
	v_mfma_f32_16x16x32_bf16 v[66:69], v[182:185], v[214:217], 0
	v_mfma_f32_16x16x32_bf16 v[70:73], v[170:173], v[214:217], 0
	v_mfma_f32_16x16x32_bf16 v[118:121], v[178:181], v[194:197], v[118:121]
	v_mfma_f32_16x16x32_bf16 v[110:113], v[186:189], v[194:197], v[110:113]
	v_mfma_f32_16x16x32_bf16 v[94:97], v[186:189], v[202:205], v[94:97]
	v_mfma_f32_16x16x32_bf16 v[102:105], v[178:181], v[202:205], v[102:105]
	v_mfma_f32_16x16x32_bf16 v[86:89], v[178:181], v[210:213], v[86:89]
	v_mfma_f32_16x16x32_bf16 v[78:81], v[186:189], v[210:213], v[78:81]
	v_mfma_f32_16x16x32_bf16 v[66:69], v[186:189], v[218:221], v[66:69]
	v_mfma_f32_16x16x32_bf16 v[70:73], v[178:181], v[218:221], v[70:73]
	s_setprio 0
	s_barrier
	s_add_i32 s53, s44, s34
	v_lshl_add_u64 v[144:145], s[28:29], 0, v[134:135]
	s_mov_b32 m0, s53
	ds_read_b128 v[190:193], v153 offset:16384
	ds_read_b128 v[194:197], v153 offset:17408
	ds_read_b128 v[198:201], v153 offset:18432
	ds_read_b128 v[202:205], v153 offset:19456
	ds_read_b128 v[206:209], v153 offset:20480
	ds_read_b128 v[210:213], v153 offset:21504
	ds_read_b128 v[214:217], v153 offset:22528
	ds_read_b128 v[218:221], v153 offset:23552
	global_load_lds_dwordx4 v[144:145], off
	s_add_i32 m0, s53, 0x2000
	s_add_u32 s54, s28, 0x40000
	v_lshl_add_u64 v[174:175], s[28:29], 0, v[130:131]
	s_addc_u32 s55, s29, 0
	s_add_i32 s53, s45, s34
	global_load_lds_dwordx4 v[174:175], off
	v_lshl_add_u64 v[222:223], s[54:55], 0, v[134:135]
	s_mov_b32 m0, s53
	v_lshl_add_u64 v[224:225], s[2:3], 0, v[132:133]
	global_load_lds_dwordx4 v[222:223], off
	v_lshl_add_u64 v[222:223], s[54:55], 0, v[130:131]
	s_add_i32 m0, s53, 0x2000
	s_nop 0
	global_load_lds_dwordx4 v[222:223], off
	v_lshl_add_u64 v[222:223], s[2:3], 0, v[136:137]
	s_mov_b32 m0, s37
	s_nop 0
	global_load_lds_dwordx4 v[222:223], off
	s_mov_b32 m0, s25
	s_nop 0
	global_load_lds_dwordx4 v[224:225], off
	s_waitcnt vmcnt(8)
	s_waitcnt lgkmcnt(0)
	s_barrier
	s_setprio 1
	s_waitcnt lgkmcnt(0)
	v_mfma_f32_16x16x32_bf16 v[62:65], v[154:157], v[190:193], 0
	v_mfma_f32_16x16x32_bf16 v[58:61], v[162:165], v[190:193], 0
	v_mfma_f32_16x16x32_bf16 v[42:45], v[162:165], v[198:201], 0
	v_mfma_f32_16x16x32_bf16 v[50:53], v[154:157], v[198:201], 0
	v_mfma_f32_16x16x32_bf16 v[34:37], v[154:157], v[206:209], 0
	v_mfma_f32_16x16x32_bf16 v[26:29], v[162:165], v[206:209], 0
	v_mfma_f32_16x16x32_bf16 v[10:13], v[162:165], v[214:217], 0
	v_mfma_f32_16x16x32_bf16 v[18:21], v[154:157], v[214:217], 0
	v_mfma_f32_16x16x32_bf16 v[62:65], v[158:161], v[194:197], v[62:65]
	v_mfma_f32_16x16x32_bf16 v[58:61], v[166:169], v[194:197], v[58:61]
	v_mfma_f32_16x16x32_bf16 v[42:45], v[166:169], v[202:205], v[42:45]
	v_mfma_f32_16x16x32_bf16 v[50:53], v[158:161], v[202:205], v[50:53]
	v_mfma_f32_16x16x32_bf16 v[34:37], v[158:161], v[210:213], v[34:37]
	v_mfma_f32_16x16x32_bf16 v[26:29], v[166:169], v[210:213], v[26:29]
	v_mfma_f32_16x16x32_bf16 v[10:13], v[166:169], v[218:221], v[10:13]
	v_mfma_f32_16x16x32_bf16 v[18:21], v[158:161], v[218:221], v[18:21]
	s_setprio 0
	s_setprio 1
	v_mfma_f32_16x16x32_bf16 v[54:57], v[170:173], v[190:193], 0
	v_mfma_f32_16x16x32_bf16 v[46:49], v[182:185], v[190:193], 0
	v_mfma_f32_16x16x32_bf16 v[30:33], v[182:185], v[198:201], 0
	v_mfma_f32_16x16x32_bf16 v[38:41], v[170:173], v[198:201], 0
	v_mfma_f32_16x16x32_bf16 v[22:25], v[170:173], v[206:209], 0
	v_mfma_f32_16x16x32_bf16 v[14:17], v[182:185], v[206:209], 0
	v_mfma_f32_16x16x32_bf16 v[2:5], v[182:185], v[214:217], 0
	v_mfma_f32_16x16x32_bf16 v[6:9], v[170:173], v[214:217], 0
	v_mfma_f32_16x16x32_bf16 v[54:57], v[178:181], v[194:197], v[54:57]
	v_mfma_f32_16x16x32_bf16 v[46:49], v[186:189], v[194:197], v[46:49]
	v_mfma_f32_16x16x32_bf16 v[30:33], v[186:189], v[202:205], v[30:33]
	v_mfma_f32_16x16x32_bf16 v[38:41], v[178:181], v[202:205], v[38:41]
	v_mfma_f32_16x16x32_bf16 v[22:25], v[178:181], v[210:213], v[22:25]
	v_mfma_f32_16x16x32_bf16 v[14:17], v[186:189], v[210:213], v[14:17]
	v_mfma_f32_16x16x32_bf16 v[2:5], v[186:189], v[218:221], v[2:5]
	v_mfma_f32_16x16x32_bf16 v[6:9], v[178:181], v[218:221], v[6:9]
	s_setprio 0
	s_barrier
	s_add_i32 s53, 0, 0x18000
	s_add_i32 s54, 0, 0x1c000
	v_add_u32_e32 v166, s53, v149
	v_add_u32_e32 v176, s54, v149
	ds_read_b128 v[154:157], v166
	ds_read_b128 v[158:161], v166 offset:1024
	ds_read_b128 v[162:165], v166 offset:2048
	ds_read_b128 v[166:169], v166 offset:3072
	ds_read_b128 v[170:173], v176
	ds_read_b128 v[178:181], v176 offset:1024
	ds_read_b128 v[182:185], v176 offset:2048
	ds_read_b128 v[186:189], v176 offset:3072
	s_add_u32 s2, s2, 0x40000
	s_addc_u32 s3, s3, 0
	s_mov_b32 m0, s38
	v_lshl_add_u64 v[226:227], s[2:3], 0, v[136:137]
	ds_read_b128 v[190:193], v153 offset:32768
	ds_read_b128 v[194:197], v153 offset:33792
	ds_read_b128 v[198:201], v153 offset:34816
	ds_read_b128 v[202:205], v153 offset:35840
	ds_read_b128 v[206:209], v153 offset:36864
	ds_read_b128 v[210:213], v153 offset:37888
	ds_read_b128 v[214:217], v153 offset:38912
	ds_read_b128 v[218:221], v153 offset:39936
	global_load_lds_dwordx4 v[226:227], off
	v_lshl_add_u64 v[226:227], s[2:3], 0, v[132:133]
	s_mov_b32 m0, s39
	s_nop 0
	global_load_lds_dwordx4 v[226:227], off
	s_waitcnt vmcnt(8)
	s_waitcnt lgkmcnt(0)
	s_barrier
	s_setprio 1
	s_waitcnt lgkmcnt(0)
	v_mfma_f32_16x16x32_bf16 v[126:129], v[154:157], v[190:193], v[126:129]
	v_mfma_f32_16x16x32_bf16 v[122:125], v[162:165], v[190:193], v[122:125]
	v_mfma_f32_16x16x32_bf16 v[106:109], v[162:165], v[198:201], v[106:109]
	v_mfma_f32_16x16x32_bf16 v[114:117], v[154:157], v[198:201], v[114:117]
	v_mfma_f32_16x16x32_bf16 v[98:101], v[154:157], v[206:209], v[98:101]
	v_mfma_f32_16x16x32_bf16 v[90:93], v[162:165], v[206:209], v[90:93]
	v_mfma_f32_16x16x32_bf16 v[74:77], v[162:165], v[214:217], v[74:77]
	v_mfma_f32_16x16x32_bf16 v[82:85], v[154:157], v[214:217], v[82:85]
	v_mfma_f32_16x16x32_bf16 v[126:129], v[158:161], v[194:197], v[126:129]
	v_mfma_f32_16x16x32_bf16 v[122:125], v[166:169], v[194:197], v[122:125]
	v_mfma_f32_16x16x32_bf16 v[106:109], v[166:169], v[202:205], v[106:109]
	v_mfma_f32_16x16x32_bf16 v[114:117], v[158:161], v[202:205], v[114:117]
	v_mfma_f32_16x16x32_bf16 v[98:101], v[158:161], v[210:213], v[98:101]
	v_mfma_f32_16x16x32_bf16 v[90:93], v[166:169], v[210:213], v[90:93]
	v_mfma_f32_16x16x32_bf16 v[74:77], v[166:169], v[218:221], v[74:77]
	v_mfma_f32_16x16x32_bf16 v[82:85], v[158:161], v[218:221], v[82:85]
	s_setprio 0
	s_setprio 1
	v_mfma_f32_16x16x32_bf16 v[118:121], v[170:173], v[190:193], v[118:121]
	v_mfma_f32_16x16x32_bf16 v[110:113], v[182:185], v[190:193], v[110:113]
	v_mfma_f32_16x16x32_bf16 v[94:97], v[182:185], v[198:201], v[94:97]
	v_mfma_f32_16x16x32_bf16 v[102:105], v[170:173], v[198:201], v[102:105]
	v_mfma_f32_16x16x32_bf16 v[86:89], v[170:173], v[206:209], v[86:89]
	v_mfma_f32_16x16x32_bf16 v[78:81], v[182:185], v[206:209], v[78:81]
	v_mfma_f32_16x16x32_bf16 v[66:69], v[182:185], v[214:217], v[66:69]
	v_mfma_f32_16x16x32_bf16 v[70:73], v[170:173], v[214:217], v[70:73]
	v_mfma_f32_16x16x32_bf16 v[118:121], v[178:181], v[194:197], v[118:121]
	v_mfma_f32_16x16x32_bf16 v[110:113], v[186:189], v[194:197], v[110:113]
	v_mfma_f32_16x16x32_bf16 v[94:97], v[186:189], v[202:205], v[94:97]
	v_mfma_f32_16x16x32_bf16 v[102:105], v[178:181], v[202:205], v[102:105]
	v_mfma_f32_16x16x32_bf16 v[86:89], v[178:181], v[210:213], v[86:89]
	v_mfma_f32_16x16x32_bf16 v[78:81], v[186:189], v[210:213], v[78:81]
	v_mfma_f32_16x16x32_bf16 v[66:69], v[186:189], v[218:221], v[66:69]
	v_mfma_f32_16x16x32_bf16 v[70:73], v[178:181], v[218:221], v[70:73]
	s_setprio 0
	s_barrier
	s_add_i32 s2, s53, s34
	v_lshl_add_u64 v[144:145], v[144:145], 0, s[6:7]
	s_mov_b32 m0, s2
	ds_read_b128 v[190:193], v153 offset:49152
	ds_read_b128 v[194:197], v153 offset:50176
	ds_read_b128 v[198:201], v153 offset:51200
	ds_read_b128 v[202:205], v153 offset:52224
	ds_read_b128 v[206:209], v153 offset:53248
	ds_read_b128 v[210:213], v153 offset:54272
	ds_read_b128 v[214:217], v153 offset:55296
	ds_read_b128 v[218:221], v153 offset:56320
	global_load_lds_dwordx4 v[144:145], off
	s_add_i32 m0, s2, 0x2000
	s_add_u32 s2, s28, 0x40080
	v_lshl_add_u64 v[144:145], v[174:175], 0, s[6:7]
	s_addc_u32 s3, s29, 0
	s_add_i32 s28, s54, s34
	global_load_lds_dwordx4 v[144:145], off
	v_lshl_add_u64 v[144:145], s[2:3], 0, v[134:135]
	s_mov_b32 m0, s28
	s_nop 0
	global_load_lds_dwordx4 v[144:145], off
	v_lshl_add_u64 v[144:145], s[2:3], 0, v[130:131]
	s_add_i32 m0, s28, 0x2000
	s_nop 0
	global_load_lds_dwordx4 v[144:145], off
	v_lshl_add_u64 v[144:145], v[222:223], 0, s[6:7]
	s_mov_b32 m0, s41
	s_nop 0
	global_load_lds_dwordx4 v[144:145], off
	v_lshl_add_u64 v[144:145], v[224:225], 0, s[6:7]
	s_mov_b32 m0, s42
	s_nop 0
	global_load_lds_dwordx4 v[144:145], off
	s_waitcnt vmcnt(8)
	s_waitcnt lgkmcnt(0)
	s_barrier
	s_setprio 1
	s_waitcnt lgkmcnt(0)
	v_mfma_f32_16x16x32_bf16 v[62:65], v[154:157], v[190:193], v[62:65]
	v_mfma_f32_16x16x32_bf16 v[58:61], v[162:165], v[190:193], v[58:61]
	v_mfma_f32_16x16x32_bf16 v[42:45], v[162:165], v[198:201], v[42:45]
	v_mfma_f32_16x16x32_bf16 v[50:53], v[154:157], v[198:201], v[50:53]
	v_mfma_f32_16x16x32_bf16 v[34:37], v[154:157], v[206:209], v[34:37]
	v_mfma_f32_16x16x32_bf16 v[26:29], v[162:165], v[206:209], v[26:29]
	v_mfma_f32_16x16x32_bf16 v[10:13], v[162:165], v[214:217], v[10:13]
	v_mfma_f32_16x16x32_bf16 v[18:21], v[154:157], v[214:217], v[18:21]
	v_mfma_f32_16x16x32_bf16 v[62:65], v[158:161], v[194:197], v[62:65]
	v_mfma_f32_16x16x32_bf16 v[58:61], v[166:169], v[194:197], v[58:61]
	v_mfma_f32_16x16x32_bf16 v[42:45], v[166:169], v[202:205], v[42:45]
	v_mfma_f32_16x16x32_bf16 v[50:53], v[158:161], v[202:205], v[50:53]
	v_mfma_f32_16x16x32_bf16 v[34:37], v[158:161], v[210:213], v[34:37]
	v_mfma_f32_16x16x32_bf16 v[26:29], v[166:169], v[210:213], v[26:29]
	v_mfma_f32_16x16x32_bf16 v[10:13], v[166:169], v[218:221], v[10:13]
	v_mfma_f32_16x16x32_bf16 v[18:21], v[158:161], v[218:221], v[18:21]
	s_setprio 0
	s_setprio 1
	v_mfma_f32_16x16x32_bf16 v[54:57], v[170:173], v[190:193], v[54:57]
	v_mfma_f32_16x16x32_bf16 v[46:49], v[182:185], v[190:193], v[46:49]
	v_mfma_f32_16x16x32_bf16 v[30:33], v[182:185], v[198:201], v[30:33]
	v_mfma_f32_16x16x32_bf16 v[38:41], v[170:173], v[198:201], v[38:41]
	v_mfma_f32_16x16x32_bf16 v[22:25], v[170:173], v[206:209], v[22:25]
	v_mfma_f32_16x16x32_bf16 v[14:17], v[182:185], v[206:209], v[14:17]
	v_mfma_f32_16x16x32_bf16 v[2:5], v[182:185], v[214:217], v[2:5]
	v_mfma_f32_16x16x32_bf16 v[6:9], v[170:173], v[214:217], v[6:9]
	v_mfma_f32_16x16x32_bf16 v[54:57], v[178:181], v[194:197], v[54:57]
	v_mfma_f32_16x16x32_bf16 v[46:49], v[186:189], v[194:197], v[46:49]
	v_mfma_f32_16x16x32_bf16 v[30:33], v[186:189], v[202:205], v[30:33]
	v_mfma_f32_16x16x32_bf16 v[38:41], v[178:181], v[202:205], v[38:41]
	v_mfma_f32_16x16x32_bf16 v[22:25], v[178:181], v[210:213], v[22:25]
	v_mfma_f32_16x16x32_bf16 v[14:17], v[186:189], v[210:213], v[14:17]
	v_mfma_f32_16x16x32_bf16 v[2:5], v[186:189], v[218:221], v[2:5]
	v_mfma_f32_16x16x32_bf16 v[6:9], v[178:181], v[218:221], v[6:9]
	s_setprio 0
	s_barrier
	s_add_i32 s52, s52, 2
	s_add_u32 s26, s26, 0x100
	s_addc_u32 s27, s27, 0
	s_add_u32 s50, s50, 0x100
	s_addc_u32 s51, s51, 0
	s_cmp_gt_u32 s52, 13
	s_cbranch_scc0 .LBB0_555
	s_branch .Lpk555_exit
.LBB0_555:
	ds_read_b128 v[154:157], v151
	ds_read_b128 v[158:161], v151 offset:1024
	ds_read_b128 v[162:165], v151 offset:2048
	ds_read_b128 v[166:169], v151 offset:3072
	ds_read_b128 v[170:173], v152
	ds_read_b128 v[178:181], v152 offset:1024
	ds_read_b128 v[182:185], v152 offset:2048
	ds_read_b128 v[186:189], v152 offset:3072
	s_add_u32 s2, s26, 0xfffc0080
	s_addc_u32 s3, s27, -1
	s_cmp_eq_u32 s52, 12
	s_cselect_b32 s3, s11, s3
	s_cselect_b32 s2, s13, s2
	s_cselect_b32 s29, s48, s51
	s_cselect_b32 s28, s49, s50
	v_lshl_add_u64 v[144:145], s[26:27], 0, v[138:139]
	s_add_i32 m0, s37, 0xc000
	ds_read_b128 v[190:193], v153
	ds_read_b128 v[194:197], v153 offset:1024
	ds_read_b128 v[198:201], v153 offset:2048
	ds_read_b128 v[202:205], v153 offset:3072
	ds_read_b128 v[206:209], v153 offset:4096
	ds_read_b128 v[210:213], v153 offset:5120
	ds_read_b128 v[214:217], v153 offset:6144
	ds_read_b128 v[218:221], v153 offset:7168
	global_load_lds_dwordx4 v[144:145], off
	v_lshl_add_u64 v[144:145], s[26:27], 0, v[140:141]
	s_add_i32 m0, s37, 0xe000
	s_nop 0
	global_load_lds_dwordx4 v[144:145], off
	s_waitcnt vmcnt(8)
	s_waitcnt lgkmcnt(0)
	s_barrier
	s_setprio 1
	s_waitcnt lgkmcnt(0)
	v_mfma_f32_16x16x32_bf16 v[126:129], v[154:157], v[190:193], v[126:129]
	v_mfma_f32_16x16x32_bf16 v[122:125], v[162:165], v[190:193], v[122:125]
	v_mfma_f32_16x16x32_bf16 v[106:109], v[162:165], v[198:201], v[106:109]
	v_mfma_f32_16x16x32_bf16 v[114:117], v[154:157], v[198:201], v[114:117]
	v_mfma_f32_16x16x32_bf16 v[98:101], v[154:157], v[206:209], v[98:101]
	v_mfma_f32_16x16x32_bf16 v[90:93], v[162:165], v[206:209], v[90:93]
	v_mfma_f32_16x16x32_bf16 v[74:77], v[162:165], v[214:217], v[74:77]
	v_mfma_f32_16x16x32_bf16 v[82:85], v[154:157], v[214:217], v[82:85]
	v_mfma_f32_16x16x32_bf16 v[126:129], v[158:161], v[194:197], v[126:129]
	v_mfma_f32_16x16x32_bf16 v[122:125], v[166:169], v[194:197], v[122:125]
	v_mfma_f32_16x16x32_bf16 v[106:109], v[166:169], v[202:205], v[106:109]
	v_mfma_f32_16x16x32_bf16 v[114:117], v[158:161], v[202:205], v[114:117]
	v_mfma_f32_16x16x32_bf16 v[98:101], v[158:161], v[210:213], v[98:101]
	v_mfma_f32_16x16x32_bf16 v[90:93], v[166:169], v[210:213], v[90:93]
	v_mfma_f32_16x16x32_bf16 v[74:77], v[166:169], v[218:221], v[74:77]
	v_mfma_f32_16x16x32_bf16 v[82:85], v[158:161], v[218:221], v[82:85]
	s_setprio 0
	s_setprio 1
	v_mfma_f32_16x16x32_bf16 v[118:121], v[170:173], v[190:193], v[118:121]
	v_mfma_f32_16x16x32_bf16 v[110:113], v[182:185], v[190:193], v[110:113]
	v_mfma_f32_16x16x32_bf16 v[94:97], v[182:185], v[198:201], v[94:97]
	v_mfma_f32_16x16x32_bf16 v[102:105], v[170:173], v[198:201], v[102:105]
	v_mfma_f32_16x16x32_bf16 v[86:89], v[170:173], v[206:209], v[86:89]
	v_mfma_f32_16x16x32_bf16 v[78:81], v[182:185], v[206:209], v[78:81]
	v_mfma_f32_16x16x32_bf16 v[66:69], v[182:185], v[214:217], v[66:69]
	v_mfma_f32_16x16x32_bf16 v[70:73], v[170:173], v[214:217], v[70:73]
	v_mfma_f32_16x16x32_bf16 v[118:121], v[178:181], v[194:197], v[118:121]
	v_mfma_f32_16x16x32_bf16 v[110:113], v[186:189], v[194:197], v[110:113]
	v_mfma_f32_16x16x32_bf16 v[94:97], v[186:189], v[202:205], v[94:97]
	v_mfma_f32_16x16x32_bf16 v[102:105], v[178:181], v[202:205], v[102:105]
	v_mfma_f32_16x16x32_bf16 v[86:89], v[178:181], v[210:213], v[86:89]
	v_mfma_f32_16x16x32_bf16 v[78:81], v[186:189], v[210:213], v[78:81]
	v_mfma_f32_16x16x32_bf16 v[66:69], v[186:189], v[218:221], v[66:69]
	v_mfma_f32_16x16x32_bf16 v[70:73], v[178:181], v[218:221], v[70:73]
	s_setprio 0
	s_barrier
	s_add_i32 s53, s44, s34
	v_lshl_add_u64 v[144:145], s[28:29], 0, v[134:135]
	s_mov_b32 m0, s53
	ds_read_b128 v[190:193], v153 offset:16384
	ds_read_b128 v[194:197], v153 offset:17408
	ds_read_b128 v[198:201], v153 offset:18432
	ds_read_b128 v[202:205], v153 offset:19456
	ds_read_b128 v[206:209], v153 offset:20480
	ds_read_b128 v[210:213], v153 offset:21504
	ds_read_b128 v[214:217], v153 offset:22528
	ds_read_b128 v[218:221], v153 offset:23552
	global_load_lds_dwordx4 v[144:145], off
	s_add_i32 m0, s53, 0x2000
	s_add_u32 s54, s28, 0x40000
	v_lshl_add_u64 v[174:175], s[28:29], 0, v[130:131]
	s_addc_u32 s55, s29, 0
	s_add_i32 s53, s45, s34
	global_load_lds_dwordx4 v[174:175], off
	v_lshl_add_u64 v[222:223], s[54:55], 0, v[134:135]
	s_mov_b32 m0, s53
	v_lshl_add_u64 v[224:225], s[2:3], 0, v[132:133]
	global_load_lds_dwordx4 v[222:223], off
	v_lshl_add_u64 v[222:223], s[54:55], 0, v[130:131]
	s_add_i32 m0, s53, 0x2000
	s_nop 0
	global_load_lds_dwordx4 v[222:223], off
	v_lshl_add_u64 v[222:223], s[2:3], 0, v[136:137]
	s_mov_b32 m0, s37
	s_nop 0
	global_load_lds_dwordx4 v[222:223], off
	s_mov_b32 m0, s25
	s_nop 0
	global_load_lds_dwordx4 v[224:225], off
	s_waitcnt vmcnt(8)
	s_waitcnt lgkmcnt(0)
	s_barrier
	s_setprio 1
	s_waitcnt lgkmcnt(0)
	v_mfma_f32_16x16x32_bf16 v[62:65], v[154:157], v[190:193], v[62:65]
	v_mfma_f32_16x16x32_bf16 v[58:61], v[162:165], v[190:193], v[58:61]
	v_mfma_f32_16x16x32_bf16 v[42:45], v[162:165], v[198:201], v[42:45]
	v_mfma_f32_16x16x32_bf16 v[50:53], v[154:157], v[198:201], v[50:53]
	v_mfma_f32_16x16x32_bf16 v[34:37], v[154:157], v[206:209], v[34:37]
	v_mfma_f32_16x16x32_bf16 v[26:29], v[162:165], v[206:209], v[26:29]
	v_mfma_f32_16x16x32_bf16 v[10:13], v[162:165], v[214:217], v[10:13]
	v_mfma_f32_16x16x32_bf16 v[18:21], v[154:157], v[214:217], v[18:21]
	v_mfma_f32_16x16x32_bf16 v[62:65], v[158:161], v[194:197], v[62:65]
	v_mfma_f32_16x16x32_bf16 v[58:61], v[166:169], v[194:197], v[58:61]
	v_mfma_f32_16x16x32_bf16 v[42:45], v[166:169], v[202:205], v[42:45]
	v_mfma_f32_16x16x32_bf16 v[50:53], v[158:161], v[202:205], v[50:53]
	v_mfma_f32_16x16x32_bf16 v[34:37], v[158:161], v[210:213], v[34:37]
	v_mfma_f32_16x16x32_bf16 v[26:29], v[166:169], v[210:213], v[26:29]
	v_mfma_f32_16x16x32_bf16 v[10:13], v[166:169], v[218:221], v[10:13]
	v_mfma_f32_16x16x32_bf16 v[18:21], v[158:161], v[218:221], v[18:21]
	s_setprio 0
	s_setprio 1
	v_mfma_f32_16x16x32_bf16 v[54:57], v[170:173], v[190:193], v[54:57]
	v_mfma_f32_16x16x32_bf16 v[46:49], v[182:185], v[190:193], v[46:49]
	v_mfma_f32_16x16x32_bf16 v[30:33], v[182:185], v[198:201], v[30:33]
	v_mfma_f32_16x16x32_bf16 v[38:41], v[170:173], v[198:201], v[38:41]
	v_mfma_f32_16x16x32_bf16 v[22:25], v[170:173], v[206:209], v[22:25]
	v_mfma_f32_16x16x32_bf16 v[14:17], v[182:185], v[206:209], v[14:17]
	v_mfma_f32_16x16x32_bf16 v[2:5], v[182:185], v[214:217], v[2:5]
	v_mfma_f32_16x16x32_bf16 v[6:9], v[170:173], v[214:217], v[6:9]
	v_mfma_f32_16x16x32_bf16 v[54:57], v[178:181], v[194:197], v[54:57]
	v_mfma_f32_16x16x32_bf16 v[46:49], v[186:189], v[194:197], v[46:49]
	v_mfma_f32_16x16x32_bf16 v[30:33], v[186:189], v[202:205], v[30:33]
	v_mfma_f32_16x16x32_bf16 v[38:41], v[178:181], v[202:205], v[38:41]
	v_mfma_f32_16x16x32_bf16 v[22:25], v[178:181], v[210:213], v[22:25]
	v_mfma_f32_16x16x32_bf16 v[14:17], v[186:189], v[210:213], v[14:17]
	v_mfma_f32_16x16x32_bf16 v[2:5], v[186:189], v[218:221], v[2:5]
	v_mfma_f32_16x16x32_bf16 v[6:9], v[178:181], v[218:221], v[6:9]
	s_setprio 0
	s_barrier
	s_add_i32 s53, 0, 0x18000
	s_add_i32 s54, 0, 0x1c000
	v_add_u32_e32 v166, s53, v149
	v_add_u32_e32 v176, s54, v149
	ds_read_b128 v[154:157], v166
	ds_read_b128 v[158:161], v166 offset:1024
	ds_read_b128 v[162:165], v166 offset:2048
	ds_read_b128 v[166:169], v166 offset:3072
	ds_read_b128 v[170:173], v176
	ds_read_b128 v[178:181], v176 offset:1024
	ds_read_b128 v[182:185], v176 offset:2048
	ds_read_b128 v[186:189], v176 offset:3072
	s_add_u32 s2, s2, 0x40000
	s_addc_u32 s3, s3, 0
	s_mov_b32 m0, s38
	v_lshl_add_u64 v[226:227], s[2:3], 0, v[136:137]
	ds_read_b128 v[190:193], v153 offset:32768
	ds_read_b128 v[194:197], v153 offset:33792
	ds_read_b128 v[198:201], v153 offset:34816
	ds_read_b128 v[202:205], v153 offset:35840
	ds_read_b128 v[206:209], v153 offset:36864
	ds_read_b128 v[210:213], v153 offset:37888
	ds_read_b128 v[214:217], v153 offset:38912
	ds_read_b128 v[218:221], v153 offset:39936
	global_load_lds_dwordx4 v[226:227], off
	v_lshl_add_u64 v[226:227], s[2:3], 0, v[132:133]
	s_mov_b32 m0, s39
	s_nop 0
	global_load_lds_dwordx4 v[226:227], off
	s_waitcnt vmcnt(8)
	s_waitcnt lgkmcnt(0)
	s_barrier
	s_setprio 1
	s_waitcnt lgkmcnt(0)
	v_mfma_f32_16x16x32_bf16 v[126:129], v[154:157], v[190:193], v[126:129]
	v_mfma_f32_16x16x32_bf16 v[122:125], v[162:165], v[190:193], v[122:125]
	v_mfma_f32_16x16x32_bf16 v[106:109], v[162:165], v[198:201], v[106:109]
	v_mfma_f32_16x16x32_bf16 v[114:117], v[154:157], v[198:201], v[114:117]
	v_mfma_f32_16x16x32_bf16 v[98:101], v[154:157], v[206:209], v[98:101]
	v_mfma_f32_16x16x32_bf16 v[90:93], v[162:165], v[206:209], v[90:93]
	v_mfma_f32_16x16x32_bf16 v[74:77], v[162:165], v[214:217], v[74:77]
	v_mfma_f32_16x16x32_bf16 v[82:85], v[154:157], v[214:217], v[82:85]
	v_mfma_f32_16x16x32_bf16 v[126:129], v[158:161], v[194:197], v[126:129]
	v_mfma_f32_16x16x32_bf16 v[122:125], v[166:169], v[194:197], v[122:125]
	v_mfma_f32_16x16x32_bf16 v[106:109], v[166:169], v[202:205], v[106:109]
	v_mfma_f32_16x16x32_bf16 v[114:117], v[158:161], v[202:205], v[114:117]
	v_mfma_f32_16x16x32_bf16 v[98:101], v[158:161], v[210:213], v[98:101]
	v_mfma_f32_16x16x32_bf16 v[90:93], v[166:169], v[210:213], v[90:93]
	v_mfma_f32_16x16x32_bf16 v[74:77], v[166:169], v[218:221], v[74:77]
	v_mfma_f32_16x16x32_bf16 v[82:85], v[158:161], v[218:221], v[82:85]
	s_setprio 0
	s_setprio 1
	v_mfma_f32_16x16x32_bf16 v[118:121], v[170:173], v[190:193], v[118:121]
	v_mfma_f32_16x16x32_bf16 v[110:113], v[182:185], v[190:193], v[110:113]
	v_mfma_f32_16x16x32_bf16 v[94:97], v[182:185], v[198:201], v[94:97]
	v_mfma_f32_16x16x32_bf16 v[102:105], v[170:173], v[198:201], v[102:105]
	v_mfma_f32_16x16x32_bf16 v[86:89], v[170:173], v[206:209], v[86:89]
	v_mfma_f32_16x16x32_bf16 v[78:81], v[182:185], v[206:209], v[78:81]
	v_mfma_f32_16x16x32_bf16 v[66:69], v[182:185], v[214:217], v[66:69]
	v_mfma_f32_16x16x32_bf16 v[70:73], v[170:173], v[214:217], v[70:73]
	v_mfma_f32_16x16x32_bf16 v[118:121], v[178:181], v[194:197], v[118:121]
	v_mfma_f32_16x16x32_bf16 v[110:113], v[186:189], v[194:197], v[110:113]
	v_mfma_f32_16x16x32_bf16 v[94:97], v[186:189], v[202:205], v[94:97]
	v_mfma_f32_16x16x32_bf16 v[102:105], v[178:181], v[202:205], v[102:105]
	v_mfma_f32_16x16x32_bf16 v[86:89], v[178:181], v[210:213], v[86:89]
	v_mfma_f32_16x16x32_bf16 v[78:81], v[186:189], v[210:213], v[78:81]
	v_mfma_f32_16x16x32_bf16 v[66:69], v[186:189], v[218:221], v[66:69]
	v_mfma_f32_16x16x32_bf16 v[70:73], v[178:181], v[218:221], v[70:73]
	s_setprio 0
	s_barrier
	s_add_i32 s2, s53, s34
	v_lshl_add_u64 v[144:145], v[144:145], 0, s[6:7]
	s_mov_b32 m0, s2
	ds_read_b128 v[190:193], v153 offset:49152
	ds_read_b128 v[194:197], v153 offset:50176
	ds_read_b128 v[198:201], v153 offset:51200
	ds_read_b128 v[202:205], v153 offset:52224
	ds_read_b128 v[206:209], v153 offset:53248
	ds_read_b128 v[210:213], v153 offset:54272
	ds_read_b128 v[214:217], v153 offset:55296
	ds_read_b128 v[218:221], v153 offset:56320
	global_load_lds_dwordx4 v[144:145], off
	s_add_i32 m0, s2, 0x2000
	s_add_u32 s2, s28, 0x40080
	v_lshl_add_u64 v[144:145], v[174:175], 0, s[6:7]
	s_addc_u32 s3, s29, 0
	s_add_i32 s28, s54, s34
	global_load_lds_dwordx4 v[144:145], off
	v_lshl_add_u64 v[144:145], s[2:3], 0, v[134:135]
	s_mov_b32 m0, s28
	s_nop 0
	global_load_lds_dwordx4 v[144:145], off
	v_lshl_add_u64 v[144:145], s[2:3], 0, v[130:131]
	s_add_i32 m0, s28, 0x2000
	s_nop 0
	global_load_lds_dwordx4 v[144:145], off
	v_lshl_add_u64 v[144:145], v[222:223], 0, s[6:7]
	s_mov_b32 m0, s41
	s_nop 0
	global_load_lds_dwordx4 v[144:145], off
	v_lshl_add_u64 v[144:145], v[224:225], 0, s[6:7]
	s_mov_b32 m0, s42
	s_nop 0
	global_load_lds_dwordx4 v[144:145], off
	s_waitcnt vmcnt(8)
	s_waitcnt lgkmcnt(0)
	s_barrier
	s_setprio 1
	s_waitcnt lgkmcnt(0)
	v_mfma_f32_16x16x32_bf16 v[62:65], v[154:157], v[190:193], v[62:65]
	v_mfma_f32_16x16x32_bf16 v[58:61], v[162:165], v[190:193], v[58:61]
	v_mfma_f32_16x16x32_bf16 v[42:45], v[162:165], v[198:201], v[42:45]
	v_mfma_f32_16x16x32_bf16 v[50:53], v[154:157], v[198:201], v[50:53]
	v_mfma_f32_16x16x32_bf16 v[34:37], v[154:157], v[206:209], v[34:37]
	v_mfma_f32_16x16x32_bf16 v[26:29], v[162:165], v[206:209], v[26:29]
	v_mfma_f32_16x16x32_bf16 v[10:13], v[162:165], v[214:217], v[10:13]
	v_mfma_f32_16x16x32_bf16 v[18:21], v[154:157], v[214:217], v[18:21]
	v_mfma_f32_16x16x32_bf16 v[62:65], v[158:161], v[194:197], v[62:65]
	v_mfma_f32_16x16x32_bf16 v[58:61], v[166:169], v[194:197], v[58:61]
	v_mfma_f32_16x16x32_bf16 v[42:45], v[166:169], v[202:205], v[42:45]
	v_mfma_f32_16x16x32_bf16 v[50:53], v[158:161], v[202:205], v[50:53]
	v_mfma_f32_16x16x32_bf16 v[34:37], v[158:161], v[210:213], v[34:37]
	v_mfma_f32_16x16x32_bf16 v[26:29], v[166:169], v[210:213], v[26:29]
	v_mfma_f32_16x16x32_bf16 v[10:13], v[166:169], v[218:221], v[10:13]
	v_mfma_f32_16x16x32_bf16 v[18:21], v[158:161], v[218:221], v[18:21]
	s_setprio 0
	s_setprio 1
	v_mfma_f32_16x16x32_bf16 v[54:57], v[170:173], v[190:193], v[54:57]
	v_mfma_f32_16x16x32_bf16 v[46:49], v[182:185], v[190:193], v[46:49]
	v_mfma_f32_16x16x32_bf16 v[30:33], v[182:185], v[198:201], v[30:33]
	v_mfma_f32_16x16x32_bf16 v[38:41], v[170:173], v[198:201], v[38:41]
	v_mfma_f32_16x16x32_bf16 v[22:25], v[170:173], v[206:209], v[22:25]
	v_mfma_f32_16x16x32_bf16 v[14:17], v[182:185], v[206:209], v[14:17]
	v_mfma_f32_16x16x32_bf16 v[2:5], v[182:185], v[214:217], v[2:5]
	v_mfma_f32_16x16x32_bf16 v[6:9], v[170:173], v[214:217], v[6:9]
	v_mfma_f32_16x16x32_bf16 v[54:57], v[178:181], v[194:197], v[54:57]
	v_mfma_f32_16x16x32_bf16 v[46:49], v[186:189], v[194:197], v[46:49]
	v_mfma_f32_16x16x32_bf16 v[30:33], v[186:189], v[202:205], v[30:33]
	v_mfma_f32_16x16x32_bf16 v[38:41], v[178:181], v[202:205], v[38:41]
	v_mfma_f32_16x16x32_bf16 v[22:25], v[178:181], v[210:213], v[22:25]
	v_mfma_f32_16x16x32_bf16 v[14:17], v[186:189], v[210:213], v[14:17]
	v_mfma_f32_16x16x32_bf16 v[2:5], v[186:189], v[218:221], v[2:5]
	v_mfma_f32_16x16x32_bf16 v[6:9], v[178:181], v[218:221], v[6:9]
	s_setprio 0
	s_barrier
	s_add_i32 s52, s52, 2
	s_add_u32 s26, s26, 0x100
	s_addc_u32 s27, s27, 0
	s_add_u32 s50, s50, 0x100
	s_addc_u32 s51, s51, 0
	s_cmp_gt_u32 s52, 13
	s_cbranch_scc0 .LBB0_555

.LBB0_646:
	ds_read_b128 v[152:155], v146
	ds_read_b128 v[156:159], v146 offset:1024
	ds_read_b128 v[160:163], v146 offset:2048
	ds_read_b128 v[164:167], v146 offset:3072
	ds_read_b128 v[168:171], v147
	ds_read_b128 v[172:175], v147 offset:1024
	ds_read_b128 v[178:181], v147 offset:2048
	ds_read_b128 v[182:185], v147 offset:3072
	s_add_u32 s2, s10, s12
	s_addc_u32 s3, s11, s13
	s_add_u32 s2, s2, 0x3400100
	s_addc_u32 s3, s3, 0
	s_add_u32 s14, s24, s12
	s_addc_u32 s15, s25, s13
	s_cmpk_eq_i32 s12, 0x700
	s_cselect_b32 s3, s7, s3
	s_cselect_b32 s2, s6, s2
	s_cselect_b32 s15, s5, s15
	s_cselect_b32 s14, s4, s14
	s_mov_b32 m0, s27
	v_lshl_add_u64 v[218:219], v[138:139], 0, s[12:13]
	ds_read_b128 v[186:189], v148
	ds_read_b128 v[190:193], v148 offset:1024
	ds_read_b128 v[194:197], v148 offset:2048
	ds_read_b128 v[198:201], v148 offset:3072
	ds_read_b128 v[202:205], v148 offset:4096
	ds_read_b128 v[206:209], v148 offset:5120
	ds_read_b128 v[210:213], v148 offset:6144
	ds_read_b128 v[214:217], v148 offset:7168
	global_load_lds_dwordx4 v[218:219], off
	v_lshl_add_u64 v[218:219], v[140:141], 0, s[12:13]
	s_mov_b32 m0, s28
	s_nop 0
	global_load_lds_dwordx4 v[218:219], off
	s_waitcnt vmcnt(8)
	s_waitcnt lgkmcnt(0)
	s_barrier
	s_setprio 1
	s_waitcnt lgkmcnt(0)
	v_mfma_f32_16x16x32_bf16 v[126:129], v[152:155], v[186:189], v[126:129]
	v_mfma_f32_16x16x32_bf16 v[122:125], v[160:163], v[186:189], v[122:125]
	v_mfma_f32_16x16x32_bf16 v[106:109], v[160:163], v[194:197], v[106:109]
	v_mfma_f32_16x16x32_bf16 v[114:117], v[152:155], v[194:197], v[114:117]
	v_mfma_f32_16x16x32_bf16 v[98:101], v[152:155], v[202:205], v[98:101]
	v_mfma_f32_16x16x32_bf16 v[90:93], v[160:163], v[202:205], v[90:93]
	v_mfma_f32_16x16x32_bf16 v[74:77], v[160:163], v[210:213], v[74:77]
	v_mfma_f32_16x16x32_bf16 v[82:85], v[152:155], v[210:213], v[82:85]
	v_mfma_f32_16x16x32_bf16 v[126:129], v[156:159], v[190:193], v[126:129]
	v_mfma_f32_16x16x32_bf16 v[122:125], v[164:167], v[190:193], v[122:125]
	v_mfma_f32_16x16x32_bf16 v[106:109], v[164:167], v[198:201], v[106:109]
	v_mfma_f32_16x16x32_bf16 v[114:117], v[156:159], v[198:201], v[114:117]
	v_mfma_f32_16x16x32_bf16 v[98:101], v[156:159], v[206:209], v[98:101]
	v_mfma_f32_16x16x32_bf16 v[90:93], v[164:167], v[206:209], v[90:93]
	v_mfma_f32_16x16x32_bf16 v[74:77], v[164:167], v[214:217], v[74:77]
	v_mfma_f32_16x16x32_bf16 v[82:85], v[156:159], v[214:217], v[82:85]
	s_setprio 0
	s_setprio 1
	v_mfma_f32_16x16x32_bf16 v[118:121], v[168:171], v[186:189], v[118:121]
	v_mfma_f32_16x16x32_bf16 v[110:113], v[178:181], v[186:189], v[110:113]
	v_mfma_f32_16x16x32_bf16 v[94:97], v[178:181], v[194:197], v[94:97]
	v_mfma_f32_16x16x32_bf16 v[102:105], v[168:171], v[194:197], v[102:105]
	v_mfma_f32_16x16x32_bf16 v[86:89], v[168:171], v[202:205], v[86:89]
	v_mfma_f32_16x16x32_bf16 v[78:81], v[178:181], v[202:205], v[78:81]
	v_mfma_f32_16x16x32_bf16 v[66:69], v[178:181], v[210:213], v[66:69]
	v_mfma_f32_16x16x32_bf16 v[70:73], v[168:171], v[210:213], v[70:73]
	v_mfma_f32_16x16x32_bf16 v[118:121], v[172:175], v[190:193], v[118:121]
	v_mfma_f32_16x16x32_bf16 v[110:113], v[182:185], v[190:193], v[110:113]
	v_mfma_f32_16x16x32_bf16 v[94:97], v[182:185], v[198:201], v[94:97]
	v_mfma_f32_16x16x32_bf16 v[102:105], v[172:175], v[198:201], v[102:105]
	v_mfma_f32_16x16x32_bf16 v[86:89], v[172:175], v[206:209], v[86:89]
	v_mfma_f32_16x16x32_bf16 v[78:81], v[182:185], v[206:209], v[78:81]
	v_mfma_f32_16x16x32_bf16 v[66:69], v[182:185], v[214:217], v[66:69]
	v_mfma_f32_16x16x32_bf16 v[70:73], v[172:175], v[214:217], v[70:73]
	s_setprio 0
	s_barrier
	s_mov_b32 m0, s29
	v_lshl_add_u64 v[218:219], s[14:15], 0, v[134:135]
	s_add_u32 s40, s14, 0x40000
	ds_read_b128 v[186:189], v148 offset:16384
	ds_read_b128 v[190:193], v148 offset:17408
	ds_read_b128 v[194:197], v148 offset:18432
	ds_read_b128 v[198:201], v148 offset:19456
	ds_read_b128 v[202:205], v148 offset:20480
	ds_read_b128 v[206:209], v148 offset:21504
	ds_read_b128 v[210:213], v148 offset:22528
	ds_read_b128 v[214:217], v148 offset:23552
	global_load_lds_dwordx4 v[218:219], off
	v_lshl_add_u64 v[220:221], s[14:15], 0, v[130:131]
	s_mov_b32 m0, s30
	s_addc_u32 s41, s15, 0
	global_load_lds_dwordx4 v[220:221], off
	v_lshl_add_u64 v[222:223], s[40:41], 0, v[134:135]
	s_mov_b32 m0, s31
	v_lshl_add_u64 v[224:225], s[2:3], 0, v[132:133]
	global_load_lds_dwordx4 v[222:223], off
	v_lshl_add_u64 v[222:223], s[40:41], 0, v[130:131]
	s_mov_b32 m0, s34
	s_nop 0
	global_load_lds_dwordx4 v[222:223], off
	v_lshl_add_u64 v[222:223], s[2:3], 0, v[136:137]
	s_mov_b32 m0, s18
	s_nop 0
	global_load_lds_dwordx4 v[222:223], off
	s_mov_b32 m0, s1
	s_nop 0
	global_load_lds_dwordx4 v[224:225], off
	s_waitcnt vmcnt(8)
	s_waitcnt lgkmcnt(0)
	s_barrier
	s_setprio 1
	s_waitcnt lgkmcnt(0)
	v_mfma_f32_16x16x32_bf16 v[62:65], v[152:155], v[186:189], v[62:65]
	v_mfma_f32_16x16x32_bf16 v[58:61], v[160:163], v[186:189], v[58:61]
	v_mfma_f32_16x16x32_bf16 v[42:45], v[160:163], v[194:197], v[42:45]
	v_mfma_f32_16x16x32_bf16 v[50:53], v[152:155], v[194:197], v[50:53]
	v_mfma_f32_16x16x32_bf16 v[34:37], v[152:155], v[202:205], v[34:37]
	v_mfma_f32_16x16x32_bf16 v[26:29], v[160:163], v[202:205], v[26:29]
	v_mfma_f32_16x16x32_bf16 v[10:13], v[160:163], v[210:213], v[10:13]
	v_mfma_f32_16x16x32_bf16 v[18:21], v[152:155], v[210:213], v[18:21]
	v_mfma_f32_16x16x32_bf16 v[62:65], v[156:159], v[190:193], v[62:65]
	v_mfma_f32_16x16x32_bf16 v[58:61], v[164:167], v[190:193], v[58:61]
	v_mfma_f32_16x16x32_bf16 v[42:45], v[164:167], v[198:201], v[42:45]
	v_mfma_f32_16x16x32_bf16 v[50:53], v[156:159], v[198:201], v[50:53]
	v_mfma_f32_16x16x32_bf16 v[34:37], v[156:159], v[206:209], v[34:37]
	v_mfma_f32_16x16x32_bf16 v[26:29], v[164:167], v[206:209], v[26:29]
	v_mfma_f32_16x16x32_bf16 v[10:13], v[164:167], v[214:217], v[10:13]
	v_mfma_f32_16x16x32_bf16 v[18:21], v[156:159], v[214:217], v[18:21]
	s_setprio 0
	s_setprio 1
	v_mfma_f32_16x16x32_bf16 v[54:57], v[168:171], v[186:189], v[54:57]
	v_mfma_f32_16x16x32_bf16 v[46:49], v[178:181], v[186:189], v[46:49]
	v_mfma_f32_16x16x32_bf16 v[30:33], v[178:181], v[194:197], v[30:33]
	v_mfma_f32_16x16x32_bf16 v[38:41], v[168:171], v[194:197], v[38:41]
	v_mfma_f32_16x16x32_bf16 v[22:25], v[168:171], v[202:205], v[22:25]
	v_mfma_f32_16x16x32_bf16 v[14:17], v[178:181], v[202:205], v[14:17]
	v_mfma_f32_16x16x32_bf16 v[2:5], v[178:181], v[210:213], v[2:5]
	v_mfma_f32_16x16x32_bf16 v[6:9], v[168:171], v[210:213], v[6:9]
	v_mfma_f32_16x16x32_bf16 v[54:57], v[172:175], v[190:193], v[54:57]
	v_mfma_f32_16x16x32_bf16 v[46:49], v[182:185], v[190:193], v[46:49]
	v_mfma_f32_16x16x32_bf16 v[30:33], v[182:185], v[198:201], v[30:33]
	v_mfma_f32_16x16x32_bf16 v[38:41], v[172:175], v[198:201], v[38:41]
	v_mfma_f32_16x16x32_bf16 v[22:25], v[172:175], v[206:209], v[22:25]
	v_mfma_f32_16x16x32_bf16 v[14:17], v[182:185], v[206:209], v[14:17]
	v_mfma_f32_16x16x32_bf16 v[2:5], v[182:185], v[214:217], v[2:5]
	v_mfma_f32_16x16x32_bf16 v[6:9], v[172:175], v[214:217], v[6:9]
	s_setprio 0
	s_barrier
	ds_read_b128 v[152:155], v149
	ds_read_b128 v[156:159], v149 offset:1024
	ds_read_b128 v[160:163], v149 offset:2048
	ds_read_b128 v[164:167], v149 offset:3072
	ds_read_b128 v[168:171], v150
	ds_read_b128 v[172:175], v150 offset:1024
	ds_read_b128 v[178:181], v150 offset:2048
	ds_read_b128 v[182:185], v150 offset:3072
	s_add_u32 s2, s2, 0x40000
	s_addc_u32 s3, s3, 0
	s_mov_b32 m0, s19
	v_lshl_add_u64 v[226:227], s[2:3], 0, v[136:137]
	ds_read_b128 v[186:189], v148 offset:32768
	ds_read_b128 v[190:193], v148 offset:33792
	ds_read_b128 v[194:197], v148 offset:34816
	ds_read_b128 v[198:201], v148 offset:35840
	ds_read_b128 v[202:205], v148 offset:36864
	ds_read_b128 v[206:209], v148 offset:37888
	ds_read_b128 v[210:213], v148 offset:38912
	ds_read_b128 v[214:217], v148 offset:39936
	global_load_lds_dwordx4 v[226:227], off
	v_lshl_add_u64 v[226:227], s[2:3], 0, v[132:133]
	s_mov_b32 m0, s20
	s_nop 0
	global_load_lds_dwordx4 v[226:227], off
	s_waitcnt vmcnt(8)
	s_waitcnt lgkmcnt(0)
	s_barrier
	s_setprio 1
	s_waitcnt lgkmcnt(0)
	v_mfma_f32_16x16x32_bf16 v[126:129], v[152:155], v[186:189], v[126:129]
	v_mfma_f32_16x16x32_bf16 v[122:125], v[160:163], v[186:189], v[122:125]
	v_mfma_f32_16x16x32_bf16 v[106:109], v[160:163], v[194:197], v[106:109]
	v_mfma_f32_16x16x32_bf16 v[114:117], v[152:155], v[194:197], v[114:117]
	v_mfma_f32_16x16x32_bf16 v[98:101], v[152:155], v[202:205], v[98:101]
	v_mfma_f32_16x16x32_bf16 v[90:93], v[160:163], v[202:205], v[90:93]
	v_mfma_f32_16x16x32_bf16 v[74:77], v[160:163], v[210:213], v[74:77]
	v_mfma_f32_16x16x32_bf16 v[82:85], v[152:155], v[210:213], v[82:85]
	v_mfma_f32_16x16x32_bf16 v[126:129], v[156:159], v[190:193], v[126:129]
	v_mfma_f32_16x16x32_bf16 v[122:125], v[164:167], v[190:193], v[122:125]
	v_mfma_f32_16x16x32_bf16 v[106:109], v[164:167], v[198:201], v[106:109]
	v_mfma_f32_16x16x32_bf16 v[114:117], v[156:159], v[198:201], v[114:117]
	v_mfma_f32_16x16x32_bf16 v[98:101], v[156:159], v[206:209], v[98:101]
	v_mfma_f32_16x16x32_bf16 v[90:93], v[164:167], v[206:209], v[90:93]
	v_mfma_f32_16x16x32_bf16 v[74:77], v[164:167], v[214:217], v[74:77]
	v_mfma_f32_16x16x32_bf16 v[82:85], v[156:159], v[214:217], v[82:85]
	s_setprio 0
	s_setprio 1
	v_mfma_f32_16x16x32_bf16 v[118:121], v[168:171], v[186:189], v[118:121]
	v_mfma_f32_16x16x32_bf16 v[110:113], v[178:181], v[186:189], v[110:113]
	v_mfma_f32_16x16x32_bf16 v[94:97], v[178:181], v[194:197], v[94:97]
	v_mfma_f32_16x16x32_bf16 v[102:105], v[168:171], v[194:197], v[102:105]
	v_mfma_f32_16x16x32_bf16 v[86:89], v[168:171], v[202:205], v[86:89]
	v_mfma_f32_16x16x32_bf16 v[78:81], v[178:181], v[202:205], v[78:81]
	v_mfma_f32_16x16x32_bf16 v[66:69], v[178:181], v[210:213], v[66:69]
	v_mfma_f32_16x16x32_bf16 v[70:73], v[168:171], v[210:213], v[70:73]
	v_mfma_f32_16x16x32_bf16 v[118:121], v[172:175], v[190:193], v[118:121]
	v_mfma_f32_16x16x32_bf16 v[110:113], v[182:185], v[190:193], v[110:113]
	v_mfma_f32_16x16x32_bf16 v[94:97], v[182:185], v[198:201], v[94:97]
	v_mfma_f32_16x16x32_bf16 v[102:105], v[172:175], v[198:201], v[102:105]
	v_mfma_f32_16x16x32_bf16 v[86:89], v[172:175], v[206:209], v[86:89]
	v_mfma_f32_16x16x32_bf16 v[78:81], v[182:185], v[206:209], v[78:81]
	v_mfma_f32_16x16x32_bf16 v[66:69], v[182:185], v[214:217], v[66:69]
	v_mfma_f32_16x16x32_bf16 v[70:73], v[172:175], v[214:217], v[70:73]
	s_setprio 0
	s_barrier
	s_mov_b32 m0, s35
	v_lshl_add_u64 v[218:219], v[218:219], 0, s[8:9]
	s_add_u32 s2, s14, 0x40080
	ds_read_b128 v[186:189], v148 offset:49152
	ds_read_b128 v[190:193], v148 offset:50176
	ds_read_b128 v[194:197], v148 offset:51200
	ds_read_b128 v[198:201], v148 offset:52224
	ds_read_b128 v[202:205], v148 offset:53248
	ds_read_b128 v[206:209], v148 offset:54272
	ds_read_b128 v[210:213], v148 offset:55296
	ds_read_b128 v[214:217], v148 offset:56320
	global_load_lds_dwordx4 v[218:219], off
	v_lshl_add_u64 v[218:219], v[220:221], 0, s[8:9]
	s_mov_b32 m0, s36
	s_addc_u32 s3, s15, 0
	global_load_lds_dwordx4 v[218:219], off
	v_lshl_add_u64 v[218:219], s[2:3], 0, v[134:135]
	s_mov_b32 m0, s37
	s_nop 0
	global_load_lds_dwordx4 v[218:219], off
	v_lshl_add_u64 v[218:219], s[2:3], 0, v[130:131]
	s_mov_b32 m0, s38
	s_nop 0
	global_load_lds_dwordx4 v[218:219], off
	v_lshl_add_u64 v[218:219], v[222:223], 0, s[8:9]
	s_mov_b32 m0, s22
	s_nop 0
	global_load_lds_dwordx4 v[218:219], off
	v_lshl_add_u64 v[218:219], v[224:225], 0, s[8:9]
	s_mov_b32 m0, s23
	s_nop 0
	global_load_lds_dwordx4 v[218:219], off
	s_waitcnt vmcnt(8)
	s_waitcnt lgkmcnt(0)
	s_barrier
	s_setprio 1
	s_waitcnt lgkmcnt(0)
	v_mfma_f32_16x16x32_bf16 v[62:65], v[152:155], v[186:189], v[62:65]
	v_mfma_f32_16x16x32_bf16 v[58:61], v[160:163], v[186:189], v[58:61]
	v_mfma_f32_16x16x32_bf16 v[42:45], v[160:163], v[194:197], v[42:45]
	v_mfma_f32_16x16x32_bf16 v[50:53], v[152:155], v[194:197], v[50:53]
	v_mfma_f32_16x16x32_bf16 v[34:37], v[152:155], v[202:205], v[34:37]
	v_mfma_f32_16x16x32_bf16 v[26:29], v[160:163], v[202:205], v[26:29]
	v_mfma_f32_16x16x32_bf16 v[10:13], v[160:163], v[210:213], v[10:13]
	v_mfma_f32_16x16x32_bf16 v[18:21], v[152:155], v[210:213], v[18:21]
	v_mfma_f32_16x16x32_bf16 v[62:65], v[156:159], v[190:193], v[62:65]
	v_mfma_f32_16x16x32_bf16 v[58:61], v[164:167], v[190:193], v[58:61]
	v_mfma_f32_16x16x32_bf16 v[42:45], v[164:167], v[198:201], v[42:45]
	v_mfma_f32_16x16x32_bf16 v[50:53], v[156:159], v[198:201], v[50:53]
	v_mfma_f32_16x16x32_bf16 v[34:37], v[156:159], v[206:209], v[34:37]
	v_mfma_f32_16x16x32_bf16 v[26:29], v[164:167], v[206:209], v[26:29]
	v_mfma_f32_16x16x32_bf16 v[10:13], v[164:167], v[214:217], v[10:13]
	v_mfma_f32_16x16x32_bf16 v[18:21], v[156:159], v[214:217], v[18:21]
	s_setprio 0
	s_setprio 1
	v_mfma_f32_16x16x32_bf16 v[54:57], v[168:171], v[186:189], v[54:57]
	v_mfma_f32_16x16x32_bf16 v[46:49], v[178:181], v[186:189], v[46:49]
	v_mfma_f32_16x16x32_bf16 v[30:33], v[178:181], v[194:197], v[30:33]
	v_mfma_f32_16x16x32_bf16 v[38:41], v[168:171], v[194:197], v[38:41]
	v_mfma_f32_16x16x32_bf16 v[22:25], v[168:171], v[202:205], v[22:25]
	v_mfma_f32_16x16x32_bf16 v[14:17], v[178:181], v[202:205], v[14:17]
	v_mfma_f32_16x16x32_bf16 v[2:5], v[178:181], v[210:213], v[2:5]
	v_mfma_f32_16x16x32_bf16 v[6:9], v[168:171], v[210:213], v[6:9]
	v_mfma_f32_16x16x32_bf16 v[54:57], v[172:175], v[190:193], v[54:57]
	v_mfma_f32_16x16x32_bf16 v[46:49], v[182:185], v[190:193], v[46:49]
	v_mfma_f32_16x16x32_bf16 v[30:33], v[182:185], v[198:201], v[30:33]
	v_mfma_f32_16x16x32_bf16 v[38:41], v[172:175], v[198:201], v[38:41]
	v_mfma_f32_16x16x32_bf16 v[22:25], v[172:175], v[206:209], v[22:25]
	v_mfma_f32_16x16x32_bf16 v[14:17], v[182:185], v[206:209], v[14:17]
	v_mfma_f32_16x16x32_bf16 v[2:5], v[182:185], v[214:217], v[2:5]
	v_mfma_f32_16x16x32_bf16 v[6:9], v[172:175], v[214:217], v[6:9]
	s_setprio 0
	s_barrier
	s_add_i32 s26, s26, 2
	s_add_u32 s12, s12, 0x100
	s_addc_u32 s13, s13, 0
	s_cmp_gt_u32 s26, 13
	s_cbranch_scc0 .LBB0_646
	s_cmpk_lt_u32 s16, 0x100
	s_mov_b32 s28, s33
	v_readlane_b32 s30, v253, 58
	s_cbranch_scc0 .LBB0_649
	s_barrier

.Lpk1098_peel:
	ds_read_b128 v[152:155], v148
	ds_read_b128 v[156:159], v148 offset:1024
	ds_read_b128 v[160:163], v148 offset:2048
	ds_read_b128 v[164:167], v148 offset:3072
	ds_read_b128 v[168:171], v149
	ds_read_b128 v[172:175], v149 offset:1024
	ds_read_b128 v[178:181], v149 offset:2048
	ds_read_b128 v[182:185], v149 offset:3072
	s_add_u32 s2, s30, 0xfffc0080
	s_addc_u32 s3, s31, -1
	s_cmp_eq_u32 s56, 12
	s_cselect_b32 s3, s15, s3
	s_cselect_b32 s2, s17, s2
	s_cselect_b32 s35, s52, s55
	s_cselect_b32 s34, s53, s54
	v_lshl_add_u64 v[144:145], s[30:31], 0, v[138:139]
	s_add_i32 m0, s40, 0xc000
	ds_read_b128 v[186:189], v150
	ds_read_b128 v[190:193], v150 offset:1024
	ds_read_b128 v[194:197], v150 offset:2048
	ds_read_b128 v[198:201], v150 offset:3072
	ds_read_b128 v[202:205], v150 offset:4096
	ds_read_b128 v[206:209], v150 offset:5120
	ds_read_b128 v[210:213], v150 offset:6144
	ds_read_b128 v[214:217], v150 offset:7168
	global_load_lds_dwordx4 v[144:145], off
	v_lshl_add_u64 v[144:145], s[30:31], 0, v[140:141]
	s_add_i32 m0, s40, 0xe000
	s_nop 0
	global_load_lds_dwordx4 v[144:145], off
	s_waitcnt vmcnt(8)
	s_waitcnt lgkmcnt(0)
	s_barrier
	s_setprio 1
	s_waitcnt lgkmcnt(0)
	v_mfma_f32_16x16x32_bf16 v[126:129], v[152:155], v[186:189], 0
	v_mfma_f32_16x16x32_bf16 v[122:125], v[160:163], v[186:189], 0
	v_mfma_f32_16x16x32_bf16 v[106:109], v[160:163], v[194:197], 0
	v_mfma_f32_16x16x32_bf16 v[114:117], v[152:155], v[194:197], 0
	v_mfma_f32_16x16x32_bf16 v[98:101], v[152:155], v[202:205], 0
	v_mfma_f32_16x16x32_bf16 v[90:93], v[160:163], v[202:205], 0
	v_mfma_f32_16x16x32_bf16 v[74:77], v[160:163], v[210:213], 0
	v_mfma_f32_16x16x32_bf16 v[82:85], v[152:155], v[210:213], 0
	v_mfma_f32_16x16x32_bf16 v[126:129], v[156:159], v[190:193], v[126:129]
	v_mfma_f32_16x16x32_bf16 v[122:125], v[164:167], v[190:193], v[122:125]
	v_mfma_f32_16x16x32_bf16 v[106:109], v[164:167], v[198:201], v[106:109]
	v_mfma_f32_16x16x32_bf16 v[114:117], v[156:159], v[198:201], v[114:117]
	v_mfma_f32_16x16x32_bf16 v[98:101], v[156:159], v[206:209], v[98:101]
	v_mfma_f32_16x16x32_bf16 v[90:93], v[164:167], v[206:209], v[90:93]
	v_mfma_f32_16x16x32_bf16 v[74:77], v[164:167], v[214:217], v[74:77]
	v_mfma_f32_16x16x32_bf16 v[82:85], v[156:159], v[214:217], v[82:85]
	s_setprio 0
	s_setprio 1
	v_mfma_f32_16x16x32_bf16 v[118:121], v[168:171], v[186:189], 0
	v_mfma_f32_16x16x32_bf16 v[110:113], v[178:181], v[186:189], 0
	v_mfma_f32_16x16x32_bf16 v[94:97], v[178:181], v[194:197], 0
	v_mfma_f32_16x16x32_bf16 v[102:105], v[168:171], v[194:197], 0
	v_mfma_f32_16x16x32_bf16 v[86:89], v[168:171], v[202:205], 0
	v_mfma_f32_16x16x32_bf16 v[78:81], v[178:181], v[202:205], 0
	v_mfma_f32_16x16x32_bf16 v[66:69], v[178:181], v[210:213], 0
	v_mfma_f32_16x16x32_bf16 v[70:73], v[168:171], v[210:213], 0
	v_mfma_f32_16x16x32_bf16 v[118:121], v[172:175], v[190:193], v[118:121]
	v_mfma_f32_16x16x32_bf16 v[110:113], v[182:185], v[190:193], v[110:113]
	v_mfma_f32_16x16x32_bf16 v[94:97], v[182:185], v[198:201], v[94:97]
	v_mfma_f32_16x16x32_bf16 v[102:105], v[172:175], v[198:201], v[102:105]
	v_mfma_f32_16x16x32_bf16 v[86:89], v[172:175], v[206:209], v[86:89]
	v_mfma_f32_16x16x32_bf16 v[78:81], v[182:185], v[206:209], v[78:81]
	v_mfma_f32_16x16x32_bf16 v[66:69], v[182:185], v[214:217], v[66:69]
	v_mfma_f32_16x16x32_bf16 v[70:73], v[172:175], v[214:217], v[70:73]
	s_setprio 0
	s_barrier
	s_add_i32 s57, s47, s39
	v_lshl_add_u64 v[144:145], s[34:35], 0, v[132:133]
	s_mov_b32 m0, s57
	ds_read_b128 v[186:189], v150 offset:16384
	ds_read_b128 v[190:193], v150 offset:17408
	ds_read_b128 v[194:197], v150 offset:18432
	ds_read_b128 v[198:201], v150 offset:19456
	ds_read_b128 v[202:205], v150 offset:20480
	ds_read_b128 v[206:209], v150 offset:21504
	ds_read_b128 v[210:213], v150 offset:22528
	ds_read_b128 v[214:217], v150 offset:23552
	global_load_lds_dwordx4 v[144:145], off
	s_add_i32 m0, s57, 0x2000
	s_add_u32 s58, s34, 0x40000
	v_lshl_add_u64 v[218:219], s[34:35], 0, v[136:137]
	s_addc_u32 s59, s35, 0
	s_add_i32 s57, s48, s39
	global_load_lds_dwordx4 v[218:219], off
	v_lshl_add_u64 v[220:221], s[58:59], 0, v[132:133]
	s_mov_b32 m0, s57
	v_lshl_add_u64 v[222:223], s[2:3], 0, v[134:135]
	global_load_lds_dwordx4 v[220:221], off
	v_lshl_add_u64 v[220:221], s[58:59], 0, v[136:137]
	s_add_i32 m0, s57, 0x2000
	s_nop 0
	global_load_lds_dwordx4 v[220:221], off
	v_lshl_add_u64 v[220:221], s[2:3], 0, v[130:131]
	s_mov_b32 m0, s40
	s_nop 0
	global_load_lds_dwordx4 v[220:221], off
	s_mov_b32 m0, s29
	s_nop 0
	global_load_lds_dwordx4 v[222:223], off
	s_waitcnt vmcnt(8)
	s_waitcnt lgkmcnt(0)
	s_barrier
	s_setprio 1
	s_waitcnt lgkmcnt(0)
	v_mfma_f32_16x16x32_bf16 v[62:65], v[152:155], v[186:189], 0
	v_mfma_f32_16x16x32_bf16 v[58:61], v[160:163], v[186:189], 0
	v_mfma_f32_16x16x32_bf16 v[42:45], v[160:163], v[194:197], 0
	v_mfma_f32_16x16x32_bf16 v[50:53], v[152:155], v[194:197], 0
	v_mfma_f32_16x16x32_bf16 v[34:37], v[152:155], v[202:205], 0
	v_mfma_f32_16x16x32_bf16 v[26:29], v[160:163], v[202:205], 0
	v_mfma_f32_16x16x32_bf16 v[10:13], v[160:163], v[210:213], 0
	v_mfma_f32_16x16x32_bf16 v[18:21], v[152:155], v[210:213], 0
	v_mfma_f32_16x16x32_bf16 v[62:65], v[156:159], v[190:193], v[62:65]
	v_mfma_f32_16x16x32_bf16 v[58:61], v[164:167], v[190:193], v[58:61]
	v_mfma_f32_16x16x32_bf16 v[42:45], v[164:167], v[198:201], v[42:45]
	v_mfma_f32_16x16x32_bf16 v[50:53], v[156:159], v[198:201], v[50:53]
	v_mfma_f32_16x16x32_bf16 v[34:37], v[156:159], v[206:209], v[34:37]
	v_mfma_f32_16x16x32_bf16 v[26:29], v[164:167], v[206:209], v[26:29]
	v_mfma_f32_16x16x32_bf16 v[10:13], v[164:167], v[214:217], v[10:13]
	v_mfma_f32_16x16x32_bf16 v[18:21], v[156:159], v[214:217], v[18:21]
	s_setprio 0
	s_setprio 1
	v_mfma_f32_16x16x32_bf16 v[54:57], v[168:171], v[186:189], 0
	v_mfma_f32_16x16x32_bf16 v[46:49], v[178:181], v[186:189], 0
	v_mfma_f32_16x16x32_bf16 v[30:33], v[178:181], v[194:197], 0
	v_mfma_f32_16x16x32_bf16 v[38:41], v[168:171], v[194:197], 0
	v_mfma_f32_16x16x32_bf16 v[22:25], v[168:171], v[202:205], 0
	v_mfma_f32_16x16x32_bf16 v[14:17], v[178:181], v[202:205], 0
	v_mfma_f32_16x16x32_bf16 v[2:5], v[178:181], v[210:213], 0
	v_mfma_f32_16x16x32_bf16 v[6:9], v[168:171], v[210:213], 0
	v_mfma_f32_16x16x32_bf16 v[54:57], v[172:175], v[190:193], v[54:57]
	v_mfma_f32_16x16x32_bf16 v[46:49], v[182:185], v[190:193], v[46:49]
	v_mfma_f32_16x16x32_bf16 v[30:33], v[182:185], v[198:201], v[30:33]
	v_mfma_f32_16x16x32_bf16 v[38:41], v[172:175], v[198:201], v[38:41]
	v_mfma_f32_16x16x32_bf16 v[22:25], v[172:175], v[206:209], v[22:25]
	v_mfma_f32_16x16x32_bf16 v[14:17], v[182:185], v[206:209], v[14:17]
	v_mfma_f32_16x16x32_bf16 v[2:5], v[182:185], v[214:217], v[2:5]
	v_mfma_f32_16x16x32_bf16 v[6:9], v[172:175], v[214:217], v[6:9]
	s_setprio 0
	s_barrier
	s_add_i32 s57, 0, 0x18000
	v_add_u32_e32 v151, s57, v146
	s_add_i32 s58, 0, 0x1c000
	ds_read_b128 v[152:155], v151
	ds_read_b128 v[156:159], v151 offset:1024
	ds_read_b128 v[160:163], v151 offset:2048
	ds_read_b128 v[164:167], v151 offset:3072
	v_add_u32_e32 v151, s58, v146
	ds_read_b128 v[168:171], v151
	ds_read_b128 v[172:175], v151 offset:1024
	ds_read_b128 v[178:181], v151 offset:2048
	ds_read_b128 v[182:185], v151 offset:3072
	s_add_u32 s2, s2, 0x40000
	s_addc_u32 s3, s3, 0
	s_mov_b32 m0, s41
	v_lshl_add_u64 v[224:225], s[2:3], 0, v[130:131]
	ds_read_b128 v[186:189], v150 offset:32768
	ds_read_b128 v[190:193], v150 offset:33792
	ds_read_b128 v[194:197], v150 offset:34816
	ds_read_b128 v[198:201], v150 offset:35840
	ds_read_b128 v[202:205], v150 offset:36864
	ds_read_b128 v[206:209], v150 offset:37888
	ds_read_b128 v[210:213], v150 offset:38912
	ds_read_b128 v[214:217], v150 offset:39936
	global_load_lds_dwordx4 v[224:225], off
	v_lshl_add_u64 v[224:225], s[2:3], 0, v[134:135]
	s_mov_b32 m0, s42
	s_nop 0
	global_load_lds_dwordx4 v[224:225], off
	s_waitcnt vmcnt(8)
	s_waitcnt lgkmcnt(0)
	s_barrier
	s_setprio 1
	s_waitcnt lgkmcnt(0)
	v_mfma_f32_16x16x32_bf16 v[126:129], v[152:155], v[186:189], v[126:129]
	v_mfma_f32_16x16x32_bf16 v[122:125], v[160:163], v[186:189], v[122:125]
	v_mfma_f32_16x16x32_bf16 v[106:109], v[160:163], v[194:197], v[106:109]
	v_mfma_f32_16x16x32_bf16 v[114:117], v[152:155], v[194:197], v[114:117]
	v_mfma_f32_16x16x32_bf16 v[98:101], v[152:155], v[202:205], v[98:101]
	v_mfma_f32_16x16x32_bf16 v[90:93], v[160:163], v[202:205], v[90:93]
	v_mfma_f32_16x16x32_bf16 v[74:77], v[160:163], v[210:213], v[74:77]
	v_mfma_f32_16x16x32_bf16 v[82:85], v[152:155], v[210:213], v[82:85]
	v_mfma_f32_16x16x32_bf16 v[126:129], v[156:159], v[190:193], v[126:129]
	v_mfma_f32_16x16x32_bf16 v[122:125], v[164:167], v[190:193], v[122:125]
	v_mfma_f32_16x16x32_bf16 v[106:109], v[164:167], v[198:201], v[106:109]
	v_mfma_f32_16x16x32_bf16 v[114:117], v[156:159], v[198:201], v[114:117]
	v_mfma_f32_16x16x32_bf16 v[98:101], v[156:159], v[206:209], v[98:101]
	v_mfma_f32_16x16x32_bf16 v[90:93], v[164:167], v[206:209], v[90:93]
	v_mfma_f32_16x16x32_bf16 v[74:77], v[164:167], v[214:217], v[74:77]
	v_mfma_f32_16x16x32_bf16 v[82:85], v[156:159], v[214:217], v[82:85]
	s_setprio 0
	s_setprio 1
	v_mfma_f32_16x16x32_bf16 v[118:121], v[168:171], v[186:189], v[118:121]
	v_mfma_f32_16x16x32_bf16 v[110:113], v[178:181], v[186:189], v[110:113]
	v_mfma_f32_16x16x32_bf16 v[94:97], v[178:181], v[194:197], v[94:97]
	v_mfma_f32_16x16x32_bf16 v[102:105], v[168:171], v[194:197], v[102:105]
	v_mfma_f32_16x16x32_bf16 v[86:89], v[168:171], v[202:205], v[86:89]
	v_mfma_f32_16x16x32_bf16 v[78:81], v[178:181], v[202:205], v[78:81]
	v_mfma_f32_16x16x32_bf16 v[66:69], v[178:181], v[210:213], v[66:69]
	v_mfma_f32_16x16x32_bf16 v[70:73], v[168:171], v[210:213], v[70:73]
	v_mfma_f32_16x16x32_bf16 v[118:121], v[172:175], v[190:193], v[118:121]
	v_mfma_f32_16x16x32_bf16 v[110:113], v[182:185], v[190:193], v[110:113]
	v_mfma_f32_16x16x32_bf16 v[94:97], v[182:185], v[198:201], v[94:97]
	v_mfma_f32_16x16x32_bf16 v[102:105], v[172:175], v[198:201], v[102:105]
	v_mfma_f32_16x16x32_bf16 v[86:89], v[172:175], v[206:209], v[86:89]
	v_mfma_f32_16x16x32_bf16 v[78:81], v[182:185], v[206:209], v[78:81]
	v_mfma_f32_16x16x32_bf16 v[66:69], v[182:185], v[214:217], v[66:69]
	v_mfma_f32_16x16x32_bf16 v[70:73], v[172:175], v[214:217], v[70:73]
	s_setprio 0
	s_barrier
	s_add_i32 s2, s57, s39
	v_lshl_add_u64 v[144:145], v[144:145], 0, s[6:7]
	s_mov_b32 m0, s2
	ds_read_b128 v[186:189], v150 offset:49152
	ds_read_b128 v[190:193], v150 offset:50176
	ds_read_b128 v[194:197], v150 offset:51200
	ds_read_b128 v[198:201], v150 offset:52224
	ds_read_b128 v[202:205], v150 offset:53248
	ds_read_b128 v[206:209], v150 offset:54272
	ds_read_b128 v[210:213], v150 offset:55296
	ds_read_b128 v[214:217], v150 offset:56320
	global_load_lds_dwordx4 v[144:145], off
	s_add_i32 m0, s2, 0x2000
	s_add_u32 s2, s34, 0x40080
	v_lshl_add_u64 v[144:145], v[218:219], 0, s[6:7]
	s_addc_u32 s3, s35, 0
	s_add_i32 s34, s58, s39
	global_load_lds_dwordx4 v[144:145], off
	v_lshl_add_u64 v[144:145], s[2:3], 0, v[132:133]
	s_mov_b32 m0, s34
	s_nop 0
	global_load_lds_dwordx4 v[144:145], off
	v_lshl_add_u64 v[144:145], s[2:3], 0, v[136:137]
	s_add_i32 m0, s34, 0x2000
	s_nop 0
	global_load_lds_dwordx4 v[144:145], off
	v_lshl_add_u64 v[144:145], v[220:221], 0, s[6:7]
	s_mov_b32 m0, s44
	s_nop 0
	global_load_lds_dwordx4 v[144:145], off
	v_lshl_add_u64 v[144:145], v[222:223], 0, s[6:7]
	s_mov_b32 m0, s45
	s_nop 0
	global_load_lds_dwordx4 v[144:145], off
	s_waitcnt vmcnt(8)
	s_waitcnt lgkmcnt(0)
	s_barrier
	s_setprio 1
	s_waitcnt lgkmcnt(0)
	v_mfma_f32_16x16x32_bf16 v[62:65], v[152:155], v[186:189], v[62:65]
	v_mfma_f32_16x16x32_bf16 v[58:61], v[160:163], v[186:189], v[58:61]
	v_mfma_f32_16x16x32_bf16 v[42:45], v[160:163], v[194:197], v[42:45]
	v_mfma_f32_16x16x32_bf16 v[50:53], v[152:155], v[194:197], v[50:53]
	v_mfma_f32_16x16x32_bf16 v[34:37], v[152:155], v[202:205], v[34:37]
	v_mfma_f32_16x16x32_bf16 v[26:29], v[160:163], v[202:205], v[26:29]
	v_mfma_f32_16x16x32_bf16 v[10:13], v[160:163], v[210:213], v[10:13]
	v_mfma_f32_16x16x32_bf16 v[18:21], v[152:155], v[210:213], v[18:21]
	v_mfma_f32_16x16x32_bf16 v[62:65], v[156:159], v[190:193], v[62:65]
	v_mfma_f32_16x16x32_bf16 v[58:61], v[164:167], v[190:193], v[58:61]
	v_mfma_f32_16x16x32_bf16 v[42:45], v[164:167], v[198:201], v[42:45]
	v_mfma_f32_16x16x32_bf16 v[50:53], v[156:159], v[198:201], v[50:53]
	v_mfma_f32_16x16x32_bf16 v[34:37], v[156:159], v[206:209], v[34:37]
	v_mfma_f32_16x16x32_bf16 v[26:29], v[164:167], v[206:209], v[26:29]
	v_mfma_f32_16x16x32_bf16 v[10:13], v[164:167], v[214:217], v[10:13]
	v_mfma_f32_16x16x32_bf16 v[18:21], v[156:159], v[214:217], v[18:21]
	s_setprio 0
	s_setprio 1
	v_mfma_f32_16x16x32_bf16 v[54:57], v[168:171], v[186:189], v[54:57]
	v_mfma_f32_16x16x32_bf16 v[46:49], v[178:181], v[186:189], v[46:49]
	v_mfma_f32_16x16x32_bf16 v[30:33], v[178:181], v[194:197], v[30:33]
	v_mfma_f32_16x16x32_bf16 v[38:41], v[168:171], v[194:197], v[38:41]
	v_mfma_f32_16x16x32_bf16 v[22:25], v[168:171], v[202:205], v[22:25]
	v_mfma_f32_16x16x32_bf16 v[14:17], v[178:181], v[202:205], v[14:17]
	v_mfma_f32_16x16x32_bf16 v[2:5], v[178:181], v[210:213], v[2:5]
	v_mfma_f32_16x16x32_bf16 v[6:9], v[168:171], v[210:213], v[6:9]
	v_mfma_f32_16x16x32_bf16 v[54:57], v[172:175], v[190:193], v[54:57]
	v_mfma_f32_16x16x32_bf16 v[46:49], v[182:185], v[190:193], v[46:49]
	v_mfma_f32_16x16x32_bf16 v[30:33], v[182:185], v[198:201], v[30:33]
	v_mfma_f32_16x16x32_bf16 v[38:41], v[172:175], v[198:201], v[38:41]
	v_mfma_f32_16x16x32_bf16 v[22:25], v[172:175], v[206:209], v[22:25]
	v_mfma_f32_16x16x32_bf16 v[14:17], v[182:185], v[206:209], v[14:17]
	v_mfma_f32_16x16x32_bf16 v[2:5], v[182:185], v[214:217], v[2:5]
	v_mfma_f32_16x16x32_bf16 v[6:9], v[172:175], v[214:217], v[6:9]
	s_setprio 0
	s_barrier
	s_add_i32 s56, s56, 2
	s_add_u32 s30, s30, 0x100
	s_addc_u32 s31, s31, 0
	s_add_u32 s54, s54, 0x100
	s_addc_u32 s55, s55, 0
	s_cmp_gt_u32 s56, 13
	s_cbranch_scc0 .LBB0_1098
	s_branch .Lpk1098_exit
.LBB0_1098:
	ds_read_b128 v[152:155], v148
	ds_read_b128 v[156:159], v148 offset:1024
	ds_read_b128 v[160:163], v148 offset:2048
	ds_read_b128 v[164:167], v148 offset:3072
	ds_read_b128 v[168:171], v149
	ds_read_b128 v[172:175], v149 offset:1024
	ds_read_b128 v[178:181], v149 offset:2048
	ds_read_b128 v[182:185], v149 offset:3072
	s_add_u32 s2, s30, 0xfffc0080
	s_addc_u32 s3, s31, -1
	s_cmp_eq_u32 s56, 12
	s_cselect_b32 s3, s15, s3
	s_cselect_b32 s2, s17, s2
	s_cselect_b32 s35, s52, s55
	s_cselect_b32 s34, s53, s54
	v_lshl_add_u64 v[144:145], s[30:31], 0, v[138:139]
	s_add_i32 m0, s40, 0xc000
	ds_read_b128 v[186:189], v150
	ds_read_b128 v[190:193], v150 offset:1024
	ds_read_b128 v[194:197], v150 offset:2048
	ds_read_b128 v[198:201], v150 offset:3072
	ds_read_b128 v[202:205], v150 offset:4096
	ds_read_b128 v[206:209], v150 offset:5120
	ds_read_b128 v[210:213], v150 offset:6144
	ds_read_b128 v[214:217], v150 offset:7168
	global_load_lds_dwordx4 v[144:145], off
	v_lshl_add_u64 v[144:145], s[30:31], 0, v[140:141]
	s_add_i32 m0, s40, 0xe000
	s_nop 0
	global_load_lds_dwordx4 v[144:145], off
	s_waitcnt vmcnt(8)
	s_waitcnt lgkmcnt(0)
	s_barrier
	s_setprio 1
	s_waitcnt lgkmcnt(0)
	v_mfma_f32_16x16x32_bf16 v[126:129], v[152:155], v[186:189], v[126:129]
	v_mfma_f32_16x16x32_bf16 v[122:125], v[160:163], v[186:189], v[122:125]
	v_mfma_f32_16x16x32_bf16 v[106:109], v[160:163], v[194:197], v[106:109]
	v_mfma_f32_16x16x32_bf16 v[114:117], v[152:155], v[194:197], v[114:117]
	v_mfma_f32_16x16x32_bf16 v[98:101], v[152:155], v[202:205], v[98:101]
	v_mfma_f32_16x16x32_bf16 v[90:93], v[160:163], v[202:205], v[90:93]
	v_mfma_f32_16x16x32_bf16 v[74:77], v[160:163], v[210:213], v[74:77]
	v_mfma_f32_16x16x32_bf16 v[82:85], v[152:155], v[210:213], v[82:85]
	v_mfma_f32_16x16x32_bf16 v[126:129], v[156:159], v[190:193], v[126:129]
	v_mfma_f32_16x16x32_bf16 v[122:125], v[164:167], v[190:193], v[122:125]
	v_mfma_f32_16x16x32_bf16 v[106:109], v[164:167], v[198:201], v[106:109]
	v_mfma_f32_16x16x32_bf16 v[114:117], v[156:159], v[198:201], v[114:117]
	v_mfma_f32_16x16x32_bf16 v[98:101], v[156:159], v[206:209], v[98:101]
	v_mfma_f32_16x16x32_bf16 v[90:93], v[164:167], v[206:209], v[90:93]
	v_mfma_f32_16x16x32_bf16 v[74:77], v[164:167], v[214:217], v[74:77]
	v_mfma_f32_16x16x32_bf16 v[82:85], v[156:159], v[214:217], v[82:85]
	s_setprio 0
	s_setprio 1
	v_mfma_f32_16x16x32_bf16 v[118:121], v[168:171], v[186:189], v[118:121]
	v_mfma_f32_16x16x32_bf16 v[110:113], v[178:181], v[186:189], v[110:113]
	v_mfma_f32_16x16x32_bf16 v[94:97], v[178:181], v[194:197], v[94:97]
	v_mfma_f32_16x16x32_bf16 v[102:105], v[168:171], v[194:197], v[102:105]
	v_mfma_f32_16x16x32_bf16 v[86:89], v[168:171], v[202:205], v[86:89]
	v_mfma_f32_16x16x32_bf16 v[78:81], v[178:181], v[202:205], v[78:81]
	v_mfma_f32_16x16x32_bf16 v[66:69], v[178:181], v[210:213], v[66:69]
	v_mfma_f32_16x16x32_bf16 v[70:73], v[168:171], v[210:213], v[70:73]
	v_mfma_f32_16x16x32_bf16 v[118:121], v[172:175], v[190:193], v[118:121]
	v_mfma_f32_16x16x32_bf16 v[110:113], v[182:185], v[190:193], v[110:113]
	v_mfma_f32_16x16x32_bf16 v[94:97], v[182:185], v[198:201], v[94:97]
	v_mfma_f32_16x16x32_bf16 v[102:105], v[172:175], v[198:201], v[102:105]
	v_mfma_f32_16x16x32_bf16 v[86:89], v[172:175], v[206:209], v[86:89]
	v_mfma_f32_16x16x32_bf16 v[78:81], v[182:185], v[206:209], v[78:81]
	v_mfma_f32_16x16x32_bf16 v[66:69], v[182:185], v[214:217], v[66:69]
	v_mfma_f32_16x16x32_bf16 v[70:73], v[172:175], v[214:217], v[70:73]
	s_setprio 0
	s_barrier
	s_add_i32 s57, s47, s39
	v_lshl_add_u64 v[144:145], s[34:35], 0, v[132:133]
	s_mov_b32 m0, s57
	ds_read_b128 v[186:189], v150 offset:16384
	ds_read_b128 v[190:193], v150 offset:17408
	ds_read_b128 v[194:197], v150 offset:18432
	ds_read_b128 v[198:201], v150 offset:19456
	ds_read_b128 v[202:205], v150 offset:20480
	ds_read_b128 v[206:209], v150 offset:21504
	ds_read_b128 v[210:213], v150 offset:22528
	ds_read_b128 v[214:217], v150 offset:23552
	global_load_lds_dwordx4 v[144:145], off
	s_add_i32 m0, s57, 0x2000
	s_add_u32 s58, s34, 0x40000
	v_lshl_add_u64 v[218:219], s[34:35], 0, v[136:137]
	s_addc_u32 s59, s35, 0
	s_add_i32 s57, s48, s39
	global_load_lds_dwordx4 v[218:219], off
	v_lshl_add_u64 v[220:221], s[58:59], 0, v[132:133]
	s_mov_b32 m0, s57
	v_lshl_add_u64 v[222:223], s[2:3], 0, v[134:135]
	global_load_lds_dwordx4 v[220:221], off
	v_lshl_add_u64 v[220:221], s[58:59], 0, v[136:137]
	s_add_i32 m0, s57, 0x2000
	s_nop 0
	global_load_lds_dwordx4 v[220:221], off
	v_lshl_add_u64 v[220:221], s[2:3], 0, v[130:131]
	s_mov_b32 m0, s40
	s_nop 0
	global_load_lds_dwordx4 v[220:221], off
	s_mov_b32 m0, s29
	s_nop 0
	global_load_lds_dwordx4 v[222:223], off
	s_waitcnt vmcnt(8)
	s_waitcnt lgkmcnt(0)
	s_barrier
	s_setprio 1
	s_waitcnt lgkmcnt(0)
	v_mfma_f32_16x16x32_bf16 v[62:65], v[152:155], v[186:189], v[62:65]
	v_mfma_f32_16x16x32_bf16 v[58:61], v[160:163], v[186:189], v[58:61]
	v_mfma_f32_16x16x32_bf16 v[42:45], v[160:163], v[194:197], v[42:45]
	v_mfma_f32_16x16x32_bf16 v[50:53], v[152:155], v[194:197], v[50:53]
	v_mfma_f32_16x16x32_bf16 v[34:37], v[152:155], v[202:205], v[34:37]
	v_mfma_f32_16x16x32_bf16 v[26:29], v[160:163], v[202:205], v[26:29]
	v_mfma_f32_16x16x32_bf16 v[10:13], v[160:163], v[210:213], v[10:13]
	v_mfma_f32_16x16x32_bf16 v[18:21], v[152:155], v[210:213], v[18:21]
	v_mfma_f32_16x16x32_bf16 v[62:65], v[156:159], v[190:193], v[62:65]
	v_mfma_f32_16x16x32_bf16 v[58:61], v[164:167], v[190:193], v[58:61]
	v_mfma_f32_16x16x32_bf16 v[42:45], v[164:167], v[198:201], v[42:45]
	v_mfma_f32_16x16x32_bf16 v[50:53], v[156:159], v[198:201], v[50:53]
	v_mfma_f32_16x16x32_bf16 v[34:37], v[156:159], v[206:209], v[34:37]
	v_mfma_f32_16x16x32_bf16 v[26:29], v[164:167], v[206:209], v[26:29]
	v_mfma_f32_16x16x32_bf16 v[10:13], v[164:167], v[214:217], v[10:13]
	v_mfma_f32_16x16x32_bf16 v[18:21], v[156:159], v[214:217], v[18:21]
	s_setprio 0
	s_setprio 1
	v_mfma_f32_16x16x32_bf16 v[54:57], v[168:171], v[186:189], v[54:57]
	v_mfma_f32_16x16x32_bf16 v[46:49], v[178:181], v[186:189], v[46:49]
	v_mfma_f32_16x16x32_bf16 v[30:33], v[178:181], v[194:197], v[30:33]
	v_mfma_f32_16x16x32_bf16 v[38:41], v[168:171], v[194:197], v[38:41]
	v_mfma_f32_16x16x32_bf16 v[22:25], v[168:171], v[202:205], v[22:25]
	v_mfma_f32_16x16x32_bf16 v[14:17], v[178:181], v[202:205], v[14:17]
	v_mfma_f32_16x16x32_bf16 v[2:5], v[178:181], v[210:213], v[2:5]
	v_mfma_f32_16x16x32_bf16 v[6:9], v[168:171], v[210:213], v[6:9]
	v_mfma_f32_16x16x32_bf16 v[54:57], v[172:175], v[190:193], v[54:57]
	v_mfma_f32_16x16x32_bf16 v[46:49], v[182:185], v[190:193], v[46:49]
	v_mfma_f32_16x16x32_bf16 v[30:33], v[182:185], v[198:201], v[30:33]
	v_mfma_f32_16x16x32_bf16 v[38:41], v[172:175], v[198:201], v[38:41]
	v_mfma_f32_16x16x32_bf16 v[22:25], v[172:175], v[206:209], v[22:25]
	v_mfma_f32_16x16x32_bf16 v[14:17], v[182:185], v[206:209], v[14:17]
	v_mfma_f32_16x16x32_bf16 v[2:5], v[182:185], v[214:217], v[2:5]
	v_mfma_f32_16x16x32_bf16 v[6:9], v[172:175], v[214:217], v[6:9]
	s_setprio 0
	s_barrier
	s_add_i32 s57, 0, 0x18000
	v_add_u32_e32 v151, s57, v146
	s_add_i32 s58, 0, 0x1c000
	ds_read_b128 v[152:155], v151
	ds_read_b128 v[156:159], v151 offset:1024
	ds_read_b128 v[160:163], v151 offset:2048
	ds_read_b128 v[164:167], v151 offset:3072
	v_add_u32_e32 v151, s58, v146
	ds_read_b128 v[168:171], v151
	ds_read_b128 v[172:175], v151 offset:1024
	ds_read_b128 v[178:181], v151 offset:2048
	ds_read_b128 v[182:185], v151 offset:3072
	s_add_u32 s2, s2, 0x40000
	s_addc_u32 s3, s3, 0
	s_mov_b32 m0, s41
	v_lshl_add_u64 v[224:225], s[2:3], 0, v[130:131]
	ds_read_b128 v[186:189], v150 offset:32768
	ds_read_b128 v[190:193], v150 offset:33792
	ds_read_b128 v[194:197], v150 offset:34816
	ds_read_b128 v[198:201], v150 offset:35840
	ds_read_b128 v[202:205], v150 offset:36864
	ds_read_b128 v[206:209], v150 offset:37888
	ds_read_b128 v[210:213], v150 offset:38912
	ds_read_b128 v[214:217], v150 offset:39936
	global_load_lds_dwordx4 v[224:225], off
	v_lshl_add_u64 v[224:225], s[2:3], 0, v[134:135]
	s_mov_b32 m0, s42
	s_nop 0
	global_load_lds_dwordx4 v[224:225], off
	s_waitcnt vmcnt(8)
	s_waitcnt lgkmcnt(0)
	s_barrier
	s_setprio 1
	s_waitcnt lgkmcnt(0)
	v_mfma_f32_16x16x32_bf16 v[126:129], v[152:155], v[186:189], v[126:129]
	v_mfma_f32_16x16x32_bf16 v[122:125], v[160:163], v[186:189], v[122:125]
	v_mfma_f32_16x16x32_bf16 v[106:109], v[160:163], v[194:197], v[106:109]
	v_mfma_f32_16x16x32_bf16 v[114:117], v[152:155], v[194:197], v[114:117]
	v_mfma_f32_16x16x32_bf16 v[98:101], v[152:155], v[202:205], v[98:101]
	v_mfma_f32_16x16x32_bf16 v[90:93], v[160:163], v[202:205], v[90:93]
	v_mfma_f32_16x16x32_bf16 v[74:77], v[160:163], v[210:213], v[74:77]
	v_mfma_f32_16x16x32_bf16 v[82:85], v[152:155], v[210:213], v[82:85]
	v_mfma_f32_16x16x32_bf16 v[126:129], v[156:159], v[190:193], v[126:129]
	v_mfma_f32_16x16x32_bf16 v[122:125], v[164:167], v[190:193], v[122:125]
	v_mfma_f32_16x16x32_bf16 v[106:109], v[164:167], v[198:201], v[106:109]
	v_mfma_f32_16x16x32_bf16 v[114:117], v[156:159], v[198:201], v[114:117]
	v_mfma_f32_16x16x32_bf16 v[98:101], v[156:159], v[206:209], v[98:101]
	v_mfma_f32_16x16x32_bf16 v[90:93], v[164:167], v[206:209], v[90:93]
	v_mfma_f32_16x16x32_bf16 v[74:77], v[164:167], v[214:217], v[74:77]
	v_mfma_f32_16x16x32_bf16 v[82:85], v[156:159], v[214:217], v[82:85]
	s_setprio 0
	s_setprio 1
	v_mfma_f32_16x16x32_bf16 v[118:121], v[168:171], v[186:189], v[118:121]
	v_mfma_f32_16x16x32_bf16 v[110:113], v[178:181], v[186:189], v[110:113]
	v_mfma_f32_16x16x32_bf16 v[94:97], v[178:181], v[194:197], v[94:97]
	v_mfma_f32_16x16x32_bf16 v[102:105], v[168:171], v[194:197], v[102:105]
	v_mfma_f32_16x16x32_bf16 v[86:89], v[168:171], v[202:205], v[86:89]
	v_mfma_f32_16x16x32_bf16 v[78:81], v[178:181], v[202:205], v[78:81]
	v_mfma_f32_16x16x32_bf16 v[66:69], v[178:181], v[210:213], v[66:69]
	v_mfma_f32_16x16x32_bf16 v[70:73], v[168:171], v[210:213], v[70:73]
	v_mfma_f32_16x16x32_bf16 v[118:121], v[172:175], v[190:193], v[118:121]
	v_mfma_f32_16x16x32_bf16 v[110:113], v[182:185], v[190:193], v[110:113]
	v_mfma_f32_16x16x32_bf16 v[94:97], v[182:185], v[198:201], v[94:97]
	v_mfma_f32_16x16x32_bf16 v[102:105], v[172:175], v[198:201], v[102:105]
	v_mfma_f32_16x16x32_bf16 v[86:89], v[172:175], v[206:209], v[86:89]
	v_mfma_f32_16x16x32_bf16 v[78:81], v[182:185], v[206:209], v[78:81]
	v_mfma_f32_16x16x32_bf16 v[66:69], v[182:185], v[214:217], v[66:69]
	v_mfma_f32_16x16x32_bf16 v[70:73], v[172:175], v[214:217], v[70:73]
	s_setprio 0
	s_barrier
	s_add_i32 s2, s57, s39
	v_lshl_add_u64 v[144:145], v[144:145], 0, s[6:7]
	s_mov_b32 m0, s2
	ds_read_b128 v[186:189], v150 offset:49152
	ds_read_b128 v[190:193], v150 offset:50176
	ds_read_b128 v[194:197], v150 offset:51200
	ds_read_b128 v[198:201], v150 offset:52224
	ds_read_b128 v[202:205], v150 offset:53248
	ds_read_b128 v[206:209], v150 offset:54272
	ds_read_b128 v[210:213], v150 offset:55296
	ds_read_b128 v[214:217], v150 offset:56320
	global_load_lds_dwordx4 v[144:145], off
	s_add_i32 m0, s2, 0x2000
	s_add_u32 s2, s34, 0x40080
	v_lshl_add_u64 v[144:145], v[218:219], 0, s[6:7]
	s_addc_u32 s3, s35, 0
	s_add_i32 s34, s58, s39
	global_load_lds_dwordx4 v[144:145], off
	v_lshl_add_u64 v[144:145], s[2:3], 0, v[132:133]
	s_mov_b32 m0, s34
	s_nop 0
	global_load_lds_dwordx4 v[144:145], off
	v_lshl_add_u64 v[144:145], s[2:3], 0, v[136:137]
	s_add_i32 m0, s34, 0x2000
	s_nop 0
	global_load_lds_dwordx4 v[144:145], off
	v_lshl_add_u64 v[144:145], v[220:221], 0, s[6:7]
	s_mov_b32 m0, s44
	s_nop 0
	global_load_lds_dwordx4 v[144:145], off
	v_lshl_add_u64 v[144:145], v[222:223], 0, s[6:7]
	s_mov_b32 m0, s45
	s_nop 0
	global_load_lds_dwordx4 v[144:145], off
	s_waitcnt vmcnt(8)
	s_waitcnt lgkmcnt(0)
	s_barrier
	s_setprio 1
	s_waitcnt lgkmcnt(0)
	v_mfma_f32_16x16x32_bf16 v[62:65], v[152:155], v[186:189], v[62:65]
	v_mfma_f32_16x16x32_bf16 v[58:61], v[160:163], v[186:189], v[58:61]
	v_mfma_f32_16x16x32_bf16 v[42:45], v[160:163], v[194:197], v[42:45]
	v_mfma_f32_16x16x32_bf16 v[50:53], v[152:155], v[194:197], v[50:53]
	v_mfma_f32_16x16x32_bf16 v[34:37], v[152:155], v[202:205], v[34:37]
	v_mfma_f32_16x16x32_bf16 v[26:29], v[160:163], v[202:205], v[26:29]
	v_mfma_f32_16x16x32_bf16 v[10:13], v[160:163], v[210:213], v[10:13]
	v_mfma_f32_16x16x32_bf16 v[18:21], v[152:155], v[210:213], v[18:21]
	v_mfma_f32_16x16x32_bf16 v[62:65], v[156:159], v[190:193], v[62:65]
	v_mfma_f32_16x16x32_bf16 v[58:61], v[164:167], v[190:193], v[58:61]
	v_mfma_f32_16x16x32_bf16 v[42:45], v[164:167], v[198:201], v[42:45]
	v_mfma_f32_16x16x32_bf16 v[50:53], v[156:159], v[198:201], v[50:53]
	v_mfma_f32_16x16x32_bf16 v[34:37], v[156:159], v[206:209], v[34:37]
	v_mfma_f32_16x16x32_bf16 v[26:29], v[164:167], v[206:209], v[26:29]
	v_mfma_f32_16x16x32_bf16 v[10:13], v[164:167], v[214:217], v[10:13]
	v_mfma_f32_16x16x32_bf16 v[18:21], v[156:159], v[214:217], v[18:21]
	s_setprio 0
	s_setprio 1
	v_mfma_f32_16x16x32_bf16 v[54:57], v[168:171], v[186:189], v[54:57]
	v_mfma_f32_16x16x32_bf16 v[46:49], v[178:181], v[186:189], v[46:49]
	v_mfma_f32_16x16x32_bf16 v[30:33], v[178:181], v[194:197], v[30:33]
	v_mfma_f32_16x16x32_bf16 v[38:41], v[168:171], v[194:197], v[38:41]
	v_mfma_f32_16x16x32_bf16 v[22:25], v[168:171], v[202:205], v[22:25]
	v_mfma_f32_16x16x32_bf16 v[14:17], v[178:181], v[202:205], v[14:17]
	v_mfma_f32_16x16x32_bf16 v[2:5], v[178:181], v[210:213], v[2:5]
	v_mfma_f32_16x16x32_bf16 v[6:9], v[168:171], v[210:213], v[6:9]
	v_mfma_f32_16x16x32_bf16 v[54:57], v[172:175], v[190:193], v[54:57]
	v_mfma_f32_16x16x32_bf16 v[46:49], v[182:185], v[190:193], v[46:49]
	v_mfma_f32_16x16x32_bf16 v[30:33], v[182:185], v[198:201], v[30:33]
	v_mfma_f32_16x16x32_bf16 v[38:41], v[172:175], v[198:201], v[38:41]
	v_mfma_f32_16x16x32_bf16 v[22:25], v[172:175], v[206:209], v[22:25]
	v_mfma_f32_16x16x32_bf16 v[14:17], v[182:185], v[206:209], v[14:17]
	v_mfma_f32_16x16x32_bf16 v[2:5], v[182:185], v[214:217], v[2:5]
	v_mfma_f32_16x16x32_bf16 v[6:9], v[172:175], v[214:217], v[6:9]
	s_setprio 0
	s_barrier
	s_add_i32 s56, s56, 2
	s_add_u32 s30, s30, 0x100
	s_addc_u32 s31, s31, 0
	s_add_u32 s54, s54, 0x100
	s_addc_u32 s55, s55, 0
	s_cmp_gt_u32 s56, 13
	s_cbranch_scc0 .LBB0_1098

.LBB0_1137:
	s_add_i32 s26, 0, 0x18000
	s_add_i32 s3, s26, s18
	s_mov_b64 s[24:25], 0x80
	v_lshl_add_u64 v[4:5], v[26:27], 0, s[24:25]
	s_mov_b32 m0, s3
	s_add_i32 s5, s3, 0x2000
	s_waitcnt vmcnt(2)
	s_barrier
	global_load_lds_dwordx4 v[4:5], off
	v_lshl_add_u64 v[6:7], v[28:29], 0, s[24:25]
	s_mov_b32 m0, s5
	s_add_i32 s4, s15, 0x8000
	global_load_lds_dwordx4 v[6:7], off
	v_lshl_add_u64 v[2:3], v[20:21], 0, s[24:25]
	s_mov_b32 m0, s4
	s_add_i32 s9, s15, 0xa000
	s_add_i32 s27, 0, 0x1c000
	global_load_lds_dwordx4 v[2:3], off
	v_lshl_add_u64 v[8:9], v[22:23], 0, s[24:25]
	s_mov_b32 m0, s9
	s_add_i32 s13, s27, s18
	global_load_lds_dwordx4 v[8:9], off
	v_lshl_add_u64 v[10:11], v[24:25], 0, s[24:25]
	s_mov_b32 m0, s13
	s_add_i32 s14, s13, 0x2000
	global_load_lds_dwordx4 v[10:11], off
	v_lshl_add_u64 v[12:13], v[18:19], 0, s[24:25]
	s_mov_b32 m0, s14
	v_and_b32_e32 v30, 15, v0
	global_load_lds_dwordx4 v[12:13], off
	v_lshlrev_b32_e32 v31, 1, v1
	v_lshlrev_b32_e32 v32, 2, v0
	v_lshl_or_b32 v130, s17, 6, v30
	v_lshl_or_b32 v30, v30, 6, v31
	s_lshl_b32 s2, s17, 13
	v_and_b32_e32 v32, 32, v32
	v_bitop3_b32 v62, v30, s2, v32 bitop3:0xde
	s_lshl_b32 s2, s19, 5
	s_and_b32 s2, s2, 0x60
	v_lshlrev_b32_e32 v30, 6, v0
	s_movk_i32 s17, 0x3c0
	v_and_or_b32 v30, v30, s17, v31
	s_lshl_b32 s17, s2, 7
	v_bitop3_b32 v63, s17, v30, v32 bitop3:0xf6
	s_add_i32 s29, 0, 0x10000
	s_add_i32 s28, 0, 0x14000
	v_add_u32_e32 v176, s29, v63
	s_waitcnt vmcnt(6)
	s_barrier
	v_add_u32_e32 v131, s28, v63
	ds_read_b128 v[30:33], v176
	ds_read_b128 v[34:37], v176 offset:1024
	ds_read_b128 v[38:41], v176 offset:2048
	ds_read_b128 v[42:45], v176 offset:3072
	ds_read_b128 v[46:49], v131
	ds_read_b128 v[50:53], v131 offset:1024
	ds_read_b128 v[54:57], v131 offset:2048
	ds_read_b128 v[58:61], v131 offset:3072
	s_add_i32 s20, s29, s18
	s_add_i32 s18, s28, s18
	s_add_i32 s22, s15, 0xc000
	s_add_i32 s21, s15, 0xe000
	s_add_i32 s19, s20, 0x2000
	s_add_i32 s17, s18, 0x2000
	s_cmpk_gt_u32 s23, 0xff
	v_add_u32_e32 v242, 0, v62
	v_add_u32_e32 v238, s27, v63
	v_add_u32_e32 v239, s26, v63
	s_mov_b32 m0, s22
	v_lshl_add_u64 v[94:95], v[14:15], 0, s[24:25]
	ds_read_b128 v[62:65], v242
	ds_read_b128 v[66:69], v242 offset:1024
	ds_read_b128 v[70:73], v242 offset:2048
	ds_read_b128 v[74:77], v242 offset:3072
	ds_read_b128 v[78:81], v242 offset:4096
	ds_read_b128 v[82:85], v242 offset:5120
	ds_read_b128 v[86:89], v242 offset:6144
	ds_read_b128 v[90:93], v242 offset:7168
	global_load_lds_dwordx4 v[94:95], off
	v_lshl_add_u64 v[94:95], v[16:17], 0, s[24:25]
	s_mov_b32 m0, s21
	s_nop 0
	global_load_lds_dwordx4 v[94:95], off
	s_waitcnt vmcnt(8)
	s_waitcnt lgkmcnt(0)
	s_barrier
	s_setprio 1
	s_waitcnt lgkmcnt(0)
	v_mfma_f32_16x16x32_bf16 v[94:97], v[30:33], v[62:65], 0
	v_mfma_f32_16x16x32_bf16 v[98:101], v[38:41], v[62:65], 0
	v_mfma_f32_16x16x32_bf16 v[106:109], v[38:41], v[70:73], 0
	v_mfma_f32_16x16x32_bf16 v[102:105], v[30:33], v[70:73], 0
	v_mfma_f32_16x16x32_bf16 v[110:113], v[30:33], v[78:81], 0
	v_mfma_f32_16x16x32_bf16 v[114:117], v[38:41], v[78:81], 0
	v_mfma_f32_16x16x32_bf16 v[122:125], v[38:41], v[86:89], 0
	v_mfma_f32_16x16x32_bf16 v[118:121], v[30:33], v[86:89], 0
	v_mfma_f32_16x16x32_bf16 v[94:97], v[34:37], v[66:69], v[94:97]
	v_mfma_f32_16x16x32_bf16 v[98:101], v[42:45], v[66:69], v[98:101]
	v_mfma_f32_16x16x32_bf16 v[106:109], v[42:45], v[74:77], v[106:109]
	v_mfma_f32_16x16x32_bf16 v[102:105], v[34:37], v[74:77], v[102:105]
	v_mfma_f32_16x16x32_bf16 v[110:113], v[34:37], v[82:85], v[110:113]
	v_mfma_f32_16x16x32_bf16 v[114:117], v[42:45], v[82:85], v[114:117]
	v_mfma_f32_16x16x32_bf16 v[122:125], v[42:45], v[90:93], v[122:125]
	v_mfma_f32_16x16x32_bf16 v[118:121], v[34:37], v[90:93], v[118:121]
	s_setprio 0
	s_setprio 1
	v_mfma_f32_16x16x32_bf16 v[126:129], v[46:49], v[62:65], 0
	v_mfma_f32_16x16x32_bf16 v[62:65], v[54:57], v[62:65], 0
	v_mfma_f32_16x16x32_bf16 v[126:129], v[50:53], v[66:69], v[126:129]
	v_mfma_f32_16x16x32_bf16 v[62:65], v[58:61], v[66:69], v[62:65]
	v_mfma_f32_16x16x32_bf16 v[66:69], v[46:49], v[70:73], 0
	v_mfma_f32_16x16x32_bf16 v[70:73], v[54:57], v[70:73], 0
	v_mfma_f32_16x16x32_bf16 v[66:69], v[50:53], v[74:77], v[66:69]
	v_mfma_f32_16x16x32_bf16 v[70:73], v[58:61], v[74:77], v[70:73]
	v_mfma_f32_16x16x32_bf16 v[74:77], v[46:49], v[78:81], 0
	v_mfma_f32_16x16x32_bf16 v[78:81], v[54:57], v[78:81], 0
	v_mfma_f32_16x16x32_bf16 v[74:77], v[50:53], v[82:85], v[74:77]
	v_mfma_f32_16x16x32_bf16 v[78:81], v[58:61], v[82:85], v[78:81]
	v_mfma_f32_16x16x32_bf16 v[82:85], v[46:49], v[86:89], 0
	v_mfma_f32_16x16x32_bf16 v[86:89], v[54:57], v[86:89], 0
	v_mfma_f32_16x16x32_bf16 v[82:85], v[50:53], v[90:93], v[82:85]
	v_mfma_f32_16x16x32_bf16 v[86:89], v[58:61], v[90:93], v[86:89]
	s_setprio 0
	s_barrier
	s_mov_b64 s[24:25], 0x100
	s_mov_b32 m0, s20
	v_lshl_add_u64 v[160:161], v[26:27], 0, s[24:25]
	ds_read_b128 v[90:93], v242 offset:16384
	ds_read_b128 v[132:135], v242 offset:17408
	ds_read_b128 v[136:139], v242 offset:18432
	ds_read_b128 v[140:143], v242 offset:19456
	ds_read_b128 v[144:147], v242 offset:20480
	ds_read_b128 v[148:151], v242 offset:21504
	ds_read_b128 v[152:155], v242 offset:22528
	ds_read_b128 v[156:159], v242 offset:23552
	global_load_lds_dwordx4 v[160:161], off
	v_lshl_add_u64 v[160:161], v[28:29], 0, s[24:25]
	s_mov_b32 m0, s19
	s_nop 0
	global_load_lds_dwordx4 v[160:161], off
	v_lshl_add_u64 v[160:161], v[24:25], 0, s[24:25]
	s_mov_b32 m0, s18
	s_nop 0
	global_load_lds_dwordx4 v[160:161], off
	v_lshl_add_u64 v[160:161], v[18:19], 0, s[24:25]
	s_mov_b32 m0, s17
	s_nop 0
	global_load_lds_dwordx4 v[160:161], off
	v_lshl_add_u64 v[160:161], v[20:21], 0, s[24:25]
	s_mov_b32 m0, s15
	s_nop 0
	global_load_lds_dwordx4 v[160:161], off
	v_lshl_add_u64 v[160:161], v[22:23], 0, s[24:25]
	s_mov_b32 m0, s16
	s_nop 0
	global_load_lds_dwordx4 v[160:161], off
	s_waitcnt vmcnt(8)
	s_waitcnt lgkmcnt(0)
	s_barrier
	s_setprio 1
	s_waitcnt lgkmcnt(0)
	v_mfma_f32_16x16x32_bf16 v[160:163], v[30:33], v[90:93], 0
	v_mfma_f32_16x16x32_bf16 v[168:171], v[30:33], v[136:139], 0
	v_mfma_f32_16x16x32_bf16 v[178:181], v[30:33], v[144:147], 0
	v_mfma_f32_16x16x32_bf16 v[30:33], v[30:33], v[152:155], 0
	v_mfma_f32_16x16x32_bf16 v[160:163], v[34:37], v[132:135], v[160:163]
	v_mfma_f32_16x16x32_bf16 v[168:171], v[34:37], v[140:143], v[168:171]
	v_mfma_f32_16x16x32_bf16 v[178:181], v[34:37], v[148:151], v[178:181]
	v_mfma_f32_16x16x32_bf16 v[30:33], v[34:37], v[156:159], v[30:33]
	v_mfma_f32_16x16x32_bf16 v[34:37], v[38:41], v[152:155], 0
	v_mfma_f32_16x16x32_bf16 v[164:167], v[38:41], v[90:93], 0
	v_mfma_f32_16x16x32_bf16 v[172:175], v[38:41], v[136:139], 0
	v_mfma_f32_16x16x32_bf16 v[182:185], v[38:41], v[144:147], 0
	v_mfma_f32_16x16x32_bf16 v[34:37], v[42:45], v[156:159], v[34:37]
	v_mfma_f32_16x16x32_bf16 v[164:167], v[42:45], v[132:135], v[164:167]
	v_mfma_f32_16x16x32_bf16 v[172:175], v[42:45], v[140:143], v[172:175]
	v_mfma_f32_16x16x32_bf16 v[182:185], v[42:45], v[148:151], v[182:185]
	s_setprio 0
	s_setprio 1
	v_mfma_f32_16x16x32_bf16 v[38:41], v[46:49], v[90:93], 0
	v_mfma_f32_16x16x32_bf16 v[42:45], v[54:57], v[90:93], 0
	v_mfma_f32_16x16x32_bf16 v[38:41], v[50:53], v[132:135], v[38:41]
	v_mfma_f32_16x16x32_bf16 v[42:45], v[58:61], v[132:135], v[42:45]
	v_mfma_f32_16x16x32_bf16 v[90:93], v[46:49], v[136:139], 0
	v_mfma_f32_16x16x32_bf16 v[132:135], v[54:57], v[136:139], 0
	v_mfma_f32_16x16x32_bf16 v[136:139], v[46:49], v[144:147], 0
	v_mfma_f32_16x16x32_bf16 v[46:49], v[46:49], v[152:155], 0
	v_mfma_f32_16x16x32_bf16 v[90:93], v[50:53], v[140:143], v[90:93]
	v_mfma_f32_16x16x32_bf16 v[136:139], v[50:53], v[148:151], v[136:139]
	v_mfma_f32_16x16x32_bf16 v[46:49], v[50:53], v[156:159], v[46:49]
	v_mfma_f32_16x16x32_bf16 v[50:53], v[54:57], v[152:155], 0
	v_mfma_f32_16x16x32_bf16 v[132:135], v[58:61], v[140:143], v[132:135]
	v_mfma_f32_16x16x32_bf16 v[140:143], v[54:57], v[144:147], 0
	v_mfma_f32_16x16x32_bf16 v[50:53], v[58:61], v[156:159], v[50:53]
	v_mfma_f32_16x16x32_bf16 v[140:143], v[58:61], v[148:151], v[140:143]
	s_setprio 0
	s_barrier
	ds_read_b128 v[54:57], v239
	ds_read_b128 v[58:61], v239 offset:1024
	ds_read_b128 v[144:147], v239 offset:2048
	ds_read_b128 v[148:151], v239 offset:3072
	ds_read_b128 v[152:155], v238
	ds_read_b128 v[156:159], v238 offset:1024
	ds_read_b128 v[186:189], v238 offset:2048
	ds_read_b128 v[190:193], v238 offset:3072
	s_mov_b32 m0, s11
	v_lshl_add_u64 v[226:227], v[14:15], 0, s[24:25]
	ds_read_b128 v[194:197], v242 offset:32768
	ds_read_b128 v[198:201], v242 offset:33792
	ds_read_b128 v[202:205], v242 offset:34816
	ds_read_b128 v[206:209], v242 offset:35840
	ds_read_b128 v[210:213], v242 offset:36864
	ds_read_b128 v[214:217], v242 offset:37888
	ds_read_b128 v[218:221], v242 offset:38912
	ds_read_b128 v[222:225], v242 offset:39936
	global_load_lds_dwordx4 v[226:227], off
	v_lshl_add_u64 v[226:227], v[16:17], 0, s[24:25]
	s_mov_b32 m0, s12
	s_nop 0
	global_load_lds_dwordx4 v[226:227], off
	s_waitcnt vmcnt(8)
	s_waitcnt lgkmcnt(0)
	s_barrier
	s_setprio 1
	s_waitcnt lgkmcnt(0)
	v_mfma_f32_16x16x32_bf16 v[94:97], v[54:57], v[194:197], v[94:97]
	v_mfma_f32_16x16x32_bf16 v[98:101], v[144:147], v[194:197], v[98:101]
	v_mfma_f32_16x16x32_bf16 v[106:109], v[144:147], v[202:205], v[106:109]
	v_mfma_f32_16x16x32_bf16 v[102:105], v[54:57], v[202:205], v[102:105]
	v_mfma_f32_16x16x32_bf16 v[110:113], v[54:57], v[210:213], v[110:113]
	v_mfma_f32_16x16x32_bf16 v[114:117], v[144:147], v[210:213], v[114:117]
	v_mfma_f32_16x16x32_bf16 v[122:125], v[144:147], v[218:221], v[122:125]
	v_mfma_f32_16x16x32_bf16 v[118:121], v[54:57], v[218:221], v[118:121]
	v_mfma_f32_16x16x32_bf16 v[94:97], v[58:61], v[198:201], v[94:97]
	v_mfma_f32_16x16x32_bf16 v[98:101], v[148:151], v[198:201], v[98:101]
	v_mfma_f32_16x16x32_bf16 v[106:109], v[148:151], v[206:209], v[106:109]
	v_mfma_f32_16x16x32_bf16 v[102:105], v[58:61], v[206:209], v[102:105]
	v_mfma_f32_16x16x32_bf16 v[110:113], v[58:61], v[214:217], v[110:113]
	v_mfma_f32_16x16x32_bf16 v[114:117], v[148:151], v[214:217], v[114:117]
	v_mfma_f32_16x16x32_bf16 v[122:125], v[148:151], v[222:225], v[122:125]
	v_mfma_f32_16x16x32_bf16 v[118:121], v[58:61], v[222:225], v[118:121]
	s_setprio 0
	s_setprio 1
	v_mfma_f32_16x16x32_bf16 v[126:129], v[152:155], v[194:197], v[126:129]
	v_mfma_f32_16x16x32_bf16 v[62:65], v[186:189], v[194:197], v[62:65]
	v_mfma_f32_16x16x32_bf16 v[70:73], v[186:189], v[202:205], v[70:73]
	v_mfma_f32_16x16x32_bf16 v[66:69], v[152:155], v[202:205], v[66:69]
	v_mfma_f32_16x16x32_bf16 v[74:77], v[152:155], v[210:213], v[74:77]
	v_mfma_f32_16x16x32_bf16 v[78:81], v[186:189], v[210:213], v[78:81]
	v_mfma_f32_16x16x32_bf16 v[86:89], v[186:189], v[218:221], v[86:89]
	v_mfma_f32_16x16x32_bf16 v[82:85], v[152:155], v[218:221], v[82:85]
	v_mfma_f32_16x16x32_bf16 v[126:129], v[156:159], v[198:201], v[126:129]
	v_mfma_f32_16x16x32_bf16 v[62:65], v[190:193], v[198:201], v[62:65]
	v_mfma_f32_16x16x32_bf16 v[70:73], v[190:193], v[206:209], v[70:73]
	v_mfma_f32_16x16x32_bf16 v[66:69], v[156:159], v[206:209], v[66:69]
	v_mfma_f32_16x16x32_bf16 v[74:77], v[156:159], v[214:217], v[74:77]
	v_mfma_f32_16x16x32_bf16 v[78:81], v[190:193], v[214:217], v[78:81]
	v_mfma_f32_16x16x32_bf16 v[86:89], v[190:193], v[222:225], v[86:89]
	v_mfma_f32_16x16x32_bf16 v[82:85], v[156:159], v[222:225], v[82:85]
	s_setprio 0
	s_barrier
	s_mov_b64 s[24:25], 0x180
	s_mov_b32 m0, s3
	v_lshl_add_u64 v[226:227], v[26:27], 0, s[24:25]
	ds_read_b128 v[194:197], v242 offset:49152
	ds_read_b128 v[198:201], v242 offset:50176
	ds_read_b128 v[202:205], v242 offset:51200
	ds_read_b128 v[206:209], v242 offset:52224
	ds_read_b128 v[210:213], v242 offset:53248
	ds_read_b128 v[214:217], v242 offset:54272
	ds_read_b128 v[218:221], v242 offset:55296
	ds_read_b128 v[222:225], v242 offset:56320
	global_load_lds_dwordx4 v[226:227], off
	v_lshl_add_u64 v[226:227], v[28:29], 0, s[24:25]
	s_mov_b32 m0, s5
	s_nop 0
	global_load_lds_dwordx4 v[226:227], off
	v_lshl_add_u64 v[226:227], v[24:25], 0, s[24:25]
	s_mov_b32 m0, s13
	s_nop 0
	global_load_lds_dwordx4 v[226:227], off
	v_lshl_add_u64 v[226:227], v[18:19], 0, s[24:25]
	s_mov_b32 m0, s14
	s_nop 0
	global_load_lds_dwordx4 v[226:227], off
	v_lshl_add_u64 v[226:227], v[20:21], 0, s[24:25]
	s_mov_b32 m0, s4
	s_nop 0
	global_load_lds_dwordx4 v[226:227], off
	v_lshl_add_u64 v[226:227], v[22:23], 0, s[24:25]
	s_mov_b32 m0, s9
	s_nop 0
	global_load_lds_dwordx4 v[226:227], off
	s_waitcnt vmcnt(8)
	s_waitcnt lgkmcnt(0)
	s_barrier
	s_setprio 1
	s_waitcnt lgkmcnt(0)
	v_mfma_f32_16x16x32_bf16 v[30:33], v[54:57], v[218:221], v[30:33]
	v_mfma_f32_16x16x32_bf16 v[34:37], v[144:147], v[218:221], v[34:37]
	v_mfma_f32_16x16x32_bf16 v[164:167], v[144:147], v[194:197], v[164:167]
	v_mfma_f32_16x16x32_bf16 v[160:163], v[54:57], v[194:197], v[160:163]
	v_mfma_f32_16x16x32_bf16 v[168:171], v[54:57], v[202:205], v[168:171]
	v_mfma_f32_16x16x32_bf16 v[172:175], v[144:147], v[202:205], v[172:175]
	v_mfma_f32_16x16x32_bf16 v[182:185], v[144:147], v[210:213], v[182:185]
	v_mfma_f32_16x16x32_bf16 v[178:181], v[54:57], v[210:213], v[178:181]
	v_mfma_f32_16x16x32_bf16 v[30:33], v[58:61], v[222:225], v[30:33]
	v_mfma_f32_16x16x32_bf16 v[34:37], v[148:151], v[222:225], v[34:37]
	v_mfma_f32_16x16x32_bf16 v[164:167], v[148:151], v[198:201], v[164:167]
	v_mfma_f32_16x16x32_bf16 v[160:163], v[58:61], v[198:201], v[160:163]
	v_mfma_f32_16x16x32_bf16 v[168:171], v[58:61], v[206:209], v[168:171]
	v_mfma_f32_16x16x32_bf16 v[172:175], v[148:151], v[206:209], v[172:175]
	v_mfma_f32_16x16x32_bf16 v[182:185], v[148:151], v[214:217], v[182:185]
	v_mfma_f32_16x16x32_bf16 v[178:181], v[58:61], v[214:217], v[178:181]
	s_setprio 0
	s_setprio 1
	v_mfma_f32_16x16x32_bf16 v[38:41], v[152:155], v[194:197], v[38:41]
	v_mfma_f32_16x16x32_bf16 v[42:45], v[186:189], v[194:197], v[42:45]
	v_mfma_f32_16x16x32_bf16 v[54:57], v[152:155], v[202:205], v[90:93]
	v_mfma_f32_16x16x32_bf16 v[58:61], v[186:189], v[202:205], v[132:135]
	v_mfma_f32_16x16x32_bf16 v[90:93], v[152:155], v[210:213], v[136:139]
	v_mfma_f32_16x16x32_bf16 v[46:49], v[152:155], v[218:221], v[46:49]
	v_mfma_f32_16x16x32_bf16 v[50:53], v[186:189], v[218:221], v[50:53]
	v_mfma_f32_16x16x32_bf16 v[38:41], v[156:159], v[198:201], v[38:41]
	v_mfma_f32_16x16x32_bf16 v[42:45], v[190:193], v[198:201], v[42:45]
	v_mfma_f32_16x16x32_bf16 v[54:57], v[156:159], v[206:209], v[54:57]
	v_mfma_f32_16x16x32_bf16 v[58:61], v[190:193], v[206:209], v[58:61]
	v_mfma_f32_16x16x32_bf16 v[90:93], v[156:159], v[214:217], v[90:93]
	v_mfma_f32_16x16x32_bf16 v[132:135], v[186:189], v[210:213], v[140:143]
	v_mfma_f32_16x16x32_bf16 v[46:49], v[156:159], v[222:225], v[46:49]
	v_mfma_f32_16x16x32_bf16 v[50:53], v[190:193], v[222:225], v[50:53]
	v_mfma_f32_16x16x32_bf16 v[132:135], v[190:193], v[214:217], v[132:135]
	s_setprio 0
	s_barrier
	ds_read_b128 v[136:139], v176
	ds_read_b128 v[140:143], v176 offset:1024
	ds_read_b128 v[144:147], v176 offset:2048
	ds_read_b128 v[148:151], v176 offset:3072
	ds_read_b128 v[152:155], v131
	ds_read_b128 v[156:159], v131 offset:1024
	ds_read_b128 v[186:189], v131 offset:2048
	ds_read_b128 v[190:193], v131 offset:3072
	s_mov_b32 m0, s22
	v_lshl_add_u64 v[226:227], v[14:15], 0, s[24:25]
	ds_read_b128 v[194:197], v242
	ds_read_b128 v[198:201], v242 offset:1024
	ds_read_b128 v[202:205], v242 offset:2048
	ds_read_b128 v[206:209], v242 offset:3072
	ds_read_b128 v[210:213], v242 offset:4096
	ds_read_b128 v[214:217], v242 offset:5120
	ds_read_b128 v[218:221], v242 offset:6144
	ds_read_b128 v[222:225], v242 offset:7168
	global_load_lds_dwordx4 v[226:227], off
	v_lshl_add_u64 v[226:227], v[16:17], 0, s[24:25]
	s_mov_b32 m0, s21
	s_nop 0
	global_load_lds_dwordx4 v[226:227], off
	s_waitcnt vmcnt(8)
	s_waitcnt lgkmcnt(0)
	s_barrier
	s_setprio 1
	s_waitcnt lgkmcnt(0)
	v_mfma_f32_16x16x32_bf16 v[110:113], v[136:139], v[210:213], v[110:113]
	v_mfma_f32_16x16x32_bf16 v[226:229], v[140:143], v[214:217], v[110:113]
	v_mfma_f32_16x16x32_bf16 v[110:113], v[144:147], v[210:213], v[114:117]
	v_mfma_f32_16x16x32_bf16 v[94:97], v[136:139], v[194:197], v[94:97]
	v_mfma_f32_16x16x32_bf16 v[98:101], v[144:147], v[194:197], v[98:101]
	v_mfma_f32_16x16x32_bf16 v[102:105], v[136:139], v[202:205], v[102:105]
	v_mfma_f32_16x16x32_bf16 v[106:109], v[144:147], v[202:205], v[106:109]
	v_mfma_f32_16x16x32_bf16 v[114:117], v[148:151], v[214:217], v[110:113]
	v_mfma_f32_16x16x32_bf16 v[110:113], v[136:139], v[218:221], v[118:121]
	v_mfma_f32_16x16x32_bf16 v[94:97], v[140:143], v[198:201], v[94:97]
	v_mfma_f32_16x16x32_bf16 v[98:101], v[148:151], v[198:201], v[98:101]
	v_mfma_f32_16x16x32_bf16 v[102:105], v[140:143], v[206:209], v[102:105]
	v_mfma_f32_16x16x32_bf16 v[106:109], v[148:151], v[206:209], v[106:109]
	v_mfma_f32_16x16x32_bf16 v[118:121], v[140:143], v[222:225], v[110:113]
	v_mfma_f32_16x16x32_bf16 v[110:113], v[144:147], v[218:221], v[122:125]
	v_mfma_f32_16x16x32_bf16 v[230:233], v[148:151], v[222:225], v[110:113]
	s_setprio 0
	s_setprio 1
	v_mfma_f32_16x16x32_bf16 v[74:77], v[152:155], v[210:213], v[74:77]
	v_mfma_f32_16x16x32_bf16 v[110:113], v[152:155], v[194:197], v[126:129]
	v_mfma_f32_16x16x32_bf16 v[62:65], v[186:189], v[194:197], v[62:65]
	v_mfma_f32_16x16x32_bf16 v[194:197], v[156:159], v[214:217], v[74:77]
	v_mfma_f32_16x16x32_bf16 v[74:77], v[186:189], v[210:213], v[78:81]
	v_mfma_f32_16x16x32_bf16 v[234:237], v[156:159], v[198:201], v[110:113]
	v_mfma_f32_16x16x32_bf16 v[62:65], v[190:193], v[198:201], v[62:65]
	v_mfma_f32_16x16x32_bf16 v[66:69], v[152:155], v[202:205], v[66:69]
	v_mfma_f32_16x16x32_bf16 v[70:73], v[186:189], v[202:205], v[70:73]
	v_mfma_f32_16x16x32_bf16 v[198:201], v[190:193], v[214:217], v[74:77]
	v_mfma_f32_16x16x32_bf16 v[74:77], v[152:155], v[218:221], v[82:85]
	v_mfma_f32_16x16x32_bf16 v[66:69], v[156:159], v[206:209], v[66:69]
	v_mfma_f32_16x16x32_bf16 v[70:73], v[190:193], v[206:209], v[70:73]
	v_mfma_f32_16x16x32_bf16 v[202:205], v[156:159], v[222:225], v[74:77]
	v_mfma_f32_16x16x32_bf16 v[74:77], v[186:189], v[218:221], v[86:89]
	v_mfma_f32_16x16x32_bf16 v[206:209], v[190:193], v[222:225], v[74:77]
	s_setprio 0
	s_barrier
	s_mov_b32 m0, s20
	s_nop 3
	ds_read_b128 v[74:77], v242 offset:16384
	ds_read_b128 v[78:81], v242 offset:17408
	ds_read_b128 v[82:85], v242 offset:18432
	ds_read_b128 v[86:89], v242 offset:19456
	ds_read_b128 v[110:113], v242 offset:20480
	ds_read_b128 v[122:125], v242 offset:21504
	ds_read_b128 v[126:129], v242 offset:22528
	ds_read_b128 v[210:213], v242 offset:23552
	global_load_lds_dwordx4 v[26:27], off
	s_mov_b32 m0, s19
	s_nop 0
	global_load_lds_dwordx4 v[28:29], off
	s_mov_b32 m0, s18
	s_nop 0
	global_load_lds_dwordx4 v[24:25], off
	s_mov_b32 m0, s17
	s_nop 0
	global_load_lds_dwordx4 v[18:19], off
	s_mov_b32 m0, s15
	s_nop 0
	global_load_lds_dwordx4 v[20:21], off
	s_mov_b32 m0, s16
	s_nop 0
	global_load_lds_dwordx4 v[22:23], off
	s_waitcnt vmcnt(8)
	s_waitcnt lgkmcnt(0)
	s_barrier
	s_setprio 1
	s_waitcnt lgkmcnt(0)
	v_mfma_f32_16x16x32_bf16 v[30:33], v[136:139], v[126:129], v[30:33]
	v_mfma_f32_16x16x32_bf16 v[18:21], v[136:139], v[74:77], v[160:163]
	v_mfma_f32_16x16x32_bf16 v[22:25], v[144:147], v[74:77], v[164:167]
	v_mfma_f32_16x16x32_bf16 v[26:29], v[136:139], v[82:85], v[168:171]
	v_mfma_f32_16x16x32_bf16 v[164:167], v[136:139], v[110:113], v[178:181]
	v_mfma_f32_16x16x32_bf16 v[136:139], v[140:143], v[210:213], v[30:33]
	v_mfma_f32_16x16x32_bf16 v[30:33], v[144:147], v[126:129], v[34:37]
	v_mfma_f32_16x16x32_bf16 v[18:21], v[140:143], v[78:81], v[18:21]
	v_mfma_f32_16x16x32_bf16 v[22:25], v[148:151], v[78:81], v[22:25]
	v_mfma_f32_16x16x32_bf16 v[26:29], v[140:143], v[86:89], v[26:29]
	v_mfma_f32_16x16x32_bf16 v[160:163], v[144:147], v[82:85], v[172:175]
	v_mfma_f32_16x16x32_bf16 v[168:171], v[144:147], v[110:113], v[182:185]
	v_mfma_f32_16x16x32_bf16 v[34:37], v[148:151], v[210:213], v[30:33]
	v_mfma_f32_16x16x32_bf16 v[160:163], v[148:151], v[86:89], v[160:163]
	v_mfma_f32_16x16x32_bf16 v[164:167], v[140:143], v[122:125], v[164:167]
	v_mfma_f32_16x16x32_bf16 v[168:171], v[148:151], v[122:125], v[168:171]
	s_setprio 0
	s_setprio 1
	v_mfma_f32_16x16x32_bf16 v[30:33], v[152:155], v[74:77], v[38:41]
	v_mfma_f32_16x16x32_bf16 v[38:41], v[156:159], v[78:81], v[30:33]
	v_mfma_f32_16x16x32_bf16 v[30:33], v[186:189], v[74:77], v[42:45]
	v_mfma_f32_16x16x32_bf16 v[140:143], v[190:193], v[78:81], v[30:33]
	v_mfma_f32_16x16x32_bf16 v[30:33], v[152:155], v[82:85], v[54:57]
	v_mfma_f32_16x16x32_bf16 v[144:147], v[156:159], v[86:89], v[30:33]
	v_mfma_f32_16x16x32_bf16 v[30:33], v[186:189], v[82:85], v[58:61]
	v_mfma_f32_16x16x32_bf16 v[148:151], v[190:193], v[86:89], v[30:33]
	v_mfma_f32_16x16x32_bf16 v[30:33], v[152:155], v[110:113], v[90:93]
	v_mfma_f32_16x16x32_bf16 v[172:175], v[156:159], v[122:125], v[30:33]
	v_mfma_f32_16x16x32_bf16 v[30:33], v[186:189], v[110:113], v[132:135]
	v_mfma_f32_16x16x32_bf16 v[132:135], v[190:193], v[122:125], v[30:33]
	v_mfma_f32_16x16x32_bf16 v[30:33], v[152:155], v[126:129], v[46:49]
	v_mfma_f32_16x16x32_bf16 v[152:155], v[156:159], v[210:213], v[30:33]
	v_mfma_f32_16x16x32_bf16 v[30:33], v[186:189], v[126:129], v[50:53]
	v_mfma_f32_16x16x32_bf16 v[156:159], v[190:193], v[210:213], v[30:33]
	s_setprio 0
	s_barrier
	ds_read_b128 v[50:53], v239
	ds_read_b128 v[54:57], v239 offset:1024
	ds_read_b128 v[178:181], v239 offset:2048
	ds_read_b128 v[182:185], v239 offset:3072
	ds_read_b128 v[186:189], v238
	ds_read_b128 v[190:193], v238 offset:1024
	ds_read_b128 v[210:213], v238 offset:2048
	ds_read_b128 v[214:217], v238 offset:3072
	s_mov_b32 m0, s11
	ds_read_b128 v[30:33], v242 offset:32768
	ds_read_b128 v[42:45], v242 offset:33792
	ds_read_b128 v[46:49], v242 offset:34816
	ds_read_b128 v[58:61], v242 offset:35840
	ds_read_b128 v[82:85], v242 offset:36864
	ds_read_b128 v[218:221], v242 offset:37888
	ds_read_b128 v[222:225], v242 offset:38912
	ds_read_b128 v[238:241], v242 offset:39936
	global_load_lds_dwordx4 v[14:15], off
	s_mov_b32 m0, s12
	s_nop 0
	global_load_lds_dwordx4 v[16:17], off
	s_waitcnt vmcnt(8)
	s_waitcnt lgkmcnt(0)
	s_barrier
	s_setprio 1
	s_waitcnt lgkmcnt(0)
	v_mfma_f32_16x16x32_bf16 v[14:17], v[50:53], v[30:33], v[94:97]
	v_mfma_f32_16x16x32_bf16 v[126:129], v[54:57], v[42:45], v[14:17]
	v_mfma_f32_16x16x32_bf16 v[14:17], v[178:181], v[30:33], v[98:101]
	v_mfma_f32_16x16x32_bf16 v[122:125], v[182:185], v[42:45], v[14:17]
	v_mfma_f32_16x16x32_bf16 v[14:17], v[50:53], v[46:49], v[102:105]
	v_mfma_f32_16x16x32_bf16 v[110:113], v[54:57], v[58:61], v[14:17]
	v_mfma_f32_16x16x32_bf16 v[14:17], v[178:181], v[46:49], v[106:109]
	v_mfma_f32_16x16x32_bf16 v[106:109], v[182:185], v[58:61], v[14:17]
	v_mfma_f32_16x16x32_bf16 v[14:17], v[50:53], v[82:85], v[226:229]
	v_mfma_f32_16x16x32_bf16 v[94:97], v[54:57], v[218:221], v[14:17]
	v_mfma_f32_16x16x32_bf16 v[14:17], v[178:181], v[82:85], v[114:117]
	v_mfma_f32_16x16x32_bf16 v[90:93], v[182:185], v[218:221], v[14:17]
	v_mfma_f32_16x16x32_bf16 v[14:17], v[50:53], v[222:225], v[118:121]
	v_mfma_f32_16x16x32_bf16 v[78:81], v[54:57], v[238:241], v[14:17]
	v_mfma_f32_16x16x32_bf16 v[14:17], v[178:181], v[222:225], v[230:233]
	v_mfma_f32_16x16x32_bf16 v[74:77], v[182:185], v[238:241], v[14:17]
	s_setprio 0
	s_setprio 1
	v_mfma_f32_16x16x32_bf16 v[14:17], v[186:189], v[30:33], v[234:237]
	v_mfma_f32_16x16x32_bf16 v[118:121], v[190:193], v[42:45], v[14:17]
	v_mfma_f32_16x16x32_bf16 v[14:17], v[210:213], v[30:33], v[62:65]
	v_mfma_f32_16x16x32_bf16 v[114:117], v[214:217], v[42:45], v[14:17]
	v_mfma_f32_16x16x32_bf16 v[14:17], v[186:189], v[46:49], v[66:69]
	v_mfma_f32_16x16x32_bf16 v[102:105], v[190:193], v[58:61], v[14:17]
	v_mfma_f32_16x16x32_bf16 v[14:17], v[210:213], v[46:49], v[70:73]
	v_mfma_f32_16x16x32_bf16 v[98:101], v[214:217], v[58:61], v[14:17]
	v_mfma_f32_16x16x32_bf16 v[14:17], v[186:189], v[82:85], v[194:197]
	v_mfma_f32_16x16x32_bf16 v[86:89], v[190:193], v[218:221], v[14:17]
	v_mfma_f32_16x16x32_bf16 v[14:17], v[210:213], v[82:85], v[198:201]
	v_mfma_f32_16x16x32_bf16 v[82:85], v[214:217], v[218:221], v[14:17]
	v_mfma_f32_16x16x32_bf16 v[14:17], v[186:189], v[222:225], v[202:205]
	v_mfma_f32_16x16x32_bf16 v[66:69], v[190:193], v[238:241], v[14:17]
	v_mfma_f32_16x16x32_bf16 v[14:17], v[210:213], v[222:225], v[206:209]
	v_mfma_f32_16x16x32_bf16 v[58:61], v[214:217], v[238:241], v[14:17]
	s_setprio 0
	s_barrier
	s_mov_b32 m0, s3
	ds_read_b128 v[194:197], v242 offset:49152
	ds_read_b128 v[198:201], v242 offset:50176
	ds_read_b128 v[202:205], v242 offset:51200
	ds_read_b128 v[206:209], v242 offset:52224
	ds_read_b128 v[218:221], v242 offset:53248
	ds_read_b128 v[222:225], v242 offset:54272
	ds_read_b128 v[226:229], v242 offset:55296
	ds_read_b128 v[230:233], v242 offset:56320
	global_load_lds_dwordx4 v[4:5], off
	s_mov_b32 m0, s5
	s_nop 0
	global_load_lds_dwordx4 v[6:7], off
	s_mov_b32 m0, s13
	s_nop 0
	global_load_lds_dwordx4 v[10:11], off
	s_mov_b32 m0, s14
	s_nop 0
	global_load_lds_dwordx4 v[12:13], off
	s_mov_b32 m0, s4
	s_nop 0
	global_load_lds_dwordx4 v[2:3], off
	s_mov_b32 m0, s9
	s_nop 0
	global_load_lds_dwordx4 v[8:9], off
	s_waitcnt vmcnt(8)
	s_waitcnt lgkmcnt(0)
	s_barrier
	s_setprio 1
	s_waitcnt lgkmcnt(0)
	v_mfma_f32_16x16x32_bf16 v[2:5], v[50:53], v[194:197], v[18:21]
	v_mfma_f32_16x16x32_bf16 v[70:73], v[54:57], v[198:201], v[2:5]
	v_mfma_f32_16x16x32_bf16 v[2:5], v[178:181], v[194:197], v[22:25]
	v_mfma_f32_16x16x32_bf16 v[62:65], v[182:185], v[198:201], v[2:5]
	v_mfma_f32_16x16x32_bf16 v[2:5], v[50:53], v[202:205], v[26:29]
	v_mfma_f32_16x16x32_bf16 v[46:49], v[54:57], v[206:209], v[2:5]
	v_mfma_f32_16x16x32_bf16 v[2:5], v[178:181], v[202:205], v[160:163]
	v_mfma_f32_16x16x32_bf16 v[42:45], v[182:185], v[206:209], v[2:5]
	v_mfma_f32_16x16x32_bf16 v[2:5], v[50:53], v[218:221], v[164:167]
	v_mfma_f32_16x16x32_bf16 v[30:33], v[54:57], v[222:225], v[2:5]
	v_mfma_f32_16x16x32_bf16 v[2:5], v[178:181], v[218:221], v[168:171]
	v_mfma_f32_16x16x32_bf16 v[26:29], v[182:185], v[222:225], v[2:5]
	v_mfma_f32_16x16x32_bf16 v[2:5], v[50:53], v[226:229], v[136:139]
	v_mfma_f32_16x16x32_bf16 v[14:17], v[54:57], v[230:233], v[2:5]
	v_mfma_f32_16x16x32_bf16 v[2:5], v[178:181], v[226:229], v[34:37]
	v_mfma_f32_16x16x32_bf16 v[10:13], v[182:185], v[230:233], v[2:5]
	s_setprio 0
	s_setprio 1
	v_mfma_f32_16x16x32_bf16 v[2:5], v[186:189], v[194:197], v[38:41]
	v_mfma_f32_16x16x32_bf16 v[54:57], v[190:193], v[198:201], v[2:5]
	v_mfma_f32_16x16x32_bf16 v[2:5], v[210:213], v[194:197], v[140:143]
	v_mfma_f32_16x16x32_bf16 v[50:53], v[214:217], v[198:201], v[2:5]
	v_mfma_f32_16x16x32_bf16 v[2:5], v[186:189], v[202:205], v[144:147]
	v_mfma_f32_16x16x32_bf16 v[38:41], v[190:193], v[206:209], v[2:5]
	v_mfma_f32_16x16x32_bf16 v[2:5], v[210:213], v[202:205], v[148:151]
	v_mfma_f32_16x16x32_bf16 v[34:37], v[214:217], v[206:209], v[2:5]
	v_mfma_f32_16x16x32_bf16 v[2:5], v[186:189], v[218:221], v[172:175]
	v_mfma_f32_16x16x32_bf16 v[22:25], v[190:193], v[222:225], v[2:5]
	v_mfma_f32_16x16x32_bf16 v[2:5], v[210:213], v[218:221], v[132:135]
	v_mfma_f32_16x16x32_bf16 v[18:21], v[214:217], v[222:225], v[2:5]
	v_mfma_f32_16x16x32_bf16 v[2:5], v[186:189], v[226:229], v[152:155]
	v_mfma_f32_16x16x32_bf16 v[6:9], v[190:193], v[230:233], v[2:5]
	v_mfma_f32_16x16x32_bf16 v[2:5], v[210:213], v[226:229], v[156:159]
	v_mfma_f32_16x16x32_bf16 v[2:5], v[214:217], v[230:233], v[2:5]
	s_setprio 0
	s_barrier
	s_cbranch_scc1 .LBB0_1139
	s_barrier

.Lpk1179_peel:
	ds_read_b128 v[144:147], v158
	ds_read_b128 v[164:167], v158 offset:1024
	ds_read_b128 v[168:171], v158 offset:2048
	ds_read_b128 v[172:175], v158 offset:3072
	ds_read_b128 v[178:181], v159
	ds_read_b128 v[182:185], v159 offset:1024
	ds_read_b128 v[186:189], v159 offset:2048
	ds_read_b128 v[190:193], v159 offset:3072
	s_add_u32 s2, s36, 0xfffc0080
	s_addc_u32 s3, s37, -1
	s_cmp_eq_u32 s61, 12
	s_cselect_b32 s3, s19, s3
	s_cselect_b32 s2, s21, s2
	s_cselect_b32 s39, s57, s60
	s_cselect_b32 s38, s58, s59
	v_lshl_add_u64 v[226:227], s[36:37], 0, v[138:139]
	s_add_i32 m0, s42, 0xc000
	ds_read_b128 v[194:197], v160
	ds_read_b128 v[198:201], v160 offset:1024
	ds_read_b128 v[202:205], v160 offset:2048
	ds_read_b128 v[206:209], v160 offset:3072
	ds_read_b128 v[210:213], v160 offset:4096
	ds_read_b128 v[214:217], v160 offset:5120
	ds_read_b128 v[218:221], v160 offset:6144
	ds_read_b128 v[222:225], v160 offset:7168
	global_load_lds_dwordx4 v[226:227], off
	v_lshl_add_u64 v[226:227], s[36:37], 0, v[140:141]
	s_add_i32 m0, s42, 0xe000
	s_nop 0
	global_load_lds_dwordx4 v[226:227], off
	s_waitcnt vmcnt(8)
	s_waitcnt lgkmcnt(0)
	s_barrier
	s_setprio 1
	s_waitcnt lgkmcnt(0)
	v_mfma_f32_16x16x32_bf16 v[126:129], v[144:147], v[194:197], 0
	v_mfma_f32_16x16x32_bf16 v[122:125], v[168:171], v[194:197], 0
	v_mfma_f32_16x16x32_bf16 v[106:109], v[168:171], v[202:205], 0
	v_mfma_f32_16x16x32_bf16 v[114:117], v[144:147], v[202:205], 0
	v_mfma_f32_16x16x32_bf16 v[98:101], v[144:147], v[210:213], 0
	v_mfma_f32_16x16x32_bf16 v[90:93], v[168:171], v[210:213], 0
	v_mfma_f32_16x16x32_bf16 v[74:77], v[168:171], v[218:221], 0
	v_mfma_f32_16x16x32_bf16 v[82:85], v[144:147], v[218:221], 0
	v_mfma_f32_16x16x32_bf16 v[126:129], v[164:167], v[198:201], v[126:129]
	v_mfma_f32_16x16x32_bf16 v[122:125], v[172:175], v[198:201], v[122:125]
	v_mfma_f32_16x16x32_bf16 v[106:109], v[172:175], v[206:209], v[106:109]
	v_mfma_f32_16x16x32_bf16 v[114:117], v[164:167], v[206:209], v[114:117]
	v_mfma_f32_16x16x32_bf16 v[98:101], v[164:167], v[214:217], v[98:101]
	v_mfma_f32_16x16x32_bf16 v[90:93], v[172:175], v[214:217], v[90:93]
	v_mfma_f32_16x16x32_bf16 v[74:77], v[172:175], v[222:225], v[74:77]
	v_mfma_f32_16x16x32_bf16 v[82:85], v[164:167], v[222:225], v[82:85]
	s_setprio 0
	s_setprio 1
	v_mfma_f32_16x16x32_bf16 v[118:121], v[178:181], v[194:197], 0
	v_mfma_f32_16x16x32_bf16 v[110:113], v[186:189], v[194:197], 0
	v_mfma_f32_16x16x32_bf16 v[94:97], v[186:189], v[202:205], 0
	v_mfma_f32_16x16x32_bf16 v[102:105], v[178:181], v[202:205], 0
	v_mfma_f32_16x16x32_bf16 v[86:89], v[178:181], v[210:213], 0
	v_mfma_f32_16x16x32_bf16 v[78:81], v[186:189], v[210:213], 0
	v_mfma_f32_16x16x32_bf16 v[66:69], v[186:189], v[218:221], 0
	v_mfma_f32_16x16x32_bf16 v[70:73], v[178:181], v[218:221], 0
	v_mfma_f32_16x16x32_bf16 v[118:121], v[182:185], v[198:201], v[118:121]
	v_mfma_f32_16x16x32_bf16 v[110:113], v[190:193], v[198:201], v[110:113]
	v_mfma_f32_16x16x32_bf16 v[94:97], v[190:193], v[206:209], v[94:97]
	v_mfma_f32_16x16x32_bf16 v[102:105], v[182:185], v[206:209], v[102:105]
	v_mfma_f32_16x16x32_bf16 v[86:89], v[182:185], v[214:217], v[86:89]
	v_mfma_f32_16x16x32_bf16 v[78:81], v[190:193], v[214:217], v[78:81]
	v_mfma_f32_16x16x32_bf16 v[66:69], v[190:193], v[222:225], v[66:69]
	v_mfma_f32_16x16x32_bf16 v[70:73], v[182:185], v[222:225], v[70:73]
	s_setprio 0
	s_barrier
	s_add_i32 s62, s51, s41
	v_lshl_add_u64 v[226:227], s[38:39], 0, v[132:133]
	s_mov_b32 m0, s62
	ds_read_b128 v[194:197], v160 offset:16384
	ds_read_b128 v[198:201], v160 offset:17408
	ds_read_b128 v[202:205], v160 offset:18432
	ds_read_b128 v[206:209], v160 offset:19456
	ds_read_b128 v[210:213], v160 offset:20480
	ds_read_b128 v[214:217], v160 offset:21504
	ds_read_b128 v[218:221], v160 offset:22528
	ds_read_b128 v[222:225], v160 offset:23552
	global_load_lds_dwordx4 v[226:227], off
	s_add_i32 m0, s62, 0x2000
	s_add_u32 s62, s38, 0x40000
	v_lshl_add_u64 v[228:229], s[38:39], 0, v[136:137]
	s_addc_u32 s63, s39, 0
	s_add_i32 s64, s52, s41
	global_load_lds_dwordx4 v[228:229], off
	v_lshl_add_u64 v[230:231], s[62:63], 0, v[132:133]
	s_mov_b32 m0, s64
	v_lshl_add_u64 v[232:233], s[2:3], 0, v[134:135]
	global_load_lds_dwordx4 v[230:231], off
	v_lshl_add_u64 v[230:231], s[62:63], 0, v[136:137]
	s_add_i32 m0, s64, 0x2000
	s_nop 0
	global_load_lds_dwordx4 v[230:231], off
	v_lshl_add_u64 v[230:231], s[2:3], 0, v[130:131]
	s_mov_b32 m0, s42
	s_nop 0
	global_load_lds_dwordx4 v[230:231], off
	s_mov_b32 m0, s43
	s_nop 0
	global_load_lds_dwordx4 v[232:233], off
	s_waitcnt vmcnt(8)
	s_waitcnt lgkmcnt(0)
	s_barrier
	s_setprio 1
	s_waitcnt lgkmcnt(0)
	v_mfma_f32_16x16x32_bf16 v[62:65], v[144:147], v[194:197], 0
	v_mfma_f32_16x16x32_bf16 v[58:61], v[168:171], v[194:197], 0
	v_mfma_f32_16x16x32_bf16 v[42:45], v[168:171], v[202:205], 0
	v_mfma_f32_16x16x32_bf16 v[50:53], v[144:147], v[202:205], 0
	v_mfma_f32_16x16x32_bf16 v[34:37], v[144:147], v[210:213], 0
	v_mfma_f32_16x16x32_bf16 v[26:29], v[168:171], v[210:213], 0
	v_mfma_f32_16x16x32_bf16 v[10:13], v[168:171], v[218:221], 0
	v_mfma_f32_16x16x32_bf16 v[18:21], v[144:147], v[218:221], 0
	v_mfma_f32_16x16x32_bf16 v[62:65], v[164:167], v[198:201], v[62:65]
	v_mfma_f32_16x16x32_bf16 v[58:61], v[172:175], v[198:201], v[58:61]
	v_mfma_f32_16x16x32_bf16 v[42:45], v[172:175], v[206:209], v[42:45]
	v_mfma_f32_16x16x32_bf16 v[50:53], v[164:167], v[206:209], v[50:53]
	v_mfma_f32_16x16x32_bf16 v[34:37], v[164:167], v[214:217], v[34:37]
	v_mfma_f32_16x16x32_bf16 v[26:29], v[172:175], v[214:217], v[26:29]
	v_mfma_f32_16x16x32_bf16 v[10:13], v[172:175], v[222:225], v[10:13]
	v_mfma_f32_16x16x32_bf16 v[18:21], v[164:167], v[222:225], v[18:21]
	s_setprio 0
	s_setprio 1
	v_mfma_f32_16x16x32_bf16 v[54:57], v[178:181], v[194:197], 0
	v_mfma_f32_16x16x32_bf16 v[46:49], v[186:189], v[194:197], 0
	v_mfma_f32_16x16x32_bf16 v[30:33], v[186:189], v[202:205], 0
	v_mfma_f32_16x16x32_bf16 v[38:41], v[178:181], v[202:205], 0
	v_mfma_f32_16x16x32_bf16 v[22:25], v[178:181], v[210:213], 0
	v_mfma_f32_16x16x32_bf16 v[14:17], v[186:189], v[210:213], 0
	v_mfma_f32_16x16x32_bf16 v[2:5], v[186:189], v[218:221], 0
	v_mfma_f32_16x16x32_bf16 v[6:9], v[178:181], v[218:221], 0
	v_mfma_f32_16x16x32_bf16 v[54:57], v[182:185], v[198:201], v[54:57]
	v_mfma_f32_16x16x32_bf16 v[46:49], v[190:193], v[198:201], v[46:49]
	v_mfma_f32_16x16x32_bf16 v[30:33], v[190:193], v[206:209], v[30:33]
	v_mfma_f32_16x16x32_bf16 v[38:41], v[182:185], v[206:209], v[38:41]
	v_mfma_f32_16x16x32_bf16 v[22:25], v[182:185], v[214:217], v[22:25]
	v_mfma_f32_16x16x32_bf16 v[14:17], v[190:193], v[214:217], v[14:17]
	v_mfma_f32_16x16x32_bf16 v[2:5], v[190:193], v[222:225], v[2:5]
	v_mfma_f32_16x16x32_bf16 v[6:9], v[182:185], v[222:225], v[6:9]
	s_setprio 0
	s_barrier
	s_add_i32 s62, 0, 0x18000
	v_add_u32_e32 v163, s62, v148
	s_add_i32 s63, 0, 0x1c000
	ds_read_b128 v[144:147], v163
	ds_read_b128 v[164:167], v163 offset:1024
	ds_read_b128 v[168:171], v163 offset:2048
	ds_read_b128 v[172:175], v163 offset:3072
	v_add_u32_e32 v163, s63, v148
	ds_read_b128 v[178:181], v163
	ds_read_b128 v[182:185], v163 offset:1024
	ds_read_b128 v[186:189], v163 offset:2048
	ds_read_b128 v[190:193], v163 offset:3072
	s_add_u32 s2, s2, 0x40000
	s_addc_u32 s3, s3, 0
	s_mov_b32 m0, s44
	v_lshl_add_u64 v[234:235], s[2:3], 0, v[130:131]
	ds_read_b128 v[194:197], v160 offset:32768
	ds_read_b128 v[198:201], v160 offset:33792
	ds_read_b128 v[202:205], v160 offset:34816
	ds_read_b128 v[206:209], v160 offset:35840
	ds_read_b128 v[210:213], v160 offset:36864
	ds_read_b128 v[214:217], v160 offset:37888
	ds_read_b128 v[218:221], v160 offset:38912
	ds_read_b128 v[222:225], v160 offset:39936
	global_load_lds_dwordx4 v[234:235], off
	v_lshl_add_u64 v[234:235], s[2:3], 0, v[134:135]
	s_mov_b32 m0, s45
	s_nop 0
	global_load_lds_dwordx4 v[234:235], off
	s_waitcnt vmcnt(8)
	s_waitcnt lgkmcnt(0)
	s_barrier
	s_setprio 1
	s_waitcnt lgkmcnt(0)
	v_mfma_f32_16x16x32_bf16 v[126:129], v[144:147], v[194:197], v[126:129]
	v_mfma_f32_16x16x32_bf16 v[122:125], v[168:171], v[194:197], v[122:125]
	v_mfma_f32_16x16x32_bf16 v[106:109], v[168:171], v[202:205], v[106:109]
	v_mfma_f32_16x16x32_bf16 v[114:117], v[144:147], v[202:205], v[114:117]
	v_mfma_f32_16x16x32_bf16 v[98:101], v[144:147], v[210:213], v[98:101]
	v_mfma_f32_16x16x32_bf16 v[90:93], v[168:171], v[210:213], v[90:93]
	v_mfma_f32_16x16x32_bf16 v[74:77], v[168:171], v[218:221], v[74:77]
	v_mfma_f32_16x16x32_bf16 v[82:85], v[144:147], v[218:221], v[82:85]
	v_mfma_f32_16x16x32_bf16 v[126:129], v[164:167], v[198:201], v[126:129]
	v_mfma_f32_16x16x32_bf16 v[122:125], v[172:175], v[198:201], v[122:125]
	v_mfma_f32_16x16x32_bf16 v[106:109], v[172:175], v[206:209], v[106:109]
	v_mfma_f32_16x16x32_bf16 v[114:117], v[164:167], v[206:209], v[114:117]
	v_mfma_f32_16x16x32_bf16 v[98:101], v[164:167], v[214:217], v[98:101]
	v_mfma_f32_16x16x32_bf16 v[90:93], v[172:175], v[214:217], v[90:93]
	v_mfma_f32_16x16x32_bf16 v[74:77], v[172:175], v[222:225], v[74:77]
	v_mfma_f32_16x16x32_bf16 v[82:85], v[164:167], v[222:225], v[82:85]
	s_setprio 0
	s_setprio 1
	v_mfma_f32_16x16x32_bf16 v[118:121], v[178:181], v[194:197], v[118:121]
	v_mfma_f32_16x16x32_bf16 v[110:113], v[186:189], v[194:197], v[110:113]
	v_mfma_f32_16x16x32_bf16 v[94:97], v[186:189], v[202:205], v[94:97]
	v_mfma_f32_16x16x32_bf16 v[102:105], v[178:181], v[202:205], v[102:105]
	v_mfma_f32_16x16x32_bf16 v[86:89], v[178:181], v[210:213], v[86:89]
	v_mfma_f32_16x16x32_bf16 v[78:81], v[186:189], v[210:213], v[78:81]
	v_mfma_f32_16x16x32_bf16 v[66:69], v[186:189], v[218:221], v[66:69]
	v_mfma_f32_16x16x32_bf16 v[70:73], v[178:181], v[218:221], v[70:73]
	v_mfma_f32_16x16x32_bf16 v[118:121], v[182:185], v[198:201], v[118:121]
	v_mfma_f32_16x16x32_bf16 v[110:113], v[190:193], v[198:201], v[110:113]
	v_mfma_f32_16x16x32_bf16 v[94:97], v[190:193], v[206:209], v[94:97]
	v_mfma_f32_16x16x32_bf16 v[102:105], v[182:185], v[206:209], v[102:105]
	v_mfma_f32_16x16x32_bf16 v[86:89], v[182:185], v[214:217], v[86:89]
	v_mfma_f32_16x16x32_bf16 v[78:81], v[190:193], v[214:217], v[78:81]
	v_mfma_f32_16x16x32_bf16 v[66:69], v[190:193], v[222:225], v[66:69]
	v_mfma_f32_16x16x32_bf16 v[70:73], v[182:185], v[222:225], v[70:73]
	s_setprio 0
	s_barrier
	s_add_i32 s2, s62, s41
	v_lshl_add_u64 v[226:227], v[226:227], 0, s[10:11]
	s_mov_b32 m0, s2
	ds_read_b128 v[194:197], v160 offset:49152
	ds_read_b128 v[198:201], v160 offset:50176
	ds_read_b128 v[202:205], v160 offset:51200
	ds_read_b128 v[206:209], v160 offset:52224
	ds_read_b128 v[210:213], v160 offset:53248
	ds_read_b128 v[214:217], v160 offset:54272
	ds_read_b128 v[218:221], v160 offset:55296
	ds_read_b128 v[222:225], v160 offset:56320
	global_load_lds_dwordx4 v[226:227], off
	s_add_i32 m0, s2, 0x2000
	s_add_u32 s2, s38, 0x40080
	v_lshl_add_u64 v[226:227], v[228:229], 0, s[10:11]
	s_addc_u32 s3, s39, 0
	s_add_i32 s38, s63, s41
	global_load_lds_dwordx4 v[226:227], off
	v_lshl_add_u64 v[226:227], s[2:3], 0, v[132:133]
	s_mov_b32 m0, s38
	s_nop 0
	global_load_lds_dwordx4 v[226:227], off
	v_lshl_add_u64 v[226:227], s[2:3], 0, v[136:137]
	s_add_i32 m0, s38, 0x2000
	s_nop 0
	global_load_lds_dwordx4 v[226:227], off
	v_lshl_add_u64 v[226:227], v[230:231], 0, s[10:11]
	s_mov_b32 m0, s47
	s_nop 0
	global_load_lds_dwordx4 v[226:227], off
	v_lshl_add_u64 v[226:227], v[232:233], 0, s[10:11]
	s_mov_b32 m0, s48
	s_nop 0
	global_load_lds_dwordx4 v[226:227], off
	s_waitcnt vmcnt(8)
	s_waitcnt lgkmcnt(0)
	s_barrier
	s_setprio 1
	s_waitcnt lgkmcnt(0)
	v_mfma_f32_16x16x32_bf16 v[62:65], v[144:147], v[194:197], v[62:65]
	v_mfma_f32_16x16x32_bf16 v[58:61], v[168:171], v[194:197], v[58:61]
	v_mfma_f32_16x16x32_bf16 v[42:45], v[168:171], v[202:205], v[42:45]
	v_mfma_f32_16x16x32_bf16 v[50:53], v[144:147], v[202:205], v[50:53]
	v_mfma_f32_16x16x32_bf16 v[34:37], v[144:147], v[210:213], v[34:37]
	v_mfma_f32_16x16x32_bf16 v[26:29], v[168:171], v[210:213], v[26:29]
	v_mfma_f32_16x16x32_bf16 v[10:13], v[168:171], v[218:221], v[10:13]
	v_mfma_f32_16x16x32_bf16 v[18:21], v[144:147], v[218:221], v[18:21]
	v_mfma_f32_16x16x32_bf16 v[62:65], v[164:167], v[198:201], v[62:65]
	v_mfma_f32_16x16x32_bf16 v[58:61], v[172:175], v[198:201], v[58:61]
	v_mfma_f32_16x16x32_bf16 v[42:45], v[172:175], v[206:209], v[42:45]
	v_mfma_f32_16x16x32_bf16 v[50:53], v[164:167], v[206:209], v[50:53]
	v_mfma_f32_16x16x32_bf16 v[34:37], v[164:167], v[214:217], v[34:37]
	v_mfma_f32_16x16x32_bf16 v[26:29], v[172:175], v[214:217], v[26:29]
	v_mfma_f32_16x16x32_bf16 v[10:13], v[172:175], v[222:225], v[10:13]
	v_mfma_f32_16x16x32_bf16 v[18:21], v[164:167], v[222:225], v[18:21]
	s_setprio 0
	s_setprio 1
	v_mfma_f32_16x16x32_bf16 v[54:57], v[178:181], v[194:197], v[54:57]
	v_mfma_f32_16x16x32_bf16 v[46:49], v[186:189], v[194:197], v[46:49]
	v_mfma_f32_16x16x32_bf16 v[30:33], v[186:189], v[202:205], v[30:33]
	v_mfma_f32_16x16x32_bf16 v[38:41], v[178:181], v[202:205], v[38:41]
	v_mfma_f32_16x16x32_bf16 v[22:25], v[178:181], v[210:213], v[22:25]
	v_mfma_f32_16x16x32_bf16 v[14:17], v[186:189], v[210:213], v[14:17]
	v_mfma_f32_16x16x32_bf16 v[2:5], v[186:189], v[218:221], v[2:5]
	v_mfma_f32_16x16x32_bf16 v[6:9], v[178:181], v[218:221], v[6:9]
	v_mfma_f32_16x16x32_bf16 v[54:57], v[182:185], v[198:201], v[54:57]
	v_mfma_f32_16x16x32_bf16 v[46:49], v[190:193], v[198:201], v[46:49]
	v_mfma_f32_16x16x32_bf16 v[30:33], v[190:193], v[206:209], v[30:33]
	v_mfma_f32_16x16x32_bf16 v[38:41], v[182:185], v[206:209], v[38:41]
	v_mfma_f32_16x16x32_bf16 v[22:25], v[182:185], v[214:217], v[22:25]
	v_mfma_f32_16x16x32_bf16 v[14:17], v[190:193], v[214:217], v[14:17]
	v_mfma_f32_16x16x32_bf16 v[2:5], v[190:193], v[222:225], v[2:5]
	v_mfma_f32_16x16x32_bf16 v[6:9], v[182:185], v[222:225], v[6:9]
	s_setprio 0
	s_barrier
	s_add_i32 s61, s61, 2
	s_add_u32 s36, s36, 0x100
	s_addc_u32 s37, s37, 0
	s_add_u32 s59, s59, 0x100
	s_addc_u32 s60, s60, 0
	s_cmp_gt_u32 s61, 13
	s_cbranch_scc0 .LBB0_1179
	s_branch .Lpk1179_exit
.LBB0_1179:
	ds_read_b128 v[144:147], v158
	ds_read_b128 v[164:167], v158 offset:1024
	ds_read_b128 v[168:171], v158 offset:2048
	ds_read_b128 v[172:175], v158 offset:3072
	ds_read_b128 v[178:181], v159
	ds_read_b128 v[182:185], v159 offset:1024
	ds_read_b128 v[186:189], v159 offset:2048
	ds_read_b128 v[190:193], v159 offset:3072
	s_add_u32 s2, s36, 0xfffc0080
	s_addc_u32 s3, s37, -1
	s_cmp_eq_u32 s61, 12
	s_cselect_b32 s3, s19, s3
	s_cselect_b32 s2, s21, s2
	s_cselect_b32 s39, s57, s60
	s_cselect_b32 s38, s58, s59
	v_lshl_add_u64 v[226:227], s[36:37], 0, v[138:139]
	s_add_i32 m0, s42, 0xc000
	ds_read_b128 v[194:197], v160
	ds_read_b128 v[198:201], v160 offset:1024
	ds_read_b128 v[202:205], v160 offset:2048
	ds_read_b128 v[206:209], v160 offset:3072
	ds_read_b128 v[210:213], v160 offset:4096
	ds_read_b128 v[214:217], v160 offset:5120
	ds_read_b128 v[218:221], v160 offset:6144
	ds_read_b128 v[222:225], v160 offset:7168
	global_load_lds_dwordx4 v[226:227], off
	v_lshl_add_u64 v[226:227], s[36:37], 0, v[140:141]
	s_add_i32 m0, s42, 0xe000
	s_nop 0
	global_load_lds_dwordx4 v[226:227], off
	s_waitcnt vmcnt(8)
	s_waitcnt lgkmcnt(0)
	s_barrier
	s_setprio 1
	s_waitcnt lgkmcnt(0)
	v_mfma_f32_16x16x32_bf16 v[126:129], v[144:147], v[194:197], v[126:129]
	v_mfma_f32_16x16x32_bf16 v[122:125], v[168:171], v[194:197], v[122:125]
	v_mfma_f32_16x16x32_bf16 v[106:109], v[168:171], v[202:205], v[106:109]
	v_mfma_f32_16x16x32_bf16 v[114:117], v[144:147], v[202:205], v[114:117]
	v_mfma_f32_16x16x32_bf16 v[98:101], v[144:147], v[210:213], v[98:101]
	v_mfma_f32_16x16x32_bf16 v[90:93], v[168:171], v[210:213], v[90:93]
	v_mfma_f32_16x16x32_bf16 v[74:77], v[168:171], v[218:221], v[74:77]
	v_mfma_f32_16x16x32_bf16 v[82:85], v[144:147], v[218:221], v[82:85]
	v_mfma_f32_16x16x32_bf16 v[126:129], v[164:167], v[198:201], v[126:129]
	v_mfma_f32_16x16x32_bf16 v[122:125], v[172:175], v[198:201], v[122:125]
	v_mfma_f32_16x16x32_bf16 v[106:109], v[172:175], v[206:209], v[106:109]
	v_mfma_f32_16x16x32_bf16 v[114:117], v[164:167], v[206:209], v[114:117]
	v_mfma_f32_16x16x32_bf16 v[98:101], v[164:167], v[214:217], v[98:101]
	v_mfma_f32_16x16x32_bf16 v[90:93], v[172:175], v[214:217], v[90:93]
	v_mfma_f32_16x16x32_bf16 v[74:77], v[172:175], v[222:225], v[74:77]
	v_mfma_f32_16x16x32_bf16 v[82:85], v[164:167], v[222:225], v[82:85]
	s_setprio 0
	s_setprio 1
	v_mfma_f32_16x16x32_bf16 v[118:121], v[178:181], v[194:197], v[118:121]
	v_mfma_f32_16x16x32_bf16 v[110:113], v[186:189], v[194:197], v[110:113]
	v_mfma_f32_16x16x32_bf16 v[94:97], v[186:189], v[202:205], v[94:97]
	v_mfma_f32_16x16x32_bf16 v[102:105], v[178:181], v[202:205], v[102:105]
	v_mfma_f32_16x16x32_bf16 v[86:89], v[178:181], v[210:213], v[86:89]
	v_mfma_f32_16x16x32_bf16 v[78:81], v[186:189], v[210:213], v[78:81]
	v_mfma_f32_16x16x32_bf16 v[66:69], v[186:189], v[218:221], v[66:69]
	v_mfma_f32_16x16x32_bf16 v[70:73], v[178:181], v[218:221], v[70:73]
	v_mfma_f32_16x16x32_bf16 v[118:121], v[182:185], v[198:201], v[118:121]
	v_mfma_f32_16x16x32_bf16 v[110:113], v[190:193], v[198:201], v[110:113]
	v_mfma_f32_16x16x32_bf16 v[94:97], v[190:193], v[206:209], v[94:97]
	v_mfma_f32_16x16x32_bf16 v[102:105], v[182:185], v[206:209], v[102:105]
	v_mfma_f32_16x16x32_bf16 v[86:89], v[182:185], v[214:217], v[86:89]
	v_mfma_f32_16x16x32_bf16 v[78:81], v[190:193], v[214:217], v[78:81]
	v_mfma_f32_16x16x32_bf16 v[66:69], v[190:193], v[222:225], v[66:69]
	v_mfma_f32_16x16x32_bf16 v[70:73], v[182:185], v[222:225], v[70:73]
	s_setprio 0
	s_barrier
	s_add_i32 s62, s51, s41
	v_lshl_add_u64 v[226:227], s[38:39], 0, v[132:133]
	s_mov_b32 m0, s62
	ds_read_b128 v[194:197], v160 offset:16384
	ds_read_b128 v[198:201], v160 offset:17408
	ds_read_b128 v[202:205], v160 offset:18432
	ds_read_b128 v[206:209], v160 offset:19456
	ds_read_b128 v[210:213], v160 offset:20480
	ds_read_b128 v[214:217], v160 offset:21504
	ds_read_b128 v[218:221], v160 offset:22528
	ds_read_b128 v[222:225], v160 offset:23552
	global_load_lds_dwordx4 v[226:227], off
	s_add_i32 m0, s62, 0x2000
	s_add_u32 s62, s38, 0x40000
	v_lshl_add_u64 v[228:229], s[38:39], 0, v[136:137]
	s_addc_u32 s63, s39, 0
	s_add_i32 s64, s52, s41
	global_load_lds_dwordx4 v[228:229], off
	v_lshl_add_u64 v[230:231], s[62:63], 0, v[132:133]
	s_mov_b32 m0, s64
	v_lshl_add_u64 v[232:233], s[2:3], 0, v[134:135]
	global_load_lds_dwordx4 v[230:231], off
	v_lshl_add_u64 v[230:231], s[62:63], 0, v[136:137]
	s_add_i32 m0, s64, 0x2000
	s_nop 0
	global_load_lds_dwordx4 v[230:231], off
	v_lshl_add_u64 v[230:231], s[2:3], 0, v[130:131]
	s_mov_b32 m0, s42
	s_nop 0
	global_load_lds_dwordx4 v[230:231], off
	s_mov_b32 m0, s43
	s_nop 0
	global_load_lds_dwordx4 v[232:233], off
	s_waitcnt vmcnt(8)
	s_waitcnt lgkmcnt(0)
	s_barrier
	s_setprio 1
	s_waitcnt lgkmcnt(0)
	v_mfma_f32_16x16x32_bf16 v[62:65], v[144:147], v[194:197], v[62:65]
	v_mfma_f32_16x16x32_bf16 v[58:61], v[168:171], v[194:197], v[58:61]
	v_mfma_f32_16x16x32_bf16 v[42:45], v[168:171], v[202:205], v[42:45]
	v_mfma_f32_16x16x32_bf16 v[50:53], v[144:147], v[202:205], v[50:53]
	v_mfma_f32_16x16x32_bf16 v[34:37], v[144:147], v[210:213], v[34:37]
	v_mfma_f32_16x16x32_bf16 v[26:29], v[168:171], v[210:213], v[26:29]
	v_mfma_f32_16x16x32_bf16 v[10:13], v[168:171], v[218:221], v[10:13]
	v_mfma_f32_16x16x32_bf16 v[18:21], v[144:147], v[218:221], v[18:21]
	v_mfma_f32_16x16x32_bf16 v[62:65], v[164:167], v[198:201], v[62:65]
	v_mfma_f32_16x16x32_bf16 v[58:61], v[172:175], v[198:201], v[58:61]
	v_mfma_f32_16x16x32_bf16 v[42:45], v[172:175], v[206:209], v[42:45]
	v_mfma_f32_16x16x32_bf16 v[50:53], v[164:167], v[206:209], v[50:53]
	v_mfma_f32_16x16x32_bf16 v[34:37], v[164:167], v[214:217], v[34:37]
	v_mfma_f32_16x16x32_bf16 v[26:29], v[172:175], v[214:217], v[26:29]
	v_mfma_f32_16x16x32_bf16 v[10:13], v[172:175], v[222:225], v[10:13]
	v_mfma_f32_16x16x32_bf16 v[18:21], v[164:167], v[222:225], v[18:21]
	s_setprio 0
	s_setprio 1
	v_mfma_f32_16x16x32_bf16 v[54:57], v[178:181], v[194:197], v[54:57]
	v_mfma_f32_16x16x32_bf16 v[46:49], v[186:189], v[194:197], v[46:49]
	v_mfma_f32_16x16x32_bf16 v[30:33], v[186:189], v[202:205], v[30:33]
	v_mfma_f32_16x16x32_bf16 v[38:41], v[178:181], v[202:205], v[38:41]
	v_mfma_f32_16x16x32_bf16 v[22:25], v[178:181], v[210:213], v[22:25]
	v_mfma_f32_16x16x32_bf16 v[14:17], v[186:189], v[210:213], v[14:17]
	v_mfma_f32_16x16x32_bf16 v[2:5], v[186:189], v[218:221], v[2:5]
	v_mfma_f32_16x16x32_bf16 v[6:9], v[178:181], v[218:221], v[6:9]
	v_mfma_f32_16x16x32_bf16 v[54:57], v[182:185], v[198:201], v[54:57]
	v_mfma_f32_16x16x32_bf16 v[46:49], v[190:193], v[198:201], v[46:49]
	v_mfma_f32_16x16x32_bf16 v[30:33], v[190:193], v[206:209], v[30:33]
	v_mfma_f32_16x16x32_bf16 v[38:41], v[182:185], v[206:209], v[38:41]
	v_mfma_f32_16x16x32_bf16 v[22:25], v[182:185], v[214:217], v[22:25]
	v_mfma_f32_16x16x32_bf16 v[14:17], v[190:193], v[214:217], v[14:17]
	v_mfma_f32_16x16x32_bf16 v[2:5], v[190:193], v[222:225], v[2:5]
	v_mfma_f32_16x16x32_bf16 v[6:9], v[182:185], v[222:225], v[6:9]
	s_setprio 0
	s_barrier
	s_add_i32 s62, 0, 0x18000
	v_add_u32_e32 v163, s62, v148
	s_add_i32 s63, 0, 0x1c000
	ds_read_b128 v[144:147], v163
	ds_read_b128 v[164:167], v163 offset:1024
	ds_read_b128 v[168:171], v163 offset:2048
	ds_read_b128 v[172:175], v163 offset:3072
	v_add_u32_e32 v163, s63, v148
	ds_read_b128 v[178:181], v163
	ds_read_b128 v[182:185], v163 offset:1024
	ds_read_b128 v[186:189], v163 offset:2048
	ds_read_b128 v[190:193], v163 offset:3072
	s_add_u32 s2, s2, 0x40000
	s_addc_u32 s3, s3, 0
	s_mov_b32 m0, s44
	v_lshl_add_u64 v[234:235], s[2:3], 0, v[130:131]
	ds_read_b128 v[194:197], v160 offset:32768
	ds_read_b128 v[198:201], v160 offset:33792
	ds_read_b128 v[202:205], v160 offset:34816
	ds_read_b128 v[206:209], v160 offset:35840
	ds_read_b128 v[210:213], v160 offset:36864
	ds_read_b128 v[214:217], v160 offset:37888
	ds_read_b128 v[218:221], v160 offset:38912
	ds_read_b128 v[222:225], v160 offset:39936
	global_load_lds_dwordx4 v[234:235], off
	v_lshl_add_u64 v[234:235], s[2:3], 0, v[134:135]
	s_mov_b32 m0, s45
	s_nop 0
	global_load_lds_dwordx4 v[234:235], off
	s_waitcnt vmcnt(8)
	s_waitcnt lgkmcnt(0)
	s_barrier
	s_setprio 1
	s_waitcnt lgkmcnt(0)
	v_mfma_f32_16x16x32_bf16 v[126:129], v[144:147], v[194:197], v[126:129]
	v_mfma_f32_16x16x32_bf16 v[122:125], v[168:171], v[194:197], v[122:125]
	v_mfma_f32_16x16x32_bf16 v[106:109], v[168:171], v[202:205], v[106:109]
	v_mfma_f32_16x16x32_bf16 v[114:117], v[144:147], v[202:205], v[114:117]
	v_mfma_f32_16x16x32_bf16 v[98:101], v[144:147], v[210:213], v[98:101]
	v_mfma_f32_16x16x32_bf16 v[90:93], v[168:171], v[210:213], v[90:93]
	v_mfma_f32_16x16x32_bf16 v[74:77], v[168:171], v[218:221], v[74:77]
	v_mfma_f32_16x16x32_bf16 v[82:85], v[144:147], v[218:221], v[82:85]
	v_mfma_f32_16x16x32_bf16 v[126:129], v[164:167], v[198:201], v[126:129]
	v_mfma_f32_16x16x32_bf16 v[122:125], v[172:175], v[198:201], v[122:125]
	v_mfma_f32_16x16x32_bf16 v[106:109], v[172:175], v[206:209], v[106:109]
	v_mfma_f32_16x16x32_bf16 v[114:117], v[164:167], v[206:209], v[114:117]
	v_mfma_f32_16x16x32_bf16 v[98:101], v[164:167], v[214:217], v[98:101]
	v_mfma_f32_16x16x32_bf16 v[90:93], v[172:175], v[214:217], v[90:93]
	v_mfma_f32_16x16x32_bf16 v[74:77], v[172:175], v[222:225], v[74:77]
	v_mfma_f32_16x16x32_bf16 v[82:85], v[164:167], v[222:225], v[82:85]
	s_setprio 0
	s_setprio 1
	v_mfma_f32_16x16x32_bf16 v[118:121], v[178:181], v[194:197], v[118:121]
	v_mfma_f32_16x16x32_bf16 v[110:113], v[186:189], v[194:197], v[110:113]
	v_mfma_f32_16x16x32_bf16 v[94:97], v[186:189], v[202:205], v[94:97]
	v_mfma_f32_16x16x32_bf16 v[102:105], v[178:181], v[202:205], v[102:105]
	v_mfma_f32_16x16x32_bf16 v[86:89], v[178:181], v[210:213], v[86:89]
	v_mfma_f32_16x16x32_bf16 v[78:81], v[186:189], v[210:213], v[78:81]
	v_mfma_f32_16x16x32_bf16 v[66:69], v[186:189], v[218:221], v[66:69]
	v_mfma_f32_16x16x32_bf16 v[70:73], v[178:181], v[218:221], v[70:73]
	v_mfma_f32_16x16x32_bf16 v[118:121], v[182:185], v[198:201], v[118:121]
	v_mfma_f32_16x16x32_bf16 v[110:113], v[190:193], v[198:201], v[110:113]
	v_mfma_f32_16x16x32_bf16 v[94:97], v[190:193], v[206:209], v[94:97]
	v_mfma_f32_16x16x32_bf16 v[102:105], v[182:185], v[206:209], v[102:105]
	v_mfma_f32_16x16x32_bf16 v[86:89], v[182:185], v[214:217], v[86:89]
	v_mfma_f32_16x16x32_bf16 v[78:81], v[190:193], v[214:217], v[78:81]
	v_mfma_f32_16x16x32_bf16 v[66:69], v[190:193], v[222:225], v[66:69]
	v_mfma_f32_16x16x32_bf16 v[70:73], v[182:185], v[222:225], v[70:73]
	s_setprio 0
	s_barrier
	s_add_i32 s2, s62, s41
	v_lshl_add_u64 v[226:227], v[226:227], 0, s[10:11]
	s_mov_b32 m0, s2
	ds_read_b128 v[194:197], v160 offset:49152
	ds_read_b128 v[198:201], v160 offset:50176
	ds_read_b128 v[202:205], v160 offset:51200
	ds_read_b128 v[206:209], v160 offset:52224
	ds_read_b128 v[210:213], v160 offset:53248
	ds_read_b128 v[214:217], v160 offset:54272
	ds_read_b128 v[218:221], v160 offset:55296
	ds_read_b128 v[222:225], v160 offset:56320
	global_load_lds_dwordx4 v[226:227], off
	s_add_i32 m0, s2, 0x2000
	s_add_u32 s2, s38, 0x40080
	v_lshl_add_u64 v[226:227], v[228:229], 0, s[10:11]
	s_addc_u32 s3, s39, 0
	s_add_i32 s38, s63, s41
	global_load_lds_dwordx4 v[226:227], off
	v_lshl_add_u64 v[226:227], s[2:3], 0, v[132:133]
	s_mov_b32 m0, s38
	s_nop 0
	global_load_lds_dwordx4 v[226:227], off
	v_lshl_add_u64 v[226:227], s[2:3], 0, v[136:137]
	s_add_i32 m0, s38, 0x2000
	s_nop 0
	global_load_lds_dwordx4 v[226:227], off
	v_lshl_add_u64 v[226:227], v[230:231], 0, s[10:11]
	s_mov_b32 m0, s47
	s_nop 0
	global_load_lds_dwordx4 v[226:227], off
	v_lshl_add_u64 v[226:227], v[232:233], 0, s[10:11]
	s_mov_b32 m0, s48
	s_nop 0
	global_load_lds_dwordx4 v[226:227], off
	s_waitcnt vmcnt(8)
	s_waitcnt lgkmcnt(0)
	s_barrier
	s_setprio 1
	s_waitcnt lgkmcnt(0)
	v_mfma_f32_16x16x32_bf16 v[62:65], v[144:147], v[194:197], v[62:65]
	v_mfma_f32_16x16x32_bf16 v[58:61], v[168:171], v[194:197], v[58:61]
	v_mfma_f32_16x16x32_bf16 v[42:45], v[168:171], v[202:205], v[42:45]
	v_mfma_f32_16x16x32_bf16 v[50:53], v[144:147], v[202:205], v[50:53]
	v_mfma_f32_16x16x32_bf16 v[34:37], v[144:147], v[210:213], v[34:37]
	v_mfma_f32_16x16x32_bf16 v[26:29], v[168:171], v[210:213], v[26:29]
	v_mfma_f32_16x16x32_bf16 v[10:13], v[168:171], v[218:221], v[10:13]
	v_mfma_f32_16x16x32_bf16 v[18:21], v[144:147], v[218:221], v[18:21]
	v_mfma_f32_16x16x32_bf16 v[62:65], v[164:167], v[198:201], v[62:65]
	v_mfma_f32_16x16x32_bf16 v[58:61], v[172:175], v[198:201], v[58:61]
	v_mfma_f32_16x16x32_bf16 v[42:45], v[172:175], v[206:209], v[42:45]
	v_mfma_f32_16x16x32_bf16 v[50:53], v[164:167], v[206:209], v[50:53]
	v_mfma_f32_16x16x32_bf16 v[34:37], v[164:167], v[214:217], v[34:37]
	v_mfma_f32_16x16x32_bf16 v[26:29], v[172:175], v[214:217], v[26:29]
	v_mfma_f32_16x16x32_bf16 v[10:13], v[172:175], v[222:225], v[10:13]
	v_mfma_f32_16x16x32_bf16 v[18:21], v[164:167], v[222:225], v[18:21]
	s_setprio 0
	s_setprio 1
	v_mfma_f32_16x16x32_bf16 v[54:57], v[178:181], v[194:197], v[54:57]
	v_mfma_f32_16x16x32_bf16 v[46:49], v[186:189], v[194:197], v[46:49]
	v_mfma_f32_16x16x32_bf16 v[30:33], v[186:189], v[202:205], v[30:33]
	v_mfma_f32_16x16x32_bf16 v[38:41], v[178:181], v[202:205], v[38:41]
	v_mfma_f32_16x16x32_bf16 v[22:25], v[178:181], v[210:213], v[22:25]
	v_mfma_f32_16x16x32_bf16 v[14:17], v[186:189], v[210:213], v[14:17]
	v_mfma_f32_16x16x32_bf16 v[2:5], v[186:189], v[218:221], v[2:5]
	v_mfma_f32_16x16x32_bf16 v[6:9], v[178:181], v[218:221], v[6:9]
	v_mfma_f32_16x16x32_bf16 v[54:57], v[182:185], v[198:201], v[54:57]
	v_mfma_f32_16x16x32_bf16 v[46:49], v[190:193], v[198:201], v[46:49]
	v_mfma_f32_16x16x32_bf16 v[30:33], v[190:193], v[206:209], v[30:33]
	v_mfma_f32_16x16x32_bf16 v[38:41], v[182:185], v[206:209], v[38:41]
	v_mfma_f32_16x16x32_bf16 v[22:25], v[182:185], v[214:217], v[22:25]
	v_mfma_f32_16x16x32_bf16 v[14:17], v[190:193], v[214:217], v[14:17]
	v_mfma_f32_16x16x32_bf16 v[2:5], v[190:193], v[222:225], v[2:5]
	v_mfma_f32_16x16x32_bf16 v[6:9], v[182:185], v[222:225], v[6:9]
	s_setprio 0
	s_barrier
	s_add_i32 s61, s61, 2
	s_add_u32 s36, s36, 0x100
	s_addc_u32 s37, s37, 0
	s_add_u32 s59, s59, 0x100
	s_addc_u32 s60, s60, 0
	s_cmp_gt_u32 s61, 13
	s_cbranch_scc0 .LBB0_1179

.Lpk1239_peel:
	ds_read_b128 v[152:155], v148
	ds_read_b128 v[156:159], v148 offset:1024
	ds_read_b128 v[160:163], v148 offset:2048
	ds_read_b128 v[164:167], v148 offset:3072
	ds_read_b128 v[168:171], v149
	ds_read_b128 v[172:175], v149 offset:1024
	ds_read_b128 v[178:181], v149 offset:2048
	ds_read_b128 v[182:185], v149 offset:3072
	s_add_u32 s2, s36, 0xfffc0080
	s_addc_u32 s3, s37, -1
	s_cmp_eq_u32 s62, 12
	s_cselect_b32 s3, s19, s3
	s_cselect_b32 s2, s21, s2
	s_cselect_b32 s39, s58, s61
	s_cselect_b32 s38, s59, s60
	v_lshl_add_u64 v[144:145], s[36:37], 0, v[138:139]
	s_add_i32 m0, s44, 0xc000
	ds_read_b128 v[186:189], v150
	ds_read_b128 v[190:193], v150 offset:1024
	ds_read_b128 v[194:197], v150 offset:2048
	ds_read_b128 v[198:201], v150 offset:3072
	ds_read_b128 v[202:205], v150 offset:4096
	ds_read_b128 v[206:209], v150 offset:5120
	ds_read_b128 v[210:213], v150 offset:6144
	ds_read_b128 v[214:217], v150 offset:7168
	global_load_lds_dwordx4 v[144:145], off
	v_lshl_add_u64 v[144:145], s[36:37], 0, v[140:141]
	s_add_i32 m0, s44, 0xe000
	s_nop 0
	global_load_lds_dwordx4 v[144:145], off
	s_waitcnt vmcnt(8)
	s_waitcnt lgkmcnt(0)
	s_barrier
	s_setprio 1
	s_waitcnt lgkmcnt(0)
	v_mfma_f32_16x16x32_bf16 v[126:129], v[152:155], v[186:189], 0
	v_mfma_f32_16x16x32_bf16 v[122:125], v[160:163], v[186:189], 0
	v_mfma_f32_16x16x32_bf16 v[106:109], v[160:163], v[194:197], 0
	v_mfma_f32_16x16x32_bf16 v[114:117], v[152:155], v[194:197], 0
	v_mfma_f32_16x16x32_bf16 v[98:101], v[152:155], v[202:205], 0
	v_mfma_f32_16x16x32_bf16 v[90:93], v[160:163], v[202:205], 0
	v_mfma_f32_16x16x32_bf16 v[74:77], v[160:163], v[210:213], 0
	v_mfma_f32_16x16x32_bf16 v[82:85], v[152:155], v[210:213], 0
	v_mfma_f32_16x16x32_bf16 v[126:129], v[156:159], v[190:193], v[126:129]
	v_mfma_f32_16x16x32_bf16 v[122:125], v[164:167], v[190:193], v[122:125]
	v_mfma_f32_16x16x32_bf16 v[106:109], v[164:167], v[198:201], v[106:109]
	v_mfma_f32_16x16x32_bf16 v[114:117], v[156:159], v[198:201], v[114:117]
	v_mfma_f32_16x16x32_bf16 v[98:101], v[156:159], v[206:209], v[98:101]
	v_mfma_f32_16x16x32_bf16 v[90:93], v[164:167], v[206:209], v[90:93]
	v_mfma_f32_16x16x32_bf16 v[74:77], v[164:167], v[214:217], v[74:77]
	v_mfma_f32_16x16x32_bf16 v[82:85], v[156:159], v[214:217], v[82:85]
	s_setprio 0
	s_setprio 1
	v_mfma_f32_16x16x32_bf16 v[118:121], v[168:171], v[186:189], 0
	v_mfma_f32_16x16x32_bf16 v[110:113], v[178:181], v[186:189], 0
	v_mfma_f32_16x16x32_bf16 v[94:97], v[178:181], v[194:197], 0
	v_mfma_f32_16x16x32_bf16 v[102:105], v[168:171], v[194:197], 0
	v_mfma_f32_16x16x32_bf16 v[86:89], v[168:171], v[202:205], 0
	v_mfma_f32_16x16x32_bf16 v[78:81], v[178:181], v[202:205], 0
	v_mfma_f32_16x16x32_bf16 v[66:69], v[178:181], v[210:213], 0
	v_mfma_f32_16x16x32_bf16 v[70:73], v[168:171], v[210:213], 0
	v_mfma_f32_16x16x32_bf16 v[118:121], v[172:175], v[190:193], v[118:121]
	v_mfma_f32_16x16x32_bf16 v[110:113], v[182:185], v[190:193], v[110:113]
	v_mfma_f32_16x16x32_bf16 v[94:97], v[182:185], v[198:201], v[94:97]
	v_mfma_f32_16x16x32_bf16 v[102:105], v[172:175], v[198:201], v[102:105]
	v_mfma_f32_16x16x32_bf16 v[86:89], v[172:175], v[206:209], v[86:89]
	v_mfma_f32_16x16x32_bf16 v[78:81], v[182:185], v[206:209], v[78:81]
	v_mfma_f32_16x16x32_bf16 v[66:69], v[182:185], v[214:217], v[66:69]
	v_mfma_f32_16x16x32_bf16 v[70:73], v[172:175], v[214:217], v[70:73]
	s_setprio 0
	s_barrier
	s_add_i32 s63, s51, s43
	v_lshl_add_u64 v[144:145], s[38:39], 0, v[132:133]
	s_mov_b32 m0, s63
	ds_read_b128 v[186:189], v150 offset:16384
	ds_read_b128 v[190:193], v150 offset:17408
	ds_read_b128 v[194:197], v150 offset:18432
	ds_read_b128 v[198:201], v150 offset:19456
	ds_read_b128 v[202:205], v150 offset:20480
	ds_read_b128 v[206:209], v150 offset:21504
	ds_read_b128 v[210:213], v150 offset:22528
	ds_read_b128 v[214:217], v150 offset:23552
	global_load_lds_dwordx4 v[144:145], off
	s_add_i32 m0, s63, 0x2000
	s_add_u32 s64, s38, 0x40000
	v_lshl_add_u64 v[218:219], s[38:39], 0, v[136:137]
	s_addc_u32 s65, s39, 0
	s_add_i32 s63, s52, s43
	global_load_lds_dwordx4 v[218:219], off
	v_lshl_add_u64 v[220:221], s[64:65], 0, v[132:133]
	s_mov_b32 m0, s63
	v_lshl_add_u64 v[222:223], s[2:3], 0, v[134:135]
	global_load_lds_dwordx4 v[220:221], off
	v_lshl_add_u64 v[220:221], s[64:65], 0, v[136:137]
	s_add_i32 m0, s63, 0x2000
	s_nop 0
	global_load_lds_dwordx4 v[220:221], off
	v_lshl_add_u64 v[220:221], s[2:3], 0, v[130:131]
	s_mov_b32 m0, s44
	s_nop 0
	global_load_lds_dwordx4 v[220:221], off
	s_mov_b32 m0, s35
	s_nop 0
	global_load_lds_dwordx4 v[222:223], off
	s_waitcnt vmcnt(8)
	s_waitcnt lgkmcnt(0)
	s_barrier
	s_setprio 1
	s_waitcnt lgkmcnt(0)
	v_mfma_f32_16x16x32_bf16 v[62:65], v[152:155], v[186:189], 0
	v_mfma_f32_16x16x32_bf16 v[58:61], v[160:163], v[186:189], 0
	v_mfma_f32_16x16x32_bf16 v[42:45], v[160:163], v[194:197], 0
	v_mfma_f32_16x16x32_bf16 v[50:53], v[152:155], v[194:197], 0
	v_mfma_f32_16x16x32_bf16 v[34:37], v[152:155], v[202:205], 0
	v_mfma_f32_16x16x32_bf16 v[26:29], v[160:163], v[202:205], 0
	v_mfma_f32_16x16x32_bf16 v[10:13], v[160:163], v[210:213], 0
	v_mfma_f32_16x16x32_bf16 v[18:21], v[152:155], v[210:213], 0
	v_mfma_f32_16x16x32_bf16 v[62:65], v[156:159], v[190:193], v[62:65]
	v_mfma_f32_16x16x32_bf16 v[58:61], v[164:167], v[190:193], v[58:61]
	v_mfma_f32_16x16x32_bf16 v[42:45], v[164:167], v[198:201], v[42:45]
	v_mfma_f32_16x16x32_bf16 v[50:53], v[156:159], v[198:201], v[50:53]
	v_mfma_f32_16x16x32_bf16 v[34:37], v[156:159], v[206:209], v[34:37]
	v_mfma_f32_16x16x32_bf16 v[26:29], v[164:167], v[206:209], v[26:29]
	v_mfma_f32_16x16x32_bf16 v[10:13], v[164:167], v[214:217], v[10:13]
	v_mfma_f32_16x16x32_bf16 v[18:21], v[156:159], v[214:217], v[18:21]
	s_setprio 0
	s_setprio 1
	v_mfma_f32_16x16x32_bf16 v[54:57], v[168:171], v[186:189], 0
	v_mfma_f32_16x16x32_bf16 v[46:49], v[178:181], v[186:189], 0
	v_mfma_f32_16x16x32_bf16 v[30:33], v[178:181], v[194:197], 0
	v_mfma_f32_16x16x32_bf16 v[38:41], v[168:171], v[194:197], 0
	v_mfma_f32_16x16x32_bf16 v[22:25], v[168:171], v[202:205], 0
	v_mfma_f32_16x16x32_bf16 v[14:17], v[178:181], v[202:205], 0
	v_mfma_f32_16x16x32_bf16 v[2:5], v[178:181], v[210:213], 0
	v_mfma_f32_16x16x32_bf16 v[6:9], v[168:171], v[210:213], 0
	v_mfma_f32_16x16x32_bf16 v[54:57], v[172:175], v[190:193], v[54:57]
	v_mfma_f32_16x16x32_bf16 v[46:49], v[182:185], v[190:193], v[46:49]
	v_mfma_f32_16x16x32_bf16 v[30:33], v[182:185], v[198:201], v[30:33]
	v_mfma_f32_16x16x32_bf16 v[38:41], v[172:175], v[198:201], v[38:41]
	v_mfma_f32_16x16x32_bf16 v[22:25], v[172:175], v[206:209], v[22:25]
	v_mfma_f32_16x16x32_bf16 v[14:17], v[182:185], v[206:209], v[14:17]
	v_mfma_f32_16x16x32_bf16 v[2:5], v[182:185], v[214:217], v[2:5]
	v_mfma_f32_16x16x32_bf16 v[6:9], v[172:175], v[214:217], v[6:9]
	s_setprio 0
	s_barrier
	s_add_i32 s63, 0, 0x18000
	v_add_u32_e32 v151, s63, v146
	s_add_i32 s64, 0, 0x1c000
	ds_read_b128 v[152:155], v151
	ds_read_b128 v[156:159], v151 offset:1024
	ds_read_b128 v[160:163], v151 offset:2048
	ds_read_b128 v[164:167], v151 offset:3072
	v_add_u32_e32 v151, s64, v146
	ds_read_b128 v[168:171], v151
	ds_read_b128 v[172:175], v151 offset:1024
	ds_read_b128 v[178:181], v151 offset:2048
	ds_read_b128 v[182:185], v151 offset:3072
	s_add_u32 s2, s2, 0x40000
	s_addc_u32 s3, s3, 0
	s_mov_b32 m0, s45
	v_lshl_add_u64 v[224:225], s[2:3], 0, v[130:131]
	ds_read_b128 v[186:189], v150 offset:32768
	ds_read_b128 v[190:193], v150 offset:33792
	ds_read_b128 v[194:197], v150 offset:34816
	ds_read_b128 v[198:201], v150 offset:35840
	ds_read_b128 v[202:205], v150 offset:36864
	ds_read_b128 v[206:209], v150 offset:37888
	ds_read_b128 v[210:213], v150 offset:38912
	ds_read_b128 v[214:217], v150 offset:39936
	global_load_lds_dwordx4 v[224:225], off
	v_lshl_add_u64 v[224:225], s[2:3], 0, v[134:135]
	s_mov_b32 m0, s46
	s_nop 0
	global_load_lds_dwordx4 v[224:225], off
	s_waitcnt vmcnt(8)
	s_waitcnt lgkmcnt(0)
	s_barrier
	s_setprio 1
	s_waitcnt lgkmcnt(0)
	v_mfma_f32_16x16x32_bf16 v[126:129], v[152:155], v[186:189], v[126:129]
	v_mfma_f32_16x16x32_bf16 v[122:125], v[160:163], v[186:189], v[122:125]
	v_mfma_f32_16x16x32_bf16 v[106:109], v[160:163], v[194:197], v[106:109]
	v_mfma_f32_16x16x32_bf16 v[114:117], v[152:155], v[194:197], v[114:117]
	v_mfma_f32_16x16x32_bf16 v[98:101], v[152:155], v[202:205], v[98:101]
	v_mfma_f32_16x16x32_bf16 v[90:93], v[160:163], v[202:205], v[90:93]
	v_mfma_f32_16x16x32_bf16 v[74:77], v[160:163], v[210:213], v[74:77]
	v_mfma_f32_16x16x32_bf16 v[82:85], v[152:155], v[210:213], v[82:85]
	v_mfma_f32_16x16x32_bf16 v[126:129], v[156:159], v[190:193], v[126:129]
	v_mfma_f32_16x16x32_bf16 v[122:125], v[164:167], v[190:193], v[122:125]
	v_mfma_f32_16x16x32_bf16 v[106:109], v[164:167], v[198:201], v[106:109]
	v_mfma_f32_16x16x32_bf16 v[114:117], v[156:159], v[198:201], v[114:117]
	v_mfma_f32_16x16x32_bf16 v[98:101], v[156:159], v[206:209], v[98:101]
	v_mfma_f32_16x16x32_bf16 v[90:93], v[164:167], v[206:209], v[90:93]
	v_mfma_f32_16x16x32_bf16 v[74:77], v[164:167], v[214:217], v[74:77]
	v_mfma_f32_16x16x32_bf16 v[82:85], v[156:159], v[214:217], v[82:85]
	s_setprio 0
	s_setprio 1
	v_mfma_f32_16x16x32_bf16 v[118:121], v[168:171], v[186:189], v[118:121]
	v_mfma_f32_16x16x32_bf16 v[110:113], v[178:181], v[186:189], v[110:113]
	v_mfma_f32_16x16x32_bf16 v[94:97], v[178:181], v[194:197], v[94:97]
	v_mfma_f32_16x16x32_bf16 v[102:105], v[168:171], v[194:197], v[102:105]
	v_mfma_f32_16x16x32_bf16 v[86:89], v[168:171], v[202:205], v[86:89]
	v_mfma_f32_16x16x32_bf16 v[78:81], v[178:181], v[202:205], v[78:81]
	v_mfma_f32_16x16x32_bf16 v[66:69], v[178:181], v[210:213], v[66:69]
	v_mfma_f32_16x16x32_bf16 v[70:73], v[168:171], v[210:213], v[70:73]
	v_mfma_f32_16x16x32_bf16 v[118:121], v[172:175], v[190:193], v[118:121]
	v_mfma_f32_16x16x32_bf16 v[110:113], v[182:185], v[190:193], v[110:113]
	v_mfma_f32_16x16x32_bf16 v[94:97], v[182:185], v[198:201], v[94:97]
	v_mfma_f32_16x16x32_bf16 v[102:105], v[172:175], v[198:201], v[102:105]
	v_mfma_f32_16x16x32_bf16 v[86:89], v[172:175], v[206:209], v[86:89]
	v_mfma_f32_16x16x32_bf16 v[78:81], v[182:185], v[206:209], v[78:81]
	v_mfma_f32_16x16x32_bf16 v[66:69], v[182:185], v[214:217], v[66:69]
	v_mfma_f32_16x16x32_bf16 v[70:73], v[172:175], v[214:217], v[70:73]
	s_setprio 0
	s_barrier
	s_add_i32 s2, s63, s43
	v_lshl_add_u64 v[144:145], v[144:145], 0, s[8:9]
	s_mov_b32 m0, s2
	ds_read_b128 v[186:189], v150 offset:49152
	ds_read_b128 v[190:193], v150 offset:50176
	ds_read_b128 v[194:197], v150 offset:51200
	ds_read_b128 v[198:201], v150 offset:52224
	ds_read_b128 v[202:205], v150 offset:53248
	ds_read_b128 v[206:209], v150 offset:54272
	ds_read_b128 v[210:213], v150 offset:55296
	ds_read_b128 v[214:217], v150 offset:56320
	global_load_lds_dwordx4 v[144:145], off
	s_add_i32 m0, s2, 0x2000
	s_add_u32 s2, s38, 0x40080
	v_lshl_add_u64 v[144:145], v[218:219], 0, s[8:9]
	s_addc_u32 s3, s39, 0
	s_add_i32 s38, s64, s43
	global_load_lds_dwordx4 v[144:145], off
	v_lshl_add_u64 v[144:145], s[2:3], 0, v[132:133]
	s_mov_b32 m0, s38
	s_nop 0
	global_load_lds_dwordx4 v[144:145], off
	v_lshl_add_u64 v[144:145], s[2:3], 0, v[136:137]
	s_add_i32 m0, s38, 0x2000
	s_nop 0
	global_load_lds_dwordx4 v[144:145], off
	v_lshl_add_u64 v[144:145], v[220:221], 0, s[8:9]
	s_mov_b32 m0, s48
	s_nop 0
	global_load_lds_dwordx4 v[144:145], off
	v_lshl_add_u64 v[144:145], v[222:223], 0, s[8:9]
	s_mov_b32 m0, s49
	s_nop 0
	global_load_lds_dwordx4 v[144:145], off
	s_waitcnt vmcnt(8)
	s_waitcnt lgkmcnt(0)
	s_barrier
	s_setprio 1
	s_waitcnt lgkmcnt(0)
	v_mfma_f32_16x16x32_bf16 v[62:65], v[152:155], v[186:189], v[62:65]
	v_mfma_f32_16x16x32_bf16 v[58:61], v[160:163], v[186:189], v[58:61]
	v_mfma_f32_16x16x32_bf16 v[42:45], v[160:163], v[194:197], v[42:45]
	v_mfma_f32_16x16x32_bf16 v[50:53], v[152:155], v[194:197], v[50:53]
	v_mfma_f32_16x16x32_bf16 v[34:37], v[152:155], v[202:205], v[34:37]
	v_mfma_f32_16x16x32_bf16 v[26:29], v[160:163], v[202:205], v[26:29]
	v_mfma_f32_16x16x32_bf16 v[10:13], v[160:163], v[210:213], v[10:13]
	v_mfma_f32_16x16x32_bf16 v[18:21], v[152:155], v[210:213], v[18:21]
	v_mfma_f32_16x16x32_bf16 v[62:65], v[156:159], v[190:193], v[62:65]
	v_mfma_f32_16x16x32_bf16 v[58:61], v[164:167], v[190:193], v[58:61]
	v_mfma_f32_16x16x32_bf16 v[42:45], v[164:167], v[198:201], v[42:45]
	v_mfma_f32_16x16x32_bf16 v[50:53], v[156:159], v[198:201], v[50:53]
	v_mfma_f32_16x16x32_bf16 v[34:37], v[156:159], v[206:209], v[34:37]
	v_mfma_f32_16x16x32_bf16 v[26:29], v[164:167], v[206:209], v[26:29]
	v_mfma_f32_16x16x32_bf16 v[10:13], v[164:167], v[214:217], v[10:13]
	v_mfma_f32_16x16x32_bf16 v[18:21], v[156:159], v[214:217], v[18:21]
	s_setprio 0
	s_setprio 1
	v_mfma_f32_16x16x32_bf16 v[54:57], v[168:171], v[186:189], v[54:57]
	v_mfma_f32_16x16x32_bf16 v[46:49], v[178:181], v[186:189], v[46:49]
	v_mfma_f32_16x16x32_bf16 v[30:33], v[178:181], v[194:197], v[30:33]
	v_mfma_f32_16x16x32_bf16 v[38:41], v[168:171], v[194:197], v[38:41]
	v_mfma_f32_16x16x32_bf16 v[22:25], v[168:171], v[202:205], v[22:25]
	v_mfma_f32_16x16x32_bf16 v[14:17], v[178:181], v[202:205], v[14:17]
	v_mfma_f32_16x16x32_bf16 v[2:5], v[178:181], v[210:213], v[2:5]
	v_mfma_f32_16x16x32_bf16 v[6:9], v[168:171], v[210:213], v[6:9]
	v_mfma_f32_16x16x32_bf16 v[54:57], v[172:175], v[190:193], v[54:57]
	v_mfma_f32_16x16x32_bf16 v[46:49], v[182:185], v[190:193], v[46:49]
	v_mfma_f32_16x16x32_bf16 v[30:33], v[182:185], v[198:201], v[30:33]
	v_mfma_f32_16x16x32_bf16 v[38:41], v[172:175], v[198:201], v[38:41]
	v_mfma_f32_16x16x32_bf16 v[22:25], v[172:175], v[206:209], v[22:25]
	v_mfma_f32_16x16x32_bf16 v[14:17], v[182:185], v[206:209], v[14:17]
	v_mfma_f32_16x16x32_bf16 v[2:5], v[182:185], v[214:217], v[2:5]
	v_mfma_f32_16x16x32_bf16 v[6:9], v[172:175], v[214:217], v[6:9]
	s_setprio 0
	s_barrier
	s_add_i32 s62, s62, 2
	s_add_u32 s36, s36, 0x100
	s_addc_u32 s37, s37, 0
	s_add_u32 s60, s60, 0x100
	s_addc_u32 s61, s61, 0
	s_cmp_gt_u32 s62, 13
	s_cbranch_scc0 .LBB0_1239
	s_branch .Lpk1239_exit
.LBB0_1239:
	ds_read_b128 v[152:155], v148
	ds_read_b128 v[156:159], v148 offset:1024
	ds_read_b128 v[160:163], v148 offset:2048
	ds_read_b128 v[164:167], v148 offset:3072
	ds_read_b128 v[168:171], v149
	ds_read_b128 v[172:175], v149 offset:1024
	ds_read_b128 v[178:181], v149 offset:2048
	ds_read_b128 v[182:185], v149 offset:3072
	s_add_u32 s2, s36, 0xfffc0080
	s_addc_u32 s3, s37, -1
	s_cmp_eq_u32 s62, 12
	s_cselect_b32 s3, s19, s3
	s_cselect_b32 s2, s21, s2
	s_cselect_b32 s39, s58, s61
	s_cselect_b32 s38, s59, s60
	v_lshl_add_u64 v[144:145], s[36:37], 0, v[138:139]
	s_add_i32 m0, s44, 0xc000
	ds_read_b128 v[186:189], v150
	ds_read_b128 v[190:193], v150 offset:1024
	ds_read_b128 v[194:197], v150 offset:2048
	ds_read_b128 v[198:201], v150 offset:3072
	ds_read_b128 v[202:205], v150 offset:4096
	ds_read_b128 v[206:209], v150 offset:5120
	ds_read_b128 v[210:213], v150 offset:6144
	ds_read_b128 v[214:217], v150 offset:7168
	global_load_lds_dwordx4 v[144:145], off
	v_lshl_add_u64 v[144:145], s[36:37], 0, v[140:141]
	s_add_i32 m0, s44, 0xe000
	s_nop 0
	global_load_lds_dwordx4 v[144:145], off
	s_waitcnt vmcnt(8)
	s_waitcnt lgkmcnt(0)
	s_barrier
	s_setprio 1
	s_waitcnt lgkmcnt(0)
	v_mfma_f32_16x16x32_bf16 v[126:129], v[152:155], v[186:189], v[126:129]
	v_mfma_f32_16x16x32_bf16 v[122:125], v[160:163], v[186:189], v[122:125]
	v_mfma_f32_16x16x32_bf16 v[106:109], v[160:163], v[194:197], v[106:109]
	v_mfma_f32_16x16x32_bf16 v[114:117], v[152:155], v[194:197], v[114:117]
	v_mfma_f32_16x16x32_bf16 v[98:101], v[152:155], v[202:205], v[98:101]
	v_mfma_f32_16x16x32_bf16 v[90:93], v[160:163], v[202:205], v[90:93]
	v_mfma_f32_16x16x32_bf16 v[74:77], v[160:163], v[210:213], v[74:77]
	v_mfma_f32_16x16x32_bf16 v[82:85], v[152:155], v[210:213], v[82:85]
	v_mfma_f32_16x16x32_bf16 v[126:129], v[156:159], v[190:193], v[126:129]
	v_mfma_f32_16x16x32_bf16 v[122:125], v[164:167], v[190:193], v[122:125]
	v_mfma_f32_16x16x32_bf16 v[106:109], v[164:167], v[198:201], v[106:109]
	v_mfma_f32_16x16x32_bf16 v[114:117], v[156:159], v[198:201], v[114:117]
	v_mfma_f32_16x16x32_bf16 v[98:101], v[156:159], v[206:209], v[98:101]
	v_mfma_f32_16x16x32_bf16 v[90:93], v[164:167], v[206:209], v[90:93]
	v_mfma_f32_16x16x32_bf16 v[74:77], v[164:167], v[214:217], v[74:77]
	v_mfma_f32_16x16x32_bf16 v[82:85], v[156:159], v[214:217], v[82:85]
	s_setprio 0
	s_setprio 1
	v_mfma_f32_16x16x32_bf16 v[118:121], v[168:171], v[186:189], v[118:121]
	v_mfma_f32_16x16x32_bf16 v[110:113], v[178:181], v[186:189], v[110:113]
	v_mfma_f32_16x16x32_bf16 v[94:97], v[178:181], v[194:197], v[94:97]
	v_mfma_f32_16x16x32_bf16 v[102:105], v[168:171], v[194:197], v[102:105]
	v_mfma_f32_16x16x32_bf16 v[86:89], v[168:171], v[202:205], v[86:89]
	v_mfma_f32_16x16x32_bf16 v[78:81], v[178:181], v[202:205], v[78:81]
	v_mfma_f32_16x16x32_bf16 v[66:69], v[178:181], v[210:213], v[66:69]
	v_mfma_f32_16x16x32_bf16 v[70:73], v[168:171], v[210:213], v[70:73]
	v_mfma_f32_16x16x32_bf16 v[118:121], v[172:175], v[190:193], v[118:121]
	v_mfma_f32_16x16x32_bf16 v[110:113], v[182:185], v[190:193], v[110:113]
	v_mfma_f32_16x16x32_bf16 v[94:97], v[182:185], v[198:201], v[94:97]
	v_mfma_f32_16x16x32_bf16 v[102:105], v[172:175], v[198:201], v[102:105]
	v_mfma_f32_16x16x32_bf16 v[86:89], v[172:175], v[206:209], v[86:89]
	v_mfma_f32_16x16x32_bf16 v[78:81], v[182:185], v[206:209], v[78:81]
	v_mfma_f32_16x16x32_bf16 v[66:69], v[182:185], v[214:217], v[66:69]
	v_mfma_f32_16x16x32_bf16 v[70:73], v[172:175], v[214:217], v[70:73]
	s_setprio 0
	s_barrier
	s_add_i32 s63, s51, s43
	v_lshl_add_u64 v[144:145], s[38:39], 0, v[132:133]
	s_mov_b32 m0, s63
	ds_read_b128 v[186:189], v150 offset:16384
	ds_read_b128 v[190:193], v150 offset:17408
	ds_read_b128 v[194:197], v150 offset:18432
	ds_read_b128 v[198:201], v150 offset:19456
	ds_read_b128 v[202:205], v150 offset:20480
	ds_read_b128 v[206:209], v150 offset:21504
	ds_read_b128 v[210:213], v150 offset:22528
	ds_read_b128 v[214:217], v150 offset:23552
	global_load_lds_dwordx4 v[144:145], off
	s_add_i32 m0, s63, 0x2000
	s_add_u32 s64, s38, 0x40000
	v_lshl_add_u64 v[218:219], s[38:39], 0, v[136:137]
	s_addc_u32 s65, s39, 0
	s_add_i32 s63, s52, s43
	global_load_lds_dwordx4 v[218:219], off
	v_lshl_add_u64 v[220:221], s[64:65], 0, v[132:133]
	s_mov_b32 m0, s63
	v_lshl_add_u64 v[222:223], s[2:3], 0, v[134:135]
	global_load_lds_dwordx4 v[220:221], off
	v_lshl_add_u64 v[220:221], s[64:65], 0, v[136:137]
	s_add_i32 m0, s63, 0x2000
	s_nop 0
	global_load_lds_dwordx4 v[220:221], off
	v_lshl_add_u64 v[220:221], s[2:3], 0, v[130:131]
	s_mov_b32 m0, s44
	s_nop 0
	global_load_lds_dwordx4 v[220:221], off
	s_mov_b32 m0, s35
	s_nop 0
	global_load_lds_dwordx4 v[222:223], off
	s_waitcnt vmcnt(8)
	s_waitcnt lgkmcnt(0)
	s_barrier
	s_setprio 1
	s_waitcnt lgkmcnt(0)
	v_mfma_f32_16x16x32_bf16 v[62:65], v[152:155], v[186:189], v[62:65]
	v_mfma_f32_16x16x32_bf16 v[58:61], v[160:163], v[186:189], v[58:61]
	v_mfma_f32_16x16x32_bf16 v[42:45], v[160:163], v[194:197], v[42:45]
	v_mfma_f32_16x16x32_bf16 v[50:53], v[152:155], v[194:197], v[50:53]
	v_mfma_f32_16x16x32_bf16 v[34:37], v[152:155], v[202:205], v[34:37]
	v_mfma_f32_16x16x32_bf16 v[26:29], v[160:163], v[202:205], v[26:29]
	v_mfma_f32_16x16x32_bf16 v[10:13], v[160:163], v[210:213], v[10:13]
	v_mfma_f32_16x16x32_bf16 v[18:21], v[152:155], v[210:213], v[18:21]
	v_mfma_f32_16x16x32_bf16 v[62:65], v[156:159], v[190:193], v[62:65]
	v_mfma_f32_16x16x32_bf16 v[58:61], v[164:167], v[190:193], v[58:61]
	v_mfma_f32_16x16x32_bf16 v[42:45], v[164:167], v[198:201], v[42:45]
	v_mfma_f32_16x16x32_bf16 v[50:53], v[156:159], v[198:201], v[50:53]
	v_mfma_f32_16x16x32_bf16 v[34:37], v[156:159], v[206:209], v[34:37]
	v_mfma_f32_16x16x32_bf16 v[26:29], v[164:167], v[206:209], v[26:29]
	v_mfma_f32_16x16x32_bf16 v[10:13], v[164:167], v[214:217], v[10:13]
	v_mfma_f32_16x16x32_bf16 v[18:21], v[156:159], v[214:217], v[18:21]
	s_setprio 0
	s_setprio 1
	v_mfma_f32_16x16x32_bf16 v[54:57], v[168:171], v[186:189], v[54:57]
	v_mfma_f32_16x16x32_bf16 v[46:49], v[178:181], v[186:189], v[46:49]
	v_mfma_f32_16x16x32_bf16 v[30:33], v[178:181], v[194:197], v[30:33]
	v_mfma_f32_16x16x32_bf16 v[38:41], v[168:171], v[194:197], v[38:41]
	v_mfma_f32_16x16x32_bf16 v[22:25], v[168:171], v[202:205], v[22:25]
	v_mfma_f32_16x16x32_bf16 v[14:17], v[178:181], v[202:205], v[14:17]
	v_mfma_f32_16x16x32_bf16 v[2:5], v[178:181], v[210:213], v[2:5]
	v_mfma_f32_16x16x32_bf16 v[6:9], v[168:171], v[210:213], v[6:9]
	v_mfma_f32_16x16x32_bf16 v[54:57], v[172:175], v[190:193], v[54:57]
	v_mfma_f32_16x16x32_bf16 v[46:49], v[182:185], v[190:193], v[46:49]
	v_mfma_f32_16x16x32_bf16 v[30:33], v[182:185], v[198:201], v[30:33]
	v_mfma_f32_16x16x32_bf16 v[38:41], v[172:175], v[198:201], v[38:41]
	v_mfma_f32_16x16x32_bf16 v[22:25], v[172:175], v[206:209], v[22:25]
	v_mfma_f32_16x16x32_bf16 v[14:17], v[182:185], v[206:209], v[14:17]
	v_mfma_f32_16x16x32_bf16 v[2:5], v[182:185], v[214:217], v[2:5]
	v_mfma_f32_16x16x32_bf16 v[6:9], v[172:175], v[214:217], v[6:9]
	s_setprio 0
	s_barrier
	s_add_i32 s63, 0, 0x18000
	v_add_u32_e32 v151, s63, v146
	s_add_i32 s64, 0, 0x1c000
	ds_read_b128 v[152:155], v151
	ds_read_b128 v[156:159], v151 offset:1024
	ds_read_b128 v[160:163], v151 offset:2048
	ds_read_b128 v[164:167], v151 offset:3072
	v_add_u32_e32 v151, s64, v146
	ds_read_b128 v[168:171], v151
	ds_read_b128 v[172:175], v151 offset:1024
	ds_read_b128 v[178:181], v151 offset:2048
	ds_read_b128 v[182:185], v151 offset:3072
	s_add_u32 s2, s2, 0x40000
	s_addc_u32 s3, s3, 0
	s_mov_b32 m0, s45
	v_lshl_add_u64 v[224:225], s[2:3], 0, v[130:131]
	ds_read_b128 v[186:189], v150 offset:32768
	ds_read_b128 v[190:193], v150 offset:33792
	ds_read_b128 v[194:197], v150 offset:34816
	ds_read_b128 v[198:201], v150 offset:35840
	ds_read_b128 v[202:205], v150 offset:36864
	ds_read_b128 v[206:209], v150 offset:37888
	ds_read_b128 v[210:213], v150 offset:38912
	ds_read_b128 v[214:217], v150 offset:39936
	global_load_lds_dwordx4 v[224:225], off
	v_lshl_add_u64 v[224:225], s[2:3], 0, v[134:135]
	s_mov_b32 m0, s46
	s_nop 0
	global_load_lds_dwordx4 v[224:225], off
	s_waitcnt vmcnt(8)
	s_waitcnt lgkmcnt(0)
	s_barrier
	s_setprio 1
	s_waitcnt lgkmcnt(0)
	v_mfma_f32_16x16x32_bf16 v[126:129], v[152:155], v[186:189], v[126:129]
	v_mfma_f32_16x16x32_bf16 v[122:125], v[160:163], v[186:189], v[122:125]
	v_mfma_f32_16x16x32_bf16 v[106:109], v[160:163], v[194:197], v[106:109]
	v_mfma_f32_16x16x32_bf16 v[114:117], v[152:155], v[194:197], v[114:117]
	v_mfma_f32_16x16x32_bf16 v[98:101], v[152:155], v[202:205], v[98:101]
	v_mfma_f32_16x16x32_bf16 v[90:93], v[160:163], v[202:205], v[90:93]
	v_mfma_f32_16x16x32_bf16 v[74:77], v[160:163], v[210:213], v[74:77]
	v_mfma_f32_16x16x32_bf16 v[82:85], v[152:155], v[210:213], v[82:85]
	v_mfma_f32_16x16x32_bf16 v[126:129], v[156:159], v[190:193], v[126:129]
	v_mfma_f32_16x16x32_bf16 v[122:125], v[164:167], v[190:193], v[122:125]
	v_mfma_f32_16x16x32_bf16 v[106:109], v[164:167], v[198:201], v[106:109]
	v_mfma_f32_16x16x32_bf16 v[114:117], v[156:159], v[198:201], v[114:117]
	v_mfma_f32_16x16x32_bf16 v[98:101], v[156:159], v[206:209], v[98:101]
	v_mfma_f32_16x16x32_bf16 v[90:93], v[164:167], v[206:209], v[90:93]
	v_mfma_f32_16x16x32_bf16 v[74:77], v[164:167], v[214:217], v[74:77]
	v_mfma_f32_16x16x32_bf16 v[82:85], v[156:159], v[214:217], v[82:85]
	s_setprio 0
	s_setprio 1
	v_mfma_f32_16x16x32_bf16 v[118:121], v[168:171], v[186:189], v[118:121]
	v_mfma_f32_16x16x32_bf16 v[110:113], v[178:181], v[186:189], v[110:113]
	v_mfma_f32_16x16x32_bf16 v[94:97], v[178:181], v[194:197], v[94:97]
	v_mfma_f32_16x16x32_bf16 v[102:105], v[168:171], v[194:197], v[102:105]
	v_mfma_f32_16x16x32_bf16 v[86:89], v[168:171], v[202:205], v[86:89]
	v_mfma_f32_16x16x32_bf16 v[78:81], v[178:181], v[202:205], v[78:81]
	v_mfma_f32_16x16x32_bf16 v[66:69], v[178:181], v[210:213], v[66:69]
	v_mfma_f32_16x16x32_bf16 v[70:73], v[168:171], v[210:213], v[70:73]
	v_mfma_f32_16x16x32_bf16 v[118:121], v[172:175], v[190:193], v[118:121]
	v_mfma_f32_16x16x32_bf16 v[110:113], v[182:185], v[190:193], v[110:113]
	v_mfma_f32_16x16x32_bf16 v[94:97], v[182:185], v[198:201], v[94:97]
	v_mfma_f32_16x16x32_bf16 v[102:105], v[172:175], v[198:201], v[102:105]
	v_mfma_f32_16x16x32_bf16 v[86:89], v[172:175], v[206:209], v[86:89]
	v_mfma_f32_16x16x32_bf16 v[78:81], v[182:185], v[206:209], v[78:81]
	v_mfma_f32_16x16x32_bf16 v[66:69], v[182:185], v[214:217], v[66:69]
	v_mfma_f32_16x16x32_bf16 v[70:73], v[172:175], v[214:217], v[70:73]
	s_setprio 0
	s_barrier
	s_add_i32 s2, s63, s43
	v_lshl_add_u64 v[144:145], v[144:145], 0, s[8:9]
	s_mov_b32 m0, s2
	ds_read_b128 v[186:189], v150 offset:49152
	ds_read_b128 v[190:193], v150 offset:50176
	ds_read_b128 v[194:197], v150 offset:51200
	ds_read_b128 v[198:201], v150 offset:52224
	ds_read_b128 v[202:205], v150 offset:53248
	ds_read_b128 v[206:209], v150 offset:54272
	ds_read_b128 v[210:213], v150 offset:55296
	ds_read_b128 v[214:217], v150 offset:56320
	global_load_lds_dwordx4 v[144:145], off
	s_add_i32 m0, s2, 0x2000
	s_add_u32 s2, s38, 0x40080
	v_lshl_add_u64 v[144:145], v[218:219], 0, s[8:9]
	s_addc_u32 s3, s39, 0
	s_add_i32 s38, s64, s43
	global_load_lds_dwordx4 v[144:145], off
	v_lshl_add_u64 v[144:145], s[2:3], 0, v[132:133]
	s_mov_b32 m0, s38
	s_nop 0
	global_load_lds_dwordx4 v[144:145], off
	v_lshl_add_u64 v[144:145], s[2:3], 0, v[136:137]
	s_add_i32 m0, s38, 0x2000
	s_nop 0
	global_load_lds_dwordx4 v[144:145], off
	v_lshl_add_u64 v[144:145], v[220:221], 0, s[8:9]
	s_mov_b32 m0, s48
	s_nop 0
	global_load_lds_dwordx4 v[144:145], off
	v_lshl_add_u64 v[144:145], v[222:223], 0, s[8:9]
	s_mov_b32 m0, s49
	s_nop 0
	global_load_lds_dwordx4 v[144:145], off
	s_waitcnt vmcnt(8)
	s_waitcnt lgkmcnt(0)
	s_barrier
	s_setprio 1
	s_waitcnt lgkmcnt(0)
	v_mfma_f32_16x16x32_bf16 v[62:65], v[152:155], v[186:189], v[62:65]
	v_mfma_f32_16x16x32_bf16 v[58:61], v[160:163], v[186:189], v[58:61]
	v_mfma_f32_16x16x32_bf16 v[42:45], v[160:163], v[194:197], v[42:45]
	v_mfma_f32_16x16x32_bf16 v[50:53], v[152:155], v[194:197], v[50:53]
	v_mfma_f32_16x16x32_bf16 v[34:37], v[152:155], v[202:205], v[34:37]
	v_mfma_f32_16x16x32_bf16 v[26:29], v[160:163], v[202:205], v[26:29]
	v_mfma_f32_16x16x32_bf16 v[10:13], v[160:163], v[210:213], v[10:13]
	v_mfma_f32_16x16x32_bf16 v[18:21], v[152:155], v[210:213], v[18:21]
	v_mfma_f32_16x16x32_bf16 v[62:65], v[156:159], v[190:193], v[62:65]
	v_mfma_f32_16x16x32_bf16 v[58:61], v[164:167], v[190:193], v[58:61]
	v_mfma_f32_16x16x32_bf16 v[42:45], v[164:167], v[198:201], v[42:45]
	v_mfma_f32_16x16x32_bf16 v[50:53], v[156:159], v[198:201], v[50:53]
	v_mfma_f32_16x16x32_bf16 v[34:37], v[156:159], v[206:209], v[34:37]
	v_mfma_f32_16x16x32_bf16 v[26:29], v[164:167], v[206:209], v[26:29]
	v_mfma_f32_16x16x32_bf16 v[10:13], v[164:167], v[214:217], v[10:13]
	v_mfma_f32_16x16x32_bf16 v[18:21], v[156:159], v[214:217], v[18:21]
	s_setprio 0
	s_setprio 1
	v_mfma_f32_16x16x32_bf16 v[54:57], v[168:171], v[186:189], v[54:57]
	v_mfma_f32_16x16x32_bf16 v[46:49], v[178:181], v[186:189], v[46:49]
	v_mfma_f32_16x16x32_bf16 v[30:33], v[178:181], v[194:197], v[30:33]
	v_mfma_f32_16x16x32_bf16 v[38:41], v[168:171], v[194:197], v[38:41]
	v_mfma_f32_16x16x32_bf16 v[22:25], v[168:171], v[202:205], v[22:25]
	v_mfma_f32_16x16x32_bf16 v[14:17], v[178:181], v[202:205], v[14:17]
	v_mfma_f32_16x16x32_bf16 v[2:5], v[178:181], v[210:213], v[2:5]
	v_mfma_f32_16x16x32_bf16 v[6:9], v[168:171], v[210:213], v[6:9]
	v_mfma_f32_16x16x32_bf16 v[54:57], v[172:175], v[190:193], v[54:57]
	v_mfma_f32_16x16x32_bf16 v[46:49], v[182:185], v[190:193], v[46:49]
	v_mfma_f32_16x16x32_bf16 v[30:33], v[182:185], v[198:201], v[30:33]
	v_mfma_f32_16x16x32_bf16 v[38:41], v[172:175], v[198:201], v[38:41]
	v_mfma_f32_16x16x32_bf16 v[22:25], v[172:175], v[206:209], v[22:25]
	v_mfma_f32_16x16x32_bf16 v[14:17], v[182:185], v[206:209], v[14:17]
	v_mfma_f32_16x16x32_bf16 v[2:5], v[182:185], v[214:217], v[2:5]
	v_mfma_f32_16x16x32_bf16 v[6:9], v[172:175], v[214:217], v[6:9]
	s_setprio 0
	s_barrier
	s_add_i32 s62, s62, 2
	s_add_u32 s36, s36, 0x100
	s_addc_u32 s37, s37, 0
	s_add_u32 s60, s60, 0x100
	s_addc_u32 s61, s61, 0
	s_cmp_gt_u32 s62, 13
	s_cbranch_scc0 .LBB0_1239

.Lpk1303_peel:
	ds_read_b128 v[166:169], v139
	ds_read_b128 v[170:173], v139 offset:1024
	ds_read_b128 v[178:181], v139 offset:2048
	ds_read_b128 v[182:185], v139 offset:3072
	ds_read_b128 v[186:189], v163
	ds_read_b128 v[190:193], v163 offset:1024
	ds_read_b128 v[194:197], v163 offset:2048
	ds_read_b128 v[198:201], v163 offset:3072
	s_add_u32 s2, s26, 0xfffc0080
	s_addc_u32 s3, s27, -1
	s_cmp_eq_u32 s55, 12
	s_cselect_b32 s3, s11, s3
	s_cselect_b32 s2, s13, s2
	s_cselect_b32 s29, s47, s54
	s_cselect_b32 s28, s52, s53
	v_lshl_add_u64 v[148:149], s[26:27], 0, v[142:143]
	s_add_i32 m0, s34, 0xc000
	ds_read_b128 v[202:205], v164
	ds_read_b128 v[206:209], v164 offset:1024
	ds_read_b128 v[210:213], v164 offset:2048
	ds_read_b128 v[214:217], v164 offset:3072
	ds_read_b128 v[218:221], v164 offset:4096
	ds_read_b128 v[222:225], v164 offset:5120
	ds_read_b128 v[226:229], v164 offset:6144
	ds_read_b128 v[230:233], v164 offset:7168
	global_load_lds_dwordx4 v[148:149], off
	v_lshl_add_u64 v[148:149], s[26:27], 0, v[144:145]
	s_add_i32 m0, s34, 0xe000
	s_nop 0
	global_load_lds_dwordx4 v[148:149], off
	s_waitcnt vmcnt(8)
	s_waitcnt lgkmcnt(0)
	s_barrier
	s_setprio 1
	s_waitcnt lgkmcnt(0)
	v_mfma_f32_16x16x32_bf16 v[126:129], v[166:169], v[202:205], 0
	v_mfma_f32_16x16x32_bf16 v[122:125], v[178:181], v[202:205], 0
	v_mfma_f32_16x16x32_bf16 v[106:109], v[178:181], v[210:213], 0
	v_mfma_f32_16x16x32_bf16 v[110:113], v[166:169], v[210:213], 0
	v_mfma_f32_16x16x32_bf16 v[94:97], v[166:169], v[218:221], 0
	v_mfma_f32_16x16x32_bf16 v[90:93], v[178:181], v[218:221], 0
	v_mfma_f32_16x16x32_bf16 v[74:77], v[178:181], v[226:229], 0
	v_mfma_f32_16x16x32_bf16 v[78:81], v[166:169], v[226:229], 0
	v_mfma_f32_16x16x32_bf16 v[126:129], v[170:173], v[206:209], v[126:129]
	v_mfma_f32_16x16x32_bf16 v[122:125], v[182:185], v[206:209], v[122:125]
	v_mfma_f32_16x16x32_bf16 v[106:109], v[182:185], v[214:217], v[106:109]
	v_mfma_f32_16x16x32_bf16 v[110:113], v[170:173], v[214:217], v[110:113]
	v_mfma_f32_16x16x32_bf16 v[94:97], v[170:173], v[222:225], v[94:97]
	v_mfma_f32_16x16x32_bf16 v[90:93], v[182:185], v[222:225], v[90:93]
	v_mfma_f32_16x16x32_bf16 v[74:77], v[182:185], v[230:233], v[74:77]
	v_mfma_f32_16x16x32_bf16 v[78:81], v[170:173], v[230:233], v[78:81]
	s_setprio 0
	s_setprio 1
	v_mfma_f32_16x16x32_bf16 v[118:121], v[186:189], v[202:205], 0
	v_mfma_f32_16x16x32_bf16 v[114:117], v[194:197], v[202:205], 0
	v_mfma_f32_16x16x32_bf16 v[98:101], v[194:197], v[210:213], 0
	v_mfma_f32_16x16x32_bf16 v[102:105], v[186:189], v[210:213], 0
	v_mfma_f32_16x16x32_bf16 v[86:89], v[186:189], v[218:221], 0
	v_mfma_f32_16x16x32_bf16 v[82:85], v[194:197], v[218:221], 0
	v_mfma_f32_16x16x32_bf16 v[66:69], v[194:197], v[226:229], 0
	v_mfma_f32_16x16x32_bf16 v[70:73], v[186:189], v[226:229], 0
	v_mfma_f32_16x16x32_bf16 v[118:121], v[190:193], v[206:209], v[118:121]
	v_mfma_f32_16x16x32_bf16 v[114:117], v[198:201], v[206:209], v[114:117]
	v_mfma_f32_16x16x32_bf16 v[98:101], v[198:201], v[214:217], v[98:101]
	v_mfma_f32_16x16x32_bf16 v[102:105], v[190:193], v[214:217], v[102:105]
	v_mfma_f32_16x16x32_bf16 v[86:89], v[190:193], v[222:225], v[86:89]
	v_mfma_f32_16x16x32_bf16 v[82:85], v[198:201], v[222:225], v[82:85]
	v_mfma_f32_16x16x32_bf16 v[66:69], v[198:201], v[230:233], v[66:69]
	v_mfma_f32_16x16x32_bf16 v[70:73], v[190:193], v[230:233], v[70:73]
	s_setprio 0
	s_barrier
	s_add_i32 s56, s42, s30
	v_lshl_add_u64 v[148:149], s[28:29], 0, v[132:133]
	s_mov_b32 m0, s56
	ds_read_b128 v[202:205], v164 offset:16384
	ds_read_b128 v[206:209], v164 offset:17408
	ds_read_b128 v[210:213], v164 offset:18432
	ds_read_b128 v[214:217], v164 offset:19456
	ds_read_b128 v[218:221], v164 offset:20480
	ds_read_b128 v[222:225], v164 offset:21504
	ds_read_b128 v[226:229], v164 offset:22528
	ds_read_b128 v[230:233], v164 offset:23552
	global_load_lds_dwordx4 v[148:149], off
	s_add_i32 m0, s56, 0x2000
	s_add_u32 s56, s28, 0x40000
	v_lshl_add_u64 v[174:175], s[28:29], 0, v[136:137]
	s_addc_u32 s57, s29, 0
	s_add_i32 s58, s43, s30
	global_load_lds_dwordx4 v[174:175], off
	v_lshl_add_u64 v[234:235], s[56:57], 0, v[132:133]
	s_mov_b32 m0, s58
	v_lshl_add_u64 v[236:237], s[2:3], 0, v[134:135]
	global_load_lds_dwordx4 v[234:235], off
	v_lshl_add_u64 v[234:235], s[56:57], 0, v[136:137]
	s_add_i32 m0, s58, 0x2000
	s_nop 0
	global_load_lds_dwordx4 v[234:235], off
	v_lshl_add_u64 v[234:235], s[2:3], 0, v[130:131]
	s_mov_b32 m0, s34
	s_nop 0
	global_load_lds_dwordx4 v[234:235], off
	s_mov_b32 m0, s25
	s_nop 0
	global_load_lds_dwordx4 v[236:237], off
	s_waitcnt vmcnt(8)
	s_waitcnt lgkmcnt(0)
	s_barrier
	s_setprio 1
	s_waitcnt lgkmcnt(0)
	v_mfma_f32_16x16x32_bf16 v[62:65], v[166:169], v[202:205], 0
	v_mfma_f32_16x16x32_bf16 v[58:61], v[178:181], v[202:205], 0
	v_mfma_f32_16x16x32_bf16 v[42:45], v[178:181], v[210:213], 0
	v_mfma_f32_16x16x32_bf16 v[46:49], v[166:169], v[210:213], 0
	v_mfma_f32_16x16x32_bf16 v[30:33], v[166:169], v[218:221], 0
	v_mfma_f32_16x16x32_bf16 v[26:29], v[178:181], v[218:221], 0
	v_mfma_f32_16x16x32_bf16 v[10:13], v[178:181], v[226:229], 0
	v_mfma_f32_16x16x32_bf16 v[14:17], v[166:169], v[226:229], 0
	v_mfma_f32_16x16x32_bf16 v[62:65], v[170:173], v[206:209], v[62:65]
	v_mfma_f32_16x16x32_bf16 v[58:61], v[182:185], v[206:209], v[58:61]
	v_mfma_f32_16x16x32_bf16 v[42:45], v[182:185], v[214:217], v[42:45]
	v_mfma_f32_16x16x32_bf16 v[46:49], v[170:173], v[214:217], v[46:49]
	v_mfma_f32_16x16x32_bf16 v[30:33], v[170:173], v[222:225], v[30:33]
	v_mfma_f32_16x16x32_bf16 v[26:29], v[182:185], v[222:225], v[26:29]
	v_mfma_f32_16x16x32_bf16 v[10:13], v[182:185], v[230:233], v[10:13]
	v_mfma_f32_16x16x32_bf16 v[14:17], v[170:173], v[230:233], v[14:17]
	s_setprio 0
	s_setprio 1
	v_mfma_f32_16x16x32_bf16 v[54:57], v[186:189], v[202:205], 0
	v_mfma_f32_16x16x32_bf16 v[50:53], v[194:197], v[202:205], 0
	v_mfma_f32_16x16x32_bf16 v[34:37], v[194:197], v[210:213], 0
	v_mfma_f32_16x16x32_bf16 v[38:41], v[186:189], v[210:213], 0
	v_mfma_f32_16x16x32_bf16 v[22:25], v[186:189], v[218:221], 0
	v_mfma_f32_16x16x32_bf16 v[18:21], v[194:197], v[218:221], 0
	v_mfma_f32_16x16x32_bf16 v[2:5], v[194:197], v[226:229], 0
	v_mfma_f32_16x16x32_bf16 v[6:9], v[186:189], v[226:229], 0
	v_mfma_f32_16x16x32_bf16 v[54:57], v[190:193], v[206:209], v[54:57]
	v_mfma_f32_16x16x32_bf16 v[50:53], v[198:201], v[206:209], v[50:53]
	v_mfma_f32_16x16x32_bf16 v[34:37], v[198:201], v[214:217], v[34:37]
	v_mfma_f32_16x16x32_bf16 v[38:41], v[190:193], v[214:217], v[38:41]
	v_mfma_f32_16x16x32_bf16 v[22:25], v[190:193], v[222:225], v[22:25]
	v_mfma_f32_16x16x32_bf16 v[18:21], v[198:201], v[222:225], v[18:21]
	v_mfma_f32_16x16x32_bf16 v[2:5], v[198:201], v[230:233], v[2:5]
	v_mfma_f32_16x16x32_bf16 v[6:9], v[190:193], v[230:233], v[6:9]
	s_setprio 0
	s_barrier
	s_add_i32 s56, 0, 0x18000
	v_add_u32_e32 v165, s56, v162
	s_add_i32 s57, 0, 0x1c000
	ds_read_b128 v[166:169], v165
	ds_read_b128 v[170:173], v165 offset:1024
	ds_read_b128 v[178:181], v165 offset:2048
	ds_read_b128 v[182:185], v165 offset:3072
	v_add_u32_e32 v165, s57, v162
	ds_read_b128 v[186:189], v165
	ds_read_b128 v[190:193], v165 offset:1024
	ds_read_b128 v[194:197], v165 offset:2048
	ds_read_b128 v[198:201], v165 offset:3072
	s_add_u32 s2, s2, 0x40000
	s_addc_u32 s3, s3, 0
	s_mov_b32 m0, s35
	v_lshl_add_u64 v[238:239], s[2:3], 0, v[130:131]
	ds_read_b128 v[202:205], v164 offset:32768
	ds_read_b128 v[206:209], v164 offset:33792
	ds_read_b128 v[210:213], v164 offset:34816
	ds_read_b128 v[214:217], v164 offset:35840
	ds_read_b128 v[218:221], v164 offset:36864
	ds_read_b128 v[222:225], v164 offset:37888
	ds_read_b128 v[226:229], v164 offset:38912
	ds_read_b128 v[230:233], v164 offset:39936
	global_load_lds_dwordx4 v[238:239], off
	v_lshl_add_u64 v[238:239], s[2:3], 0, v[134:135]
	s_mov_b32 m0, s36
	s_nop 0
	global_load_lds_dwordx4 v[238:239], off
	s_waitcnt vmcnt(8)
	s_waitcnt lgkmcnt(0)
	s_barrier
	s_setprio 1
	s_waitcnt lgkmcnt(0)
	v_mfma_f32_16x16x32_bf16 v[126:129], v[166:169], v[202:205], v[126:129]
	v_mfma_f32_16x16x32_bf16 v[122:125], v[178:181], v[202:205], v[122:125]
	v_mfma_f32_16x16x32_bf16 v[106:109], v[178:181], v[210:213], v[106:109]
	v_mfma_f32_16x16x32_bf16 v[110:113], v[166:169], v[210:213], v[110:113]
	v_mfma_f32_16x16x32_bf16 v[94:97], v[166:169], v[218:221], v[94:97]
	v_mfma_f32_16x16x32_bf16 v[90:93], v[178:181], v[218:221], v[90:93]
	v_mfma_f32_16x16x32_bf16 v[74:77], v[178:181], v[226:229], v[74:77]
	v_mfma_f32_16x16x32_bf16 v[78:81], v[166:169], v[226:229], v[78:81]
	v_mfma_f32_16x16x32_bf16 v[126:129], v[170:173], v[206:209], v[126:129]
	v_mfma_f32_16x16x32_bf16 v[122:125], v[182:185], v[206:209], v[122:125]
	v_mfma_f32_16x16x32_bf16 v[106:109], v[182:185], v[214:217], v[106:109]
	v_mfma_f32_16x16x32_bf16 v[110:113], v[170:173], v[214:217], v[110:113]
	v_mfma_f32_16x16x32_bf16 v[94:97], v[170:173], v[222:225], v[94:97]
	v_mfma_f32_16x16x32_bf16 v[90:93], v[182:185], v[222:225], v[90:93]
	v_mfma_f32_16x16x32_bf16 v[74:77], v[182:185], v[230:233], v[74:77]
	v_mfma_f32_16x16x32_bf16 v[78:81], v[170:173], v[230:233], v[78:81]
	s_setprio 0
	s_setprio 1
	v_mfma_f32_16x16x32_bf16 v[118:121], v[186:189], v[202:205], v[118:121]
	v_mfma_f32_16x16x32_bf16 v[114:117], v[194:197], v[202:205], v[114:117]
	v_mfma_f32_16x16x32_bf16 v[98:101], v[194:197], v[210:213], v[98:101]
	v_mfma_f32_16x16x32_bf16 v[102:105], v[186:189], v[210:213], v[102:105]
	v_mfma_f32_16x16x32_bf16 v[86:89], v[186:189], v[218:221], v[86:89]
	v_mfma_f32_16x16x32_bf16 v[82:85], v[194:197], v[218:221], v[82:85]
	v_mfma_f32_16x16x32_bf16 v[66:69], v[194:197], v[226:229], v[66:69]
	v_mfma_f32_16x16x32_bf16 v[70:73], v[186:189], v[226:229], v[70:73]
	v_mfma_f32_16x16x32_bf16 v[118:121], v[190:193], v[206:209], v[118:121]
	v_mfma_f32_16x16x32_bf16 v[114:117], v[198:201], v[206:209], v[114:117]
	v_mfma_f32_16x16x32_bf16 v[98:101], v[198:201], v[214:217], v[98:101]
	v_mfma_f32_16x16x32_bf16 v[102:105], v[190:193], v[214:217], v[102:105]
	v_mfma_f32_16x16x32_bf16 v[86:89], v[190:193], v[222:225], v[86:89]
	v_mfma_f32_16x16x32_bf16 v[82:85], v[198:201], v[222:225], v[82:85]
	v_mfma_f32_16x16x32_bf16 v[66:69], v[198:201], v[230:233], v[66:69]
	v_mfma_f32_16x16x32_bf16 v[70:73], v[190:193], v[230:233], v[70:73]
	s_setprio 0
	s_barrier
	s_add_i32 s2, s56, s30
	v_lshl_add_u64 v[148:149], v[148:149], 0, s[6:7]
	s_mov_b32 m0, s2
	ds_read_b128 v[202:205], v164 offset:49152
	ds_read_b128 v[206:209], v164 offset:50176
	ds_read_b128 v[210:213], v164 offset:51200
	ds_read_b128 v[214:217], v164 offset:52224
	ds_read_b128 v[218:221], v164 offset:53248
	ds_read_b128 v[222:225], v164 offset:54272
	ds_read_b128 v[226:229], v164 offset:55296
	ds_read_b128 v[230:233], v164 offset:56320
	global_load_lds_dwordx4 v[148:149], off
	s_add_i32 m0, s2, 0x2000
	s_add_u32 s2, s28, 0x40080
	v_lshl_add_u64 v[148:149], v[174:175], 0, s[6:7]
	s_addc_u32 s3, s29, 0
	s_add_i32 s28, s57, s30
	global_load_lds_dwordx4 v[148:149], off
	v_lshl_add_u64 v[148:149], s[2:3], 0, v[132:133]
	s_mov_b32 m0, s28
	s_nop 0
	global_load_lds_dwordx4 v[148:149], off
	v_lshl_add_u64 v[148:149], s[2:3], 0, v[136:137]
	s_add_i32 m0, s28, 0x2000
	s_nop 0
	global_load_lds_dwordx4 v[148:149], off
	v_lshl_add_u64 v[148:149], v[234:235], 0, s[6:7]
	s_mov_b32 m0, s39
	s_nop 0
	global_load_lds_dwordx4 v[148:149], off
	v_lshl_add_u64 v[148:149], v[236:237], 0, s[6:7]
	s_mov_b32 m0, s40
	s_nop 0
	global_load_lds_dwordx4 v[148:149], off
	s_waitcnt vmcnt(8)
	s_waitcnt lgkmcnt(0)
	s_barrier
	s_setprio 1
	s_waitcnt lgkmcnt(0)
	v_mfma_f32_16x16x32_bf16 v[62:65], v[166:169], v[202:205], v[62:65]
	v_mfma_f32_16x16x32_bf16 v[58:61], v[178:181], v[202:205], v[58:61]
	v_mfma_f32_16x16x32_bf16 v[42:45], v[178:181], v[210:213], v[42:45]
	v_mfma_f32_16x16x32_bf16 v[46:49], v[166:169], v[210:213], v[46:49]
	v_mfma_f32_16x16x32_bf16 v[30:33], v[166:169], v[218:221], v[30:33]
	v_mfma_f32_16x16x32_bf16 v[26:29], v[178:181], v[218:221], v[26:29]
	v_mfma_f32_16x16x32_bf16 v[10:13], v[178:181], v[226:229], v[10:13]
	v_mfma_f32_16x16x32_bf16 v[14:17], v[166:169], v[226:229], v[14:17]
	v_mfma_f32_16x16x32_bf16 v[62:65], v[170:173], v[206:209], v[62:65]
	v_mfma_f32_16x16x32_bf16 v[58:61], v[182:185], v[206:209], v[58:61]
	v_mfma_f32_16x16x32_bf16 v[42:45], v[182:185], v[214:217], v[42:45]
	v_mfma_f32_16x16x32_bf16 v[46:49], v[170:173], v[214:217], v[46:49]
	v_mfma_f32_16x16x32_bf16 v[30:33], v[170:173], v[222:225], v[30:33]
	v_mfma_f32_16x16x32_bf16 v[26:29], v[182:185], v[222:225], v[26:29]
	v_mfma_f32_16x16x32_bf16 v[10:13], v[182:185], v[230:233], v[10:13]
	v_mfma_f32_16x16x32_bf16 v[14:17], v[170:173], v[230:233], v[14:17]
	s_setprio 0
	s_setprio 1
	v_mfma_f32_16x16x32_bf16 v[54:57], v[186:189], v[202:205], v[54:57]
	v_mfma_f32_16x16x32_bf16 v[50:53], v[194:197], v[202:205], v[50:53]
	v_mfma_f32_16x16x32_bf16 v[34:37], v[194:197], v[210:213], v[34:37]
	v_mfma_f32_16x16x32_bf16 v[38:41], v[186:189], v[210:213], v[38:41]
	v_mfma_f32_16x16x32_bf16 v[22:25], v[186:189], v[218:221], v[22:25]
	v_mfma_f32_16x16x32_bf16 v[18:21], v[194:197], v[218:221], v[18:21]
	v_mfma_f32_16x16x32_bf16 v[2:5], v[194:197], v[226:229], v[2:5]
	v_mfma_f32_16x16x32_bf16 v[6:9], v[186:189], v[226:229], v[6:9]
	v_mfma_f32_16x16x32_bf16 v[54:57], v[190:193], v[206:209], v[54:57]
	v_mfma_f32_16x16x32_bf16 v[50:53], v[198:201], v[206:209], v[50:53]
	v_mfma_f32_16x16x32_bf16 v[34:37], v[198:201], v[214:217], v[34:37]
	v_mfma_f32_16x16x32_bf16 v[38:41], v[190:193], v[214:217], v[38:41]
	v_mfma_f32_16x16x32_bf16 v[22:25], v[190:193], v[222:225], v[22:25]
	v_mfma_f32_16x16x32_bf16 v[18:21], v[198:201], v[222:225], v[18:21]
	v_mfma_f32_16x16x32_bf16 v[2:5], v[198:201], v[230:233], v[2:5]
	v_mfma_f32_16x16x32_bf16 v[6:9], v[190:193], v[230:233], v[6:9]
	s_setprio 0
	s_barrier
	s_add_i32 s55, s55, 2
	s_add_u32 s26, s26, 0x100
	s_addc_u32 s27, s27, 0
	s_add_u32 s53, s53, 0x100
	s_addc_u32 s54, s54, 0
	s_cmp_gt_u32 s55, 13
	s_cbranch_scc0 .LBB0_1303
	s_branch .Lpk1303_exit
.LBB0_1303:
	ds_read_b128 v[166:169], v139
	ds_read_b128 v[170:173], v139 offset:1024
	ds_read_b128 v[178:181], v139 offset:2048
	ds_read_b128 v[182:185], v139 offset:3072
	ds_read_b128 v[186:189], v163
	ds_read_b128 v[190:193], v163 offset:1024
	ds_read_b128 v[194:197], v163 offset:2048
	ds_read_b128 v[198:201], v163 offset:3072
	s_add_u32 s2, s26, 0xfffc0080
	s_addc_u32 s3, s27, -1
	s_cmp_eq_u32 s55, 12
	s_cselect_b32 s3, s11, s3
	s_cselect_b32 s2, s13, s2
	s_cselect_b32 s29, s47, s54
	s_cselect_b32 s28, s52, s53
	v_lshl_add_u64 v[148:149], s[26:27], 0, v[142:143]
	s_add_i32 m0, s34, 0xc000
	ds_read_b128 v[202:205], v164
	ds_read_b128 v[206:209], v164 offset:1024
	ds_read_b128 v[210:213], v164 offset:2048
	ds_read_b128 v[214:217], v164 offset:3072
	ds_read_b128 v[218:221], v164 offset:4096
	ds_read_b128 v[222:225], v164 offset:5120
	ds_read_b128 v[226:229], v164 offset:6144
	ds_read_b128 v[230:233], v164 offset:7168
	global_load_lds_dwordx4 v[148:149], off
	v_lshl_add_u64 v[148:149], s[26:27], 0, v[144:145]
	s_add_i32 m0, s34, 0xe000
	s_nop 0
	global_load_lds_dwordx4 v[148:149], off
	s_waitcnt vmcnt(8)
	s_waitcnt lgkmcnt(0)
	s_barrier
	s_setprio 1
	s_waitcnt lgkmcnt(0)
	v_mfma_f32_16x16x32_bf16 v[126:129], v[166:169], v[202:205], v[126:129]
	v_mfma_f32_16x16x32_bf16 v[122:125], v[178:181], v[202:205], v[122:125]
	v_mfma_f32_16x16x32_bf16 v[106:109], v[178:181], v[210:213], v[106:109]
	v_mfma_f32_16x16x32_bf16 v[110:113], v[166:169], v[210:213], v[110:113]
	v_mfma_f32_16x16x32_bf16 v[94:97], v[166:169], v[218:221], v[94:97]
	v_mfma_f32_16x16x32_bf16 v[90:93], v[178:181], v[218:221], v[90:93]
	v_mfma_f32_16x16x32_bf16 v[74:77], v[178:181], v[226:229], v[74:77]
	v_mfma_f32_16x16x32_bf16 v[78:81], v[166:169], v[226:229], v[78:81]
	v_mfma_f32_16x16x32_bf16 v[126:129], v[170:173], v[206:209], v[126:129]
	v_mfma_f32_16x16x32_bf16 v[122:125], v[182:185], v[206:209], v[122:125]
	v_mfma_f32_16x16x32_bf16 v[106:109], v[182:185], v[214:217], v[106:109]
	v_mfma_f32_16x16x32_bf16 v[110:113], v[170:173], v[214:217], v[110:113]
	v_mfma_f32_16x16x32_bf16 v[94:97], v[170:173], v[222:225], v[94:97]
	v_mfma_f32_16x16x32_bf16 v[90:93], v[182:185], v[222:225], v[90:93]
	v_mfma_f32_16x16x32_bf16 v[74:77], v[182:185], v[230:233], v[74:77]
	v_mfma_f32_16x16x32_bf16 v[78:81], v[170:173], v[230:233], v[78:81]
	s_setprio 0
	s_setprio 1
	v_mfma_f32_16x16x32_bf16 v[118:121], v[186:189], v[202:205], v[118:121]
	v_mfma_f32_16x16x32_bf16 v[114:117], v[194:197], v[202:205], v[114:117]
	v_mfma_f32_16x16x32_bf16 v[98:101], v[194:197], v[210:213], v[98:101]
	v_mfma_f32_16x16x32_bf16 v[102:105], v[186:189], v[210:213], v[102:105]
	v_mfma_f32_16x16x32_bf16 v[86:89], v[186:189], v[218:221], v[86:89]
	v_mfma_f32_16x16x32_bf16 v[82:85], v[194:197], v[218:221], v[82:85]
	v_mfma_f32_16x16x32_bf16 v[66:69], v[194:197], v[226:229], v[66:69]
	v_mfma_f32_16x16x32_bf16 v[70:73], v[186:189], v[226:229], v[70:73]
	v_mfma_f32_16x16x32_bf16 v[118:121], v[190:193], v[206:209], v[118:121]
	v_mfma_f32_16x16x32_bf16 v[114:117], v[198:201], v[206:209], v[114:117]
	v_mfma_f32_16x16x32_bf16 v[98:101], v[198:201], v[214:217], v[98:101]
	v_mfma_f32_16x16x32_bf16 v[102:105], v[190:193], v[214:217], v[102:105]
	v_mfma_f32_16x16x32_bf16 v[86:89], v[190:193], v[222:225], v[86:89]
	v_mfma_f32_16x16x32_bf16 v[82:85], v[198:201], v[222:225], v[82:85]
	v_mfma_f32_16x16x32_bf16 v[66:69], v[198:201], v[230:233], v[66:69]
	v_mfma_f32_16x16x32_bf16 v[70:73], v[190:193], v[230:233], v[70:73]
	s_setprio 0
	s_barrier
	s_add_i32 s56, s42, s30
	v_lshl_add_u64 v[148:149], s[28:29], 0, v[132:133]
	s_mov_b32 m0, s56
	ds_read_b128 v[202:205], v164 offset:16384
	ds_read_b128 v[206:209], v164 offset:17408
	ds_read_b128 v[210:213], v164 offset:18432
	ds_read_b128 v[214:217], v164 offset:19456
	ds_read_b128 v[218:221], v164 offset:20480
	ds_read_b128 v[222:225], v164 offset:21504
	ds_read_b128 v[226:229], v164 offset:22528
	ds_read_b128 v[230:233], v164 offset:23552
	global_load_lds_dwordx4 v[148:149], off
	s_add_i32 m0, s56, 0x2000
	s_add_u32 s56, s28, 0x40000
	v_lshl_add_u64 v[174:175], s[28:29], 0, v[136:137]
	s_addc_u32 s57, s29, 0
	s_add_i32 s58, s43, s30
	global_load_lds_dwordx4 v[174:175], off
	v_lshl_add_u64 v[234:235], s[56:57], 0, v[132:133]
	s_mov_b32 m0, s58
	v_lshl_add_u64 v[236:237], s[2:3], 0, v[134:135]
	global_load_lds_dwordx4 v[234:235], off
	v_lshl_add_u64 v[234:235], s[56:57], 0, v[136:137]
	s_add_i32 m0, s58, 0x2000
	s_nop 0
	global_load_lds_dwordx4 v[234:235], off
	v_lshl_add_u64 v[234:235], s[2:3], 0, v[130:131]
	s_mov_b32 m0, s34
	s_nop 0
	global_load_lds_dwordx4 v[234:235], off
	s_mov_b32 m0, s25
	s_nop 0
	global_load_lds_dwordx4 v[236:237], off
	s_waitcnt vmcnt(8)
	s_waitcnt lgkmcnt(0)
	s_barrier
	s_setprio 1
	s_waitcnt lgkmcnt(0)
	v_mfma_f32_16x16x32_bf16 v[62:65], v[166:169], v[202:205], v[62:65]
	v_mfma_f32_16x16x32_bf16 v[58:61], v[178:181], v[202:205], v[58:61]
	v_mfma_f32_16x16x32_bf16 v[42:45], v[178:181], v[210:213], v[42:45]
	v_mfma_f32_16x16x32_bf16 v[46:49], v[166:169], v[210:213], v[46:49]
	v_mfma_f32_16x16x32_bf16 v[30:33], v[166:169], v[218:221], v[30:33]
	v_mfma_f32_16x16x32_bf16 v[26:29], v[178:181], v[218:221], v[26:29]
	v_mfma_f32_16x16x32_bf16 v[10:13], v[178:181], v[226:229], v[10:13]
	v_mfma_f32_16x16x32_bf16 v[14:17], v[166:169], v[226:229], v[14:17]
	v_mfma_f32_16x16x32_bf16 v[62:65], v[170:173], v[206:209], v[62:65]
	v_mfma_f32_16x16x32_bf16 v[58:61], v[182:185], v[206:209], v[58:61]
	v_mfma_f32_16x16x32_bf16 v[42:45], v[182:185], v[214:217], v[42:45]
	v_mfma_f32_16x16x32_bf16 v[46:49], v[170:173], v[214:217], v[46:49]
	v_mfma_f32_16x16x32_bf16 v[30:33], v[170:173], v[222:225], v[30:33]
	v_mfma_f32_16x16x32_bf16 v[26:29], v[182:185], v[222:225], v[26:29]
	v_mfma_f32_16x16x32_bf16 v[10:13], v[182:185], v[230:233], v[10:13]
	v_mfma_f32_16x16x32_bf16 v[14:17], v[170:173], v[230:233], v[14:17]
	s_setprio 0
	s_setprio 1
	v_mfma_f32_16x16x32_bf16 v[54:57], v[186:189], v[202:205], v[54:57]
	v_mfma_f32_16x16x32_bf16 v[50:53], v[194:197], v[202:205], v[50:53]
	v_mfma_f32_16x16x32_bf16 v[34:37], v[194:197], v[210:213], v[34:37]
	v_mfma_f32_16x16x32_bf16 v[38:41], v[186:189], v[210:213], v[38:41]
	v_mfma_f32_16x16x32_bf16 v[22:25], v[186:189], v[218:221], v[22:25]
	v_mfma_f32_16x16x32_bf16 v[18:21], v[194:197], v[218:221], v[18:21]
	v_mfma_f32_16x16x32_bf16 v[2:5], v[194:197], v[226:229], v[2:5]
	v_mfma_f32_16x16x32_bf16 v[6:9], v[186:189], v[226:229], v[6:9]
	v_mfma_f32_16x16x32_bf16 v[54:57], v[190:193], v[206:209], v[54:57]
	v_mfma_f32_16x16x32_bf16 v[50:53], v[198:201], v[206:209], v[50:53]
	v_mfma_f32_16x16x32_bf16 v[34:37], v[198:201], v[214:217], v[34:37]
	v_mfma_f32_16x16x32_bf16 v[38:41], v[190:193], v[214:217], v[38:41]
	v_mfma_f32_16x16x32_bf16 v[22:25], v[190:193], v[222:225], v[22:25]
	v_mfma_f32_16x16x32_bf16 v[18:21], v[198:201], v[222:225], v[18:21]
	v_mfma_f32_16x16x32_bf16 v[2:5], v[198:201], v[230:233], v[2:5]
	v_mfma_f32_16x16x32_bf16 v[6:9], v[190:193], v[230:233], v[6:9]
	s_setprio 0
	s_barrier
	s_add_i32 s56, 0, 0x18000
	v_add_u32_e32 v165, s56, v162
	s_add_i32 s57, 0, 0x1c000
	ds_read_b128 v[166:169], v165
	ds_read_b128 v[170:173], v165 offset:1024
	ds_read_b128 v[178:181], v165 offset:2048
	ds_read_b128 v[182:185], v165 offset:3072
	v_add_u32_e32 v165, s57, v162
	ds_read_b128 v[186:189], v165
	ds_read_b128 v[190:193], v165 offset:1024
	ds_read_b128 v[194:197], v165 offset:2048
	ds_read_b128 v[198:201], v165 offset:3072
	s_add_u32 s2, s2, 0x40000
	s_addc_u32 s3, s3, 0
	s_mov_b32 m0, s35
	v_lshl_add_u64 v[238:239], s[2:3], 0, v[130:131]
	ds_read_b128 v[202:205], v164 offset:32768
	ds_read_b128 v[206:209], v164 offset:33792
	ds_read_b128 v[210:213], v164 offset:34816
	ds_read_b128 v[214:217], v164 offset:35840
	ds_read_b128 v[218:221], v164 offset:36864
	ds_read_b128 v[222:225], v164 offset:37888
	ds_read_b128 v[226:229], v164 offset:38912
	ds_read_b128 v[230:233], v164 offset:39936
	global_load_lds_dwordx4 v[238:239], off
	v_lshl_add_u64 v[238:239], s[2:3], 0, v[134:135]
	s_mov_b32 m0, s36
	s_nop 0
	global_load_lds_dwordx4 v[238:239], off
	s_waitcnt vmcnt(8)
	s_waitcnt lgkmcnt(0)
	s_barrier
	s_setprio 1
	s_waitcnt lgkmcnt(0)
	v_mfma_f32_16x16x32_bf16 v[126:129], v[166:169], v[202:205], v[126:129]
	v_mfma_f32_16x16x32_bf16 v[122:125], v[178:181], v[202:205], v[122:125]
	v_mfma_f32_16x16x32_bf16 v[106:109], v[178:181], v[210:213], v[106:109]
	v_mfma_f32_16x16x32_bf16 v[110:113], v[166:169], v[210:213], v[110:113]
	v_mfma_f32_16x16x32_bf16 v[94:97], v[166:169], v[218:221], v[94:97]
	v_mfma_f32_16x16x32_bf16 v[90:93], v[178:181], v[218:221], v[90:93]
	v_mfma_f32_16x16x32_bf16 v[74:77], v[178:181], v[226:229], v[74:77]
	v_mfma_f32_16x16x32_bf16 v[78:81], v[166:169], v[226:229], v[78:81]
	v_mfma_f32_16x16x32_bf16 v[126:129], v[170:173], v[206:209], v[126:129]
	v_mfma_f32_16x16x32_bf16 v[122:125], v[182:185], v[206:209], v[122:125]
	v_mfma_f32_16x16x32_bf16 v[106:109], v[182:185], v[214:217], v[106:109]
	v_mfma_f32_16x16x32_bf16 v[110:113], v[170:173], v[214:217], v[110:113]
	v_mfma_f32_16x16x32_bf16 v[94:97], v[170:173], v[222:225], v[94:97]
	v_mfma_f32_16x16x32_bf16 v[90:93], v[182:185], v[222:225], v[90:93]
	v_mfma_f32_16x16x32_bf16 v[74:77], v[182:185], v[230:233], v[74:77]
	v_mfma_f32_16x16x32_bf16 v[78:81], v[170:173], v[230:233], v[78:81]
	s_setprio 0
	s_setprio 1
	v_mfma_f32_16x16x32_bf16 v[118:121], v[186:189], v[202:205], v[118:121]
	v_mfma_f32_16x16x32_bf16 v[114:117], v[194:197], v[202:205], v[114:117]
	v_mfma_f32_16x16x32_bf16 v[98:101], v[194:197], v[210:213], v[98:101]
	v_mfma_f32_16x16x32_bf16 v[102:105], v[186:189], v[210:213], v[102:105]
	v_mfma_f32_16x16x32_bf16 v[86:89], v[186:189], v[218:221], v[86:89]
	v_mfma_f32_16x16x32_bf16 v[82:85], v[194:197], v[218:221], v[82:85]
	v_mfma_f32_16x16x32_bf16 v[66:69], v[194:197], v[226:229], v[66:69]
	v_mfma_f32_16x16x32_bf16 v[70:73], v[186:189], v[226:229], v[70:73]
	v_mfma_f32_16x16x32_bf16 v[118:121], v[190:193], v[206:209], v[118:121]
	v_mfma_f32_16x16x32_bf16 v[114:117], v[198:201], v[206:209], v[114:117]
	v_mfma_f32_16x16x32_bf16 v[98:101], v[198:201], v[214:217], v[98:101]
	v_mfma_f32_16x16x32_bf16 v[102:105], v[190:193], v[214:217], v[102:105]
	v_mfma_f32_16x16x32_bf16 v[86:89], v[190:193], v[222:225], v[86:89]
	v_mfma_f32_16x16x32_bf16 v[82:85], v[198:201], v[222:225], v[82:85]
	v_mfma_f32_16x16x32_bf16 v[66:69], v[198:201], v[230:233], v[66:69]
	v_mfma_f32_16x16x32_bf16 v[70:73], v[190:193], v[230:233], v[70:73]
	s_setprio 0
	s_barrier
	s_add_i32 s2, s56, s30
	v_lshl_add_u64 v[148:149], v[148:149], 0, s[6:7]
	s_mov_b32 m0, s2
	ds_read_b128 v[202:205], v164 offset:49152
	ds_read_b128 v[206:209], v164 offset:50176
	ds_read_b128 v[210:213], v164 offset:51200
	ds_read_b128 v[214:217], v164 offset:52224
	ds_read_b128 v[218:221], v164 offset:53248
	ds_read_b128 v[222:225], v164 offset:54272
	ds_read_b128 v[226:229], v164 offset:55296
	ds_read_b128 v[230:233], v164 offset:56320
	global_load_lds_dwordx4 v[148:149], off
	s_add_i32 m0, s2, 0x2000
	s_add_u32 s2, s28, 0x40080
	v_lshl_add_u64 v[148:149], v[174:175], 0, s[6:7]
	s_addc_u32 s3, s29, 0
	s_add_i32 s28, s57, s30
	global_load_lds_dwordx4 v[148:149], off
	v_lshl_add_u64 v[148:149], s[2:3], 0, v[132:133]
	s_mov_b32 m0, s28
	s_nop 0
	global_load_lds_dwordx4 v[148:149], off
	v_lshl_add_u64 v[148:149], s[2:3], 0, v[136:137]
	s_add_i32 m0, s28, 0x2000
	s_nop 0
	global_load_lds_dwordx4 v[148:149], off
	v_lshl_add_u64 v[148:149], v[234:235], 0, s[6:7]
	s_mov_b32 m0, s39
	s_nop 0
	global_load_lds_dwordx4 v[148:149], off
	v_lshl_add_u64 v[148:149], v[236:237], 0, s[6:7]
	s_mov_b32 m0, s40
	s_nop 0
	global_load_lds_dwordx4 v[148:149], off
	s_waitcnt vmcnt(8)
	s_waitcnt lgkmcnt(0)
	s_barrier
	s_setprio 1
	s_waitcnt lgkmcnt(0)
	v_mfma_f32_16x16x32_bf16 v[62:65], v[166:169], v[202:205], v[62:65]
	v_mfma_f32_16x16x32_bf16 v[58:61], v[178:181], v[202:205], v[58:61]
	v_mfma_f32_16x16x32_bf16 v[42:45], v[178:181], v[210:213], v[42:45]
	v_mfma_f32_16x16x32_bf16 v[46:49], v[166:169], v[210:213], v[46:49]
	v_mfma_f32_16x16x32_bf16 v[30:33], v[166:169], v[218:221], v[30:33]
	v_mfma_f32_16x16x32_bf16 v[26:29], v[178:181], v[218:221], v[26:29]
	v_mfma_f32_16x16x32_bf16 v[10:13], v[178:181], v[226:229], v[10:13]
	v_mfma_f32_16x16x32_bf16 v[14:17], v[166:169], v[226:229], v[14:17]
	v_mfma_f32_16x16x32_bf16 v[62:65], v[170:173], v[206:209], v[62:65]
	v_mfma_f32_16x16x32_bf16 v[58:61], v[182:185], v[206:209], v[58:61]
	v_mfma_f32_16x16x32_bf16 v[42:45], v[182:185], v[214:217], v[42:45]
	v_mfma_f32_16x16x32_bf16 v[46:49], v[170:173], v[214:217], v[46:49]
	v_mfma_f32_16x16x32_bf16 v[30:33], v[170:173], v[222:225], v[30:33]
	v_mfma_f32_16x16x32_bf16 v[26:29], v[182:185], v[222:225], v[26:29]
	v_mfma_f32_16x16x32_bf16 v[10:13], v[182:185], v[230:233], v[10:13]
	v_mfma_f32_16x16x32_bf16 v[14:17], v[170:173], v[230:233], v[14:17]
	s_setprio 0
	s_setprio 1
	v_mfma_f32_16x16x32_bf16 v[54:57], v[186:189], v[202:205], v[54:57]
	v_mfma_f32_16x16x32_bf16 v[50:53], v[194:197], v[202:205], v[50:53]
	v_mfma_f32_16x16x32_bf16 v[34:37], v[194:197], v[210:213], v[34:37]
	v_mfma_f32_16x16x32_bf16 v[38:41], v[186:189], v[210:213], v[38:41]
	v_mfma_f32_16x16x32_bf16 v[22:25], v[186:189], v[218:221], v[22:25]
	v_mfma_f32_16x16x32_bf16 v[18:21], v[194:197], v[218:221], v[18:21]
	v_mfma_f32_16x16x32_bf16 v[2:5], v[194:197], v[226:229], v[2:5]
	v_mfma_f32_16x16x32_bf16 v[6:9], v[186:189], v[226:229], v[6:9]
	v_mfma_f32_16x16x32_bf16 v[54:57], v[190:193], v[206:209], v[54:57]
	v_mfma_f32_16x16x32_bf16 v[50:53], v[198:201], v[206:209], v[50:53]
	v_mfma_f32_16x16x32_bf16 v[34:37], v[198:201], v[214:217], v[34:37]
	v_mfma_f32_16x16x32_bf16 v[38:41], v[190:193], v[214:217], v[38:41]
	v_mfma_f32_16x16x32_bf16 v[22:25], v[190:193], v[222:225], v[22:25]
	v_mfma_f32_16x16x32_bf16 v[18:21], v[198:201], v[222:225], v[18:21]
	v_mfma_f32_16x16x32_bf16 v[2:5], v[198:201], v[230:233], v[2:5]
	v_mfma_f32_16x16x32_bf16 v[6:9], v[190:193], v[230:233], v[6:9]
	s_setprio 0
	s_barrier
	s_add_i32 s55, s55, 2
	s_add_u32 s26, s26, 0x100
	s_addc_u32 s27, s27, 0
	s_add_u32 s53, s53, 0x100
	s_addc_u32 s54, s54, 0
	s_cmp_gt_u32 s55, 13
	s_cbranch_scc0 .LBB0_1303

.LBB0_1386:
	ds_read_b128 v[160:163], v133
	ds_read_b128 v[164:167], v133 offset:1024
	ds_read_b128 v[168:171], v133 offset:2048
	ds_read_b128 v[172:175], v133 offset:3072
	ds_read_b128 v[178:181], v135
	ds_read_b128 v[182:185], v135 offset:1024
	ds_read_b128 v[186:189], v135 offset:2048
	ds_read_b128 v[190:193], v135 offset:3072
	s_cmp_lg_u32 s8, 0x160000
	s_cselect_b32 s13, s8, 0
	s_cselect_b32 s12, s9, 0
	s_add_u32 s2, s6, s13
	s_addc_u32 s3, s7, s12
	s_add_u32 s14, s0, s13
	s_addc_u32 s15, s1, s12
	s_add_u32 s12, s2, 0x8000
	s_addc_u32 s13, s3, 0
	v_lshl_add_u64 v[226:227], v[148:149], 0, s[8:9]
	s_mov_b32 m0, s27
	v_lshl_add_u64 v[226:227], v[226:227], 0, s[10:11]
	ds_read_b128 v[194:197], v137
	ds_read_b128 v[198:201], v137 offset:1024
	ds_read_b128 v[202:205], v137 offset:2048
	ds_read_b128 v[206:209], v137 offset:3072
	ds_read_b128 v[210:213], v137 offset:4096
	ds_read_b128 v[214:217], v137 offset:5120
	ds_read_b128 v[218:221], v137 offset:6144
	ds_read_b128 v[222:225], v137 offset:7168
	global_load_lds_dwordx4 v[226:227], off
	v_lshl_add_u64 v[226:227], v[150:151], 0, s[8:9]
	v_lshl_add_u64 v[226:227], v[226:227], 0, s[10:11]
	s_mov_b32 m0, s28
	s_nop 0
	global_load_lds_dwordx4 v[226:227], off
	s_waitcnt vmcnt(8)
	s_waitcnt lgkmcnt(0)
	s_barrier
	s_setprio 1
	s_waitcnt lgkmcnt(0)
	v_mfma_f32_16x16x32_bf16 v[126:129], v[160:163], v[194:197], v[126:129]
	v_mfma_f32_16x16x32_bf16 v[122:125], v[168:171], v[194:197], v[122:125]
	v_mfma_f32_16x16x32_bf16 v[106:109], v[168:171], v[202:205], v[106:109]
	v_mfma_f32_16x16x32_bf16 v[114:117], v[160:163], v[202:205], v[114:117]
	v_mfma_f32_16x16x32_bf16 v[98:101], v[160:163], v[210:213], v[98:101]
	v_mfma_f32_16x16x32_bf16 v[90:93], v[168:171], v[210:213], v[90:93]
	v_mfma_f32_16x16x32_bf16 v[74:77], v[168:171], v[218:221], v[74:77]
	v_mfma_f32_16x16x32_bf16 v[82:85], v[160:163], v[218:221], v[82:85]
	v_mfma_f32_16x16x32_bf16 v[126:129], v[164:167], v[198:201], v[126:129]
	v_mfma_f32_16x16x32_bf16 v[122:125], v[172:175], v[198:201], v[122:125]
	v_mfma_f32_16x16x32_bf16 v[106:109], v[172:175], v[206:209], v[106:109]
	v_mfma_f32_16x16x32_bf16 v[114:117], v[164:167], v[206:209], v[114:117]
	v_mfma_f32_16x16x32_bf16 v[98:101], v[164:167], v[214:217], v[98:101]
	v_mfma_f32_16x16x32_bf16 v[90:93], v[172:175], v[214:217], v[90:93]
	v_mfma_f32_16x16x32_bf16 v[74:77], v[172:175], v[222:225], v[74:77]
	v_mfma_f32_16x16x32_bf16 v[82:85], v[164:167], v[222:225], v[82:85]
	s_setprio 0
	s_setprio 1
	v_mfma_f32_16x16x32_bf16 v[118:121], v[178:181], v[194:197], v[118:121]
	v_mfma_f32_16x16x32_bf16 v[110:113], v[186:189], v[194:197], v[110:113]
	v_mfma_f32_16x16x32_bf16 v[94:97], v[186:189], v[202:205], v[94:97]
	v_mfma_f32_16x16x32_bf16 v[102:105], v[178:181], v[202:205], v[102:105]
	v_mfma_f32_16x16x32_bf16 v[86:89], v[178:181], v[210:213], v[86:89]
	v_mfma_f32_16x16x32_bf16 v[78:81], v[186:189], v[210:213], v[78:81]
	v_mfma_f32_16x16x32_bf16 v[66:69], v[186:189], v[218:221], v[66:69]
	v_mfma_f32_16x16x32_bf16 v[70:73], v[178:181], v[218:221], v[70:73]
	v_mfma_f32_16x16x32_bf16 v[118:121], v[182:185], v[198:201], v[118:121]
	v_mfma_f32_16x16x32_bf16 v[110:113], v[190:193], v[198:201], v[110:113]
	v_mfma_f32_16x16x32_bf16 v[94:97], v[190:193], v[206:209], v[94:97]
	v_mfma_f32_16x16x32_bf16 v[102:105], v[182:185], v[206:209], v[102:105]
	v_mfma_f32_16x16x32_bf16 v[86:89], v[182:185], v[214:217], v[86:89]
	v_mfma_f32_16x16x32_bf16 v[78:81], v[190:193], v[214:217], v[78:81]
	v_mfma_f32_16x16x32_bf16 v[66:69], v[190:193], v[222:225], v[66:69]
	v_mfma_f32_16x16x32_bf16 v[70:73], v[182:185], v[222:225], v[70:73]
	s_setprio 0
	s_barrier
	s_mov_b32 m0, s29
	v_lshl_add_u64 v[226:227], s[14:15], 0, v[142:143]
	s_add_u32 s40, s14, 0x4000
	ds_read_b128 v[194:197], v137 offset:16384
	ds_read_b128 v[198:201], v137 offset:17408
	ds_read_b128 v[202:205], v137 offset:18432
	ds_read_b128 v[206:209], v137 offset:19456
	ds_read_b128 v[210:213], v137 offset:20480
	ds_read_b128 v[214:217], v137 offset:21504
	ds_read_b128 v[218:221], v137 offset:22528
	ds_read_b128 v[222:225], v137 offset:23552
	global_load_lds_dwordx4 v[226:227], off
	v_lshl_add_u64 v[226:227], s[14:15], 0, v[146:147]
	s_mov_b32 m0, s30
	s_addc_u32 s41, s15, 0
	global_load_lds_dwordx4 v[226:227], off
	v_lshl_add_u64 v[226:227], s[40:41], 0, v[142:143]
	s_mov_b32 m0, s31
	s_nop 0
	global_load_lds_dwordx4 v[226:227], off
	v_lshl_add_u64 v[226:227], s[40:41], 0, v[146:147]
	s_mov_b32 m0, s34
	s_nop 0
	global_load_lds_dwordx4 v[226:227], off
	v_lshl_add_u64 v[226:227], s[2:3], 0, v[140:141]
	s_mov_b32 m0, s19
	s_nop 0
	global_load_lds_dwordx4 v[226:227], off
	v_lshl_add_u64 v[226:227], s[2:3], 0, v[144:145]
	s_mov_b32 m0, s20
	s_nop 0
	global_load_lds_dwordx4 v[226:227], off
	s_waitcnt vmcnt(8)
	s_waitcnt lgkmcnt(0)
	s_barrier
	s_setprio 1
	s_waitcnt lgkmcnt(0)
	v_mfma_f32_16x16x32_bf16 v[62:65], v[160:163], v[194:197], v[62:65]
	v_mfma_f32_16x16x32_bf16 v[58:61], v[168:171], v[194:197], v[58:61]
	v_mfma_f32_16x16x32_bf16 v[42:45], v[168:171], v[202:205], v[42:45]
	v_mfma_f32_16x16x32_bf16 v[50:53], v[160:163], v[202:205], v[50:53]
	v_mfma_f32_16x16x32_bf16 v[34:37], v[160:163], v[210:213], v[34:37]
	v_mfma_f32_16x16x32_bf16 v[26:29], v[168:171], v[210:213], v[26:29]
	v_mfma_f32_16x16x32_bf16 v[10:13], v[168:171], v[218:221], v[10:13]
	v_mfma_f32_16x16x32_bf16 v[18:21], v[160:163], v[218:221], v[18:21]
	v_mfma_f32_16x16x32_bf16 v[62:65], v[164:167], v[198:201], v[62:65]
	v_mfma_f32_16x16x32_bf16 v[58:61], v[172:175], v[198:201], v[58:61]
	v_mfma_f32_16x16x32_bf16 v[42:45], v[172:175], v[206:209], v[42:45]
	v_mfma_f32_16x16x32_bf16 v[50:53], v[164:167], v[206:209], v[50:53]
	v_mfma_f32_16x16x32_bf16 v[34:37], v[164:167], v[214:217], v[34:37]
	v_mfma_f32_16x16x32_bf16 v[26:29], v[172:175], v[214:217], v[26:29]
	v_mfma_f32_16x16x32_bf16 v[10:13], v[172:175], v[222:225], v[10:13]
	v_mfma_f32_16x16x32_bf16 v[18:21], v[164:167], v[222:225], v[18:21]
	s_setprio 0
	s_setprio 1
	v_mfma_f32_16x16x32_bf16 v[54:57], v[178:181], v[194:197], v[54:57]
	v_mfma_f32_16x16x32_bf16 v[46:49], v[186:189], v[194:197], v[46:49]
	v_mfma_f32_16x16x32_bf16 v[30:33], v[186:189], v[202:205], v[30:33]
	v_mfma_f32_16x16x32_bf16 v[38:41], v[178:181], v[202:205], v[38:41]
	v_mfma_f32_16x16x32_bf16 v[22:25], v[178:181], v[210:213], v[22:25]
	v_mfma_f32_16x16x32_bf16 v[14:17], v[186:189], v[210:213], v[14:17]
	v_mfma_f32_16x16x32_bf16 v[2:5], v[186:189], v[218:221], v[2:5]
	v_mfma_f32_16x16x32_bf16 v[6:9], v[178:181], v[218:221], v[6:9]
	v_mfma_f32_16x16x32_bf16 v[54:57], v[182:185], v[198:201], v[54:57]
	v_mfma_f32_16x16x32_bf16 v[46:49], v[190:193], v[198:201], v[46:49]
	v_mfma_f32_16x16x32_bf16 v[30:33], v[190:193], v[206:209], v[30:33]
	v_mfma_f32_16x16x32_bf16 v[38:41], v[182:185], v[206:209], v[38:41]
	v_mfma_f32_16x16x32_bf16 v[22:25], v[182:185], v[214:217], v[22:25]
	v_mfma_f32_16x16x32_bf16 v[14:17], v[190:193], v[214:217], v[14:17]
	v_mfma_f32_16x16x32_bf16 v[2:5], v[190:193], v[222:225], v[2:5]
	v_mfma_f32_16x16x32_bf16 v[6:9], v[182:185], v[222:225], v[6:9]
	s_setprio 0
	s_barrier
	ds_read_b128 v[160:163], v139
	ds_read_b128 v[164:167], v139 offset:1024
	ds_read_b128 v[168:171], v139 offset:2048
	ds_read_b128 v[172:175], v139 offset:3072
	ds_read_b128 v[178:181], v158
	ds_read_b128 v[182:185], v158 offset:1024
	ds_read_b128 v[186:189], v158 offset:2048
	ds_read_b128 v[190:193], v158 offset:3072
	s_add_u32 s2, s2, 0x4000
	s_addc_u32 s3, s3, 0
	s_mov_b32 m0, s21
	v_lshl_add_u64 v[226:227], s[2:3], 0, v[140:141]
	ds_read_b128 v[194:197], v137 offset:32768
	ds_read_b128 v[198:201], v137 offset:33792
	ds_read_b128 v[202:205], v137 offset:34816
	ds_read_b128 v[206:209], v137 offset:35840
	ds_read_b128 v[210:213], v137 offset:36864
	ds_read_b128 v[214:217], v137 offset:37888
	ds_read_b128 v[218:221], v137 offset:38912
	ds_read_b128 v[222:225], v137 offset:39936
	global_load_lds_dwordx4 v[226:227], off
	v_lshl_add_u64 v[226:227], s[2:3], 0, v[144:145]
	s_mov_b32 m0, s22
	s_nop 0
	global_load_lds_dwordx4 v[226:227], off
	s_waitcnt vmcnt(8)
	s_waitcnt lgkmcnt(0)
	s_barrier
	s_setprio 1
	s_waitcnt lgkmcnt(0)
	v_mfma_f32_16x16x32_bf16 v[126:129], v[160:163], v[194:197], v[126:129]
	v_mfma_f32_16x16x32_bf16 v[122:125], v[168:171], v[194:197], v[122:125]
	v_mfma_f32_16x16x32_bf16 v[106:109], v[168:171], v[202:205], v[106:109]
	v_mfma_f32_16x16x32_bf16 v[114:117], v[160:163], v[202:205], v[114:117]
	v_mfma_f32_16x16x32_bf16 v[98:101], v[160:163], v[210:213], v[98:101]
	v_mfma_f32_16x16x32_bf16 v[90:93], v[168:171], v[210:213], v[90:93]
	v_mfma_f32_16x16x32_bf16 v[74:77], v[168:171], v[218:221], v[74:77]
	v_mfma_f32_16x16x32_bf16 v[82:85], v[160:163], v[218:221], v[82:85]
	v_mfma_f32_16x16x32_bf16 v[126:129], v[164:167], v[198:201], v[126:129]
	v_mfma_f32_16x16x32_bf16 v[122:125], v[172:175], v[198:201], v[122:125]
	v_mfma_f32_16x16x32_bf16 v[106:109], v[172:175], v[206:209], v[106:109]
	v_mfma_f32_16x16x32_bf16 v[114:117], v[164:167], v[206:209], v[114:117]
	v_mfma_f32_16x16x32_bf16 v[98:101], v[164:167], v[214:217], v[98:101]
	v_mfma_f32_16x16x32_bf16 v[90:93], v[172:175], v[214:217], v[90:93]
	v_mfma_f32_16x16x32_bf16 v[74:77], v[172:175], v[222:225], v[74:77]
	v_mfma_f32_16x16x32_bf16 v[82:85], v[164:167], v[222:225], v[82:85]
	s_setprio 0
	s_setprio 1
	v_mfma_f32_16x16x32_bf16 v[118:121], v[178:181], v[194:197], v[118:121]
	v_mfma_f32_16x16x32_bf16 v[110:113], v[186:189], v[194:197], v[110:113]
	v_mfma_f32_16x16x32_bf16 v[94:97], v[186:189], v[202:205], v[94:97]
	v_mfma_f32_16x16x32_bf16 v[102:105], v[178:181], v[202:205], v[102:105]
	v_mfma_f32_16x16x32_bf16 v[86:89], v[178:181], v[210:213], v[86:89]
	v_mfma_f32_16x16x32_bf16 v[78:81], v[186:189], v[210:213], v[78:81]
	v_mfma_f32_16x16x32_bf16 v[66:69], v[186:189], v[218:221], v[66:69]
	v_mfma_f32_16x16x32_bf16 v[70:73], v[178:181], v[218:221], v[70:73]
	v_mfma_f32_16x16x32_bf16 v[118:121], v[182:185], v[198:201], v[118:121]
	v_mfma_f32_16x16x32_bf16 v[110:113], v[190:193], v[198:201], v[110:113]
	v_mfma_f32_16x16x32_bf16 v[94:97], v[190:193], v[206:209], v[94:97]
	v_mfma_f32_16x16x32_bf16 v[102:105], v[182:185], v[206:209], v[102:105]
	v_mfma_f32_16x16x32_bf16 v[86:89], v[182:185], v[214:217], v[86:89]
	v_mfma_f32_16x16x32_bf16 v[78:81], v[190:193], v[214:217], v[78:81]
	v_mfma_f32_16x16x32_bf16 v[66:69], v[190:193], v[222:225], v[66:69]
	v_mfma_f32_16x16x32_bf16 v[70:73], v[182:185], v[222:225], v[70:73]
	s_setprio 0
	s_barrier
	s_add_u32 s2, s14, 0x8000
	s_addc_u32 s3, s15, 0
	s_mov_b32 m0, s35
	v_lshl_add_u64 v[226:227], s[2:3], 0, v[142:143]
	ds_read_b128 v[194:197], v137 offset:49152
	ds_read_b128 v[198:201], v137 offset:50176
	ds_read_b128 v[202:205], v137 offset:51200
	ds_read_b128 v[206:209], v137 offset:52224
	ds_read_b128 v[210:213], v137 offset:53248
	ds_read_b128 v[214:217], v137 offset:54272
	ds_read_b128 v[218:221], v137 offset:55296
	ds_read_b128 v[222:225], v137 offset:56320
	global_load_lds_dwordx4 v[226:227], off
	v_lshl_add_u64 v[226:227], s[2:3], 0, v[146:147]
	s_add_u32 s2, s14, 0xc000
	s_mov_b32 m0, s36
	s_addc_u32 s3, s15, 0
	global_load_lds_dwordx4 v[226:227], off
	v_lshl_add_u64 v[226:227], s[2:3], 0, v[142:143]
	s_mov_b32 m0, s37
	s_nop 0
	global_load_lds_dwordx4 v[226:227], off
	v_lshl_add_u64 v[226:227], s[2:3], 0, v[146:147]
	s_mov_b32 m0, s38
	s_nop 0
	global_load_lds_dwordx4 v[226:227], off
	v_lshl_add_u64 v[226:227], s[12:13], 0, v[140:141]
	s_mov_b32 m0, s24
	s_nop 0
	global_load_lds_dwordx4 v[226:227], off
	v_lshl_add_u64 v[226:227], s[12:13], 0, v[144:145]
	s_mov_b32 m0, s25
	s_nop 0
	global_load_lds_dwordx4 v[226:227], off
	s_waitcnt vmcnt(8)
	s_waitcnt lgkmcnt(0)
	s_barrier
	s_setprio 1
	s_waitcnt lgkmcnt(0)
	v_mfma_f32_16x16x32_bf16 v[62:65], v[160:163], v[194:197], v[62:65]
	v_mfma_f32_16x16x32_bf16 v[58:61], v[168:171], v[194:197], v[58:61]
	v_mfma_f32_16x16x32_bf16 v[42:45], v[168:171], v[202:205], v[42:45]
	v_mfma_f32_16x16x32_bf16 v[50:53], v[160:163], v[202:205], v[50:53]
	v_mfma_f32_16x16x32_bf16 v[34:37], v[160:163], v[210:213], v[34:37]
	v_mfma_f32_16x16x32_bf16 v[26:29], v[168:171], v[210:213], v[26:29]
	v_mfma_f32_16x16x32_bf16 v[10:13], v[168:171], v[218:221], v[10:13]
	v_mfma_f32_16x16x32_bf16 v[18:21], v[160:163], v[218:221], v[18:21]
	v_mfma_f32_16x16x32_bf16 v[62:65], v[164:167], v[198:201], v[62:65]
	v_mfma_f32_16x16x32_bf16 v[58:61], v[172:175], v[198:201], v[58:61]
	v_mfma_f32_16x16x32_bf16 v[42:45], v[172:175], v[206:209], v[42:45]
	v_mfma_f32_16x16x32_bf16 v[50:53], v[164:167], v[206:209], v[50:53]
	v_mfma_f32_16x16x32_bf16 v[34:37], v[164:167], v[214:217], v[34:37]
	v_mfma_f32_16x16x32_bf16 v[26:29], v[172:175], v[214:217], v[26:29]
	v_mfma_f32_16x16x32_bf16 v[10:13], v[172:175], v[222:225], v[10:13]
	v_mfma_f32_16x16x32_bf16 v[18:21], v[164:167], v[222:225], v[18:21]
	s_setprio 0
	s_setprio 1
	v_mfma_f32_16x16x32_bf16 v[54:57], v[178:181], v[194:197], v[54:57]
	v_mfma_f32_16x16x32_bf16 v[46:49], v[186:189], v[194:197], v[46:49]
	v_mfma_f32_16x16x32_bf16 v[30:33], v[186:189], v[202:205], v[30:33]
	v_mfma_f32_16x16x32_bf16 v[38:41], v[178:181], v[202:205], v[38:41]
	v_mfma_f32_16x16x32_bf16 v[22:25], v[178:181], v[210:213], v[22:25]
	v_mfma_f32_16x16x32_bf16 v[14:17], v[186:189], v[210:213], v[14:17]
	v_mfma_f32_16x16x32_bf16 v[2:5], v[186:189], v[218:221], v[2:5]
	v_mfma_f32_16x16x32_bf16 v[6:9], v[178:181], v[218:221], v[6:9]
	v_mfma_f32_16x16x32_bf16 v[54:57], v[182:185], v[198:201], v[54:57]
	v_mfma_f32_16x16x32_bf16 v[46:49], v[190:193], v[198:201], v[46:49]
	v_mfma_f32_16x16x32_bf16 v[30:33], v[190:193], v[206:209], v[30:33]
	v_mfma_f32_16x16x32_bf16 v[38:41], v[182:185], v[206:209], v[38:41]
	v_mfma_f32_16x16x32_bf16 v[22:25], v[182:185], v[214:217], v[22:25]
	v_mfma_f32_16x16x32_bf16 v[14:17], v[190:193], v[214:217], v[14:17]
	v_mfma_f32_16x16x32_bf16 v[2:5], v[190:193], v[222:225], v[2:5]
	v_mfma_f32_16x16x32_bf16 v[6:9], v[182:185], v[222:225], v[6:9]
	s_setprio 0
	s_barrier
	s_add_i32 s26, s26, 2
	s_add_u32 s8, s8, 0x10000
	s_addc_u32 s9, s9, 0
	s_cmp_gt_u32 s26, 41
	s_cbranch_scc0 .LBB0_1386
	s_cmpk_lt_u32 s16, 0x100
	s_cbranch_scc0 .LBB0_1389
	s_barrier

.Lpk1400_peel:
	ds_read_b128 v[152:155], v1
	ds_read_b128 v[156:159], v1 offset:1024
	ds_read_b128 v[160:163], v1 offset:2048
	ds_read_b128 v[164:167], v1 offset:3072
	ds_read_b128 v[168:171], v149
	ds_read_b128 v[172:175], v149 offset:1024
	ds_read_b128 v[178:181], v149 offset:2048
	ds_read_b128 v[182:185], v149 offset:3072
	s_add_u32 s2, s28, 0xfffc0080
	s_addc_u32 s3, s29, -1
	s_cmp_eq_u32 s55, 12
	s_cselect_b32 s3, s11, s3
	s_cselect_b32 s2, s13, s2
	s_cselect_b32 s31, s47, s54
	s_cselect_b32 s30, s52, s53
	v_lshl_add_u64 v[146:147], s[28:29], 0, v[140:141]
	s_add_i32 m0, s25, 0xc000
	ds_read_b128 v[186:189], v150
	ds_read_b128 v[190:193], v150 offset:1024
	ds_read_b128 v[194:197], v150 offset:2048
	ds_read_b128 v[198:201], v150 offset:3072
	ds_read_b128 v[202:205], v150 offset:4096
	ds_read_b128 v[206:209], v150 offset:5120
	ds_read_b128 v[210:213], v150 offset:6144
	ds_read_b128 v[214:217], v150 offset:7168
	global_load_lds_dwordx4 v[146:147], off
	v_lshl_add_u64 v[146:147], s[28:29], 0, v[142:143]
	s_add_i32 m0, s25, 0xe000
	s_nop 0
	global_load_lds_dwordx4 v[146:147], off
	s_waitcnt vmcnt(8)
	s_waitcnt lgkmcnt(0)
	s_barrier
	s_setprio 1
	s_waitcnt lgkmcnt(0)
	v_mfma_f32_16x16x32_bf16 v[126:129], v[152:155], v[186:189], 0
	v_mfma_f32_16x16x32_bf16 v[122:125], v[160:163], v[186:189], 0
	v_mfma_f32_16x16x32_bf16 v[106:109], v[160:163], v[194:197], 0
	v_mfma_f32_16x16x32_bf16 v[110:113], v[152:155], v[194:197], 0
	v_mfma_f32_16x16x32_bf16 v[94:97], v[152:155], v[202:205], 0
	v_mfma_f32_16x16x32_bf16 v[90:93], v[160:163], v[202:205], 0
	v_mfma_f32_16x16x32_bf16 v[74:77], v[160:163], v[210:213], 0
	v_mfma_f32_16x16x32_bf16 v[78:81], v[152:155], v[210:213], 0
	v_mfma_f32_16x16x32_bf16 v[126:129], v[156:159], v[190:193], v[126:129]
	v_mfma_f32_16x16x32_bf16 v[122:125], v[164:167], v[190:193], v[122:125]
	v_mfma_f32_16x16x32_bf16 v[106:109], v[164:167], v[198:201], v[106:109]
	v_mfma_f32_16x16x32_bf16 v[110:113], v[156:159], v[198:201], v[110:113]
	v_mfma_f32_16x16x32_bf16 v[94:97], v[156:159], v[206:209], v[94:97]
	v_mfma_f32_16x16x32_bf16 v[90:93], v[164:167], v[206:209], v[90:93]
	v_mfma_f32_16x16x32_bf16 v[74:77], v[164:167], v[214:217], v[74:77]
	v_mfma_f32_16x16x32_bf16 v[78:81], v[156:159], v[214:217], v[78:81]
	s_setprio 0
	s_setprio 1
	v_mfma_f32_16x16x32_bf16 v[118:121], v[168:171], v[186:189], 0
	v_mfma_f32_16x16x32_bf16 v[114:117], v[178:181], v[186:189], 0
	v_mfma_f32_16x16x32_bf16 v[98:101], v[178:181], v[194:197], 0
	v_mfma_f32_16x16x32_bf16 v[102:105], v[168:171], v[194:197], 0
	v_mfma_f32_16x16x32_bf16 v[86:89], v[168:171], v[202:205], 0
	v_mfma_f32_16x16x32_bf16 v[82:85], v[178:181], v[202:205], 0
	v_mfma_f32_16x16x32_bf16 v[66:69], v[178:181], v[210:213], 0
	v_mfma_f32_16x16x32_bf16 v[70:73], v[168:171], v[210:213], 0
	v_mfma_f32_16x16x32_bf16 v[118:121], v[172:175], v[190:193], v[118:121]
	v_mfma_f32_16x16x32_bf16 v[114:117], v[182:185], v[190:193], v[114:117]
	v_mfma_f32_16x16x32_bf16 v[98:101], v[182:185], v[198:201], v[98:101]
	v_mfma_f32_16x16x32_bf16 v[102:105], v[172:175], v[198:201], v[102:105]
	v_mfma_f32_16x16x32_bf16 v[86:89], v[172:175], v[206:209], v[86:89]
	v_mfma_f32_16x16x32_bf16 v[82:85], v[182:185], v[206:209], v[82:85]
	v_mfma_f32_16x16x32_bf16 v[66:69], v[182:185], v[214:217], v[66:69]
	v_mfma_f32_16x16x32_bf16 v[70:73], v[172:175], v[214:217], v[70:73]
	s_setprio 0
	s_barrier
	s_add_i32 s56, s43, s34
	v_lshl_add_u64 v[146:147], s[30:31], 0, v[132:133]
	s_mov_b32 m0, s56
	ds_read_b128 v[186:189], v150 offset:16384
	ds_read_b128 v[190:193], v150 offset:17408
	ds_read_b128 v[194:197], v150 offset:18432
	ds_read_b128 v[198:201], v150 offset:19456
	ds_read_b128 v[202:205], v150 offset:20480
	ds_read_b128 v[206:209], v150 offset:21504
	ds_read_b128 v[210:213], v150 offset:22528
	ds_read_b128 v[214:217], v150 offset:23552
	global_load_lds_dwordx4 v[146:147], off
	s_add_i32 m0, s56, 0x2000
	s_add_u32 s56, s30, 0x40000
	v_lshl_add_u64 v[218:219], s[30:31], 0, v[136:137]
	s_addc_u32 s57, s31, 0
	s_add_i32 s58, s44, s34
	global_load_lds_dwordx4 v[218:219], off
	v_lshl_add_u64 v[220:221], s[56:57], 0, v[132:133]
	s_mov_b32 m0, s58
	v_lshl_add_u64 v[222:223], s[2:3], 0, v[134:135]
	global_load_lds_dwordx4 v[220:221], off
	v_lshl_add_u64 v[220:221], s[56:57], 0, v[136:137]
	s_add_i32 m0, s58, 0x2000
	s_nop 0
	global_load_lds_dwordx4 v[220:221], off
	v_lshl_add_u64 v[220:221], s[2:3], 0, v[130:131]
	s_mov_b32 m0, s25
	s_nop 0
	global_load_lds_dwordx4 v[220:221], off
	s_mov_b32 m0, s27
	s_nop 0
	global_load_lds_dwordx4 v[222:223], off
	s_waitcnt vmcnt(8)
	s_waitcnt lgkmcnt(0)
	s_barrier
	s_setprio 1
	s_waitcnt lgkmcnt(0)
	v_mfma_f32_16x16x32_bf16 v[62:65], v[152:155], v[186:189], 0
	v_mfma_f32_16x16x32_bf16 v[58:61], v[160:163], v[186:189], 0
	v_mfma_f32_16x16x32_bf16 v[42:45], v[160:163], v[194:197], 0
	v_mfma_f32_16x16x32_bf16 v[46:49], v[152:155], v[194:197], 0
	v_mfma_f32_16x16x32_bf16 v[30:33], v[152:155], v[202:205], 0
	v_mfma_f32_16x16x32_bf16 v[26:29], v[160:163], v[202:205], 0
	v_mfma_f32_16x16x32_bf16 v[10:13], v[160:163], v[210:213], 0
	v_mfma_f32_16x16x32_bf16 v[14:17], v[152:155], v[210:213], 0
	v_mfma_f32_16x16x32_bf16 v[62:65], v[156:159], v[190:193], v[62:65]
	v_mfma_f32_16x16x32_bf16 v[58:61], v[164:167], v[190:193], v[58:61]
	v_mfma_f32_16x16x32_bf16 v[42:45], v[164:167], v[198:201], v[42:45]
	v_mfma_f32_16x16x32_bf16 v[46:49], v[156:159], v[198:201], v[46:49]
	v_mfma_f32_16x16x32_bf16 v[30:33], v[156:159], v[206:209], v[30:33]
	v_mfma_f32_16x16x32_bf16 v[26:29], v[164:167], v[206:209], v[26:29]
	v_mfma_f32_16x16x32_bf16 v[10:13], v[164:167], v[214:217], v[10:13]
	v_mfma_f32_16x16x32_bf16 v[14:17], v[156:159], v[214:217], v[14:17]
	s_setprio 0
	s_setprio 1
	v_mfma_f32_16x16x32_bf16 v[54:57], v[168:171], v[186:189], 0
	v_mfma_f32_16x16x32_bf16 v[50:53], v[178:181], v[186:189], 0
	v_mfma_f32_16x16x32_bf16 v[34:37], v[178:181], v[194:197], 0
	v_mfma_f32_16x16x32_bf16 v[38:41], v[168:171], v[194:197], 0
	v_mfma_f32_16x16x32_bf16 v[22:25], v[168:171], v[202:205], 0
	v_mfma_f32_16x16x32_bf16 v[18:21], v[178:181], v[202:205], 0
	v_mfma_f32_16x16x32_bf16 v[2:5], v[178:181], v[210:213], 0
	v_mfma_f32_16x16x32_bf16 v[6:9], v[168:171], v[210:213], 0
	v_mfma_f32_16x16x32_bf16 v[54:57], v[172:175], v[190:193], v[54:57]
	v_mfma_f32_16x16x32_bf16 v[50:53], v[182:185], v[190:193], v[50:53]
	v_mfma_f32_16x16x32_bf16 v[34:37], v[182:185], v[198:201], v[34:37]
	v_mfma_f32_16x16x32_bf16 v[38:41], v[172:175], v[198:201], v[38:41]
	v_mfma_f32_16x16x32_bf16 v[22:25], v[172:175], v[206:209], v[22:25]
	v_mfma_f32_16x16x32_bf16 v[18:21], v[182:185], v[206:209], v[18:21]
	v_mfma_f32_16x16x32_bf16 v[2:5], v[182:185], v[214:217], v[2:5]
	v_mfma_f32_16x16x32_bf16 v[6:9], v[172:175], v[214:217], v[6:9]
	s_setprio 0
	s_barrier
	s_add_i32 s56, 0, 0x18000
	v_add_u32_e32 v151, s56, v148
	s_add_i32 s57, 0, 0x1c000
	ds_read_b128 v[152:155], v151
	ds_read_b128 v[156:159], v151 offset:1024
	ds_read_b128 v[160:163], v151 offset:2048
	ds_read_b128 v[164:167], v151 offset:3072
	v_add_u32_e32 v151, s57, v148
	ds_read_b128 v[168:171], v151
	ds_read_b128 v[172:175], v151 offset:1024
	ds_read_b128 v[178:181], v151 offset:2048
	ds_read_b128 v[182:185], v151 offset:3072
	s_add_u32 s2, s2, 0x40000
	s_addc_u32 s3, s3, 0
	s_mov_b32 m0, s36
	v_lshl_add_u64 v[224:225], s[2:3], 0, v[130:131]
	ds_read_b128 v[186:189], v150 offset:32768
	ds_read_b128 v[190:193], v150 offset:33792
	ds_read_b128 v[194:197], v150 offset:34816
	ds_read_b128 v[198:201], v150 offset:35840
	ds_read_b128 v[202:205], v150 offset:36864
	ds_read_b128 v[206:209], v150 offset:37888
	ds_read_b128 v[210:213], v150 offset:38912
	ds_read_b128 v[214:217], v150 offset:39936
	global_load_lds_dwordx4 v[224:225], off
	v_lshl_add_u64 v[224:225], s[2:3], 0, v[134:135]
	s_mov_b32 m0, s37
	s_nop 0
	global_load_lds_dwordx4 v[224:225], off
	s_waitcnt vmcnt(8)
	s_waitcnt lgkmcnt(0)
	s_barrier
	s_setprio 1
	s_waitcnt lgkmcnt(0)
	v_mfma_f32_16x16x32_bf16 v[126:129], v[152:155], v[186:189], v[126:129]
	v_mfma_f32_16x16x32_bf16 v[122:125], v[160:163], v[186:189], v[122:125]
	v_mfma_f32_16x16x32_bf16 v[106:109], v[160:163], v[194:197], v[106:109]
	v_mfma_f32_16x16x32_bf16 v[110:113], v[152:155], v[194:197], v[110:113]
	v_mfma_f32_16x16x32_bf16 v[94:97], v[152:155], v[202:205], v[94:97]
	v_mfma_f32_16x16x32_bf16 v[90:93], v[160:163], v[202:205], v[90:93]
	v_mfma_f32_16x16x32_bf16 v[74:77], v[160:163], v[210:213], v[74:77]
	v_mfma_f32_16x16x32_bf16 v[78:81], v[152:155], v[210:213], v[78:81]
	v_mfma_f32_16x16x32_bf16 v[126:129], v[156:159], v[190:193], v[126:129]
	v_mfma_f32_16x16x32_bf16 v[122:125], v[164:167], v[190:193], v[122:125]
	v_mfma_f32_16x16x32_bf16 v[106:109], v[164:167], v[198:201], v[106:109]
	v_mfma_f32_16x16x32_bf16 v[110:113], v[156:159], v[198:201], v[110:113]
	v_mfma_f32_16x16x32_bf16 v[94:97], v[156:159], v[206:209], v[94:97]
	v_mfma_f32_16x16x32_bf16 v[90:93], v[164:167], v[206:209], v[90:93]
	v_mfma_f32_16x16x32_bf16 v[74:77], v[164:167], v[214:217], v[74:77]
	v_mfma_f32_16x16x32_bf16 v[78:81], v[156:159], v[214:217], v[78:81]
	s_setprio 0
	s_setprio 1
	v_mfma_f32_16x16x32_bf16 v[118:121], v[168:171], v[186:189], v[118:121]
	v_mfma_f32_16x16x32_bf16 v[114:117], v[178:181], v[186:189], v[114:117]
	v_mfma_f32_16x16x32_bf16 v[98:101], v[178:181], v[194:197], v[98:101]
	v_mfma_f32_16x16x32_bf16 v[102:105], v[168:171], v[194:197], v[102:105]
	v_mfma_f32_16x16x32_bf16 v[86:89], v[168:171], v[202:205], v[86:89]
	v_mfma_f32_16x16x32_bf16 v[82:85], v[178:181], v[202:205], v[82:85]
	v_mfma_f32_16x16x32_bf16 v[66:69], v[178:181], v[210:213], v[66:69]
	v_mfma_f32_16x16x32_bf16 v[70:73], v[168:171], v[210:213], v[70:73]
	v_mfma_f32_16x16x32_bf16 v[118:121], v[172:175], v[190:193], v[118:121]
	v_mfma_f32_16x16x32_bf16 v[114:117], v[182:185], v[190:193], v[114:117]
	v_mfma_f32_16x16x32_bf16 v[98:101], v[182:185], v[198:201], v[98:101]
	v_mfma_f32_16x16x32_bf16 v[102:105], v[172:175], v[198:201], v[102:105]
	v_mfma_f32_16x16x32_bf16 v[86:89], v[172:175], v[206:209], v[86:89]
	v_mfma_f32_16x16x32_bf16 v[82:85], v[182:185], v[206:209], v[82:85]
	v_mfma_f32_16x16x32_bf16 v[66:69], v[182:185], v[214:217], v[66:69]
	v_mfma_f32_16x16x32_bf16 v[70:73], v[172:175], v[214:217], v[70:73]
	s_setprio 0
	s_barrier
	s_add_i32 s2, s56, s34
	v_lshl_add_u64 v[146:147], v[146:147], 0, s[6:7]
	s_mov_b32 m0, s2
	ds_read_b128 v[186:189], v150 offset:49152
	ds_read_b128 v[190:193], v150 offset:50176
	ds_read_b128 v[194:197], v150 offset:51200
	ds_read_b128 v[198:201], v150 offset:52224
	ds_read_b128 v[202:205], v150 offset:53248
	ds_read_b128 v[206:209], v150 offset:54272
	ds_read_b128 v[210:213], v150 offset:55296
	ds_read_b128 v[214:217], v150 offset:56320
	global_load_lds_dwordx4 v[146:147], off
	s_add_i32 m0, s2, 0x2000
	s_add_u32 s2, s30, 0x40080
	v_lshl_add_u64 v[146:147], v[218:219], 0, s[6:7]
	s_addc_u32 s3, s31, 0
	s_add_i32 s30, s57, s34
	global_load_lds_dwordx4 v[146:147], off
	v_lshl_add_u64 v[146:147], s[2:3], 0, v[132:133]
	s_mov_b32 m0, s30
	s_nop 0
	global_load_lds_dwordx4 v[146:147], off
	v_lshl_add_u64 v[146:147], s[2:3], 0, v[136:137]
	s_add_i32 m0, s30, 0x2000
	s_nop 0
	global_load_lds_dwordx4 v[146:147], off
	v_lshl_add_u64 v[146:147], v[220:221], 0, s[6:7]
	s_mov_b32 m0, s40
	s_nop 0
	global_load_lds_dwordx4 v[146:147], off
	v_lshl_add_u64 v[146:147], v[222:223], 0, s[6:7]
	s_mov_b32 m0, s41
	s_nop 0
	global_load_lds_dwordx4 v[146:147], off
	s_waitcnt vmcnt(8)
	s_waitcnt lgkmcnt(0)
	s_barrier
	s_setprio 1
	s_waitcnt lgkmcnt(0)
	v_mfma_f32_16x16x32_bf16 v[62:65], v[152:155], v[186:189], v[62:65]
	v_mfma_f32_16x16x32_bf16 v[58:61], v[160:163], v[186:189], v[58:61]
	v_mfma_f32_16x16x32_bf16 v[42:45], v[160:163], v[194:197], v[42:45]
	v_mfma_f32_16x16x32_bf16 v[46:49], v[152:155], v[194:197], v[46:49]
	v_mfma_f32_16x16x32_bf16 v[30:33], v[152:155], v[202:205], v[30:33]
	v_mfma_f32_16x16x32_bf16 v[26:29], v[160:163], v[202:205], v[26:29]
	v_mfma_f32_16x16x32_bf16 v[10:13], v[160:163], v[210:213], v[10:13]
	v_mfma_f32_16x16x32_bf16 v[14:17], v[152:155], v[210:213], v[14:17]
	v_mfma_f32_16x16x32_bf16 v[62:65], v[156:159], v[190:193], v[62:65]
	v_mfma_f32_16x16x32_bf16 v[58:61], v[164:167], v[190:193], v[58:61]
	v_mfma_f32_16x16x32_bf16 v[42:45], v[164:167], v[198:201], v[42:45]
	v_mfma_f32_16x16x32_bf16 v[46:49], v[156:159], v[198:201], v[46:49]
	v_mfma_f32_16x16x32_bf16 v[30:33], v[156:159], v[206:209], v[30:33]
	v_mfma_f32_16x16x32_bf16 v[26:29], v[164:167], v[206:209], v[26:29]
	v_mfma_f32_16x16x32_bf16 v[10:13], v[164:167], v[214:217], v[10:13]
	v_mfma_f32_16x16x32_bf16 v[14:17], v[156:159], v[214:217], v[14:17]
	s_setprio 0
	s_setprio 1
	v_mfma_f32_16x16x32_bf16 v[54:57], v[168:171], v[186:189], v[54:57]
	v_mfma_f32_16x16x32_bf16 v[50:53], v[178:181], v[186:189], v[50:53]
	v_mfma_f32_16x16x32_bf16 v[34:37], v[178:181], v[194:197], v[34:37]
	v_mfma_f32_16x16x32_bf16 v[38:41], v[168:171], v[194:197], v[38:41]
	v_mfma_f32_16x16x32_bf16 v[22:25], v[168:171], v[202:205], v[22:25]
	v_mfma_f32_16x16x32_bf16 v[18:21], v[178:181], v[202:205], v[18:21]
	v_mfma_f32_16x16x32_bf16 v[2:5], v[178:181], v[210:213], v[2:5]
	v_mfma_f32_16x16x32_bf16 v[6:9], v[168:171], v[210:213], v[6:9]
	v_mfma_f32_16x16x32_bf16 v[54:57], v[172:175], v[190:193], v[54:57]
	v_mfma_f32_16x16x32_bf16 v[50:53], v[182:185], v[190:193], v[50:53]
	v_mfma_f32_16x16x32_bf16 v[34:37], v[182:185], v[198:201], v[34:37]
	v_mfma_f32_16x16x32_bf16 v[38:41], v[172:175], v[198:201], v[38:41]
	v_mfma_f32_16x16x32_bf16 v[22:25], v[172:175], v[206:209], v[22:25]
	v_mfma_f32_16x16x32_bf16 v[18:21], v[182:185], v[206:209], v[18:21]
	v_mfma_f32_16x16x32_bf16 v[2:5], v[182:185], v[214:217], v[2:5]
	v_mfma_f32_16x16x32_bf16 v[6:9], v[172:175], v[214:217], v[6:9]
	s_setprio 0
	s_barrier
	s_add_i32 s55, s55, 2
	s_add_u32 s28, s28, 0x100
	s_addc_u32 s29, s29, 0
	s_add_u32 s53, s53, 0x100
	s_addc_u32 s54, s54, 0
	s_cmp_gt_u32 s55, 13
	s_cbranch_scc0 .LBB0_1400
	s_branch .Lpk1400_exit
.LBB0_1400:
	ds_read_b128 v[152:155], v1
	ds_read_b128 v[156:159], v1 offset:1024
	ds_read_b128 v[160:163], v1 offset:2048
	ds_read_b128 v[164:167], v1 offset:3072
	ds_read_b128 v[168:171], v149
	ds_read_b128 v[172:175], v149 offset:1024
	ds_read_b128 v[178:181], v149 offset:2048
	ds_read_b128 v[182:185], v149 offset:3072
	s_add_u32 s2, s28, 0xfffc0080
	s_addc_u32 s3, s29, -1
	s_cmp_eq_u32 s55, 12
	s_cselect_b32 s3, s11, s3
	s_cselect_b32 s2, s13, s2
	s_cselect_b32 s31, s47, s54
	s_cselect_b32 s30, s52, s53
	v_lshl_add_u64 v[146:147], s[28:29], 0, v[140:141]
	s_add_i32 m0, s25, 0xc000
	ds_read_b128 v[186:189], v150
	ds_read_b128 v[190:193], v150 offset:1024
	ds_read_b128 v[194:197], v150 offset:2048
	ds_read_b128 v[198:201], v150 offset:3072
	ds_read_b128 v[202:205], v150 offset:4096
	ds_read_b128 v[206:209], v150 offset:5120
	ds_read_b128 v[210:213], v150 offset:6144
	ds_read_b128 v[214:217], v150 offset:7168
	global_load_lds_dwordx4 v[146:147], off
	v_lshl_add_u64 v[146:147], s[28:29], 0, v[142:143]
	s_add_i32 m0, s25, 0xe000
	s_nop 0
	global_load_lds_dwordx4 v[146:147], off
	s_waitcnt vmcnt(8)
	s_waitcnt lgkmcnt(0)
	s_barrier
	s_setprio 1
	s_waitcnt lgkmcnt(0)
	v_mfma_f32_16x16x32_bf16 v[126:129], v[152:155], v[186:189], v[126:129]
	v_mfma_f32_16x16x32_bf16 v[122:125], v[160:163], v[186:189], v[122:125]
	v_mfma_f32_16x16x32_bf16 v[106:109], v[160:163], v[194:197], v[106:109]
	v_mfma_f32_16x16x32_bf16 v[110:113], v[152:155], v[194:197], v[110:113]
	v_mfma_f32_16x16x32_bf16 v[94:97], v[152:155], v[202:205], v[94:97]
	v_mfma_f32_16x16x32_bf16 v[90:93], v[160:163], v[202:205], v[90:93]
	v_mfma_f32_16x16x32_bf16 v[74:77], v[160:163], v[210:213], v[74:77]
	v_mfma_f32_16x16x32_bf16 v[78:81], v[152:155], v[210:213], v[78:81]
	v_mfma_f32_16x16x32_bf16 v[126:129], v[156:159], v[190:193], v[126:129]
	v_mfma_f32_16x16x32_bf16 v[122:125], v[164:167], v[190:193], v[122:125]
	v_mfma_f32_16x16x32_bf16 v[106:109], v[164:167], v[198:201], v[106:109]
	v_mfma_f32_16x16x32_bf16 v[110:113], v[156:159], v[198:201], v[110:113]
	v_mfma_f32_16x16x32_bf16 v[94:97], v[156:159], v[206:209], v[94:97]
	v_mfma_f32_16x16x32_bf16 v[90:93], v[164:167], v[206:209], v[90:93]
	v_mfma_f32_16x16x32_bf16 v[74:77], v[164:167], v[214:217], v[74:77]
	v_mfma_f32_16x16x32_bf16 v[78:81], v[156:159], v[214:217], v[78:81]
	s_setprio 0
	s_setprio 1
	v_mfma_f32_16x16x32_bf16 v[118:121], v[168:171], v[186:189], v[118:121]
	v_mfma_f32_16x16x32_bf16 v[114:117], v[178:181], v[186:189], v[114:117]
	v_mfma_f32_16x16x32_bf16 v[98:101], v[178:181], v[194:197], v[98:101]
	v_mfma_f32_16x16x32_bf16 v[102:105], v[168:171], v[194:197], v[102:105]
	v_mfma_f32_16x16x32_bf16 v[86:89], v[168:171], v[202:205], v[86:89]
	v_mfma_f32_16x16x32_bf16 v[82:85], v[178:181], v[202:205], v[82:85]
	v_mfma_f32_16x16x32_bf16 v[66:69], v[178:181], v[210:213], v[66:69]
	v_mfma_f32_16x16x32_bf16 v[70:73], v[168:171], v[210:213], v[70:73]
	v_mfma_f32_16x16x32_bf16 v[118:121], v[172:175], v[190:193], v[118:121]
	v_mfma_f32_16x16x32_bf16 v[114:117], v[182:185], v[190:193], v[114:117]
	v_mfma_f32_16x16x32_bf16 v[98:101], v[182:185], v[198:201], v[98:101]
	v_mfma_f32_16x16x32_bf16 v[102:105], v[172:175], v[198:201], v[102:105]
	v_mfma_f32_16x16x32_bf16 v[86:89], v[172:175], v[206:209], v[86:89]
	v_mfma_f32_16x16x32_bf16 v[82:85], v[182:185], v[206:209], v[82:85]
	v_mfma_f32_16x16x32_bf16 v[66:69], v[182:185], v[214:217], v[66:69]
	v_mfma_f32_16x16x32_bf16 v[70:73], v[172:175], v[214:217], v[70:73]
	s_setprio 0
	s_barrier
	s_add_i32 s56, s43, s34
	v_lshl_add_u64 v[146:147], s[30:31], 0, v[132:133]
	s_mov_b32 m0, s56
	ds_read_b128 v[186:189], v150 offset:16384
	ds_read_b128 v[190:193], v150 offset:17408
	ds_read_b128 v[194:197], v150 offset:18432
	ds_read_b128 v[198:201], v150 offset:19456
	ds_read_b128 v[202:205], v150 offset:20480
	ds_read_b128 v[206:209], v150 offset:21504
	ds_read_b128 v[210:213], v150 offset:22528
	ds_read_b128 v[214:217], v150 offset:23552
	global_load_lds_dwordx4 v[146:147], off
	s_add_i32 m0, s56, 0x2000
	s_add_u32 s56, s30, 0x40000
	v_lshl_add_u64 v[218:219], s[30:31], 0, v[136:137]
	s_addc_u32 s57, s31, 0
	s_add_i32 s58, s44, s34
	global_load_lds_dwordx4 v[218:219], off
	v_lshl_add_u64 v[220:221], s[56:57], 0, v[132:133]
	s_mov_b32 m0, s58
	v_lshl_add_u64 v[222:223], s[2:3], 0, v[134:135]
	global_load_lds_dwordx4 v[220:221], off
	v_lshl_add_u64 v[220:221], s[56:57], 0, v[136:137]
	s_add_i32 m0, s58, 0x2000
	s_nop 0
	global_load_lds_dwordx4 v[220:221], off
	v_lshl_add_u64 v[220:221], s[2:3], 0, v[130:131]
	s_mov_b32 m0, s25
	s_nop 0
	global_load_lds_dwordx4 v[220:221], off
	s_mov_b32 m0, s27
	s_nop 0
	global_load_lds_dwordx4 v[222:223], off
	s_waitcnt vmcnt(8)
	s_waitcnt lgkmcnt(0)
	s_barrier
	s_setprio 1
	s_waitcnt lgkmcnt(0)
	v_mfma_f32_16x16x32_bf16 v[62:65], v[152:155], v[186:189], v[62:65]
	v_mfma_f32_16x16x32_bf16 v[58:61], v[160:163], v[186:189], v[58:61]
	v_mfma_f32_16x16x32_bf16 v[42:45], v[160:163], v[194:197], v[42:45]
	v_mfma_f32_16x16x32_bf16 v[46:49], v[152:155], v[194:197], v[46:49]
	v_mfma_f32_16x16x32_bf16 v[30:33], v[152:155], v[202:205], v[30:33]
	v_mfma_f32_16x16x32_bf16 v[26:29], v[160:163], v[202:205], v[26:29]
	v_mfma_f32_16x16x32_bf16 v[10:13], v[160:163], v[210:213], v[10:13]
	v_mfma_f32_16x16x32_bf16 v[14:17], v[152:155], v[210:213], v[14:17]
	v_mfma_f32_16x16x32_bf16 v[62:65], v[156:159], v[190:193], v[62:65]
	v_mfma_f32_16x16x32_bf16 v[58:61], v[164:167], v[190:193], v[58:61]
	v_mfma_f32_16x16x32_bf16 v[42:45], v[164:167], v[198:201], v[42:45]
	v_mfma_f32_16x16x32_bf16 v[46:49], v[156:159], v[198:201], v[46:49]
	v_mfma_f32_16x16x32_bf16 v[30:33], v[156:159], v[206:209], v[30:33]
	v_mfma_f32_16x16x32_bf16 v[26:29], v[164:167], v[206:209], v[26:29]
	v_mfma_f32_16x16x32_bf16 v[10:13], v[164:167], v[214:217], v[10:13]
	v_mfma_f32_16x16x32_bf16 v[14:17], v[156:159], v[214:217], v[14:17]
	s_setprio 0
	s_setprio 1
	v_mfma_f32_16x16x32_bf16 v[54:57], v[168:171], v[186:189], v[54:57]
	v_mfma_f32_16x16x32_bf16 v[50:53], v[178:181], v[186:189], v[50:53]
	v_mfma_f32_16x16x32_bf16 v[34:37], v[178:181], v[194:197], v[34:37]
	v_mfma_f32_16x16x32_bf16 v[38:41], v[168:171], v[194:197], v[38:41]
	v_mfma_f32_16x16x32_bf16 v[22:25], v[168:171], v[202:205], v[22:25]
	v_mfma_f32_16x16x32_bf16 v[18:21], v[178:181], v[202:205], v[18:21]
	v_mfma_f32_16x16x32_bf16 v[2:5], v[178:181], v[210:213], v[2:5]
	v_mfma_f32_16x16x32_bf16 v[6:9], v[168:171], v[210:213], v[6:9]
	v_mfma_f32_16x16x32_bf16 v[54:57], v[172:175], v[190:193], v[54:57]
	v_mfma_f32_16x16x32_bf16 v[50:53], v[182:185], v[190:193], v[50:53]
	v_mfma_f32_16x16x32_bf16 v[34:37], v[182:185], v[198:201], v[34:37]
	v_mfma_f32_16x16x32_bf16 v[38:41], v[172:175], v[198:201], v[38:41]
	v_mfma_f32_16x16x32_bf16 v[22:25], v[172:175], v[206:209], v[22:25]
	v_mfma_f32_16x16x32_bf16 v[18:21], v[182:185], v[206:209], v[18:21]
	v_mfma_f32_16x16x32_bf16 v[2:5], v[182:185], v[214:217], v[2:5]
	v_mfma_f32_16x16x32_bf16 v[6:9], v[172:175], v[214:217], v[6:9]
	s_setprio 0
	s_barrier
	s_add_i32 s56, 0, 0x18000
	v_add_u32_e32 v151, s56, v148
	s_add_i32 s57, 0, 0x1c000
	ds_read_b128 v[152:155], v151
	ds_read_b128 v[156:159], v151 offset:1024
	ds_read_b128 v[160:163], v151 offset:2048
	ds_read_b128 v[164:167], v151 offset:3072
	v_add_u32_e32 v151, s57, v148
	ds_read_b128 v[168:171], v151
	ds_read_b128 v[172:175], v151 offset:1024
	ds_read_b128 v[178:181], v151 offset:2048
	ds_read_b128 v[182:185], v151 offset:3072
	s_add_u32 s2, s2, 0x40000
	s_addc_u32 s3, s3, 0
	s_mov_b32 m0, s36
	v_lshl_add_u64 v[224:225], s[2:3], 0, v[130:131]
	ds_read_b128 v[186:189], v150 offset:32768
	ds_read_b128 v[190:193], v150 offset:33792
	ds_read_b128 v[194:197], v150 offset:34816
	ds_read_b128 v[198:201], v150 offset:35840
	ds_read_b128 v[202:205], v150 offset:36864
	ds_read_b128 v[206:209], v150 offset:37888
	ds_read_b128 v[210:213], v150 offset:38912
	ds_read_b128 v[214:217], v150 offset:39936
	global_load_lds_dwordx4 v[224:225], off
	v_lshl_add_u64 v[224:225], s[2:3], 0, v[134:135]
	s_mov_b32 m0, s37
	s_nop 0
	global_load_lds_dwordx4 v[224:225], off
	s_waitcnt vmcnt(8)
	s_waitcnt lgkmcnt(0)
	s_barrier
	s_setprio 1
	s_waitcnt lgkmcnt(0)
	v_mfma_f32_16x16x32_bf16 v[126:129], v[152:155], v[186:189], v[126:129]
	v_mfma_f32_16x16x32_bf16 v[122:125], v[160:163], v[186:189], v[122:125]
	v_mfma_f32_16x16x32_bf16 v[106:109], v[160:163], v[194:197], v[106:109]
	v_mfma_f32_16x16x32_bf16 v[110:113], v[152:155], v[194:197], v[110:113]
	v_mfma_f32_16x16x32_bf16 v[94:97], v[152:155], v[202:205], v[94:97]
	v_mfma_f32_16x16x32_bf16 v[90:93], v[160:163], v[202:205], v[90:93]
	v_mfma_f32_16x16x32_bf16 v[74:77], v[160:163], v[210:213], v[74:77]
	v_mfma_f32_16x16x32_bf16 v[78:81], v[152:155], v[210:213], v[78:81]
	v_mfma_f32_16x16x32_bf16 v[126:129], v[156:159], v[190:193], v[126:129]
	v_mfma_f32_16x16x32_bf16 v[122:125], v[164:167], v[190:193], v[122:125]
	v_mfma_f32_16x16x32_bf16 v[106:109], v[164:167], v[198:201], v[106:109]
	v_mfma_f32_16x16x32_bf16 v[110:113], v[156:159], v[198:201], v[110:113]
	v_mfma_f32_16x16x32_bf16 v[94:97], v[156:159], v[206:209], v[94:97]
	v_mfma_f32_16x16x32_bf16 v[90:93], v[164:167], v[206:209], v[90:93]
	v_mfma_f32_16x16x32_bf16 v[74:77], v[164:167], v[214:217], v[74:77]
	v_mfma_f32_16x16x32_bf16 v[78:81], v[156:159], v[214:217], v[78:81]
	s_setprio 0
	s_setprio 1
	v_mfma_f32_16x16x32_bf16 v[118:121], v[168:171], v[186:189], v[118:121]
	v_mfma_f32_16x16x32_bf16 v[114:117], v[178:181], v[186:189], v[114:117]
	v_mfma_f32_16x16x32_bf16 v[98:101], v[178:181], v[194:197], v[98:101]
	v_mfma_f32_16x16x32_bf16 v[102:105], v[168:171], v[194:197], v[102:105]
	v_mfma_f32_16x16x32_bf16 v[86:89], v[168:171], v[202:205], v[86:89]
	v_mfma_f32_16x16x32_bf16 v[82:85], v[178:181], v[202:205], v[82:85]
	v_mfma_f32_16x16x32_bf16 v[66:69], v[178:181], v[210:213], v[66:69]
	v_mfma_f32_16x16x32_bf16 v[70:73], v[168:171], v[210:213], v[70:73]
	v_mfma_f32_16x16x32_bf16 v[118:121], v[172:175], v[190:193], v[118:121]
	v_mfma_f32_16x16x32_bf16 v[114:117], v[182:185], v[190:193], v[114:117]
	v_mfma_f32_16x16x32_bf16 v[98:101], v[182:185], v[198:201], v[98:101]
	v_mfma_f32_16x16x32_bf16 v[102:105], v[172:175], v[198:201], v[102:105]
	v_mfma_f32_16x16x32_bf16 v[86:89], v[172:175], v[206:209], v[86:89]
	v_mfma_f32_16x16x32_bf16 v[82:85], v[182:185], v[206:209], v[82:85]
	v_mfma_f32_16x16x32_bf16 v[66:69], v[182:185], v[214:217], v[66:69]
	v_mfma_f32_16x16x32_bf16 v[70:73], v[172:175], v[214:217], v[70:73]
	s_setprio 0
	s_barrier
	s_add_i32 s2, s56, s34
	v_lshl_add_u64 v[146:147], v[146:147], 0, s[6:7]
	s_mov_b32 m0, s2
	ds_read_b128 v[186:189], v150 offset:49152
	ds_read_b128 v[190:193], v150 offset:50176
	ds_read_b128 v[194:197], v150 offset:51200
	ds_read_b128 v[198:201], v150 offset:52224
	ds_read_b128 v[202:205], v150 offset:53248
	ds_read_b128 v[206:209], v150 offset:54272
	ds_read_b128 v[210:213], v150 offset:55296
	ds_read_b128 v[214:217], v150 offset:56320
	global_load_lds_dwordx4 v[146:147], off
	s_add_i32 m0, s2, 0x2000
	s_add_u32 s2, s30, 0x40080
	v_lshl_add_u64 v[146:147], v[218:219], 0, s[6:7]
	s_addc_u32 s3, s31, 0
	s_add_i32 s30, s57, s34
	global_load_lds_dwordx4 v[146:147], off
	v_lshl_add_u64 v[146:147], s[2:3], 0, v[132:133]
	s_mov_b32 m0, s30
	s_nop 0
	global_load_lds_dwordx4 v[146:147], off
	v_lshl_add_u64 v[146:147], s[2:3], 0, v[136:137]
	s_add_i32 m0, s30, 0x2000
	s_nop 0
	global_load_lds_dwordx4 v[146:147], off
	v_lshl_add_u64 v[146:147], v[220:221], 0, s[6:7]
	s_mov_b32 m0, s40
	s_nop 0
	global_load_lds_dwordx4 v[146:147], off
	v_lshl_add_u64 v[146:147], v[222:223], 0, s[6:7]
	s_mov_b32 m0, s41
	s_nop 0
	global_load_lds_dwordx4 v[146:147], off
	s_waitcnt vmcnt(8)
	s_waitcnt lgkmcnt(0)
	s_barrier
	s_setprio 1
	s_waitcnt lgkmcnt(0)
	v_mfma_f32_16x16x32_bf16 v[62:65], v[152:155], v[186:189], v[62:65]
	v_mfma_f32_16x16x32_bf16 v[58:61], v[160:163], v[186:189], v[58:61]
	v_mfma_f32_16x16x32_bf16 v[42:45], v[160:163], v[194:197], v[42:45]
	v_mfma_f32_16x16x32_bf16 v[46:49], v[152:155], v[194:197], v[46:49]
	v_mfma_f32_16x16x32_bf16 v[30:33], v[152:155], v[202:205], v[30:33]
	v_mfma_f32_16x16x32_bf16 v[26:29], v[160:163], v[202:205], v[26:29]
	v_mfma_f32_16x16x32_bf16 v[10:13], v[160:163], v[210:213], v[10:13]
	v_mfma_f32_16x16x32_bf16 v[14:17], v[152:155], v[210:213], v[14:17]
	v_mfma_f32_16x16x32_bf16 v[62:65], v[156:159], v[190:193], v[62:65]
	v_mfma_f32_16x16x32_bf16 v[58:61], v[164:167], v[190:193], v[58:61]
	v_mfma_f32_16x16x32_bf16 v[42:45], v[164:167], v[198:201], v[42:45]
	v_mfma_f32_16x16x32_bf16 v[46:49], v[156:159], v[198:201], v[46:49]
	v_mfma_f32_16x16x32_bf16 v[30:33], v[156:159], v[206:209], v[30:33]
	v_mfma_f32_16x16x32_bf16 v[26:29], v[164:167], v[206:209], v[26:29]
	v_mfma_f32_16x16x32_bf16 v[10:13], v[164:167], v[214:217], v[10:13]
	v_mfma_f32_16x16x32_bf16 v[14:17], v[156:159], v[214:217], v[14:17]
	s_setprio 0
	s_setprio 1
	v_mfma_f32_16x16x32_bf16 v[54:57], v[168:171], v[186:189], v[54:57]
	v_mfma_f32_16x16x32_bf16 v[50:53], v[178:181], v[186:189], v[50:53]
	v_mfma_f32_16x16x32_bf16 v[34:37], v[178:181], v[194:197], v[34:37]
	v_mfma_f32_16x16x32_bf16 v[38:41], v[168:171], v[194:197], v[38:41]
	v_mfma_f32_16x16x32_bf16 v[22:25], v[168:171], v[202:205], v[22:25]
	v_mfma_f32_16x16x32_bf16 v[18:21], v[178:181], v[202:205], v[18:21]
	v_mfma_f32_16x16x32_bf16 v[2:5], v[178:181], v[210:213], v[2:5]
	v_mfma_f32_16x16x32_bf16 v[6:9], v[168:171], v[210:213], v[6:9]
	v_mfma_f32_16x16x32_bf16 v[54:57], v[172:175], v[190:193], v[54:57]
	v_mfma_f32_16x16x32_bf16 v[50:53], v[182:185], v[190:193], v[50:53]
	v_mfma_f32_16x16x32_bf16 v[34:37], v[182:185], v[198:201], v[34:37]
	v_mfma_f32_16x16x32_bf16 v[38:41], v[172:175], v[198:201], v[38:41]
	v_mfma_f32_16x16x32_bf16 v[22:25], v[172:175], v[206:209], v[22:25]
	v_mfma_f32_16x16x32_bf16 v[18:21], v[182:185], v[206:209], v[18:21]
	v_mfma_f32_16x16x32_bf16 v[2:5], v[182:185], v[214:217], v[2:5]
	v_mfma_f32_16x16x32_bf16 v[6:9], v[172:175], v[214:217], v[6:9]
	s_setprio 0
	s_barrier
	s_add_i32 s55, s55, 2
	s_add_u32 s28, s28, 0x100
	s_addc_u32 s29, s29, 0
	s_add_u32 s53, s53, 0x100
	s_addc_u32 s54, s54, 0
	s_cmp_gt_u32 s55, 13
	s_cbranch_scc0 .LBB0_1400

.Lpk1444_peel:
	ds_read_b128 v[152:155], v148
	ds_read_b128 v[156:159], v148 offset:1024
	ds_read_b128 v[160:163], v148 offset:2048
	ds_read_b128 v[164:167], v148 offset:3072
	ds_read_b128 v[168:171], v149
	ds_read_b128 v[172:175], v149 offset:1024
	ds_read_b128 v[178:181], v149 offset:2048
	ds_read_b128 v[182:185], v149 offset:3072
	s_add_u32 s2, s26, 0x4000
	s_addc_u32 s3, s27, 0
	s_cmp_eq_u32 s62, 40
	s_cselect_b32 s2, s57, s2
	s_cselect_b32 s3, s56, s3
	s_cselect_b32 s31, s58, s61
	s_cselect_b32 s30, s59, s60
	s_add_u32 s28, s2, 0x8000
	s_addc_u32 s29, s3, 0
	v_lshl_add_u64 v[144:145], s[26:27], 0, v[138:139]
	s_add_i32 m0, s39, 0xc000
	ds_read_b128 v[186:189], v150
	ds_read_b128 v[190:193], v150 offset:1024
	ds_read_b128 v[194:197], v150 offset:2048
	ds_read_b128 v[198:201], v150 offset:3072
	ds_read_b128 v[202:205], v150 offset:4096
	ds_read_b128 v[206:209], v150 offset:5120
	ds_read_b128 v[210:213], v150 offset:6144
	ds_read_b128 v[214:217], v150 offset:7168
	global_load_lds_dwordx4 v[144:145], off
	v_lshl_add_u64 v[144:145], s[26:27], 0, v[140:141]
	s_add_i32 m0, s39, 0xe000
	s_nop 0
	global_load_lds_dwordx4 v[144:145], off
	s_waitcnt vmcnt(8)
	s_waitcnt lgkmcnt(0)
	s_barrier
	s_setprio 1
	s_waitcnt lgkmcnt(0)
	v_mfma_f32_16x16x32_bf16 v[126:129], v[152:155], v[186:189], 0
	v_mfma_f32_16x16x32_bf16 v[122:125], v[160:163], v[186:189], 0
	v_mfma_f32_16x16x32_bf16 v[106:109], v[160:163], v[194:197], 0
	v_mfma_f32_16x16x32_bf16 v[114:117], v[152:155], v[194:197], 0
	v_mfma_f32_16x16x32_bf16 v[98:101], v[152:155], v[202:205], 0
	v_mfma_f32_16x16x32_bf16 v[90:93], v[160:163], v[202:205], 0
	v_mfma_f32_16x16x32_bf16 v[74:77], v[160:163], v[210:213], 0
	v_mfma_f32_16x16x32_bf16 v[82:85], v[152:155], v[210:213], 0
	v_mfma_f32_16x16x32_bf16 v[126:129], v[156:159], v[190:193], v[126:129]
	v_mfma_f32_16x16x32_bf16 v[122:125], v[164:167], v[190:193], v[122:125]
	v_mfma_f32_16x16x32_bf16 v[106:109], v[164:167], v[198:201], v[106:109]
	v_mfma_f32_16x16x32_bf16 v[114:117], v[156:159], v[198:201], v[114:117]
	v_mfma_f32_16x16x32_bf16 v[98:101], v[156:159], v[206:209], v[98:101]
	v_mfma_f32_16x16x32_bf16 v[90:93], v[164:167], v[206:209], v[90:93]
	v_mfma_f32_16x16x32_bf16 v[74:77], v[164:167], v[214:217], v[74:77]
	v_mfma_f32_16x16x32_bf16 v[82:85], v[156:159], v[214:217], v[82:85]
	s_setprio 0
	s_setprio 1
	v_mfma_f32_16x16x32_bf16 v[118:121], v[168:171], v[186:189], 0
	v_mfma_f32_16x16x32_bf16 v[110:113], v[178:181], v[186:189], 0
	v_mfma_f32_16x16x32_bf16 v[94:97], v[178:181], v[194:197], 0
	v_mfma_f32_16x16x32_bf16 v[102:105], v[168:171], v[194:197], 0
	v_mfma_f32_16x16x32_bf16 v[86:89], v[168:171], v[202:205], 0
	v_mfma_f32_16x16x32_bf16 v[78:81], v[178:181], v[202:205], 0
	v_mfma_f32_16x16x32_bf16 v[66:69], v[178:181], v[210:213], 0
	v_mfma_f32_16x16x32_bf16 v[70:73], v[168:171], v[210:213], 0
	v_mfma_f32_16x16x32_bf16 v[118:121], v[172:175], v[190:193], v[118:121]
	v_mfma_f32_16x16x32_bf16 v[110:113], v[182:185], v[190:193], v[110:113]
	v_mfma_f32_16x16x32_bf16 v[94:97], v[182:185], v[198:201], v[94:97]
	v_mfma_f32_16x16x32_bf16 v[102:105], v[172:175], v[198:201], v[102:105]
	v_mfma_f32_16x16x32_bf16 v[86:89], v[172:175], v[206:209], v[86:89]
	v_mfma_f32_16x16x32_bf16 v[78:81], v[182:185], v[206:209], v[78:81]
	v_mfma_f32_16x16x32_bf16 v[66:69], v[182:185], v[214:217], v[66:69]
	v_mfma_f32_16x16x32_bf16 v[70:73], v[172:175], v[214:217], v[70:73]
	s_setprio 0
	s_barrier
	s_add_i32 s63, s46, s38
	v_lshl_add_u64 v[144:145], s[30:31], 0, v[132:133]
	s_mov_b32 m0, s63
	ds_read_b128 v[186:189], v150 offset:16384
	ds_read_b128 v[190:193], v150 offset:17408
	ds_read_b128 v[194:197], v150 offset:18432
	ds_read_b128 v[198:201], v150 offset:19456
	ds_read_b128 v[202:205], v150 offset:20480
	ds_read_b128 v[206:209], v150 offset:21504
	ds_read_b128 v[210:213], v150 offset:22528
	ds_read_b128 v[214:217], v150 offset:23552
	global_load_lds_dwordx4 v[144:145], off
	s_add_i32 m0, s63, 0x2000
	s_add_u32 s64, s30, 0x4000
	v_lshl_add_u64 v[144:145], s[30:31], 0, v[136:137]
	s_addc_u32 s65, s31, 0
	s_add_i32 s63, s47, s38
	global_load_lds_dwordx4 v[144:145], off
	v_lshl_add_u64 v[144:145], s[64:65], 0, v[132:133]
	s_mov_b32 m0, s63
	s_nop 0
	global_load_lds_dwordx4 v[144:145], off
	v_lshl_add_u64 v[144:145], s[64:65], 0, v[136:137]
	s_add_i32 m0, s63, 0x2000
	s_nop 0
	global_load_lds_dwordx4 v[144:145], off
	v_lshl_add_u64 v[144:145], s[2:3], 0, v[130:131]
	s_mov_b32 m0, s39
	s_nop 0
	global_load_lds_dwordx4 v[144:145], off
	v_lshl_add_u64 v[144:145], s[2:3], 0, v[134:135]
	s_mov_b32 m0, s40
	s_nop 0
	global_load_lds_dwordx4 v[144:145], off
	s_waitcnt vmcnt(8)
	s_waitcnt lgkmcnt(0)
	s_barrier
	s_setprio 1
	s_waitcnt lgkmcnt(0)
	v_mfma_f32_16x16x32_bf16 v[62:65], v[152:155], v[186:189], 0
	v_mfma_f32_16x16x32_bf16 v[58:61], v[160:163], v[186:189], 0
	v_mfma_f32_16x16x32_bf16 v[42:45], v[160:163], v[194:197], 0
	v_mfma_f32_16x16x32_bf16 v[50:53], v[152:155], v[194:197], 0
	v_mfma_f32_16x16x32_bf16 v[34:37], v[152:155], v[202:205], 0
	v_mfma_f32_16x16x32_bf16 v[26:29], v[160:163], v[202:205], 0
	v_mfma_f32_16x16x32_bf16 v[10:13], v[160:163], v[210:213], 0
	v_mfma_f32_16x16x32_bf16 v[18:21], v[152:155], v[210:213], 0
	v_mfma_f32_16x16x32_bf16 v[62:65], v[156:159], v[190:193], v[62:65]
	v_mfma_f32_16x16x32_bf16 v[58:61], v[164:167], v[190:193], v[58:61]
	v_mfma_f32_16x16x32_bf16 v[42:45], v[164:167], v[198:201], v[42:45]
	v_mfma_f32_16x16x32_bf16 v[50:53], v[156:159], v[198:201], v[50:53]
	v_mfma_f32_16x16x32_bf16 v[34:37], v[156:159], v[206:209], v[34:37]
	v_mfma_f32_16x16x32_bf16 v[26:29], v[164:167], v[206:209], v[26:29]
	v_mfma_f32_16x16x32_bf16 v[10:13], v[164:167], v[214:217], v[10:13]
	v_mfma_f32_16x16x32_bf16 v[18:21], v[156:159], v[214:217], v[18:21]
	s_setprio 0
	s_setprio 1
	v_mfma_f32_16x16x32_bf16 v[54:57], v[168:171], v[186:189], 0
	v_mfma_f32_16x16x32_bf16 v[46:49], v[178:181], v[186:189], 0
	v_mfma_f32_16x16x32_bf16 v[30:33], v[178:181], v[194:197], 0
	v_mfma_f32_16x16x32_bf16 v[38:41], v[168:171], v[194:197], 0
	v_mfma_f32_16x16x32_bf16 v[22:25], v[168:171], v[202:205], 0
	v_mfma_f32_16x16x32_bf16 v[14:17], v[178:181], v[202:205], 0
	v_mfma_f32_16x16x32_bf16 v[2:5], v[178:181], v[210:213], 0
	v_mfma_f32_16x16x32_bf16 v[6:9], v[168:171], v[210:213], 0
	v_mfma_f32_16x16x32_bf16 v[54:57], v[172:175], v[190:193], v[54:57]
	v_mfma_f32_16x16x32_bf16 v[46:49], v[182:185], v[190:193], v[46:49]
	v_mfma_f32_16x16x32_bf16 v[30:33], v[182:185], v[198:201], v[30:33]
	v_mfma_f32_16x16x32_bf16 v[38:41], v[172:175], v[198:201], v[38:41]
	v_mfma_f32_16x16x32_bf16 v[22:25], v[172:175], v[206:209], v[22:25]
	v_mfma_f32_16x16x32_bf16 v[14:17], v[182:185], v[206:209], v[14:17]
	v_mfma_f32_16x16x32_bf16 v[2:5], v[182:185], v[214:217], v[2:5]
	v_mfma_f32_16x16x32_bf16 v[6:9], v[172:175], v[214:217], v[6:9]
	s_setprio 0
	s_barrier
	s_add_i32 s63, 0, 0x18000
	v_add_u32_e32 v144, s63, v146
	s_add_i32 s64, 0, 0x1c000
	ds_read_b128 v[152:155], v144
	ds_read_b128 v[156:159], v144 offset:1024
	ds_read_b128 v[160:163], v144 offset:2048
	ds_read_b128 v[164:167], v144 offset:3072
	v_add_u32_e32 v144, s64, v146
	ds_read_b128 v[168:171], v144
	ds_read_b128 v[172:175], v144 offset:1024
	ds_read_b128 v[178:181], v144 offset:2048
	ds_read_b128 v[182:185], v144 offset:3072
	s_add_u32 s2, s2, 0x4000
	s_addc_u32 s3, s3, 0
	s_mov_b32 m0, s41
	v_lshl_add_u64 v[144:145], s[2:3], 0, v[130:131]
	ds_read_b128 v[186:189], v150 offset:32768
	ds_read_b128 v[190:193], v150 offset:33792
	ds_read_b128 v[194:197], v150 offset:34816
	ds_read_b128 v[198:201], v150 offset:35840
	ds_read_b128 v[202:205], v150 offset:36864
	ds_read_b128 v[206:209], v150 offset:37888
	ds_read_b128 v[210:213], v150 offset:38912
	ds_read_b128 v[214:217], v150 offset:39936
	global_load_lds_dwordx4 v[144:145], off
	v_lshl_add_u64 v[144:145], s[2:3], 0, v[134:135]
	s_mov_b32 m0, s42
	s_nop 0
	global_load_lds_dwordx4 v[144:145], off
	s_waitcnt vmcnt(8)
	s_waitcnt lgkmcnt(0)
	s_barrier
	s_setprio 1
	s_waitcnt lgkmcnt(0)
	v_mfma_f32_16x16x32_bf16 v[126:129], v[152:155], v[186:189], v[126:129]
	v_mfma_f32_16x16x32_bf16 v[122:125], v[160:163], v[186:189], v[122:125]
	v_mfma_f32_16x16x32_bf16 v[106:109], v[160:163], v[194:197], v[106:109]
	v_mfma_f32_16x16x32_bf16 v[114:117], v[152:155], v[194:197], v[114:117]
	v_mfma_f32_16x16x32_bf16 v[98:101], v[152:155], v[202:205], v[98:101]
	v_mfma_f32_16x16x32_bf16 v[90:93], v[160:163], v[202:205], v[90:93]
	v_mfma_f32_16x16x32_bf16 v[74:77], v[160:163], v[210:213], v[74:77]
	v_mfma_f32_16x16x32_bf16 v[82:85], v[152:155], v[210:213], v[82:85]
	v_mfma_f32_16x16x32_bf16 v[126:129], v[156:159], v[190:193], v[126:129]
	v_mfma_f32_16x16x32_bf16 v[122:125], v[164:167], v[190:193], v[122:125]
	v_mfma_f32_16x16x32_bf16 v[106:109], v[164:167], v[198:201], v[106:109]
	v_mfma_f32_16x16x32_bf16 v[114:117], v[156:159], v[198:201], v[114:117]
	v_mfma_f32_16x16x32_bf16 v[98:101], v[156:159], v[206:209], v[98:101]
	v_mfma_f32_16x16x32_bf16 v[90:93], v[164:167], v[206:209], v[90:93]
	v_mfma_f32_16x16x32_bf16 v[74:77], v[164:167], v[214:217], v[74:77]
	v_mfma_f32_16x16x32_bf16 v[82:85], v[156:159], v[214:217], v[82:85]
	s_setprio 0
	s_setprio 1
	v_mfma_f32_16x16x32_bf16 v[118:121], v[168:171], v[186:189], v[118:121]
	v_mfma_f32_16x16x32_bf16 v[110:113], v[178:181], v[186:189], v[110:113]
	v_mfma_f32_16x16x32_bf16 v[94:97], v[178:181], v[194:197], v[94:97]
	v_mfma_f32_16x16x32_bf16 v[102:105], v[168:171], v[194:197], v[102:105]
	v_mfma_f32_16x16x32_bf16 v[86:89], v[168:171], v[202:205], v[86:89]
	v_mfma_f32_16x16x32_bf16 v[78:81], v[178:181], v[202:205], v[78:81]
	v_mfma_f32_16x16x32_bf16 v[66:69], v[178:181], v[210:213], v[66:69]
	v_mfma_f32_16x16x32_bf16 v[70:73], v[168:171], v[210:213], v[70:73]
	v_mfma_f32_16x16x32_bf16 v[118:121], v[172:175], v[190:193], v[118:121]
	v_mfma_f32_16x16x32_bf16 v[110:113], v[182:185], v[190:193], v[110:113]
	v_mfma_f32_16x16x32_bf16 v[94:97], v[182:185], v[198:201], v[94:97]
	v_mfma_f32_16x16x32_bf16 v[102:105], v[172:175], v[198:201], v[102:105]
	v_mfma_f32_16x16x32_bf16 v[86:89], v[172:175], v[206:209], v[86:89]
	v_mfma_f32_16x16x32_bf16 v[78:81], v[182:185], v[206:209], v[78:81]
	v_mfma_f32_16x16x32_bf16 v[66:69], v[182:185], v[214:217], v[66:69]
	v_mfma_f32_16x16x32_bf16 v[70:73], v[172:175], v[214:217], v[70:73]
	s_setprio 0
	s_barrier
	s_add_u32 s2, s30, 0x8000
	s_addc_u32 s3, s31, 0
	s_add_i32 s63, s63, s38
	v_lshl_add_u64 v[144:145], s[2:3], 0, v[132:133]
	s_mov_b32 m0, s63
	ds_read_b128 v[186:189], v150 offset:49152
	ds_read_b128 v[190:193], v150 offset:50176
	ds_read_b128 v[194:197], v150 offset:51200
	ds_read_b128 v[198:201], v150 offset:52224
	ds_read_b128 v[202:205], v150 offset:53248
	ds_read_b128 v[206:209], v150 offset:54272
	ds_read_b128 v[210:213], v150 offset:55296
	ds_read_b128 v[214:217], v150 offset:56320
	global_load_lds_dwordx4 v[144:145], off
	s_add_i32 m0, s63, 0x2000
	v_lshl_add_u64 v[144:145], s[2:3], 0, v[136:137]
	s_add_u32 s2, s30, 0xc000
	s_addc_u32 s3, s31, 0
	s_add_i32 s30, s64, s38
	global_load_lds_dwordx4 v[144:145], off
	v_lshl_add_u64 v[144:145], s[2:3], 0, v[132:133]
	s_mov_b32 m0, s30
	s_nop 0
	global_load_lds_dwordx4 v[144:145], off
	v_lshl_add_u64 v[144:145], s[2:3], 0, v[136:137]
	s_add_i32 m0, s30, 0x2000
	s_nop 0
	global_load_lds_dwordx4 v[144:145], off
	v_lshl_add_u64 v[144:145], s[28:29], 0, v[130:131]
	s_mov_b32 m0, s44
	s_nop 0
	global_load_lds_dwordx4 v[144:145], off
	v_lshl_add_u64 v[144:145], s[28:29], 0, v[134:135]
	s_mov_b32 m0, s45
	s_nop 0
	global_load_lds_dwordx4 v[144:145], off
	s_waitcnt vmcnt(8)
	s_waitcnt lgkmcnt(0)
	s_barrier
	s_setprio 1
	s_waitcnt lgkmcnt(0)
	v_mfma_f32_16x16x32_bf16 v[62:65], v[152:155], v[186:189], v[62:65]
	v_mfma_f32_16x16x32_bf16 v[58:61], v[160:163], v[186:189], v[58:61]
	v_mfma_f32_16x16x32_bf16 v[42:45], v[160:163], v[194:197], v[42:45]
	v_mfma_f32_16x16x32_bf16 v[50:53], v[152:155], v[194:197], v[50:53]
	v_mfma_f32_16x16x32_bf16 v[34:37], v[152:155], v[202:205], v[34:37]
	v_mfma_f32_16x16x32_bf16 v[26:29], v[160:163], v[202:205], v[26:29]
	v_mfma_f32_16x16x32_bf16 v[10:13], v[160:163], v[210:213], v[10:13]
	v_mfma_f32_16x16x32_bf16 v[18:21], v[152:155], v[210:213], v[18:21]
	v_mfma_f32_16x16x32_bf16 v[62:65], v[156:159], v[190:193], v[62:65]
	v_mfma_f32_16x16x32_bf16 v[58:61], v[164:167], v[190:193], v[58:61]
	v_mfma_f32_16x16x32_bf16 v[42:45], v[164:167], v[198:201], v[42:45]
	v_mfma_f32_16x16x32_bf16 v[50:53], v[156:159], v[198:201], v[50:53]
	v_mfma_f32_16x16x32_bf16 v[34:37], v[156:159], v[206:209], v[34:37]
	v_mfma_f32_16x16x32_bf16 v[26:29], v[164:167], v[206:209], v[26:29]
	v_mfma_f32_16x16x32_bf16 v[10:13], v[164:167], v[214:217], v[10:13]
	v_mfma_f32_16x16x32_bf16 v[18:21], v[156:159], v[214:217], v[18:21]
	s_setprio 0
	s_setprio 1
	v_mfma_f32_16x16x32_bf16 v[54:57], v[168:171], v[186:189], v[54:57]
	v_mfma_f32_16x16x32_bf16 v[46:49], v[178:181], v[186:189], v[46:49]
	v_mfma_f32_16x16x32_bf16 v[30:33], v[178:181], v[194:197], v[30:33]
	v_mfma_f32_16x16x32_bf16 v[38:41], v[168:171], v[194:197], v[38:41]
	v_mfma_f32_16x16x32_bf16 v[22:25], v[168:171], v[202:205], v[22:25]
	v_mfma_f32_16x16x32_bf16 v[14:17], v[178:181], v[202:205], v[14:17]
	v_mfma_f32_16x16x32_bf16 v[2:5], v[178:181], v[210:213], v[2:5]
	v_mfma_f32_16x16x32_bf16 v[6:9], v[168:171], v[210:213], v[6:9]
	v_mfma_f32_16x16x32_bf16 v[54:57], v[172:175], v[190:193], v[54:57]
	v_mfma_f32_16x16x32_bf16 v[46:49], v[182:185], v[190:193], v[46:49]
	v_mfma_f32_16x16x32_bf16 v[30:33], v[182:185], v[198:201], v[30:33]
	v_mfma_f32_16x16x32_bf16 v[38:41], v[172:175], v[198:201], v[38:41]
	v_mfma_f32_16x16x32_bf16 v[22:25], v[172:175], v[206:209], v[22:25]
	v_mfma_f32_16x16x32_bf16 v[14:17], v[182:185], v[206:209], v[14:17]
	v_mfma_f32_16x16x32_bf16 v[2:5], v[182:185], v[214:217], v[2:5]
	v_mfma_f32_16x16x32_bf16 v[6:9], v[172:175], v[214:217], v[6:9]
	s_setprio 0
	s_barrier
	s_add_i32 s62, s62, 2
	s_add_u32 s26, s26, 0x10000
	s_addc_u32 s27, s27, 0
	s_add_u32 s60, s60, 0x10000
	s_addc_u32 s61, s61, 0
	s_cmp_gt_u32 s62, 41
	s_cbranch_scc0 .LBB0_1444
	s_branch .Lpk1444_exit
.LBB0_1444:
	ds_read_b128 v[152:155], v148
	ds_read_b128 v[156:159], v148 offset:1024
	ds_read_b128 v[160:163], v148 offset:2048
	ds_read_b128 v[164:167], v148 offset:3072
	ds_read_b128 v[168:171], v149
	ds_read_b128 v[172:175], v149 offset:1024
	ds_read_b128 v[178:181], v149 offset:2048
	ds_read_b128 v[182:185], v149 offset:3072
	s_add_u32 s2, s26, 0x4000
	s_addc_u32 s3, s27, 0
	s_cmp_eq_u32 s62, 40
	s_cselect_b32 s2, s57, s2
	s_cselect_b32 s3, s56, s3
	s_cselect_b32 s31, s58, s61
	s_cselect_b32 s30, s59, s60
	s_add_u32 s28, s2, 0x8000
	s_addc_u32 s29, s3, 0
	v_lshl_add_u64 v[144:145], s[26:27], 0, v[138:139]
	s_add_i32 m0, s39, 0xc000
	ds_read_b128 v[186:189], v150
	ds_read_b128 v[190:193], v150 offset:1024
	ds_read_b128 v[194:197], v150 offset:2048
	ds_read_b128 v[198:201], v150 offset:3072
	ds_read_b128 v[202:205], v150 offset:4096
	ds_read_b128 v[206:209], v150 offset:5120
	ds_read_b128 v[210:213], v150 offset:6144
	ds_read_b128 v[214:217], v150 offset:7168
	global_load_lds_dwordx4 v[144:145], off
	v_lshl_add_u64 v[144:145], s[26:27], 0, v[140:141]
	s_add_i32 m0, s39, 0xe000
	s_nop 0
	global_load_lds_dwordx4 v[144:145], off
	s_waitcnt vmcnt(8)
	s_waitcnt lgkmcnt(0)
	s_barrier
	s_setprio 1
	s_waitcnt lgkmcnt(0)
	v_mfma_f32_16x16x32_bf16 v[126:129], v[152:155], v[186:189], v[126:129]
	v_mfma_f32_16x16x32_bf16 v[122:125], v[160:163], v[186:189], v[122:125]
	v_mfma_f32_16x16x32_bf16 v[106:109], v[160:163], v[194:197], v[106:109]
	v_mfma_f32_16x16x32_bf16 v[114:117], v[152:155], v[194:197], v[114:117]
	v_mfma_f32_16x16x32_bf16 v[98:101], v[152:155], v[202:205], v[98:101]
	v_mfma_f32_16x16x32_bf16 v[90:93], v[160:163], v[202:205], v[90:93]
	v_mfma_f32_16x16x32_bf16 v[74:77], v[160:163], v[210:213], v[74:77]
	v_mfma_f32_16x16x32_bf16 v[82:85], v[152:155], v[210:213], v[82:85]
	v_mfma_f32_16x16x32_bf16 v[126:129], v[156:159], v[190:193], v[126:129]
	v_mfma_f32_16x16x32_bf16 v[122:125], v[164:167], v[190:193], v[122:125]
	v_mfma_f32_16x16x32_bf16 v[106:109], v[164:167], v[198:201], v[106:109]
	v_mfma_f32_16x16x32_bf16 v[114:117], v[156:159], v[198:201], v[114:117]
	v_mfma_f32_16x16x32_bf16 v[98:101], v[156:159], v[206:209], v[98:101]
	v_mfma_f32_16x16x32_bf16 v[90:93], v[164:167], v[206:209], v[90:93]
	v_mfma_f32_16x16x32_bf16 v[74:77], v[164:167], v[214:217], v[74:77]
	v_mfma_f32_16x16x32_bf16 v[82:85], v[156:159], v[214:217], v[82:85]
	s_setprio 0
	s_setprio 1
	v_mfma_f32_16x16x32_bf16 v[118:121], v[168:171], v[186:189], v[118:121]
	v_mfma_f32_16x16x32_bf16 v[110:113], v[178:181], v[186:189], v[110:113]
	v_mfma_f32_16x16x32_bf16 v[94:97], v[178:181], v[194:197], v[94:97]
	v_mfma_f32_16x16x32_bf16 v[102:105], v[168:171], v[194:197], v[102:105]
	v_mfma_f32_16x16x32_bf16 v[86:89], v[168:171], v[202:205], v[86:89]
	v_mfma_f32_16x16x32_bf16 v[78:81], v[178:181], v[202:205], v[78:81]
	v_mfma_f32_16x16x32_bf16 v[66:69], v[178:181], v[210:213], v[66:69]
	v_mfma_f32_16x16x32_bf16 v[70:73], v[168:171], v[210:213], v[70:73]
	v_mfma_f32_16x16x32_bf16 v[118:121], v[172:175], v[190:193], v[118:121]
	v_mfma_f32_16x16x32_bf16 v[110:113], v[182:185], v[190:193], v[110:113]
	v_mfma_f32_16x16x32_bf16 v[94:97], v[182:185], v[198:201], v[94:97]
	v_mfma_f32_16x16x32_bf16 v[102:105], v[172:175], v[198:201], v[102:105]
	v_mfma_f32_16x16x32_bf16 v[86:89], v[172:175], v[206:209], v[86:89]
	v_mfma_f32_16x16x32_bf16 v[78:81], v[182:185], v[206:209], v[78:81]
	v_mfma_f32_16x16x32_bf16 v[66:69], v[182:185], v[214:217], v[66:69]
	v_mfma_f32_16x16x32_bf16 v[70:73], v[172:175], v[214:217], v[70:73]
	s_setprio 0
	s_barrier
	s_add_i32 s63, s46, s38
	v_lshl_add_u64 v[144:145], s[30:31], 0, v[132:133]
	s_mov_b32 m0, s63
	ds_read_b128 v[186:189], v150 offset:16384
	ds_read_b128 v[190:193], v150 offset:17408
	ds_read_b128 v[194:197], v150 offset:18432
	ds_read_b128 v[198:201], v150 offset:19456
	ds_read_b128 v[202:205], v150 offset:20480
	ds_read_b128 v[206:209], v150 offset:21504
	ds_read_b128 v[210:213], v150 offset:22528
	ds_read_b128 v[214:217], v150 offset:23552
	global_load_lds_dwordx4 v[144:145], off
	s_add_i32 m0, s63, 0x2000
	s_add_u32 s64, s30, 0x4000
	v_lshl_add_u64 v[144:145], s[30:31], 0, v[136:137]
	s_addc_u32 s65, s31, 0
	s_add_i32 s63, s47, s38
	global_load_lds_dwordx4 v[144:145], off
	v_lshl_add_u64 v[144:145], s[64:65], 0, v[132:133]
	s_mov_b32 m0, s63
	s_nop 0
	global_load_lds_dwordx4 v[144:145], off
	v_lshl_add_u64 v[144:145], s[64:65], 0, v[136:137]
	s_add_i32 m0, s63, 0x2000
	s_nop 0
	global_load_lds_dwordx4 v[144:145], off
	v_lshl_add_u64 v[144:145], s[2:3], 0, v[130:131]
	s_mov_b32 m0, s39
	s_nop 0
	global_load_lds_dwordx4 v[144:145], off
	v_lshl_add_u64 v[144:145], s[2:3], 0, v[134:135]
	s_mov_b32 m0, s40
	s_nop 0
	global_load_lds_dwordx4 v[144:145], off
	s_waitcnt vmcnt(8)
	s_waitcnt lgkmcnt(0)
	s_barrier
	s_setprio 1
	s_waitcnt lgkmcnt(0)
	v_mfma_f32_16x16x32_bf16 v[62:65], v[152:155], v[186:189], v[62:65]
	v_mfma_f32_16x16x32_bf16 v[58:61], v[160:163], v[186:189], v[58:61]
	v_mfma_f32_16x16x32_bf16 v[42:45], v[160:163], v[194:197], v[42:45]
	v_mfma_f32_16x16x32_bf16 v[50:53], v[152:155], v[194:197], v[50:53]
	v_mfma_f32_16x16x32_bf16 v[34:37], v[152:155], v[202:205], v[34:37]
	v_mfma_f32_16x16x32_bf16 v[26:29], v[160:163], v[202:205], v[26:29]
	v_mfma_f32_16x16x32_bf16 v[10:13], v[160:163], v[210:213], v[10:13]
	v_mfma_f32_16x16x32_bf16 v[18:21], v[152:155], v[210:213], v[18:21]
	v_mfma_f32_16x16x32_bf16 v[62:65], v[156:159], v[190:193], v[62:65]
	v_mfma_f32_16x16x32_bf16 v[58:61], v[164:167], v[190:193], v[58:61]
	v_mfma_f32_16x16x32_bf16 v[42:45], v[164:167], v[198:201], v[42:45]
	v_mfma_f32_16x16x32_bf16 v[50:53], v[156:159], v[198:201], v[50:53]
	v_mfma_f32_16x16x32_bf16 v[34:37], v[156:159], v[206:209], v[34:37]
	v_mfma_f32_16x16x32_bf16 v[26:29], v[164:167], v[206:209], v[26:29]
	v_mfma_f32_16x16x32_bf16 v[10:13], v[164:167], v[214:217], v[10:13]
	v_mfma_f32_16x16x32_bf16 v[18:21], v[156:159], v[214:217], v[18:21]
	s_setprio 0
	s_setprio 1
	v_mfma_f32_16x16x32_bf16 v[54:57], v[168:171], v[186:189], v[54:57]
	v_mfma_f32_16x16x32_bf16 v[46:49], v[178:181], v[186:189], v[46:49]
	v_mfma_f32_16x16x32_bf16 v[30:33], v[178:181], v[194:197], v[30:33]
	v_mfma_f32_16x16x32_bf16 v[38:41], v[168:171], v[194:197], v[38:41]
	v_mfma_f32_16x16x32_bf16 v[22:25], v[168:171], v[202:205], v[22:25]
	v_mfma_f32_16x16x32_bf16 v[14:17], v[178:181], v[202:205], v[14:17]
	v_mfma_f32_16x16x32_bf16 v[2:5], v[178:181], v[210:213], v[2:5]
	v_mfma_f32_16x16x32_bf16 v[6:9], v[168:171], v[210:213], v[6:9]
	v_mfma_f32_16x16x32_bf16 v[54:57], v[172:175], v[190:193], v[54:57]
	v_mfma_f32_16x16x32_bf16 v[46:49], v[182:185], v[190:193], v[46:49]
	v_mfma_f32_16x16x32_bf16 v[30:33], v[182:185], v[198:201], v[30:33]
	v_mfma_f32_16x16x32_bf16 v[38:41], v[172:175], v[198:201], v[38:41]
	v_mfma_f32_16x16x32_bf16 v[22:25], v[172:175], v[206:209], v[22:25]
	v_mfma_f32_16x16x32_bf16 v[14:17], v[182:185], v[206:209], v[14:17]
	v_mfma_f32_16x16x32_bf16 v[2:5], v[182:185], v[214:217], v[2:5]
	v_mfma_f32_16x16x32_bf16 v[6:9], v[172:175], v[214:217], v[6:9]
	s_setprio 0
	s_barrier
	s_add_i32 s63, 0, 0x18000
	v_add_u32_e32 v144, s63, v146
	s_add_i32 s64, 0, 0x1c000
	ds_read_b128 v[152:155], v144
	ds_read_b128 v[156:159], v144 offset:1024
	ds_read_b128 v[160:163], v144 offset:2048
	ds_read_b128 v[164:167], v144 offset:3072
	v_add_u32_e32 v144, s64, v146
	ds_read_b128 v[168:171], v144
	ds_read_b128 v[172:175], v144 offset:1024
	ds_read_b128 v[178:181], v144 offset:2048
	ds_read_b128 v[182:185], v144 offset:3072
	s_add_u32 s2, s2, 0x4000
	s_addc_u32 s3, s3, 0
	s_mov_b32 m0, s41
	v_lshl_add_u64 v[144:145], s[2:3], 0, v[130:131]
	ds_read_b128 v[186:189], v150 offset:32768
	ds_read_b128 v[190:193], v150 offset:33792
	ds_read_b128 v[194:197], v150 offset:34816
	ds_read_b128 v[198:201], v150 offset:35840
	ds_read_b128 v[202:205], v150 offset:36864
	ds_read_b128 v[206:209], v150 offset:37888
	ds_read_b128 v[210:213], v150 offset:38912
	ds_read_b128 v[214:217], v150 offset:39936
	global_load_lds_dwordx4 v[144:145], off
	v_lshl_add_u64 v[144:145], s[2:3], 0, v[134:135]
	s_mov_b32 m0, s42
	s_nop 0
	global_load_lds_dwordx4 v[144:145], off
	s_waitcnt vmcnt(8)
	s_waitcnt lgkmcnt(0)
	s_barrier
	s_setprio 1
	s_waitcnt lgkmcnt(0)
	v_mfma_f32_16x16x32_bf16 v[126:129], v[152:155], v[186:189], v[126:129]
	v_mfma_f32_16x16x32_bf16 v[122:125], v[160:163], v[186:189], v[122:125]
	v_mfma_f32_16x16x32_bf16 v[106:109], v[160:163], v[194:197], v[106:109]
	v_mfma_f32_16x16x32_bf16 v[114:117], v[152:155], v[194:197], v[114:117]
	v_mfma_f32_16x16x32_bf16 v[98:101], v[152:155], v[202:205], v[98:101]
	v_mfma_f32_16x16x32_bf16 v[90:93], v[160:163], v[202:205], v[90:93]
	v_mfma_f32_16x16x32_bf16 v[74:77], v[160:163], v[210:213], v[74:77]
	v_mfma_f32_16x16x32_bf16 v[82:85], v[152:155], v[210:213], v[82:85]
	v_mfma_f32_16x16x32_bf16 v[126:129], v[156:159], v[190:193], v[126:129]
	v_mfma_f32_16x16x32_bf16 v[122:125], v[164:167], v[190:193], v[122:125]
	v_mfma_f32_16x16x32_bf16 v[106:109], v[164:167], v[198:201], v[106:109]
	v_mfma_f32_16x16x32_bf16 v[114:117], v[156:159], v[198:201], v[114:117]
	v_mfma_f32_16x16x32_bf16 v[98:101], v[156:159], v[206:209], v[98:101]
	v_mfma_f32_16x16x32_bf16 v[90:93], v[164:167], v[206:209], v[90:93]
	v_mfma_f32_16x16x32_bf16 v[74:77], v[164:167], v[214:217], v[74:77]
	v_mfma_f32_16x16x32_bf16 v[82:85], v[156:159], v[214:217], v[82:85]
	s_setprio 0
	s_setprio 1
	v_mfma_f32_16x16x32_bf16 v[118:121], v[168:171], v[186:189], v[118:121]
	v_mfma_f32_16x16x32_bf16 v[110:113], v[178:181], v[186:189], v[110:113]
	v_mfma_f32_16x16x32_bf16 v[94:97], v[178:181], v[194:197], v[94:97]
	v_mfma_f32_16x16x32_bf16 v[102:105], v[168:171], v[194:197], v[102:105]
	v_mfma_f32_16x16x32_bf16 v[86:89], v[168:171], v[202:205], v[86:89]
	v_mfma_f32_16x16x32_bf16 v[78:81], v[178:181], v[202:205], v[78:81]
	v_mfma_f32_16x16x32_bf16 v[66:69], v[178:181], v[210:213], v[66:69]
	v_mfma_f32_16x16x32_bf16 v[70:73], v[168:171], v[210:213], v[70:73]
	v_mfma_f32_16x16x32_bf16 v[118:121], v[172:175], v[190:193], v[118:121]
	v_mfma_f32_16x16x32_bf16 v[110:113], v[182:185], v[190:193], v[110:113]
	v_mfma_f32_16x16x32_bf16 v[94:97], v[182:185], v[198:201], v[94:97]
	v_mfma_f32_16x16x32_bf16 v[102:105], v[172:175], v[198:201], v[102:105]
	v_mfma_f32_16x16x32_bf16 v[86:89], v[172:175], v[206:209], v[86:89]
	v_mfma_f32_16x16x32_bf16 v[78:81], v[182:185], v[206:209], v[78:81]
	v_mfma_f32_16x16x32_bf16 v[66:69], v[182:185], v[214:217], v[66:69]
	v_mfma_f32_16x16x32_bf16 v[70:73], v[172:175], v[214:217], v[70:73]
	s_setprio 0
	s_barrier
	s_add_u32 s2, s30, 0x8000
	s_addc_u32 s3, s31, 0
	s_add_i32 s63, s63, s38
	v_lshl_add_u64 v[144:145], s[2:3], 0, v[132:133]
	s_mov_b32 m0, s63
	ds_read_b128 v[186:189], v150 offset:49152
	ds_read_b128 v[190:193], v150 offset:50176
	ds_read_b128 v[194:197], v150 offset:51200
	ds_read_b128 v[198:201], v150 offset:52224
	ds_read_b128 v[202:205], v150 offset:53248
	ds_read_b128 v[206:209], v150 offset:54272
	ds_read_b128 v[210:213], v150 offset:55296
	ds_read_b128 v[214:217], v150 offset:56320
	global_load_lds_dwordx4 v[144:145], off
	s_add_i32 m0, s63, 0x2000
	v_lshl_add_u64 v[144:145], s[2:3], 0, v[136:137]
	s_add_u32 s2, s30, 0xc000
	s_addc_u32 s3, s31, 0
	s_add_i32 s30, s64, s38
	global_load_lds_dwordx4 v[144:145], off
	v_lshl_add_u64 v[144:145], s[2:3], 0, v[132:133]
	s_mov_b32 m0, s30
	s_nop 0
	global_load_lds_dwordx4 v[144:145], off
	v_lshl_add_u64 v[144:145], s[2:3], 0, v[136:137]
	s_add_i32 m0, s30, 0x2000
	s_nop 0
	global_load_lds_dwordx4 v[144:145], off
	v_lshl_add_u64 v[144:145], s[28:29], 0, v[130:131]
	s_mov_b32 m0, s44
	s_nop 0
	global_load_lds_dwordx4 v[144:145], off
	v_lshl_add_u64 v[144:145], s[28:29], 0, v[134:135]
	s_mov_b32 m0, s45
	s_nop 0
	global_load_lds_dwordx4 v[144:145], off
	s_waitcnt vmcnt(8)
	s_waitcnt lgkmcnt(0)
	s_barrier
	s_setprio 1
	s_waitcnt lgkmcnt(0)
	v_mfma_f32_16x16x32_bf16 v[62:65], v[152:155], v[186:189], v[62:65]
	v_mfma_f32_16x16x32_bf16 v[58:61], v[160:163], v[186:189], v[58:61]
	v_mfma_f32_16x16x32_bf16 v[42:45], v[160:163], v[194:197], v[42:45]
	v_mfma_f32_16x16x32_bf16 v[50:53], v[152:155], v[194:197], v[50:53]
	v_mfma_f32_16x16x32_bf16 v[34:37], v[152:155], v[202:205], v[34:37]
	v_mfma_f32_16x16x32_bf16 v[26:29], v[160:163], v[202:205], v[26:29]
	v_mfma_f32_16x16x32_bf16 v[10:13], v[160:163], v[210:213], v[10:13]
	v_mfma_f32_16x16x32_bf16 v[18:21], v[152:155], v[210:213], v[18:21]
	v_mfma_f32_16x16x32_bf16 v[62:65], v[156:159], v[190:193], v[62:65]
	v_mfma_f32_16x16x32_bf16 v[58:61], v[164:167], v[190:193], v[58:61]
	v_mfma_f32_16x16x32_bf16 v[42:45], v[164:167], v[198:201], v[42:45]
	v_mfma_f32_16x16x32_bf16 v[50:53], v[156:159], v[198:201], v[50:53]
	v_mfma_f32_16x16x32_bf16 v[34:37], v[156:159], v[206:209], v[34:37]
	v_mfma_f32_16x16x32_bf16 v[26:29], v[164:167], v[206:209], v[26:29]
	v_mfma_f32_16x16x32_bf16 v[10:13], v[164:167], v[214:217], v[10:13]
	v_mfma_f32_16x16x32_bf16 v[18:21], v[156:159], v[214:217], v[18:21]
	s_setprio 0
	s_setprio 1
	v_mfma_f32_16x16x32_bf16 v[54:57], v[168:171], v[186:189], v[54:57]
	v_mfma_f32_16x16x32_bf16 v[46:49], v[178:181], v[186:189], v[46:49]
	v_mfma_f32_16x16x32_bf16 v[30:33], v[178:181], v[194:197], v[30:33]
	v_mfma_f32_16x16x32_bf16 v[38:41], v[168:171], v[194:197], v[38:41]
	v_mfma_f32_16x16x32_bf16 v[22:25], v[168:171], v[202:205], v[22:25]
	v_mfma_f32_16x16x32_bf16 v[14:17], v[178:181], v[202:205], v[14:17]
	v_mfma_f32_16x16x32_bf16 v[2:5], v[178:181], v[210:213], v[2:5]
	v_mfma_f32_16x16x32_bf16 v[6:9], v[168:171], v[210:213], v[6:9]
	v_mfma_f32_16x16x32_bf16 v[54:57], v[172:175], v[190:193], v[54:57]
	v_mfma_f32_16x16x32_bf16 v[46:49], v[182:185], v[190:193], v[46:49]
	v_mfma_f32_16x16x32_bf16 v[30:33], v[182:185], v[198:201], v[30:33]
	v_mfma_f32_16x16x32_bf16 v[38:41], v[172:175], v[198:201], v[38:41]
	v_mfma_f32_16x16x32_bf16 v[22:25], v[172:175], v[206:209], v[22:25]
	v_mfma_f32_16x16x32_bf16 v[14:17], v[182:185], v[206:209], v[14:17]
	v_mfma_f32_16x16x32_bf16 v[2:5], v[182:185], v[214:217], v[2:5]
	v_mfma_f32_16x16x32_bf16 v[6:9], v[172:175], v[214:217], v[6:9]
	s_setprio 0
	s_barrier
	s_add_i32 s62, s62, 2
	s_add_u32 s26, s26, 0x10000
	s_addc_u32 s27, s27, 0
	s_add_u32 s60, s60, 0x10000
	s_addc_u32 s61, s61, 0
	s_cmp_gt_u32 s62, 41
	s_cbranch_scc0 .LBB0_1444
